# LDS-DMA m0 setup on the scalar unit (one wave base per tile + s_or) instead of a VALU v_readfirstlane per load, in all GEMM tile prologues and K loops; on top of v42
# baseline (speedup 1.0000x reference)
; #define BAR8 __builtin_amdgcn_s_barrier()
; #define G_SS ((float*)(wsp() + OFF_SS))
;     ...
;     STAGE8(SB8(0, 0), Bt, K, bcol, 0); STAGE8(SA8(0, 0), A, lda, brow, 0);
;     STAGE8(SB8(0, 1), Bt, K, bcol + 128, 0); STAGE8(SA8(0, 1), A, lda, brow + 128, 0);
;   }
;   if (wr == 1) BAR8;
; __global__ void __launch_bounds__(512, 2) mega(Params p) {
;     ...
;         const int nt = item >> 6, mt = item & 63;
;         e.ss = G_SS; e.nss = 16; e.inv_n = 1.f / 1024.f; e.out = G_ZB; e.ldo = ZLD;
;         if (!odd) {
;           e.g_a = inp(4) + j * 64; e.g_b = inp(5) + j * 64;
;           gemm_tile<EPI_IN_AB, 256, true>(G_XB, DM, wb + W_IN, DM, mt * 256, nt * 256, e);
.LBB0_188:
	s_and_b32 s0, s25, 63
	s_lshl_b32 s30, s0, 19
	s_and_b32 s0, s24, 0xffffff00
	s_ashr_i32 s1, s0, 31
	s_lshl_b64 s[56:57], s[0:1], 11
	s_mov_b32 s0, 25
	s_ashr_i32 s1, s0, 31
	s_and_b32 s20, s33, 63
	s_lshl_b64 s[0:1], s[0:1], 3
	s_add_u32 s0, s70, s0
	s_addc_u32 s1, s71, s1
	v_readlane_b32 s0, v255, 60
	v_readlane_b32 s1, v255, 61
	s_nop 4
	v_readlane_b32 s12, v254, 35
	s_mov_b32 s31, s12
	v_readlane_b32 s13, v254, 36
	v_readlane_b32 s14, v254, 37
	s_waitcnt lgkmcnt(0)
	s_add_u32 s54, s0, 0xf640000
	s_mov_b32 s0, 25
	s_addc_u32 s55, s1, 0
	s_ashr_i32 s1, s0, 31
	s_lshl_b64 s[0:1], s[0:1], 3
	s_add_u32 s0, s70, s0
	s_addc_u32 s1, s71, s1
	v_readlane_b32 s0, v255, 60
	v_readlane_b32 s1, v255, 61
	s_nop 4
	v_readlane_b32 s15, v254, 38
	s_waitcnt lgkmcnt(0)
	s_add_u32 s50, s0, 0x2000000
	s_addc_u32 s51, s1, 0
	s_lshl_b32 s0, s33, 2
	s_lshl_b32 s36, s20, 8
	s_and_b32 s52, s0, 0xffffff00
	s_andn2_b64 vcc, exec, s[40:41]
	s_mov_b64 s[0:1], -1
	s_cbranch_vccnz .LBB0_238
	s_mov_b32 s0, 4
	s_ashr_i32 s1, s0, 31
	s_lshl_b64 s[0:1], s[0:1], 3
	s_add_u32 s0, s70, s0
	s_addc_u32 s1, s71, s1
	s_mov_b32 s2, 5
	s_load_dwordx2 s[0:1], s[0:1], 0x0
	s_ashr_i32 s3, s2, 31
	s_lshl_b64 s[2:3], s[2:3], 3
	s_add_u32 s2, s70, s2
	s_addc_u32 s3, s71, s3
	s_mov_b32 s4, 25
	s_load_dwordx2 s[2:3], s[2:3], 0x0
	s_ashr_i32 s5, s4, 31
	s_lshl_b64 s[4:5], s[4:5], 3
	s_add_u32 s4, s70, s4
	s_addc_u32 s5, s71, s5
	v_mov_b32_e32 v3, v224
	v_readlane_b32 s12, v255, 60
	v_readlane_b32 s13, v255, 61
	s_nop 4
	s_ashr_i32 s53, s52, 31
	v_bfe_i32 v1, v3, 27, 1
	s_waitcnt vmcnt(10)
	v_lshlrev_b32_e32 v150, 4, v3
	s_nop 0
	v_readfirstlane_b32 s100, v150
	v_lshrrev_b32_e32 v1, 22, v1
	v_add_u32_e32 v1, v150, v1
	v_and_b32_e32 v1, 0xfffffc00, v1
	v_ashrrev_i32_e32 v0, 31, v3
	v_sub_u32_e32 v1, v150, v1
	v_lshrrev_b32_e32 v0, 26, v0
	v_lshrrev_b32_e32 v5, 4, v1
	v_add_u32_e32 v0, v3, v0
	v_bitop3_b32 v5, v5, v1, 32 bitop3:0x6c
	v_ashrrev_i32_e32 v1, 31, v1
	v_ashrrev_i32_e32 v0, 6, v0
	v_lshrrev_b32_e32 v1, 26, v1
	v_lshlrev_b32_e32 v6, 3, v0
	v_add_u32_e32 v1, v5, v1
	v_and_b32_e32 v6, -16, v6
	v_ashrrev_i32_e32 v1, 6, v1
	v_add_u32_e32 v6, v1, v6
	v_mul_i32_i24_e32 v1, 64, v1
	v_lshlrev_b32_e32 v0, 5, v0
	v_sub_u32_e32 v1, v5, v1
	v_mov_b32_e32 v14, 1
	s_waitcnt vmcnt(9)
	v_add_u32_e32 v155, 0x2000, v150
	s_lshl_b64 s[4:5], s[52:53], 11
	v_readlane_b32 s21, v254, 44
	v_and_b32_e32 v0, 32, v0
	v_ashrrev_i16_sdwa v1, v14, sext(v1) dst_sel:DWORD dst_unused:UNUSED_PAD src0_sel:DWORD src1_sel:BYTE_0
	v_ashrrev_i32_e32 v5, 31, v155
	s_add_u32 s4, s21, s4
	v_readlane_b32 s27, v254, 45
	v_add_u32_sdwa v0, v0, sext(v1) dst_sel:DWORD dst_unused:UNUSED_PAD src0_sel:DWORD src1_sel:WORD_0
	v_ashrrev_i32_e32 v7, 31, v6
	v_lshrrev_b32_e32 v5, 22, v5
	s_addc_u32 s5, s27, s5
	v_lshlrev_b64 v[132:133], 11, v[6:7]
	v_ashrrev_i32_e32 v1, 31, v0
	v_add_u32_e32 v5, v155, v5
	v_lshl_add_u64 v[8:9], s[4:5], 0, v[132:133]
	v_lshlrev_b64 v[6:7], 1, v[0:1]
	v_ashrrev_i32_e32 v5, 10, v5
	v_lshl_add_u64 v[10:11], v[8:9], 0, v[6:7]
	v_mul_i32_i24_e32 v8, 0x400, v5
	v_sub_u32_e32 v8, v155, v8
	v_lshrrev_b32_e32 v9, 4, v8
	v_bitop3_b32 v9, v9, v8, 32 bitop3:0x6c
	v_ashrrev_i32_e32 v12, 31, v9
	v_lshrrev_b32_e32 v12, 26, v12
	v_add_u32_e32 v12, v9, v12
	v_lshlrev_b32_e32 v8, 3, v5
	v_ashrrev_i32_e32 v13, 6, v12
	v_and_b32_e32 v12, 0xc0, v12
	v_and_b32_e32 v8, -16, v8
	v_lshlrev_b32_e32 v5, 5, v5
	v_sub_u32_e32 v9, v9, v12
	v_add_u32_e32 v8, v13, v8
	v_and_b32_e32 v5, 32, v5
	v_ashrrev_i16_sdwa v9, v14, sext(v9) dst_sel:DWORD dst_unused:UNUSED_PAD src0_sel:DWORD src1_sel:BYTE_0
	v_add_u32_e32 v151, 0x10000, v150
	v_add_u32_sdwa v134, v5, sext(v9) dst_sel:DWORD dst_unused:UNUSED_PAD src0_sel:DWORD src1_sel:WORD_0
	v_ashrrev_i32_e32 v9, 31, v8
	v_lshlrev_b64 v[136:137], 11, v[8:9]
	s_waitcnt vmcnt(8)
	v_add_u32_e32 v157, 0x12000, v150
	v_mov_b32_e32 v4, v2
	s_or_b32 m0, s100, 0x10000
	v_lshl_add_u64 v[12:13], s[4:5], 0, v[136:137]
	global_load_lds_dwordx4 v[10:11], off
	s_or_b32 m0, s100, 0x12000
	s_lshl_b32 s4, s20, 19
	v_ashrrev_i32_e32 v135, 31, v134
	s_waitcnt lgkmcnt(0)
	s_add_u32 s4, s12, s4
	v_lshlrev_b64 v[8:9], 1, v[134:135]
	s_addc_u32 s5, s13, 0
	v_lshl_add_u64 v[12:13], v[12:13], 0, v[8:9]
	v_lshl_add_u64 v[14:15], s[4:5], 0, v[132:133]
	s_or_b32 s58, s52, 0x80
	global_load_lds_dwordx4 v[12:13], off
	v_lshl_add_u64 v[14:15], v[14:15], 0, v[6:7]
	s_mov_b32 m0, s100
	s_ashr_i32 s59, s58, 31
	global_load_lds_dwordx4 v[14:15], off
	s_or_b32 m0, s100, 0x2000
	s_lshl_b64 s[14:15], s[58:59], 11
	s_add_u32 s14, s21, s14
	v_lshl_add_u64 v[16:17], s[4:5], 0, v[136:137]
	s_addc_u32 s15, s27, s15
	v_add_u32_e32 v160, 0x14000, v150
	v_lshl_add_u64 v[16:17], v[16:17], 0, v[8:9]
	v_lshl_add_u64 v[18:19], s[14:15], 0, v[132:133]
	v_add_u32_e32 v161, 0x16000, v150
	global_load_lds_dwordx4 v[16:17], off
	v_lshl_add_u64 v[18:19], v[18:19], 0, v[6:7]
	s_or_b32 m0, s100, 0x14000
	v_lshl_add_u64 v[20:21], s[14:15], 0, v[136:137]
	global_load_lds_dwordx4 v[18:19], off
	s_or_b32 m0, s100, 0x16000
	s_add_u32 s14, s4, 0x40000
	s_addc_u32 s15, s5, 0
	v_add_u32_e32 v162, 0x4000, v150
	v_lshl_add_u64 v[20:21], v[20:21], 0, v[8:9]
	v_lshl_add_u64 v[22:23], s[14:15], 0, v[132:133]
	global_load_lds_dwordx4 v[20:21], off
	v_lshl_add_u64 v[22:23], v[22:23], 0, v[6:7]
	s_or_b32 m0, s100, 0x4000
	v_add_u32_e32 v163, 0x6000, v150
	global_load_lds_dwordx4 v[22:23], off
	v_lshl_add_u64 v[22:23], s[14:15], 0, v[136:137]
	v_lshl_add_u64 v[22:23], v[22:23], 0, v[8:9]
	s_or_b32 m0, s100, 0x6000
	v_ashrrev_i32_e32 v5, 8, v3
	global_load_lds_dwordx4 v[22:23], off
	v_cmp_eq_u32_e32 vcc, 1, v5
	s_and_saveexec_b64 s[14:15], vcc
	s_cbranch_execz .LBB0_191
	s_barrier
; #define WAIT_V8(n) asm volatile("s_waitcnt vmcnt(" #n ")" ::: "memory")
; #define BAR8 __builtin_amdgcn_s_barrier()
;     ...
;   const int brow = m0, bcol = n0;
;   const int wid = t >> 6, lane = t & 63, wr = wid >> 2, wc = wid & 3, fr = lane & 15, fq = lane >> 4;
;   f32x4 acc[2][2][4][2];
;   {
;     float zinit = 0.f;
;     asm volatile("" : "+v"(zinit));
; #pragma unroll
;     for (int a = 0; a < 2; ++a)
; #pragma unroll
;       for (int b = 0; b < 2; ++b)
; #pragma unroll
;         for (int m = 0; m < 4; ++m)
; #pragma unroll
;           for (int n = 0; n < 2; ++n)
; #pragma unroll
;             for (int j = 0; j < 4; ++j) acc[a][b][m][n][j] = zinit;
;   }
;   bf16x8 At[4][2], B0[2][2], B1[2][2];
;   const int nt = K / 64;
;   if (!pre) {
;     STAGE8(SB8(0, 0), Bt, K, bcol, 0); STAGE8(SA8(0, 0), A, lda, brow, 0);
;     STAGE8(SB8(0, 1), Bt, K, bcol + 128, 0); STAGE8(SA8(0, 1), A, lda, brow + 128, 0);
;   }
;   if (wr == 1) BAR8;
;   WAIT_V8(4); BAR8;
;   STAGE8(SB8(1, 0), Bt, K, bcol, 1); STAGE8(SA8(1, 0), A, lda, brow, 1); STAGE8(SB8(1, 1), Bt, K, bcol + 128, 1);
;   WAIT_V8(6); BAR8;
.LBB0_191:
	s_or_b64 exec, exec, s[14:15]
	v_add_u32_e32 v164, 0x18000, v150
	s_mov_b64 s[60:61], 0x80
	v_add_u32_e32 v165, 0x1a000, v150
	v_lshl_add_u64 v[10:11], v[10:11], 0, s[60:61]
	s_or_b32 m0, s100, 0x18000
	v_add_u32_e32 v166, 0x8000, v150
	s_waitcnt vmcnt(4)
	s_barrier
	global_load_lds_dwordx4 v[10:11], off
	v_lshl_add_u64 v[10:11], v[12:13], 0, s[60:61]
	s_or_b32 m0, s100, 0x1a000
	v_add_u32_e32 v167, 0xa000, v150
	global_load_lds_dwordx4 v[10:11], off
	v_lshl_add_u64 v[10:11], v[14:15], 0, s[60:61]
	s_or_b32 m0, s100, 0x8000
	v_add_u32_e32 v168, 0x1c000, v150
	global_load_lds_dwordx4 v[10:11], off
	v_lshl_add_u64 v[10:11], v[16:17], 0, s[60:61]
	s_or_b32 m0, s100, 0xa000
	v_add_u32_e32 v170, 0x1e000, v150
	global_load_lds_dwordx4 v[10:11], off
	v_lshl_add_u64 v[10:11], v[18:19], 0, s[60:61]
	s_or_b32 m0, s100, 0x1c000
	s_nop 0
	global_load_lds_dwordx4 v[10:11], off
	v_lshl_add_u64 v[10:11], v[20:21], 0, s[60:61]
	s_or_b32 m0, s100, 0x1e000
	v_and_b32_e32 v147, 15, v3
	global_load_lds_dwordx4 v[10:11], off
	v_bfe_u32 v148, v3, 4, 2
	v_lshlrev_b32_e32 v10, 4, v148
	v_lshlrev_b32_e32 v11, 6, v147
	v_lshlrev_b32_e32 v14, 2, v3
	v_or_b32_e32 v13, v10, v11
	v_and_b32_e32 v14, 32, v14
	s_mov_b32 s14, 0x10000
	v_bitop3_b32 v16, v13, s14, v14 bitop3:0xde
	s_mov_b32 s14, 0x14000
	v_bitop3_b32 v15, v10, v14, v11 bitop3:0x36
	v_bitop3_b32 v17, v13, s14, v14 bitop3:0xde
	s_mov_b32 s14, 0x18000
	v_lshlrev_b32_e32 v11, 6, v3
	v_bitop3_b32 v18, v13, s14, v14 bitop3:0xde
	s_mov_b32 s14, 0x1c000
	v_and_b32_e32 v11, 0x3c0, v11
	v_bitop3_b32 v13, v13, s14, v14 bitop3:0xde
	v_bitop3_b32 v14, v11, v14, v10 bitop3:0x36
	v_lshl_add_u64 v[10:11], s[30:31], 0, v[136:137]
	v_lshl_add_u64 v[10:11], v[10:11], 0, v[8:9]
	v_lshl_add_u64 v[138:139], s[12:13], 0, v[10:11]
	v_lshl_add_u64 v[10:11], s[30:31], 0, v[132:133]
	v_lshl_add_u64 v[10:11], v[10:11], 0, v[6:7]
	v_lshl_add_u64 v[140:141], s[12:13], 0, v[10:11]
	v_lshl_add_u64 v[10:11], s[56:57], 0, v[132:133]
	v_lshl_add_u64 v[6:7], v[10:11], 0, v[6:7]
	v_bfe_u32 v146, v3, 6, 2
	s_waitcnt vmcnt(6)
	v_lshlrev_b32_e32 v149, 6, v5
	v_lshlrev_b32_e32 v5, 13, v5
	v_lshl_add_u64 v[142:143], s[46:47], 0, v[6:7]
	v_lshl_add_u64 v[6:7], s[56:57], 0, v[136:137]
	v_lshlrev_b32_e32 v12, 12, v146
	v_or_b32_e32 v19, 0x800, v5
	v_or_b32_e32 v20, 0x1000, v5
	v_or_b32_e32 v21, 0x1800, v5
	v_lshl_add_u64 v[6:7], v[6:7], 0, v[8:9]
	v_lshl_add_u64 v[144:145], s[46:47], 0, v[6:7]
	s_mov_b32 s14, -2
	s_mov_b64 s[12:13], 0
	v_add_u32_e32 v173, v16, v12
	v_add_u32_e32 v156, v15, v5
	v_add_u32_e32 v154, v14, v19
	v_add_u32_e32 v153, v14, v20
	v_add_u32_e32 v152, v14, v21
	v_add_u32_e32 v172, 0xc000, v150
	v_add_u32_e32 v171, 0xe000, v150
	v_add_u32_e32 v169, v17, v12
	v_add_u32_e32 v159, v18, v12
	v_add_u32_e32 v158, v13, v12
	v_mov_b32_e32 v5, v4
	v_mov_b64_e32 v[6:7], v[4:5]
	v_mov_b64_e32 v[8:9], v[4:5]
	v_mov_b64_e32 v[10:11], v[4:5]
	v_mov_b64_e32 v[12:13], v[4:5]
	v_mov_b64_e32 v[14:15], v[4:5]
	v_mov_b64_e32 v[16:17], v[4:5]
	v_mov_b64_e32 v[18:19], v[4:5]
	v_mov_b64_e32 v[20:21], v[4:5]
	v_mov_b64_e32 v[22:23], v[4:5]
	v_mov_b64_e32 v[24:25], v[4:5]
	v_mov_b64_e32 v[26:27], v[4:5]
	v_mov_b64_e32 v[28:29], v[4:5]
	v_mov_b64_e32 v[30:31], v[4:5]
	v_mov_b64_e32 v[32:33], v[4:5]
	v_mov_b64_e32 v[34:35], v[4:5]
	v_mov_b64_e32 v[36:37], v[4:5]
	v_mov_b64_e32 v[38:39], v[4:5]
	v_mov_b64_e32 v[40:41], v[4:5]
	v_mov_b64_e32 v[42:43], v[4:5]
	v_mov_b64_e32 v[44:45], v[4:5]
	v_mov_b64_e32 v[46:47], v[4:5]
	v_mov_b64_e32 v[48:49], v[4:5]
	v_mov_b64_e32 v[50:51], v[4:5]
	v_mov_b64_e32 v[52:53], v[4:5]
	v_mov_b64_e32 v[54:55], v[4:5]
	v_mov_b64_e32 v[56:57], v[4:5]
	v_mov_b64_e32 v[58:59], v[4:5]
	v_mov_b64_e32 v[60:61], v[4:5]
	v_mov_b64_e32 v[62:63], v[4:5]
	v_mov_b64_e32 v[64:65], v[4:5]
	v_mov_b64_e32 v[66:67], v[4:5]
	v_mov_b64_e32 v[68:69], v[4:5]
	v_mov_b64_e32 v[70:71], v[4:5]
	v_mov_b64_e32 v[72:73], v[4:5]
	v_mov_b64_e32 v[74:75], v[4:5]
	v_mov_b64_e32 v[76:77], v[4:5]
	v_mov_b64_e32 v[78:79], v[4:5]
	v_mov_b64_e32 v[80:81], v[4:5]
	v_mov_b64_e32 v[82:83], v[4:5]
	v_mov_b64_e32 v[84:85], v[4:5]
	v_mov_b64_e32 v[86:87], v[4:5]
	v_mov_b64_e32 v[88:89], v[4:5]
	v_mov_b64_e32 v[90:91], v[4:5]
	v_mov_b64_e32 v[92:93], v[4:5]
	v_mov_b64_e32 v[94:95], v[4:5]
	v_mov_b64_e32 v[96:97], v[4:5]
	v_mov_b64_e32 v[98:99], v[4:5]
	v_mov_b64_e32 v[100:101], v[4:5]
	v_mov_b64_e32 v[102:103], v[4:5]
	v_mov_b64_e32 v[104:105], v[4:5]
	v_mov_b64_e32 v[106:107], v[4:5]
	v_mov_b64_e32 v[108:109], v[4:5]
	v_mov_b64_e32 v[110:111], v[4:5]
	v_mov_b64_e32 v[112:113], v[4:5]
	v_mov_b64_e32 v[114:115], v[4:5]
	v_mov_b64_e32 v[116:117], v[4:5]
	v_mov_b64_e32 v[118:119], v[4:5]
	v_mov_b64_e32 v[120:121], v[4:5]
	v_mov_b64_e32 v[122:123], v[4:5]
	v_mov_b64_e32 v[124:125], v[4:5]
	v_mov_b64_e32 v[126:127], v[4:5]
	v_mov_b64_e32 v[128:129], v[4:5]
	v_mov_b64_e32 v[130:131], v[4:5]
	s_mov_b64 s[60:61], 0xc000100
	s_mov_b64 s[62:63], 0xc040100
	s_mov_b64 s[64:65], 0xc000180
	s_mov_b64 s[66:67], 0xc040180
	s_barrier
; #define LDA8(dst, b, h) _Pragma("unroll") for (int m = 0; m < 4; ++m) _Pragma("unroll") for (int k = 0; k < 2; ++k) \
;     dst[m][k] = *(const bf16x8*)((const char*)SA8(b, h) + lds_byte8(wr * 64 + m * 16 + fr, k * 32 + fq * 8))
; #define LDB8(dst, b, h) _Pragma("unroll") for (int n = 0; n < 2; ++n) _Pragma("unroll") for (int k = 0; k < 2; ++k) \
;     dst[n][k] = *(const bf16x8*)((const char*)SB8(b, h) + lds_byte8(wc * 32 + n * 16 + fr, k * 32 + fq * 8))
; #define WAIT_V8(n) asm volatile("s_waitcnt vmcnt(" #n ")" ::: "memory")
; #define WAIT_L8(n) asm volatile("s_waitcnt lgkmcnt(" #n ")" ::: "memory")
; #define BAR8 __builtin_amdgcn_s_barrier()
; #define SCHED8 __builtin_amdgcn_sched_barrier(0)
;     ...
;     LDB8(B0, 0, 0); SCHED8; LDA8(At, 0, 0); STAGE8(SA8(1, 1), A, lda, brow + 128, tt + 1);
;     WAIT_L8(8); BAR8; WAIT_L8(0); MMA8(0, 0, At, B0); BAR8; SCHED8;
;     LDB8(B1, 0, 1); STAGE8(SB8(0, 0), Bt, K, bcol, tt + 2);
;     BAR8; WAIT_L8(0); MMA8(0, 1, At, B1); BAR8;
;     LDA8(At, 0, 1); STAGE8(SA8(0, 0), A, lda, brow, tt + 2);
;     BAR8; WAIT_L8(0); MMA8(1, 0, At, B0); BAR8; SCHED8;
;     STAGE8(SB8(0, 1), Bt, K, bcol + 128, tt + 2);
;     WAIT_V8(6); BAR8; MMA8(1, 1, At, B1); BAR8;
.LBB0_192:
	ds_read_b128 v[174:177], v173
	ds_read_b128 v[178:181], v173 offset:1024
	ds_read_b128 v[182:185], v173 offset:2048
	ds_read_b128 v[186:189], v173 offset:3072
	v_lshl_add_u64 v[222:223], v[140:141], 0, s[12:13]
	v_lshl_add_u64 v[226:227], v[222:223], 0, s[34:35]
	s_or_b32 m0, s100, 0xc000
	ds_read_b128 v[190:193], v156
	ds_read_b128 v[194:197], v156 offset:1024
	ds_read_b128 v[198:201], v154
	ds_read_b128 v[202:205], v154 offset:1024
	ds_read_b128 v[206:209], v153
	ds_read_b128 v[210:213], v153 offset:1024
	ds_read_b128 v[214:217], v152
	ds_read_b128 v[218:221], v152 offset:1024
	global_load_lds_dwordx4 v[226:227], off
	v_lshl_add_u64 v[226:227], v[138:139], 0, s[12:13]
	v_lshl_add_u64 v[228:229], v[226:227], 0, s[34:35]
	s_or_b32 m0, s100, 0xe000
	s_nop 0
	global_load_lds_dwordx4 v[228:229], off
	s_waitcnt lgkmcnt(8)
	s_barrier
	s_waitcnt lgkmcnt(0)
	s_waitcnt lgkmcnt(0)
	v_mfma_f32_16x16x32_f16 v[128:131], v[190:193], v[174:177], v[128:131]
	v_mfma_f32_16x16x32_f16 v[124:127], v[190:193], v[182:185], v[124:127]
	v_mfma_f32_16x16x32_f16 v[120:123], v[198:201], v[174:177], v[120:123]
	v_mfma_f32_16x16x32_f16 v[116:119], v[198:201], v[182:185], v[116:119]
	v_mfma_f32_16x16x32_f16 v[112:115], v[206:209], v[174:177], v[112:115]
	v_mfma_f32_16x16x32_f16 v[108:111], v[206:209], v[182:185], v[108:111]
	v_mfma_f32_16x16x32_f16 v[104:107], v[214:217], v[174:177], v[104:107]
	v_mfma_f32_16x16x32_f16 v[100:103], v[214:217], v[182:185], v[100:103]
	v_mfma_f32_16x16x32_f16 v[128:131], v[194:197], v[178:181], v[128:131]
	v_mfma_f32_16x16x32_f16 v[124:127], v[194:197], v[186:189], v[124:127]
	v_mfma_f32_16x16x32_f16 v[120:123], v[202:205], v[178:181], v[120:123]
	v_mfma_f32_16x16x32_f16 v[116:119], v[202:205], v[186:189], v[116:119]
	v_mfma_f32_16x16x32_f16 v[112:115], v[210:213], v[178:181], v[112:115]
	v_mfma_f32_16x16x32_f16 v[108:111], v[210:213], v[186:189], v[108:111]
	v_mfma_f32_16x16x32_f16 v[104:107], v[218:221], v[178:181], v[104:107]
	v_mfma_f32_16x16x32_f16 v[100:103], v[218:221], v[186:189], v[100:103]
	s_barrier
	v_lshl_add_u64 v[228:229], v[142:143], 0, s[12:13]
	v_lshl_add_u64 v[236:237], v[228:229], 0, s[60:61]
	s_or_b32 m0, s100, 0x10000
	ds_read_b128 v[238:241], v169
	ds_read_b128 v[242:245], v169 offset:1024
	ds_read_b128 v[246:249], v169 offset:2048
	ds_read_b128 v[230:233], v169 offset:3072
	global_load_lds_dwordx4 v[236:237], off
	v_lshl_add_u64 v[236:237], v[144:145], 0, s[12:13]
	v_lshl_add_u64 v[250:251], v[236:237], 0, s[60:61]
	s_or_b32 m0, s100, 0x12000
	s_nop 0
	global_load_lds_dwordx4 v[250:251], off
	s_barrier
	s_waitcnt lgkmcnt(0)
	s_waitcnt lgkmcnt(0)
	v_mfma_f32_16x16x32_f16 v[96:99], v[190:193], v[238:241], v[96:99]
	v_mfma_f32_16x16x32_f16 v[92:95], v[190:193], v[246:249], v[92:95]
	v_mfma_f32_16x16x32_f16 v[88:91], v[198:201], v[238:241], v[88:91]
	v_mfma_f32_16x16x32_f16 v[84:87], v[198:201], v[246:249], v[84:87]
	v_mfma_f32_16x16x32_f16 v[80:83], v[206:209], v[238:241], v[80:83]
	v_mfma_f32_16x16x32_f16 v[76:79], v[206:209], v[246:249], v[76:79]
	v_mfma_f32_16x16x32_f16 v[72:75], v[214:217], v[238:241], v[72:75]
	v_mfma_f32_16x16x32_f16 v[68:71], v[214:217], v[246:249], v[68:71]
	v_mfma_f32_16x16x32_f16 v[96:99], v[194:197], v[242:245], v[96:99]
	v_mfma_f32_16x16x32_f16 v[92:95], v[194:197], v[230:233], v[92:95]
	v_mfma_f32_16x16x32_f16 v[88:91], v[202:205], v[242:245], v[88:91]
	v_mfma_f32_16x16x32_f16 v[84:87], v[202:205], v[230:233], v[84:87]
	v_mfma_f32_16x16x32_f16 v[80:83], v[210:213], v[242:245], v[80:83]
	v_mfma_f32_16x16x32_f16 v[76:79], v[210:213], v[230:233], v[76:79]
	v_mfma_f32_16x16x32_f16 v[72:75], v[218:221], v[242:245], v[72:75]
	v_mfma_f32_16x16x32_f16 v[68:71], v[218:221], v[230:233], v[68:71]
	v_lshl_add_u64 v[250:251], v[222:223], 0, s[10:11]
	s_mov_b32 m0, s100
	s_barrier
	ds_read_b128 v[190:193], v156 offset:16384
	ds_read_b128 v[194:197], v156 offset:17408
	ds_read_b128 v[198:201], v154 offset:16384
	ds_read_b128 v[202:205], v154 offset:17408
	ds_read_b128 v[206:209], v153 offset:16384
	ds_read_b128 v[210:213], v153 offset:17408
	ds_read_b128 v[214:217], v152 offset:16384
	ds_read_b128 v[218:221], v152 offset:17408
	global_load_lds_dwordx4 v[250:251], off
	v_lshl_add_u64 v[250:251], v[226:227], 0, s[10:11]
	s_or_b32 m0, s100, 0x2000
	s_nop 0
	global_load_lds_dwordx4 v[250:251], off
	s_barrier
	s_waitcnt lgkmcnt(0)
	s_waitcnt lgkmcnt(0)
	v_mfma_f32_16x16x32_f16 v[64:67], v[190:193], v[174:177], v[64:67]
	v_mfma_f32_16x16x32_f16 v[60:63], v[190:193], v[182:185], v[60:63]
	v_mfma_f32_16x16x32_f16 v[56:59], v[198:201], v[174:177], v[56:59]
	v_mfma_f32_16x16x32_f16 v[52:55], v[198:201], v[182:185], v[52:55]
	v_mfma_f32_16x16x32_f16 v[48:51], v[206:209], v[174:177], v[48:51]
	v_mfma_f32_16x16x32_f16 v[44:47], v[206:209], v[182:185], v[44:47]
	v_mfma_f32_16x16x32_f16 v[40:43], v[214:217], v[174:177], v[40:43]
	v_mfma_f32_16x16x32_f16 v[36:39], v[214:217], v[182:185], v[36:39]
	v_mfma_f32_16x16x32_f16 v[64:67], v[194:197], v[178:181], v[64:67]
	v_mfma_f32_16x16x32_f16 v[60:63], v[194:197], v[186:189], v[60:63]
	v_mfma_f32_16x16x32_f16 v[56:59], v[202:205], v[178:181], v[56:59]
	v_mfma_f32_16x16x32_f16 v[52:55], v[202:205], v[186:189], v[52:55]
	v_mfma_f32_16x16x32_f16 v[48:51], v[210:213], v[178:181], v[48:51]
	v_mfma_f32_16x16x32_f16 v[44:47], v[210:213], v[186:189], v[44:47]
	v_mfma_f32_16x16x32_f16 v[40:43], v[218:221], v[178:181], v[40:43]
	v_mfma_f32_16x16x32_f16 v[36:39], v[218:221], v[186:189], v[36:39]
	s_barrier
	v_lshl_add_u64 v[174:175], v[228:229], 0, s[62:63]
	s_or_b32 m0, s100, 0x14000
	s_nop 0
	global_load_lds_dwordx4 v[174:175], off
	v_lshl_add_u64 v[174:175], v[236:237], 0, s[62:63]
	s_or_b32 m0, s100, 0x16000
	s_nop 0
	global_load_lds_dwordx4 v[174:175], off
	s_waitcnt vmcnt(6)
	s_barrier
; #define LDA8(dst, b, h) _Pragma("unroll") for (int m = 0; m < 4; ++m) _Pragma("unroll") for (int k = 0; k < 2; ++k) \
;     dst[m][k] = *(const bf16x8*)((const char*)SA8(b, h) + lds_byte8(wr * 64 + m * 16 + fr, k * 32 + fq * 8))
; #define LDB8(dst, b, h) _Pragma("unroll") for (int n = 0; n < 2; ++n) _Pragma("unroll") for (int k = 0; k < 2; ++k) \
;     dst[n][k] = *(const bf16x8*)((const char*)SB8(b, h) + lds_byte8(wc * 32 + n * 16 + fr, k * 32 + fq * 8))
; #define WAIT_V8(n) asm volatile("s_waitcnt vmcnt(" #n ")" ::: "memory")
; #define WAIT_L8(n) asm volatile("s_waitcnt lgkmcnt(" #n ")" ::: "memory")
; #define BAR8 __builtin_amdgcn_s_barrier()
; #define SCHED8 __builtin_amdgcn_sched_barrier(0)
;     ...
;     WAIT_V8(6); BAR8; MMA8(1, 1, At, B1); BAR8;
;     LDB8(B0, 1, 0); SCHED8; LDA8(At, 1, 0); STAGE8(SA8(0, 1), A, lda, brow + 128, tt + 2);
;     WAIT_L8(8); BAR8; WAIT_L8(0); MMA8(0, 0, At, B0); BAR8; SCHED8;
;     LDB8(B1, 1, 1); STAGE8(SB8(1, 0), Bt, K, bcol, tt + 3);
;     BAR8; WAIT_L8(0); MMA8(0, 1, At, B1); BAR8;
;     LDA8(At, 1, 1); STAGE8(SA8(1, 0), A, lda, brow, tt + 3);
	v_mfma_f32_16x16x32_f16 v[32:35], v[190:193], v[238:241], v[32:35]
	v_mfma_f32_16x16x32_f16 v[28:31], v[190:193], v[246:249], v[28:31]
	v_mfma_f32_16x16x32_f16 v[24:27], v[198:201], v[238:241], v[24:27]
	v_mfma_f32_16x16x32_f16 v[20:23], v[198:201], v[246:249], v[20:23]
	v_mfma_f32_16x16x32_f16 v[16:19], v[206:209], v[238:241], v[16:19]
	v_mfma_f32_16x16x32_f16 v[12:15], v[206:209], v[246:249], v[12:15]
	v_mfma_f32_16x16x32_f16 v[8:11], v[214:217], v[238:241], v[8:11]
	v_mfma_f32_16x16x32_f16 v[4:7], v[214:217], v[246:249], v[4:7]
	v_mfma_f32_16x16x32_f16 v[32:35], v[194:197], v[242:245], v[32:35]
	v_mfma_f32_16x16x32_f16 v[28:31], v[194:197], v[230:233], v[28:31]
	v_mfma_f32_16x16x32_f16 v[24:27], v[202:205], v[242:245], v[24:27]
	v_mfma_f32_16x16x32_f16 v[20:23], v[202:205], v[230:233], v[20:23]
	v_mfma_f32_16x16x32_f16 v[16:19], v[210:213], v[242:245], v[16:19]
	v_mfma_f32_16x16x32_f16 v[12:15], v[210:213], v[230:233], v[12:15]
	v_mfma_f32_16x16x32_f16 v[8:11], v[218:221], v[242:245], v[8:11]
	v_mfma_f32_16x16x32_f16 v[4:7], v[218:221], v[230:233], v[4:7]
	s_barrier
	ds_read_b128 v[174:177], v159
	ds_read_b128 v[178:181], v159 offset:1024
	ds_read_b128 v[182:185], v159 offset:2048
	ds_read_b128 v[186:189], v159 offset:3072
	v_lshl_add_u64 v[230:231], v[222:223], 0, s[18:19]
	s_or_b32 m0, s100, 0x4000
	ds_read_b128 v[190:193], v156 offset:32768
	ds_read_b128 v[194:197], v156 offset:33792
	ds_read_b128 v[198:201], v154 offset:32768
	ds_read_b128 v[202:205], v154 offset:33792
	ds_read_b128 v[206:209], v153 offset:32768
	ds_read_b128 v[210:213], v153 offset:33792
	ds_read_b128 v[214:217], v152 offset:32768
	ds_read_b128 v[218:221], v152 offset:33792
	global_load_lds_dwordx4 v[230:231], off
	v_lshl_add_u64 v[230:231], v[226:227], 0, s[18:19]
	s_or_b32 m0, s100, 0x6000
	s_nop 0
	global_load_lds_dwordx4 v[230:231], off
	s_waitcnt lgkmcnt(8)
	s_barrier
	s_waitcnt lgkmcnt(0)
	s_waitcnt lgkmcnt(0)
	v_mfma_f32_16x16x32_f16 v[128:131], v[190:193], v[174:177], v[128:131]
	v_mfma_f32_16x16x32_f16 v[124:127], v[190:193], v[182:185], v[124:127]
	v_mfma_f32_16x16x32_f16 v[120:123], v[198:201], v[174:177], v[120:123]
	v_mfma_f32_16x16x32_f16 v[116:119], v[198:201], v[182:185], v[116:119]
	v_mfma_f32_16x16x32_f16 v[112:115], v[206:209], v[174:177], v[112:115]
	v_mfma_f32_16x16x32_f16 v[108:111], v[206:209], v[182:185], v[108:111]
	v_mfma_f32_16x16x32_f16 v[104:107], v[214:217], v[174:177], v[104:107]
	v_mfma_f32_16x16x32_f16 v[100:103], v[214:217], v[182:185], v[100:103]
	v_mfma_f32_16x16x32_f16 v[128:131], v[194:197], v[178:181], v[128:131]
	v_mfma_f32_16x16x32_f16 v[124:127], v[194:197], v[186:189], v[124:127]
	v_mfma_f32_16x16x32_f16 v[120:123], v[202:205], v[178:181], v[120:123]
	v_mfma_f32_16x16x32_f16 v[116:119], v[202:205], v[186:189], v[116:119]
	v_mfma_f32_16x16x32_f16 v[112:115], v[210:213], v[178:181], v[112:115]
	v_mfma_f32_16x16x32_f16 v[108:111], v[210:213], v[186:189], v[108:111]
	v_mfma_f32_16x16x32_f16 v[104:107], v[218:221], v[178:181], v[104:107]
	v_mfma_f32_16x16x32_f16 v[100:103], v[218:221], v[186:189], v[100:103]
	s_barrier
	v_lshl_add_u64 v[250:251], v[228:229], 0, s[64:65]
	s_or_b32 m0, s100, 0x18000
	ds_read_b128 v[230:233], v158
	ds_read_b128 v[238:241], v158 offset:1024
	ds_read_b128 v[242:245], v158 offset:2048
	ds_read_b128 v[246:249], v158 offset:3072
	global_load_lds_dwordx4 v[250:251], off
	v_lshl_add_u64 v[250:251], v[236:237], 0, s[64:65]
	s_or_b32 m0, s100, 0x1a000
	s_nop 0
	global_load_lds_dwordx4 v[250:251], off
	s_barrier
	s_waitcnt lgkmcnt(0)
	s_waitcnt lgkmcnt(0)
	v_mfma_f32_16x16x32_f16 v[96:99], v[190:193], v[230:233], v[96:99]
	v_mfma_f32_16x16x32_f16 v[92:95], v[190:193], v[242:245], v[92:95]
	v_mfma_f32_16x16x32_f16 v[88:91], v[198:201], v[230:233], v[88:91]
	v_mfma_f32_16x16x32_f16 v[84:87], v[198:201], v[242:245], v[84:87]
	v_mfma_f32_16x16x32_f16 v[80:83], v[206:209], v[230:233], v[80:83]
	v_mfma_f32_16x16x32_f16 v[76:79], v[206:209], v[242:245], v[76:79]
	v_mfma_f32_16x16x32_f16 v[72:75], v[214:217], v[230:233], v[72:75]
	v_mfma_f32_16x16x32_f16 v[68:71], v[214:217], v[242:245], v[68:71]
	v_mfma_f32_16x16x32_f16 v[96:99], v[194:197], v[238:241], v[96:99]
	v_mfma_f32_16x16x32_f16 v[92:95], v[194:197], v[246:249], v[92:95]
	v_mfma_f32_16x16x32_f16 v[88:91], v[202:205], v[238:241], v[88:91]
	v_mfma_f32_16x16x32_f16 v[84:87], v[202:205], v[246:249], v[84:87]
	v_mfma_f32_16x16x32_f16 v[80:83], v[210:213], v[238:241], v[80:83]
	v_mfma_f32_16x16x32_f16 v[76:79], v[210:213], v[246:249], v[76:79]
	v_mfma_f32_16x16x32_f16 v[72:75], v[218:221], v[238:241], v[72:75]
	v_mfma_f32_16x16x32_f16 v[68:71], v[218:221], v[246:249], v[68:71]
	v_lshl_add_u64 v[222:223], v[222:223], 0, s[22:23]
	s_or_b32 m0, s100, 0x8000
	s_barrier
	ds_read_b128 v[190:193], v156 offset:49152
	ds_read_b128 v[194:197], v156 offset:50176
	ds_read_b128 v[198:201], v154 offset:49152
	ds_read_b128 v[202:205], v154 offset:50176
	ds_read_b128 v[206:209], v153 offset:49152
	ds_read_b128 v[210:213], v153 offset:50176
	ds_read_b128 v[214:217], v152 offset:49152
	ds_read_b128 v[218:221], v152 offset:50176
	global_load_lds_dwordx4 v[222:223], off
	v_lshl_add_u64 v[222:223], v[226:227], 0, s[22:23]
	s_or_b32 m0, s100, 0xa000
	s_nop 0
	global_load_lds_dwordx4 v[222:223], off
	s_barrier
; #define LDA8(dst, b, h) _Pragma("unroll") for (int m = 0; m < 4; ++m) _Pragma("unroll") for (int k = 0; k < 2; ++k) \
;     dst[m][k] = *(const bf16x8*)((const char*)SA8(b, h) + lds_byte8(wr * 64 + m * 16 + fr, k * 32 + fq * 8))
; #define LDB8(dst, b, h) _Pragma("unroll") for (int n = 0; n < 2; ++n) _Pragma("unroll") for (int k = 0; k < 2; ++k) \
;     dst[n][k] = *(const bf16x8*)((const char*)SB8(b, h) + lds_byte8(wc * 32 + n * 16 + fr, k * 32 + fq * 8))
; #define WAIT_V8(n) asm volatile("s_waitcnt vmcnt(" #n ")" ::: "memory")
; #define WAIT_L8(n) asm volatile("s_waitcnt lgkmcnt(" #n ")" ::: "memory")
; #define BAR8 __builtin_amdgcn_s_barrier()
; #define SCHED8 __builtin_amdgcn_sched_barrier(0)
;     ...
;     BAR8; WAIT_L8(0); MMA8(1, 0, At, B0); BAR8; SCHED8;
;     STAGE8(SB8(1, 1), Bt, K, bcol + 128, tt + 3);
;     WAIT_V8(6); BAR8; MMA8(1, 1, At, B1); BAR8;
;   }
;   { LDB8(B0, 0, 0); LDA8(At, 0, 0); STAGE8(SA8(1, 1), A, lda, brow + 128, nt - 1);
;     BAR8; WAIT_L8(0); MMA8(0, 0, At, B0); BAR8;
;     LDB8(B1, 0, 1); BAR8; WAIT_L8(0); MMA8(0, 1, At, B1); BAR8;
	s_waitcnt lgkmcnt(0)
	s_waitcnt lgkmcnt(0)
	v_mfma_f32_16x16x32_f16 v[64:67], v[190:193], v[174:177], v[64:67]
	v_mfma_f32_16x16x32_f16 v[60:63], v[190:193], v[182:185], v[60:63]
	v_mfma_f32_16x16x32_f16 v[56:59], v[198:201], v[174:177], v[56:59]
	v_mfma_f32_16x16x32_f16 v[52:55], v[198:201], v[182:185], v[52:55]
	v_mfma_f32_16x16x32_f16 v[48:51], v[206:209], v[174:177], v[48:51]
	v_mfma_f32_16x16x32_f16 v[44:47], v[206:209], v[182:185], v[44:47]
	v_mfma_f32_16x16x32_f16 v[40:43], v[214:217], v[174:177], v[40:43]
	v_mfma_f32_16x16x32_f16 v[36:39], v[214:217], v[182:185], v[36:39]
	v_mfma_f32_16x16x32_f16 v[64:67], v[194:197], v[178:181], v[64:67]
	v_mfma_f32_16x16x32_f16 v[60:63], v[194:197], v[186:189], v[60:63]
	v_mfma_f32_16x16x32_f16 v[56:59], v[202:205], v[178:181], v[56:59]
	v_mfma_f32_16x16x32_f16 v[52:55], v[202:205], v[186:189], v[52:55]
	v_mfma_f32_16x16x32_f16 v[48:51], v[210:213], v[178:181], v[48:51]
	v_mfma_f32_16x16x32_f16 v[44:47], v[210:213], v[186:189], v[44:47]
	v_mfma_f32_16x16x32_f16 v[40:43], v[218:221], v[178:181], v[40:43]
	v_mfma_f32_16x16x32_f16 v[36:39], v[218:221], v[186:189], v[36:39]
	s_barrier
	v_lshl_add_u64 v[174:175], v[228:229], 0, s[66:67]
	s_or_b32 m0, s100, 0x1c000
	s_nop 0
	global_load_lds_dwordx4 v[174:175], off
	v_lshl_add_u64 v[174:175], v[236:237], 0, s[66:67]
	s_or_b32 m0, s100, 0x1e000
	s_nop 0
	global_load_lds_dwordx4 v[174:175], off
	s_waitcnt vmcnt(6)
	s_barrier
	v_mfma_f32_16x16x32_f16 v[32:35], v[190:193], v[230:233], v[32:35]
	v_mfma_f32_16x16x32_f16 v[28:31], v[190:193], v[242:245], v[28:31]
	v_mfma_f32_16x16x32_f16 v[24:27], v[198:201], v[230:233], v[24:27]
	v_mfma_f32_16x16x32_f16 v[20:23], v[198:201], v[242:245], v[20:23]
	v_mfma_f32_16x16x32_f16 v[16:19], v[206:209], v[230:233], v[16:19]
	v_mfma_f32_16x16x32_f16 v[12:15], v[206:209], v[242:245], v[12:15]
	v_mfma_f32_16x16x32_f16 v[8:11], v[214:217], v[230:233], v[8:11]
	v_mfma_f32_16x16x32_f16 v[4:7], v[214:217], v[242:245], v[4:7]
	v_mfma_f32_16x16x32_f16 v[32:35], v[194:197], v[238:241], v[32:35]
	v_mfma_f32_16x16x32_f16 v[28:31], v[194:197], v[246:249], v[28:31]
	v_mfma_f32_16x16x32_f16 v[24:27], v[202:205], v[238:241], v[24:27]
	v_mfma_f32_16x16x32_f16 v[20:23], v[202:205], v[246:249], v[20:23]
	v_mfma_f32_16x16x32_f16 v[16:19], v[210:213], v[238:241], v[16:19]
	v_mfma_f32_16x16x32_f16 v[12:15], v[210:213], v[246:249], v[12:15]
	v_mfma_f32_16x16x32_f16 v[8:11], v[218:221], v[238:241], v[8:11]
	v_mfma_f32_16x16x32_f16 v[4:7], v[218:221], v[246:249], v[4:7]
	s_add_i32 s14, s14, 2
	s_add_u32 s12, s12, 0x100
	s_addc_u32 s13, s13, 0
	s_cmp_lt_u32 s14, 12
	s_barrier
	s_cbranch_scc1 .LBB0_192
	s_add_u32 s4, s4, 0x40780
	s_addc_u32 s5, s5, 0
	v_lshl_add_u64 v[132:133], s[4:5], 0, v[132:133]
	v_lshl_add_u64 v[0:1], v[0:1], 1, v[132:133]
	s_or_b32 m0, s100, 0xc000
	ds_read_b128 v[138:141], v173
	ds_read_b128 v[142:145], v173 offset:1024
	ds_read_b128 v[160:163], v173 offset:2048
	ds_read_b128 v[164:167], v173 offset:3072
	ds_read_b128 v[174:177], v156
	ds_read_b128 v[178:181], v156 offset:1024
	ds_read_b128 v[182:185], v154
	ds_read_b128 v[186:189], v154 offset:1024
	ds_read_b128 v[190:193], v153
	ds_read_b128 v[194:197], v153 offset:1024
	ds_read_b128 v[198:201], v152
	ds_read_b128 v[202:205], v152 offset:1024
	global_load_lds_dwordx4 v[0:1], off
	v_lshl_add_u64 v[0:1], s[4:5], 0, v[136:137]
	v_lshl_add_u64 v[0:1], v[134:135], 1, v[0:1]
	s_or_b32 m0, s100, 0xe000
	s_nop 0
	global_load_lds_dwordx4 v[0:1], off
	s_barrier
	s_waitcnt lgkmcnt(0)
	s_waitcnt lgkmcnt(0)
	v_mfma_f32_16x16x32_f16 v[128:131], v[174:177], v[138:141], v[128:131]
	v_mfma_f32_16x16x32_f16 v[124:127], v[174:177], v[160:163], v[124:127]
	v_mfma_f32_16x16x32_f16 v[120:123], v[182:185], v[138:141], v[120:123]
	v_mfma_f32_16x16x32_f16 v[112:115], v[190:193], v[138:141], v[112:115]
	v_mfma_f32_16x16x32_f16 v[128:131], v[178:181], v[142:145], v[128:131]
	v_mfma_f32_16x16x32_f16 v[124:127], v[178:181], v[164:167], v[124:127]
	v_mfma_f32_16x16x32_f16 v[120:123], v[186:189], v[142:145], v[120:123]
	v_mfma_f32_16x16x32_f16 v[116:119], v[182:185], v[160:163], v[116:119]
	v_mfma_f32_16x16x32_f16 v[112:115], v[194:197], v[142:145], v[112:115]
	v_mfma_f32_16x16x32_f16 v[108:111], v[190:193], v[160:163], v[108:111]
	v_mfma_f32_16x16x32_f16 v[104:107], v[198:201], v[138:141], v[104:107]
	v_mfma_f32_16x16x32_f16 v[100:103], v[198:201], v[160:163], v[100:103]
	v_mfma_f32_16x16x32_f16 v[132:135], v[186:189], v[164:167], v[116:119]
	v_mfma_f32_16x16x32_f16 v[170:173], v[194:197], v[164:167], v[108:111]
	v_mfma_f32_16x16x32_f16 v[206:209], v[202:205], v[142:145], v[104:107]
	v_mfma_f32_16x16x32_f16 v[210:213], v[202:205], v[164:167], v[100:103]
	s_barrier
	s_nop 1
	ds_read_b128 v[100:103], v169
	ds_read_b128 v[104:107], v169 offset:1024
	ds_read_b128 v[108:111], v169 offset:2048
	ds_read_b128 v[116:119], v169 offset:3072
	s_barrier
	s_waitcnt lgkmcnt(0)
	s_waitcnt lgkmcnt(0)
	v_mfma_f32_16x16x32_f16 v[80:83], v[190:193], v[100:103], v[80:83]
	v_mfma_f32_16x16x32_f16 v[76:79], v[190:193], v[108:111], v[76:79]
	v_mfma_f32_16x16x32_f16 v[72:75], v[198:201], v[100:103], v[72:75]
	v_mfma_f32_16x16x32_f16 v[68:71], v[198:201], v[108:111], v[68:71]
	v_mfma_f32_16x16x32_f16 v[96:99], v[174:177], v[100:103], v[96:99]
	v_mfma_f32_16x16x32_f16 v[92:95], v[174:177], v[108:111], v[92:95]
	v_mfma_f32_16x16x32_f16 v[88:91], v[182:185], v[100:103], v[88:91]
	v_mfma_f32_16x16x32_f16 v[84:87], v[182:185], v[108:111], v[84:87]
	v_mfma_f32_16x16x32_f16 v[80:83], v[194:197], v[104:107], v[80:83]
	v_mfma_f32_16x16x32_f16 v[76:79], v[194:197], v[116:119], v[76:79]
	v_mfma_f32_16x16x32_f16 v[72:75], v[202:205], v[104:107], v[72:75]
	v_mfma_f32_16x16x32_f16 v[68:71], v[202:205], v[116:119], v[68:71]
	v_mfma_f32_16x16x32_f16 v[214:217], v[178:181], v[104:107], v[96:99]
	v_mfma_f32_16x16x32_f16 v[174:177], v[178:181], v[116:119], v[92:95]
	v_mfma_f32_16x16x32_f16 v[178:181], v[186:189], v[104:107], v[88:91]
	v_mfma_f32_16x16x32_f16 v[182:185], v[186:189], v[116:119], v[84:87]
	s_barrier
; #define LDA8(dst, b, h) _Pragma("unroll") for (int m = 0; m < 4; ++m) _Pragma("unroll") for (int k = 0; k < 2; ++k) \
;     dst[m][k] = *(const bf16x8*)((const char*)SA8(b, h) + lds_byte8(wr * 64 + m * 16 + fr, k * 32 + fq * 8))
; #define LDB8(dst, b, h) _Pragma("unroll") for (int n = 0; n < 2; ++n) _Pragma("unroll") for (int k = 0; k < 2; ++k) \
;     dst[n][k] = *(const bf16x8*)((const char*)SB8(b, h) + lds_byte8(wc * 32 + n * 16 + fr, k * 32 + fq * 8))
; #define WAIT_V8(n) asm volatile("s_waitcnt vmcnt(" #n ")" ::: "memory")
; #define WAIT_L8(n) asm volatile("s_waitcnt lgkmcnt(" #n ")" ::: "memory")
; #define BAR8 __builtin_amdgcn_s_barrier()
;     ...
;     LDA8(At, 0, 1); WAIT_V8(4); BAR8; WAIT_L8(0); MMA8(1, 0, At, B0); MMA8(1, 1, At, B1); BAR8; }
;   { LDB8(B0, 1, 0); LDA8(At, 1, 0); WAIT_V8(2); BAR8; WAIT_L8(0); MMA8(0, 0, At, B0); BAR8;
	s_nop 0
	ds_read_b128 v[84:87], v156 offset:16384
	ds_read_b128 v[88:91], v156 offset:17408
	ds_read_b128 v[92:95], v154 offset:16384
	ds_read_b128 v[96:99], v154 offset:17408
	ds_read_b128 v[186:189], v153 offset:16384
	ds_read_b128 v[190:193], v153 offset:17408
	ds_read_b128 v[194:197], v152 offset:16384
	ds_read_b128 v[198:201], v152 offset:17408
	s_waitcnt vmcnt(4)
	s_barrier
	s_waitcnt lgkmcnt(0)
	s_waitcnt lgkmcnt(0)
	v_mfma_f32_16x16x32_f16 v[64:67], v[84:87], v[138:141], v[64:67]
	v_mfma_f32_16x16x32_f16 v[60:63], v[84:87], v[160:163], v[60:63]
	v_mfma_f32_16x16x32_f16 v[56:59], v[92:95], v[138:141], v[56:59]
	v_mfma_f32_16x16x32_f16 v[52:55], v[92:95], v[160:163], v[52:55]
	v_mfma_f32_16x16x32_f16 v[48:51], v[186:189], v[138:141], v[48:51]
	v_mfma_f32_16x16x32_f16 v[44:47], v[186:189], v[160:163], v[44:47]
	v_mfma_f32_16x16x32_f16 v[64:67], v[88:91], v[142:145], v[64:67]
	v_mfma_f32_16x16x32_f16 v[60:63], v[88:91], v[164:167], v[60:63]
	v_mfma_f32_16x16x32_f16 v[56:59], v[96:99], v[142:145], v[56:59]
	v_mfma_f32_16x16x32_f16 v[52:55], v[96:99], v[164:167], v[52:55]
	v_mfma_f32_16x16x32_f16 v[48:51], v[190:193], v[142:145], v[48:51]
	v_mfma_f32_16x16x32_f16 v[44:47], v[190:193], v[164:167], v[44:47]
	v_mfma_f32_16x16x32_f16 v[40:43], v[194:197], v[138:141], v[40:43]
	v_mfma_f32_16x16x32_f16 v[36:39], v[194:197], v[160:163], v[36:39]
	v_mfma_f32_16x16x32_f16 v[136:139], v[198:201], v[142:145], v[40:43]
	v_mfma_f32_16x16x32_f16 v[140:143], v[198:201], v[164:167], v[36:39]
	v_mfma_f32_16x16x32_f16 v[32:35], v[84:87], v[100:103], v[32:35]
	v_mfma_f32_16x16x32_f16 v[28:31], v[84:87], v[108:111], v[28:31]
	v_mfma_f32_16x16x32_f16 v[24:27], v[92:95], v[100:103], v[24:27]
	v_mfma_f32_16x16x32_f16 v[20:23], v[92:95], v[108:111], v[20:23]
	v_mfma_f32_16x16x32_f16 v[16:19], v[186:189], v[100:103], v[16:19]
	v_mfma_f32_16x16x32_f16 v[12:15], v[186:189], v[108:111], v[12:15]
	v_mfma_f32_16x16x32_f16 v[8:11], v[194:197], v[100:103], v[8:11]
	v_mfma_f32_16x16x32_f16 v[4:7], v[194:197], v[108:111], v[4:7]
	v_mfma_f32_16x16x32_f16 v[160:163], v[88:91], v[104:107], v[32:35]
	v_mfma_f32_16x16x32_f16 v[164:167], v[88:91], v[116:119], v[28:31]
	v_mfma_f32_16x16x32_f16 v[202:205], v[96:99], v[104:107], v[24:27]
	v_mfma_f32_16x16x32_f16 v[218:221], v[96:99], v[116:119], v[20:23]
	v_mfma_f32_16x16x32_f16 v[230:233], v[190:193], v[104:107], v[16:19]
	v_mfma_f32_16x16x32_f16 v[186:189], v[190:193], v[116:119], v[12:15]
	v_mfma_f32_16x16x32_f16 v[190:193], v[198:201], v[104:107], v[8:11]
	v_mfma_f32_16x16x32_f16 v[194:197], v[198:201], v[116:119], v[4:7]
	s_barrier
	s_nop 0
	ds_read_b128 v[4:7], v159
	ds_read_b128 v[8:11], v159 offset:1024
	ds_read_b128 v[198:201], v159 offset:2048
	ds_read_b128 v[238:241], v159 offset:3072
	ds_read_b128 v[16:19], v156 offset:32768
	ds_read_b128 v[20:23], v156 offset:33792
	ds_read_b128 v[24:27], v154 offset:32768
	ds_read_b128 v[32:35], v154 offset:33792
	ds_read_b128 v[36:39], v153 offset:32768
	ds_read_b128 v[40:43], v153 offset:33792
	ds_read_b128 v[242:245], v152 offset:32768
	ds_read_b128 v[246:249], v152 offset:33792
	s_waitcnt vmcnt(2)
	s_barrier
	s_waitcnt lgkmcnt(0)
	s_waitcnt lgkmcnt(0)
	v_mfma_f32_16x16x32_f16 v[12:15], v[16:19], v[4:7], v[128:131]
	v_mfma_f32_16x16x32_f16 v[104:107], v[20:23], v[8:11], v[12:15]
	v_mfma_f32_16x16x32_f16 v[12:15], v[16:19], v[198:201], v[124:127]
	v_mfma_f32_16x16x32_f16 v[116:119], v[20:23], v[238:241], v[12:15]
	v_mfma_f32_16x16x32_f16 v[12:15], v[24:27], v[4:7], v[120:123]
	v_mfma_f32_16x16x32_f16 v[100:103], v[32:35], v[8:11], v[12:15]
	v_mfma_f32_16x16x32_f16 v[12:15], v[24:27], v[198:201], v[132:135]
	v_mfma_f32_16x16x32_f16 v[108:111], v[32:35], v[238:241], v[12:15]
	v_mfma_f32_16x16x32_f16 v[12:15], v[36:39], v[4:7], v[112:115]
	v_mfma_f32_16x16x32_f16 v[92:95], v[40:43], v[8:11], v[12:15]
	v_mfma_f32_16x16x32_f16 v[12:15], v[36:39], v[198:201], v[170:173]
	v_mfma_f32_16x16x32_f16 v[96:99], v[40:43], v[238:241], v[12:15]
	v_mfma_f32_16x16x32_f16 v[12:15], v[242:245], v[4:7], v[206:209]
	v_mfma_f32_16x16x32_f16 v[84:87], v[246:249], v[8:11], v[12:15]
	v_mfma_f32_16x16x32_f16 v[12:15], v[242:245], v[198:201], v[210:213]
	v_mfma_f32_16x16x32_f16 v[88:91], v[246:249], v[238:241], v[12:15]
	s_barrier
; DI int tid_opaque() { int t = threadIdx.x; asm volatile("" : "+v"(t)); return t; }
; #define LDA8(dst, b, h) _Pragma("unroll") for (int m = 0; m < 4; ++m) _Pragma("unroll") for (int k = 0; k < 2; ++k) \
;     dst[m][k] = *(const bf16x8*)((const char*)SA8(b, h) + lds_byte8(wr * 64 + m * 16 + fr, k * 32 + fq * 8))
; #define LDB8(dst, b, h) _Pragma("unroll") for (int n = 0; n < 2; ++n) _Pragma("unroll") for (int k = 0; k < 2; ++k) \
;     dst[n][k] = *(const bf16x8*)((const char*)SB8(b, h) + lds_byte8(wc * 32 + n * 16 + fr, k * 32 + fq * 8))
; #define WAIT_V8(n) asm volatile("s_waitcnt vmcnt(" #n ")" ::: "memory")
; #define WAIT_L8(n) asm volatile("s_waitcnt lgkmcnt(" #n ")" ::: "memory")
; #define BAR8 __builtin_amdgcn_s_barrier()
;     ...
;     LDB8(B1, 1, 1); WAIT_V8(0); BAR8; WAIT_L8(0); MMA8(0, 1, At, B1); BAR8;
;     LDA8(At, 1, 1); BAR8; WAIT_L8(0); MMA8(1, 0, At, B0); MMA8(1, 1, At, B1); BAR8; }
;   if (wr == 0) BAR8;
;   __syncthreads();
;   if (EPI == EPI_GU && nm0 >= 0) {
;     const int t = tid_opaque();
;     STAGE8(SB8(0, 0), Bt, K, nn0, 0); STAGE8(SA8(0, 0), A, lda, nm0, 0);
;     STAGE8(SB8(0, 1), Bt, K, nn0 + 128, 0); STAGE8(SA8(0, 1), A, lda, nm0 + 128, 0);
;   }
;     ...
;   if (t < 256) {
	ds_read_b128 v[132:135], v158
	ds_read_b128 v[168:171], v158 offset:1024
	ds_read_b128 v[206:209], v158 offset:2048
	ds_read_b128 v[210:213], v158 offset:3072
	s_waitcnt vmcnt(0)
	s_barrier
	s_waitcnt lgkmcnt(0)
	s_waitcnt lgkmcnt(0)
	v_mfma_f32_16x16x32_f16 v[12:15], v[16:19], v[132:135], v[214:217]
	v_mfma_f32_16x16x32_f16 v[16:19], v[16:19], v[206:209], v[174:177]
	v_mfma_f32_16x16x32_f16 v[12:15], v[20:23], v[168:171], v[12:15]
	v_mfma_f32_16x16x32_f16 v[28:31], v[20:23], v[210:213], v[16:19]
	v_mfma_f32_16x16x32_f16 v[16:19], v[24:27], v[132:135], v[178:181]
	v_mfma_f32_16x16x32_f16 v[20:23], v[24:27], v[206:209], v[182:185]
	v_mfma_f32_16x16x32_f16 v[16:19], v[32:35], v[168:171], v[16:19]
	v_mfma_f32_16x16x32_f16 v[32:35], v[32:35], v[210:213], v[20:23]
	v_mfma_f32_16x16x32_f16 v[20:23], v[36:39], v[132:135], v[80:83]
	v_mfma_f32_16x16x32_f16 v[24:27], v[36:39], v[206:209], v[76:79]
	v_mfma_f32_16x16x32_f16 v[20:23], v[40:43], v[168:171], v[20:23]
	v_mfma_f32_16x16x32_f16 v[36:39], v[40:43], v[210:213], v[24:27]
	v_mfma_f32_16x16x32_f16 v[24:27], v[242:245], v[132:135], v[72:75]
	v_mfma_f32_16x16x32_f16 v[40:43], v[242:245], v[206:209], v[68:71]
	v_mfma_f32_16x16x32_f16 v[24:27], v[246:249], v[168:171], v[24:27]
	v_mfma_f32_16x16x32_f16 v[40:43], v[246:249], v[210:213], v[40:43]
	s_barrier
	ds_read_b128 v[68:71], v156 offset:49152
	ds_read_b128 v[72:75], v156 offset:50176
	ds_read_b128 v[156:159], v154 offset:49152
	ds_read_b128 v[172:175], v154 offset:50176
	ds_read_b128 v[176:179], v153 offset:49152
	ds_read_b128 v[180:183], v153 offset:50176
	ds_read_b128 v[214:217], v152 offset:49152
	ds_read_b128 v[150:153], v152 offset:50176
	s_barrier
	s_waitcnt lgkmcnt(0)
	s_waitcnt lgkmcnt(0)
	v_mfma_f32_16x16x32_f16 v[64:67], v[68:71], v[4:7], v[64:67]
	v_mfma_f32_16x16x32_f16 v[56:59], v[156:159], v[4:7], v[56:59]
	v_mfma_f32_16x16x32_f16 v[48:51], v[176:179], v[4:7], v[48:51]
	v_mfma_f32_16x16x32_f16 v[4:7], v[214:217], v[4:7], v[136:139]
	v_mfma_f32_16x16x32_f16 v[128:131], v[72:75], v[8:11], v[64:67]
	v_mfma_f32_16x16x32_f16 v[60:63], v[68:71], v[198:201], v[60:63]
	v_mfma_f32_16x16x32_f16 v[120:123], v[172:175], v[8:11], v[56:59]
	v_mfma_f32_16x16x32_f16 v[52:55], v[156:159], v[198:201], v[52:55]
	v_mfma_f32_16x16x32_f16 v[80:83], v[180:183], v[8:11], v[48:51]
	v_mfma_f32_16x16x32_f16 v[44:47], v[176:179], v[198:201], v[44:47]
	v_mfma_f32_16x16x32_f16 v[8:11], v[150:153], v[8:11], v[4:7]
	v_mfma_f32_16x16x32_f16 v[4:7], v[214:217], v[198:201], v[140:143]
	v_mfma_f32_16x16x32_f16 v[124:127], v[72:75], v[238:241], v[60:63]
	v_mfma_f32_16x16x32_f16 v[112:115], v[172:175], v[238:241], v[52:55]
	v_mfma_f32_16x16x32_f16 v[76:79], v[180:183], v[238:241], v[44:47]
	v_mfma_f32_16x16x32_f16 v[4:7], v[150:153], v[238:241], v[4:7]
	v_mfma_f32_16x16x32_f16 v[44:47], v[68:71], v[132:135], v[160:163]
	v_mfma_f32_16x16x32_f16 v[48:51], v[68:71], v[206:209], v[164:167]
	v_mfma_f32_16x16x32_f16 v[52:55], v[156:159], v[206:209], v[218:221]
	v_mfma_f32_16x16x32_f16 v[56:59], v[176:179], v[206:209], v[186:189]
	v_mfma_f32_16x16x32_f16 v[44:47], v[72:75], v[168:171], v[44:47]
	v_mfma_f32_16x16x32_f16 v[60:63], v[72:75], v[210:213], v[48:51]
	v_mfma_f32_16x16x32_f16 v[48:51], v[156:159], v[132:135], v[202:205]
	v_mfma_f32_16x16x32_f16 v[64:67], v[172:175], v[210:213], v[52:55]
	v_mfma_f32_16x16x32_f16 v[52:55], v[176:179], v[132:135], v[230:233]
	v_mfma_f32_16x16x32_f16 v[68:71], v[180:183], v[210:213], v[56:59]
	v_mfma_f32_16x16x32_f16 v[56:59], v[214:217], v[132:135], v[190:193]
	v_mfma_f32_16x16x32_f16 v[72:75], v[214:217], v[206:209], v[194:197]
	v_mfma_f32_16x16x32_f16 v[48:51], v[172:175], v[168:171], v[48:51]
	v_mfma_f32_16x16x32_f16 v[52:55], v[180:183], v[168:171], v[52:55]
	v_mfma_f32_16x16x32_f16 v[56:59], v[150:153], v[168:171], v[56:59]
	v_mfma_f32_16x16x32_f16 v[72:75], v[150:153], v[210:213], v[72:75]
	s_movk_i32 s4, 0x100
	v_cmp_gt_u32_e32 vcc, s4, v3
	s_barrier
	s_and_saveexec_b64 s[4:5], vcc
	s_cbranch_execz .LBB0_195
	s_barrier

; #define BAR8 __builtin_amdgcn_s_barrier()
; #define G_SSCQ ((float*)(wsp() + OFF_SSCQ))
; #define G_SSCKV ((float*)(wsp() + OFF_SSCKV))
;     ...
;     STAGE8(SB8(0, 0), Bt, K, bcol, 0); STAGE8(SA8(0, 0), A, lda, brow, 0);
;     STAGE8(SB8(0, 1), Bt, K, bcol + 128, 0); STAGE8(SA8(0, 1), A, lda, brow + 128, 0);
;   }
;   if (wr == 1) BAR8;
; __global__ void __launch_bounds__(512, 2) mega(Params p) {
;     ...
;         } else {
;           e.ss_cq = G_SSCQ; e.ss_ckv = G_SSCKV;
;           gemm_tile<EPI_IN_CD, 256, true>(G_XB, DM, wb + W_IN, DM, mt * 256, nt * 256, e);
.LBB0_238:
	s_and_b64 vcc, exec, s[0:1]
	s_cbranch_vccz .LBB0_187
	s_mov_b32 s0, 25
	s_ashr_i32 s1, s0, 31
	s_lshl_b64 s[0:1], s[0:1], 3
	s_add_u32 s0, s70, s0
	s_addc_u32 s1, s71, s1
	v_readlane_b32 s2, v255, 60
	v_readlane_b32 s3, v255, 61
	s_nop 4
	s_mov_b32 s0, 25
	s_ashr_i32 s1, s0, 31
	s_lshl_b64 s[0:1], s[0:1], 3
	s_add_u32 s0, s70, s0
	s_addc_u32 s1, s71, s1
	v_readlane_b32 s4, v255, 60
	v_readlane_b32 s5, v255, 61
	s_nop 4
	s_mov_b32 s0, 25
	s_ashr_i32 s1, s0, 31
	s_lshl_b64 s[0:1], s[0:1], 3
	s_add_u32 s0, s70, s0
	s_addc_u32 s1, s71, s1
	v_mov_b32_e32 v3, v224
	v_readlane_b32 s14, v255, 60
	v_readlane_b32 s15, v255, 61
	s_nop 4
	s_ashr_i32 s53, s52, 31
	v_bfe_i32 v1, v3, 27, 1
	s_waitcnt vmcnt(10)
	v_lshlrev_b32_e32 v150, 4, v3
	s_nop 0
	v_readfirstlane_b32 s100, v150
	v_lshrrev_b32_e32 v1, 22, v1
	v_add_u32_e32 v1, v150, v1
	v_and_b32_e32 v1, 0xfffffc00, v1
	v_ashrrev_i32_e32 v0, 31, v3
	v_sub_u32_e32 v1, v150, v1
	v_lshrrev_b32_e32 v0, 26, v0
	v_lshrrev_b32_e32 v5, 4, v1
	v_add_u32_e32 v0, v3, v0
	v_bitop3_b32 v5, v5, v1, 32 bitop3:0x6c
	v_ashrrev_i32_e32 v1, 31, v1
	v_ashrrev_i32_e32 v0, 6, v0
	v_lshrrev_b32_e32 v1, 26, v1
	v_lshlrev_b32_e32 v6, 3, v0
	v_add_u32_e32 v1, v5, v1
	v_and_b32_e32 v6, -16, v6
	v_ashrrev_i32_e32 v1, 6, v1
	v_add_u32_e32 v6, v1, v6
	v_mul_i32_i24_e32 v1, 64, v1
	v_lshlrev_b32_e32 v0, 5, v0
	v_sub_u32_e32 v1, v5, v1
	v_mov_b32_e32 v14, 1
	s_waitcnt vmcnt(9)
	v_add_u32_e32 v155, 0x2000, v150
	s_lshl_b64 s[0:1], s[52:53], 11
	v_readlane_b32 s27, v254, 44
	v_and_b32_e32 v0, 32, v0
	v_ashrrev_i16_sdwa v1, v14, sext(v1) dst_sel:DWORD dst_unused:UNUSED_PAD src0_sel:DWORD src1_sel:BYTE_0
	v_ashrrev_i32_e32 v5, 31, v155
	s_add_u32 s0, s27, s0
	v_readlane_b32 s29, v254, 45
	v_add_u32_sdwa v0, v0, sext(v1) dst_sel:DWORD dst_unused:UNUSED_PAD src0_sel:DWORD src1_sel:WORD_0
	v_ashrrev_i32_e32 v7, 31, v6
	v_lshrrev_b32_e32 v5, 22, v5
	s_addc_u32 s1, s29, s1
	v_lshlrev_b64 v[132:133], 11, v[6:7]
	v_ashrrev_i32_e32 v1, 31, v0
	v_add_u32_e32 v5, v155, v5
	v_lshl_add_u64 v[8:9], s[0:1], 0, v[132:133]
	v_lshlrev_b64 v[6:7], 1, v[0:1]
	v_ashrrev_i32_e32 v5, 10, v5
	v_lshl_add_u64 v[10:11], v[8:9], 0, v[6:7]
	v_mul_i32_i24_e32 v8, 0x400, v5
	v_sub_u32_e32 v8, v155, v8
	v_lshrrev_b32_e32 v9, 4, v8
	v_bitop3_b32 v9, v9, v8, 32 bitop3:0x6c
	v_ashrrev_i32_e32 v12, 31, v9
	v_lshrrev_b32_e32 v12, 26, v12
	v_add_u32_e32 v12, v9, v12
	v_lshlrev_b32_e32 v8, 3, v5
	v_ashrrev_i32_e32 v13, 6, v12
	v_and_b32_e32 v12, 0xc0, v12
	v_and_b32_e32 v8, -16, v8
	v_lshlrev_b32_e32 v5, 5, v5
	v_sub_u32_e32 v9, v9, v12
	v_add_u32_e32 v8, v13, v8
	v_and_b32_e32 v5, 32, v5
	v_ashrrev_i16_sdwa v9, v14, sext(v9) dst_sel:DWORD dst_unused:UNUSED_PAD src0_sel:DWORD src1_sel:BYTE_0
	v_add_u32_e32 v151, 0x10000, v150
	v_add_u32_sdwa v134, v5, sext(v9) dst_sel:DWORD dst_unused:UNUSED_PAD src0_sel:DWORD src1_sel:WORD_0
	v_ashrrev_i32_e32 v9, 31, v8
	v_lshlrev_b64 v[136:137], 11, v[8:9]
	s_waitcnt vmcnt(8)
	v_add_u32_e32 v158, 0x12000, v150
	v_mov_b32_e32 v4, v2
	s_or_b32 m0, s100, 0x10000
	v_lshl_add_u64 v[12:13], s[0:1], 0, v[136:137]
	global_load_lds_dwordx4 v[10:11], off
	s_or_b32 m0, s100, 0x12000
	s_lshl_b32 s0, s20, 19
	v_ashrrev_i32_e32 v135, 31, v134
	s_waitcnt lgkmcnt(0)
	s_add_u32 s12, s14, s0
	v_lshlrev_b64 v[8:9], 1, v[134:135]
	s_addc_u32 s13, s15, 0
	v_lshl_add_u64 v[12:13], v[12:13], 0, v[8:9]
	v_lshl_add_u64 v[14:15], s[12:13], 0, v[132:133]
	global_load_lds_dwordx4 v[12:13], off
	v_lshl_add_u64 v[14:15], v[14:15], 0, v[6:7]
	s_mov_b32 m0, s100
	s_nop 0
	global_load_lds_dwordx4 v[14:15], off
	s_or_b32 m0, s100, 0x2000
	s_or_b32 s0, s52, 0x80
	s_ashr_i32 s1, s0, 31
	s_lshl_b64 s[20:21], s[0:1], 11
	s_add_u32 s20, s27, s20
	v_lshl_add_u64 v[16:17], s[12:13], 0, v[136:137]
	s_addc_u32 s21, s29, s21
	v_add_u32_e32 v160, 0x14000, v150
	v_lshl_add_u64 v[16:17], v[16:17], 0, v[8:9]
	v_lshl_add_u64 v[18:19], s[20:21], 0, v[132:133]
	v_lshl_add_u64 v[20:21], s[20:21], 0, v[136:137]
	v_add_u32_e32 v161, 0x16000, v150
	s_add_u32 s20, s12, 0x40000
	global_load_lds_dwordx4 v[16:17], off
	v_lshl_add_u64 v[18:19], v[18:19], 0, v[6:7]
	s_addc_u32 s21, s13, 0
	s_or_b32 m0, s100, 0x14000
	v_add_u32_e32 v162, 0x4000, v150
	global_load_lds_dwordx4 v[18:19], off
	v_lshl_add_u64 v[20:21], v[20:21], 0, v[8:9]
	s_or_b32 m0, s100, 0x16000
	v_lshl_add_u64 v[22:23], s[20:21], 0, v[132:133]
	global_load_lds_dwordx4 v[20:21], off
	v_lshl_add_u64 v[22:23], v[22:23], 0, v[6:7]
	s_or_b32 m0, s100, 0x4000
	v_add_u32_e32 v163, 0x6000, v150
	global_load_lds_dwordx4 v[22:23], off
	v_lshl_add_u64 v[22:23], s[20:21], 0, v[136:137]
	v_lshl_add_u64 v[22:23], v[22:23], 0, v[8:9]
	s_or_b32 m0, s100, 0x6000
	v_ashrrev_i32_e32 v5, 8, v3
	global_load_lds_dwordx4 v[22:23], off
	v_cmp_eq_u32_e32 vcc, 1, v5
	s_and_saveexec_b64 s[20:21], vcc
	s_cbranch_execz .LBB0_241
	s_barrier
; #define WAIT_V8(n) asm volatile("s_waitcnt vmcnt(" #n ")" ::: "memory")
; #define BAR8 __builtin_amdgcn_s_barrier()
;     ...
;   const int brow = m0, bcol = n0;
;   const int wid = t >> 6, lane = t & 63, wr = wid >> 2, wc = wid & 3, fr = lane & 15, fq = lane >> 4;
;   f32x4 acc[2][2][4][2];
;   {
;     float zinit = 0.f;
;     asm volatile("" : "+v"(zinit));
; #pragma unroll
;     for (int a = 0; a < 2; ++a)
; #pragma unroll
;       for (int b = 0; b < 2; ++b)
; #pragma unroll
;         for (int m = 0; m < 4; ++m)
; #pragma unroll
;           for (int n = 0; n < 2; ++n)
; #pragma unroll
;             for (int j = 0; j < 4; ++j) acc[a][b][m][n][j] = zinit;
;   }
;   bf16x8 At[4][2], B0[2][2], B1[2][2];
;   const int nt = K / 64;
;   if (!pre) {
;     STAGE8(SB8(0, 0), Bt, K, bcol, 0); STAGE8(SA8(0, 0), A, lda, brow, 0);
;     STAGE8(SB8(0, 1), Bt, K, bcol + 128, 0); STAGE8(SA8(0, 1), A, lda, brow + 128, 0);
;   }
;   if (wr == 1) BAR8;
;   WAIT_V8(4); BAR8;
;   STAGE8(SB8(1, 0), Bt, K, bcol, 1); STAGE8(SA8(1, 0), A, lda, brow, 1); STAGE8(SB8(1, 1), Bt, K, bcol + 128, 1);
;   WAIT_V8(6); BAR8;
.LBB0_241:
	s_or_b64 exec, exec, s[20:21]
	v_add_u32_e32 v164, 0x18000, v150
	s_mov_b64 s[20:21], 0x80
	v_add_u32_e32 v165, 0x1a000, v150
	v_lshl_add_u64 v[10:11], v[10:11], 0, s[20:21]
	s_or_b32 m0, s100, 0x18000
	v_add_u32_e32 v166, 0x8000, v150
	s_waitcnt vmcnt(4)
	s_barrier
	global_load_lds_dwordx4 v[10:11], off
	v_lshl_add_u64 v[10:11], v[12:13], 0, s[20:21]
	s_or_b32 m0, s100, 0x1a000
	v_add_u32_e32 v167, 0xa000, v150
	global_load_lds_dwordx4 v[10:11], off
	v_lshl_add_u64 v[10:11], v[14:15], 0, s[20:21]
	s_or_b32 m0, s100, 0x8000
	v_add_u32_e32 v169, 0x1c000, v150
	global_load_lds_dwordx4 v[10:11], off
	v_lshl_add_u64 v[10:11], v[16:17], 0, s[20:21]
	s_or_b32 m0, s100, 0xa000
	v_add_u32_e32 v170, 0x1e000, v150
	global_load_lds_dwordx4 v[10:11], off
	v_lshl_add_u64 v[10:11], v[18:19], 0, s[20:21]
	s_or_b32 m0, s100, 0x1c000
	s_nop 0
	global_load_lds_dwordx4 v[10:11], off
	v_lshl_add_u64 v[10:11], v[20:21], 0, s[20:21]
	s_or_b32 m0, s100, 0x1e000
	v_and_b32_e32 v147, 15, v3
	global_load_lds_dwordx4 v[10:11], off
	v_bfe_u32 v148, v3, 4, 2
	v_lshlrev_b32_e32 v10, 4, v148
	v_lshlrev_b32_e32 v11, 6, v147
	v_lshlrev_b32_e32 v14, 2, v3
	v_or_b32_e32 v13, v10, v11
	v_and_b32_e32 v14, 32, v14
	s_mov_b32 s1, 0x10000
	v_bitop3_b32 v16, v13, s1, v14 bitop3:0xde
	s_mov_b32 s1, 0x14000
	v_bitop3_b32 v15, v10, v14, v11 bitop3:0x36
	v_bitop3_b32 v17, v13, s1, v14 bitop3:0xde
	s_mov_b32 s1, 0x18000
	v_lshlrev_b32_e32 v11, 6, v3
	v_bitop3_b32 v18, v13, s1, v14 bitop3:0xde
	s_mov_b32 s1, 0x1c000
	v_and_b32_e32 v11, 0x3c0, v11
	v_bitop3_b32 v13, v13, s1, v14 bitop3:0xde
	v_bitop3_b32 v14, v11, v14, v10 bitop3:0x36
	v_lshl_add_u64 v[10:11], s[30:31], 0, v[136:137]
	v_lshl_add_u64 v[10:11], v[10:11], 0, v[8:9]
	v_lshl_add_u64 v[138:139], s[14:15], 0, v[10:11]
	v_lshl_add_u64 v[10:11], s[30:31], 0, v[132:133]
	v_lshl_add_u64 v[10:11], v[10:11], 0, v[6:7]
	v_lshl_add_u64 v[140:141], s[14:15], 0, v[10:11]
	v_lshl_add_u64 v[10:11], s[56:57], 0, v[132:133]
	v_lshl_add_u64 v[6:7], v[10:11], 0, v[6:7]
	v_bfe_u32 v146, v3, 6, 2
	s_waitcnt vmcnt(6)
	v_lshlrev_b32_e32 v149, 6, v5
	v_lshlrev_b32_e32 v5, 13, v5
	v_lshl_add_u64 v[142:143], s[46:47], 0, v[6:7]
	v_lshl_add_u64 v[6:7], s[56:57], 0, v[136:137]
	v_lshlrev_b32_e32 v12, 12, v146
	v_or_b32_e32 v19, 0x800, v5
	v_or_b32_e32 v20, 0x1000, v5
	v_or_b32_e32 v21, 0x1800, v5
	v_lshl_add_u64 v[6:7], v[6:7], 0, v[8:9]
	v_lshl_add_u64 v[144:145], s[46:47], 0, v[6:7]
	s_mov_b32 s1, -2
	s_mov_b64 s[14:15], 0
	v_add_u32_e32 v171, v16, v12
	v_add_u32_e32 v156, v15, v5
	v_add_u32_e32 v154, v14, v19
	v_add_u32_e32 v153, v14, v20
	v_add_u32_e32 v152, v14, v21
	v_add_u32_e32 v168, v17, v12
	v_add_u32_e32 v159, v18, v12
	v_add_u32_e32 v157, v13, v12
	v_mov_b32_e32 v5, v4
	v_mov_b64_e32 v[6:7], v[4:5]
	v_mov_b64_e32 v[8:9], v[4:5]
	v_mov_b64_e32 v[10:11], v[4:5]
	v_mov_b64_e32 v[12:13], v[4:5]
	v_mov_b64_e32 v[14:15], v[4:5]
	v_mov_b64_e32 v[16:17], v[4:5]
	v_mov_b64_e32 v[18:19], v[4:5]
	v_mov_b64_e32 v[20:21], v[4:5]
	v_mov_b64_e32 v[22:23], v[4:5]
	v_mov_b64_e32 v[24:25], v[4:5]
	v_mov_b64_e32 v[26:27], v[4:5]
	v_mov_b64_e32 v[28:29], v[4:5]
	v_mov_b64_e32 v[30:31], v[4:5]
	v_mov_b64_e32 v[32:33], v[4:5]
	v_mov_b64_e32 v[34:35], v[4:5]
	v_mov_b64_e32 v[36:37], v[4:5]
	v_mov_b64_e32 v[38:39], v[4:5]
	v_mov_b64_e32 v[40:41], v[4:5]
	v_mov_b64_e32 v[42:43], v[4:5]
	v_mov_b64_e32 v[44:45], v[4:5]
	v_mov_b64_e32 v[46:47], v[4:5]
	v_mov_b64_e32 v[48:49], v[4:5]
	v_mov_b64_e32 v[50:51], v[4:5]
	v_mov_b64_e32 v[52:53], v[4:5]
	v_mov_b64_e32 v[54:55], v[4:5]
	v_mov_b64_e32 v[56:57], v[4:5]
	v_mov_b64_e32 v[58:59], v[4:5]
	v_mov_b64_e32 v[60:61], v[4:5]
	v_mov_b64_e32 v[62:63], v[4:5]
	v_mov_b64_e32 v[64:65], v[4:5]
	v_mov_b64_e32 v[66:67], v[4:5]
	v_mov_b64_e32 v[68:69], v[4:5]
	v_mov_b64_e32 v[70:71], v[4:5]
	v_mov_b64_e32 v[72:73], v[4:5]
	v_mov_b64_e32 v[74:75], v[4:5]
	v_mov_b64_e32 v[76:77], v[4:5]
	v_mov_b64_e32 v[78:79], v[4:5]
	v_mov_b64_e32 v[80:81], v[4:5]
	v_mov_b64_e32 v[82:83], v[4:5]
	v_mov_b64_e32 v[84:85], v[4:5]
	v_mov_b64_e32 v[86:87], v[4:5]
	v_mov_b64_e32 v[88:89], v[4:5]
	v_mov_b64_e32 v[90:91], v[4:5]
	v_mov_b64_e32 v[92:93], v[4:5]
	v_mov_b64_e32 v[94:95], v[4:5]
	v_mov_b64_e32 v[96:97], v[4:5]
	v_mov_b64_e32 v[98:99], v[4:5]
	v_mov_b64_e32 v[100:101], v[4:5]
	v_mov_b64_e32 v[102:103], v[4:5]
	v_mov_b64_e32 v[104:105], v[4:5]
	v_mov_b64_e32 v[106:107], v[4:5]
	v_mov_b64_e32 v[108:109], v[4:5]
	v_mov_b64_e32 v[110:111], v[4:5]
	v_mov_b64_e32 v[112:113], v[4:5]
	v_mov_b64_e32 v[114:115], v[4:5]
	v_mov_b64_e32 v[116:117], v[4:5]
	v_mov_b64_e32 v[118:119], v[4:5]
	v_mov_b64_e32 v[120:121], v[4:5]
	v_mov_b64_e32 v[122:123], v[4:5]
	v_mov_b64_e32 v[124:125], v[4:5]
	v_mov_b64_e32 v[126:127], v[4:5]
	v_mov_b64_e32 v[128:129], v[4:5]
	v_mov_b64_e32 v[130:131], v[4:5]
	s_mov_b64 s[30:31], 0xc000100
	s_mov_b64 s[56:57], 0xc040100
	s_mov_b64 s[58:59], 0xc000180
	s_mov_b64 s[60:61], 0xc040180
	s_barrier
; #define LDA8(dst, b, h) _Pragma("unroll") for (int m = 0; m < 4; ++m) _Pragma("unroll") for (int k = 0; k < 2; ++k) \
;     dst[m][k] = *(const bf16x8*)((const char*)SA8(b, h) + lds_byte8(wr * 64 + m * 16 + fr, k * 32 + fq * 8))
; #define LDB8(dst, b, h) _Pragma("unroll") for (int n = 0; n < 2; ++n) _Pragma("unroll") for (int k = 0; k < 2; ++k) \
;     dst[n][k] = *(const bf16x8*)((const char*)SB8(b, h) + lds_byte8(wc * 32 + n * 16 + fr, k * 32 + fq * 8))
; #define WAIT_L8(n) asm volatile("s_waitcnt lgkmcnt(" #n ")" ::: "memory")
; #define BAR8 __builtin_amdgcn_s_barrier()
; #define SCHED8 __builtin_amdgcn_sched_barrier(0)
;     ...
;     LDB8(B0, 0, 0); SCHED8; LDA8(At, 0, 0); STAGE8(SA8(1, 1), A, lda, brow + 128, tt + 1);
;     WAIT_L8(8); BAR8; WAIT_L8(0); MMA8(0, 0, At, B0); BAR8; SCHED8;
;     LDB8(B1, 0, 1); STAGE8(SB8(0, 0), Bt, K, bcol, tt + 2);
;     BAR8; WAIT_L8(0); MMA8(0, 1, At, B1); BAR8;
;     LDA8(At, 0, 1); STAGE8(SA8(0, 0), A, lda, brow, tt + 2);
;     BAR8; WAIT_L8(0); MMA8(1, 0, At, B0); BAR8; SCHED8;
.LBB0_242:
	ds_read_b128 v[174:177], v171
	ds_read_b128 v[178:181], v171 offset:1024
	ds_read_b128 v[182:185], v171 offset:2048
	ds_read_b128 v[186:189], v171 offset:3072
	v_add_u32_e32 v172, 0xc000, v150
	v_lshl_add_u64 v[222:223], v[140:141], 0, s[14:15]
	v_lshl_add_u64 v[226:227], v[222:223], 0, s[34:35]
	s_or_b32 m0, s100, 0xc000
	v_add_u32_e32 v173, 0xe000, v150
	ds_read_b128 v[190:193], v156
	ds_read_b128 v[194:197], v156 offset:1024
	ds_read_b128 v[198:201], v154
	ds_read_b128 v[202:205], v154 offset:1024
	ds_read_b128 v[206:209], v153
	ds_read_b128 v[210:213], v153 offset:1024
	ds_read_b128 v[214:217], v152
	ds_read_b128 v[218:221], v152 offset:1024
	global_load_lds_dwordx4 v[226:227], off
	v_lshl_add_u64 v[226:227], v[138:139], 0, s[14:15]
	v_lshl_add_u64 v[228:229], v[226:227], 0, s[34:35]
	s_or_b32 m0, s100, 0xe000
	s_nop 0
	global_load_lds_dwordx4 v[228:229], off
	s_waitcnt lgkmcnt(8)
	s_barrier
	s_waitcnt lgkmcnt(0)
	s_waitcnt lgkmcnt(0)
	v_mfma_f32_16x16x32_f16 v[128:131], v[190:193], v[174:177], v[128:131]
	v_mfma_f32_16x16x32_f16 v[124:127], v[190:193], v[182:185], v[124:127]
	v_mfma_f32_16x16x32_f16 v[120:123], v[198:201], v[174:177], v[120:123]
	v_mfma_f32_16x16x32_f16 v[116:119], v[198:201], v[182:185], v[116:119]
	v_mfma_f32_16x16x32_f16 v[112:115], v[206:209], v[174:177], v[112:115]
	v_mfma_f32_16x16x32_f16 v[108:111], v[206:209], v[182:185], v[108:111]
	v_mfma_f32_16x16x32_f16 v[104:107], v[214:217], v[174:177], v[104:107]
	v_mfma_f32_16x16x32_f16 v[100:103], v[214:217], v[182:185], v[100:103]
	v_mfma_f32_16x16x32_f16 v[128:131], v[194:197], v[178:181], v[128:131]
	v_mfma_f32_16x16x32_f16 v[124:127], v[194:197], v[186:189], v[124:127]
	v_mfma_f32_16x16x32_f16 v[120:123], v[202:205], v[178:181], v[120:123]
	v_mfma_f32_16x16x32_f16 v[116:119], v[202:205], v[186:189], v[116:119]
	v_mfma_f32_16x16x32_f16 v[112:115], v[210:213], v[178:181], v[112:115]
	v_mfma_f32_16x16x32_f16 v[108:111], v[210:213], v[186:189], v[108:111]
	v_mfma_f32_16x16x32_f16 v[104:107], v[218:221], v[178:181], v[104:107]
	v_mfma_f32_16x16x32_f16 v[100:103], v[218:221], v[186:189], v[100:103]
	s_barrier
	v_lshl_add_u64 v[228:229], v[142:143], 0, s[14:15]
	v_lshl_add_u64 v[236:237], v[228:229], 0, s[30:31]
	s_or_b32 m0, s100, 0x10000
	ds_read_b128 v[230:233], v168
	ds_read_b128 v[238:241], v168 offset:1024
	ds_read_b128 v[242:245], v168 offset:2048
	ds_read_b128 v[246:249], v168 offset:3072
	global_load_lds_dwordx4 v[236:237], off
	v_lshl_add_u64 v[236:237], v[144:145], 0, s[14:15]
	v_lshl_add_u64 v[250:251], v[236:237], 0, s[30:31]
	s_or_b32 m0, s100, 0x12000
	s_nop 0
	global_load_lds_dwordx4 v[250:251], off
	s_barrier
	s_waitcnt lgkmcnt(0)
	s_waitcnt lgkmcnt(0)
	v_mfma_f32_16x16x32_f16 v[96:99], v[190:193], v[230:233], v[96:99]
	v_mfma_f32_16x16x32_f16 v[92:95], v[190:193], v[242:245], v[92:95]
	v_mfma_f32_16x16x32_f16 v[88:91], v[198:201], v[230:233], v[88:91]
	v_mfma_f32_16x16x32_f16 v[84:87], v[198:201], v[242:245], v[84:87]
	v_mfma_f32_16x16x32_f16 v[80:83], v[206:209], v[230:233], v[80:83]
	v_mfma_f32_16x16x32_f16 v[76:79], v[206:209], v[242:245], v[76:79]
	v_mfma_f32_16x16x32_f16 v[72:75], v[214:217], v[230:233], v[72:75]
	v_mfma_f32_16x16x32_f16 v[68:71], v[214:217], v[242:245], v[68:71]
	v_mfma_f32_16x16x32_f16 v[96:99], v[194:197], v[238:241], v[96:99]
	v_mfma_f32_16x16x32_f16 v[92:95], v[194:197], v[246:249], v[92:95]
	v_mfma_f32_16x16x32_f16 v[88:91], v[202:205], v[238:241], v[88:91]
	v_mfma_f32_16x16x32_f16 v[84:87], v[202:205], v[246:249], v[84:87]
	v_mfma_f32_16x16x32_f16 v[80:83], v[210:213], v[238:241], v[80:83]
	v_mfma_f32_16x16x32_f16 v[76:79], v[210:213], v[246:249], v[76:79]
	v_mfma_f32_16x16x32_f16 v[72:75], v[218:221], v[238:241], v[72:75]
	v_mfma_f32_16x16x32_f16 v[68:71], v[218:221], v[246:249], v[68:71]
	v_lshl_add_u64 v[250:251], v[222:223], 0, s[10:11]
	s_mov_b32 m0, s100
	s_barrier
	ds_read_b128 v[190:193], v156 offset:16384
	ds_read_b128 v[194:197], v156 offset:17408
	ds_read_b128 v[198:201], v154 offset:16384
	ds_read_b128 v[202:205], v154 offset:17408
	ds_read_b128 v[206:209], v153 offset:16384
	ds_read_b128 v[210:213], v153 offset:17408
	ds_read_b128 v[214:217], v152 offset:16384
	ds_read_b128 v[218:221], v152 offset:17408
	global_load_lds_dwordx4 v[250:251], off
	v_lshl_add_u64 v[250:251], v[226:227], 0, s[10:11]
	s_or_b32 m0, s100, 0x2000
	s_nop 0
	global_load_lds_dwordx4 v[250:251], off
	s_barrier
	s_waitcnt lgkmcnt(0)
	s_waitcnt lgkmcnt(0)
	v_mfma_f32_16x16x32_f16 v[64:67], v[190:193], v[174:177], v[64:67]
	v_mfma_f32_16x16x32_f16 v[60:63], v[190:193], v[182:185], v[60:63]
	v_mfma_f32_16x16x32_f16 v[56:59], v[198:201], v[174:177], v[56:59]
	v_mfma_f32_16x16x32_f16 v[52:55], v[198:201], v[182:185], v[52:55]
	v_mfma_f32_16x16x32_f16 v[48:51], v[206:209], v[174:177], v[48:51]
	v_mfma_f32_16x16x32_f16 v[44:47], v[206:209], v[182:185], v[44:47]
	v_mfma_f32_16x16x32_f16 v[40:43], v[214:217], v[174:177], v[40:43]
	v_mfma_f32_16x16x32_f16 v[36:39], v[214:217], v[182:185], v[36:39]
	v_mfma_f32_16x16x32_f16 v[64:67], v[194:197], v[178:181], v[64:67]
	v_mfma_f32_16x16x32_f16 v[60:63], v[194:197], v[186:189], v[60:63]
	v_mfma_f32_16x16x32_f16 v[56:59], v[202:205], v[178:181], v[56:59]
	v_mfma_f32_16x16x32_f16 v[52:55], v[202:205], v[186:189], v[52:55]
	v_mfma_f32_16x16x32_f16 v[48:51], v[210:213], v[178:181], v[48:51]
	v_mfma_f32_16x16x32_f16 v[44:47], v[210:213], v[186:189], v[44:47]
	v_mfma_f32_16x16x32_f16 v[40:43], v[218:221], v[178:181], v[40:43]
	v_mfma_f32_16x16x32_f16 v[36:39], v[218:221], v[186:189], v[36:39]
	s_barrier
; #define LDA8(dst, b, h) _Pragma("unroll") for (int m = 0; m < 4; ++m) _Pragma("unroll") for (int k = 0; k < 2; ++k) \
;     dst[m][k] = *(const bf16x8*)((const char*)SA8(b, h) + lds_byte8(wr * 64 + m * 16 + fr, k * 32 + fq * 8))
; #define LDB8(dst, b, h) _Pragma("unroll") for (int n = 0; n < 2; ++n) _Pragma("unroll") for (int k = 0; k < 2; ++k) \
;     dst[n][k] = *(const bf16x8*)((const char*)SB8(b, h) + lds_byte8(wc * 32 + n * 16 + fr, k * 32 + fq * 8))
; #define WAIT_V8(n) asm volatile("s_waitcnt vmcnt(" #n ")" ::: "memory")
; #define WAIT_L8(n) asm volatile("s_waitcnt lgkmcnt(" #n ")" ::: "memory")
; #define BAR8 __builtin_amdgcn_s_barrier()
; #define SCHED8 __builtin_amdgcn_sched_barrier(0)
;     ...
;     STAGE8(SB8(0, 1), Bt, K, bcol + 128, tt + 2);
;     WAIT_V8(6); BAR8; MMA8(1, 1, At, B1); BAR8;
;     LDB8(B0, 1, 0); SCHED8; LDA8(At, 1, 0); STAGE8(SA8(0, 1), A, lda, brow + 128, tt + 2);
;     WAIT_L8(8); BAR8; WAIT_L8(0); MMA8(0, 0, At, B0); BAR8; SCHED8;
;     LDB8(B1, 1, 1); STAGE8(SB8(1, 0), Bt, K, bcol, tt + 3);
;     BAR8; WAIT_L8(0); MMA8(0, 1, At, B1); BAR8;
;     LDA8(At, 1, 1); STAGE8(SA8(1, 0), A, lda, brow, tt + 3);
	v_lshl_add_u64 v[174:175], v[228:229], 0, s[56:57]
	s_or_b32 m0, s100, 0x14000
	s_nop 0
	global_load_lds_dwordx4 v[174:175], off
	v_lshl_add_u64 v[174:175], v[236:237], 0, s[56:57]
	s_or_b32 m0, s100, 0x16000
	s_nop 0
	global_load_lds_dwordx4 v[174:175], off
	s_waitcnt vmcnt(6)
	s_barrier
	v_mfma_f32_16x16x32_f16 v[32:35], v[190:193], v[230:233], v[32:35]
	v_mfma_f32_16x16x32_f16 v[28:31], v[190:193], v[242:245], v[28:31]
	v_mfma_f32_16x16x32_f16 v[24:27], v[198:201], v[230:233], v[24:27]
	v_mfma_f32_16x16x32_f16 v[20:23], v[198:201], v[242:245], v[20:23]
	v_mfma_f32_16x16x32_f16 v[16:19], v[206:209], v[230:233], v[16:19]
	v_mfma_f32_16x16x32_f16 v[12:15], v[206:209], v[242:245], v[12:15]
	v_mfma_f32_16x16x32_f16 v[8:11], v[214:217], v[230:233], v[8:11]
	v_mfma_f32_16x16x32_f16 v[4:7], v[214:217], v[242:245], v[4:7]
	v_mfma_f32_16x16x32_f16 v[32:35], v[194:197], v[238:241], v[32:35]
	v_mfma_f32_16x16x32_f16 v[28:31], v[194:197], v[246:249], v[28:31]
	v_mfma_f32_16x16x32_f16 v[24:27], v[202:205], v[238:241], v[24:27]
	v_mfma_f32_16x16x32_f16 v[20:23], v[202:205], v[246:249], v[20:23]
	v_mfma_f32_16x16x32_f16 v[16:19], v[210:213], v[238:241], v[16:19]
	v_mfma_f32_16x16x32_f16 v[12:15], v[210:213], v[246:249], v[12:15]
	v_mfma_f32_16x16x32_f16 v[8:11], v[218:221], v[238:241], v[8:11]
	v_mfma_f32_16x16x32_f16 v[4:7], v[218:221], v[246:249], v[4:7]
	s_barrier
	ds_read_b128 v[174:177], v159
	ds_read_b128 v[178:181], v159 offset:1024
	ds_read_b128 v[182:185], v159 offset:2048
	ds_read_b128 v[186:189], v159 offset:3072
	v_lshl_add_u64 v[230:231], v[222:223], 0, s[18:19]
	s_or_b32 m0, s100, 0x4000
	ds_read_b128 v[190:193], v156 offset:32768
	ds_read_b128 v[194:197], v156 offset:33792
	ds_read_b128 v[198:201], v154 offset:32768
	ds_read_b128 v[202:205], v154 offset:33792
	ds_read_b128 v[206:209], v153 offset:32768
	ds_read_b128 v[210:213], v153 offset:33792
	ds_read_b128 v[214:217], v152 offset:32768
	ds_read_b128 v[218:221], v152 offset:33792
	global_load_lds_dwordx4 v[230:231], off
	v_lshl_add_u64 v[230:231], v[226:227], 0, s[18:19]
	s_or_b32 m0, s100, 0x6000
	s_nop 0
	global_load_lds_dwordx4 v[230:231], off
	s_waitcnt lgkmcnt(8)
	s_barrier
	s_waitcnt lgkmcnt(0)
	s_waitcnt lgkmcnt(0)
	v_mfma_f32_16x16x32_f16 v[128:131], v[190:193], v[174:177], v[128:131]
	v_mfma_f32_16x16x32_f16 v[124:127], v[190:193], v[182:185], v[124:127]
	v_mfma_f32_16x16x32_f16 v[120:123], v[198:201], v[174:177], v[120:123]
	v_mfma_f32_16x16x32_f16 v[116:119], v[198:201], v[182:185], v[116:119]
	v_mfma_f32_16x16x32_f16 v[112:115], v[206:209], v[174:177], v[112:115]
	v_mfma_f32_16x16x32_f16 v[108:111], v[206:209], v[182:185], v[108:111]
	v_mfma_f32_16x16x32_f16 v[104:107], v[214:217], v[174:177], v[104:107]
	v_mfma_f32_16x16x32_f16 v[100:103], v[214:217], v[182:185], v[100:103]
	v_mfma_f32_16x16x32_f16 v[128:131], v[194:197], v[178:181], v[128:131]
	v_mfma_f32_16x16x32_f16 v[124:127], v[194:197], v[186:189], v[124:127]
	v_mfma_f32_16x16x32_f16 v[120:123], v[202:205], v[178:181], v[120:123]
	v_mfma_f32_16x16x32_f16 v[116:119], v[202:205], v[186:189], v[116:119]
	v_mfma_f32_16x16x32_f16 v[112:115], v[210:213], v[178:181], v[112:115]
	v_mfma_f32_16x16x32_f16 v[108:111], v[210:213], v[186:189], v[108:111]
	v_mfma_f32_16x16x32_f16 v[104:107], v[218:221], v[178:181], v[104:107]
	v_mfma_f32_16x16x32_f16 v[100:103], v[218:221], v[186:189], v[100:103]
	s_barrier
	v_lshl_add_u64 v[250:251], v[228:229], 0, s[58:59]
	s_or_b32 m0, s100, 0x18000
	ds_read_b128 v[230:233], v157
	ds_read_b128 v[238:241], v157 offset:1024
	ds_read_b128 v[242:245], v157 offset:2048
	ds_read_b128 v[246:249], v157 offset:3072
	global_load_lds_dwordx4 v[250:251], off
	v_lshl_add_u64 v[250:251], v[236:237], 0, s[58:59]
	s_or_b32 m0, s100, 0x1a000
	s_nop 0
	global_load_lds_dwordx4 v[250:251], off
	s_barrier
	s_waitcnt lgkmcnt(0)
	s_waitcnt lgkmcnt(0)
	v_mfma_f32_16x16x32_f16 v[96:99], v[190:193], v[230:233], v[96:99]
	v_mfma_f32_16x16x32_f16 v[92:95], v[190:193], v[242:245], v[92:95]
	v_mfma_f32_16x16x32_f16 v[88:91], v[198:201], v[230:233], v[88:91]
	v_mfma_f32_16x16x32_f16 v[84:87], v[198:201], v[242:245], v[84:87]
	v_mfma_f32_16x16x32_f16 v[80:83], v[206:209], v[230:233], v[80:83]
	v_mfma_f32_16x16x32_f16 v[76:79], v[206:209], v[242:245], v[76:79]
	v_mfma_f32_16x16x32_f16 v[72:75], v[214:217], v[230:233], v[72:75]
	v_mfma_f32_16x16x32_f16 v[68:71], v[214:217], v[242:245], v[68:71]
	v_mfma_f32_16x16x32_f16 v[96:99], v[194:197], v[238:241], v[96:99]
	v_mfma_f32_16x16x32_f16 v[92:95], v[194:197], v[246:249], v[92:95]
	v_mfma_f32_16x16x32_f16 v[88:91], v[202:205], v[238:241], v[88:91]
	v_mfma_f32_16x16x32_f16 v[84:87], v[202:205], v[246:249], v[84:87]
	v_mfma_f32_16x16x32_f16 v[80:83], v[210:213], v[238:241], v[80:83]
	v_mfma_f32_16x16x32_f16 v[76:79], v[210:213], v[246:249], v[76:79]
	v_mfma_f32_16x16x32_f16 v[72:75], v[218:221], v[238:241], v[72:75]
	v_mfma_f32_16x16x32_f16 v[68:71], v[218:221], v[246:249], v[68:71]
	v_lshl_add_u64 v[222:223], v[222:223], 0, s[22:23]
	s_or_b32 m0, s100, 0x8000
	s_barrier
	ds_read_b128 v[190:193], v156 offset:49152
	ds_read_b128 v[194:197], v156 offset:50176
	ds_read_b128 v[198:201], v154 offset:49152
	ds_read_b128 v[202:205], v154 offset:50176
	ds_read_b128 v[206:209], v153 offset:49152
	ds_read_b128 v[210:213], v153 offset:50176
	ds_read_b128 v[214:217], v152 offset:49152
	ds_read_b128 v[218:221], v152 offset:50176
	global_load_lds_dwordx4 v[222:223], off
	v_lshl_add_u64 v[222:223], v[226:227], 0, s[22:23]
	s_or_b32 m0, s100, 0xa000
	s_nop 0
	global_load_lds_dwordx4 v[222:223], off
	s_barrier
; #define LDA8(dst, b, h) _Pragma("unroll") for (int m = 0; m < 4; ++m) _Pragma("unroll") for (int k = 0; k < 2; ++k) \
;     dst[m][k] = *(const bf16x8*)((const char*)SA8(b, h) + lds_byte8(wr * 64 + m * 16 + fr, k * 32 + fq * 8))
; #define LDB8(dst, b, h) _Pragma("unroll") for (int n = 0; n < 2; ++n) _Pragma("unroll") for (int k = 0; k < 2; ++k) \
;     dst[n][k] = *(const bf16x8*)((const char*)SB8(b, h) + lds_byte8(wc * 32 + n * 16 + fr, k * 32 + fq * 8))
; #define WAIT_V8(n) asm volatile("s_waitcnt vmcnt(" #n ")" ::: "memory")
; #define WAIT_L8(n) asm volatile("s_waitcnt lgkmcnt(" #n ")" ::: "memory")
; #define BAR8 __builtin_amdgcn_s_barrier()
; #define SCHED8 __builtin_amdgcn_sched_barrier(0)
;     ...
;     BAR8; WAIT_L8(0); MMA8(1, 0, At, B0); BAR8; SCHED8;
;     STAGE8(SB8(1, 1), Bt, K, bcol + 128, tt + 3);
;     WAIT_V8(6); BAR8; MMA8(1, 1, At, B1); BAR8;
;   }
;   { LDB8(B0, 0, 0); LDA8(At, 0, 0); STAGE8(SA8(1, 1), A, lda, brow + 128, nt - 1);
;     BAR8; WAIT_L8(0); MMA8(0, 0, At, B0); BAR8;
;     LDB8(B1, 0, 1); BAR8; WAIT_L8(0); MMA8(0, 1, At, B1); BAR8;
	s_waitcnt lgkmcnt(0)
	s_waitcnt lgkmcnt(0)
	v_mfma_f32_16x16x32_f16 v[64:67], v[190:193], v[174:177], v[64:67]
	v_mfma_f32_16x16x32_f16 v[60:63], v[190:193], v[182:185], v[60:63]
	v_mfma_f32_16x16x32_f16 v[56:59], v[198:201], v[174:177], v[56:59]
	v_mfma_f32_16x16x32_f16 v[52:55], v[198:201], v[182:185], v[52:55]
	v_mfma_f32_16x16x32_f16 v[48:51], v[206:209], v[174:177], v[48:51]
	v_mfma_f32_16x16x32_f16 v[44:47], v[206:209], v[182:185], v[44:47]
	v_mfma_f32_16x16x32_f16 v[40:43], v[214:217], v[174:177], v[40:43]
	v_mfma_f32_16x16x32_f16 v[36:39], v[214:217], v[182:185], v[36:39]
	v_mfma_f32_16x16x32_f16 v[64:67], v[194:197], v[178:181], v[64:67]
	v_mfma_f32_16x16x32_f16 v[60:63], v[194:197], v[186:189], v[60:63]
	v_mfma_f32_16x16x32_f16 v[56:59], v[202:205], v[178:181], v[56:59]
	v_mfma_f32_16x16x32_f16 v[52:55], v[202:205], v[186:189], v[52:55]
	v_mfma_f32_16x16x32_f16 v[48:51], v[210:213], v[178:181], v[48:51]
	v_mfma_f32_16x16x32_f16 v[44:47], v[210:213], v[186:189], v[44:47]
	v_mfma_f32_16x16x32_f16 v[40:43], v[218:221], v[178:181], v[40:43]
	v_mfma_f32_16x16x32_f16 v[36:39], v[218:221], v[186:189], v[36:39]
	s_barrier
	v_lshl_add_u64 v[174:175], v[228:229], 0, s[60:61]
	s_or_b32 m0, s100, 0x1c000
	s_nop 0
	global_load_lds_dwordx4 v[174:175], off
	v_lshl_add_u64 v[174:175], v[236:237], 0, s[60:61]
	s_or_b32 m0, s100, 0x1e000
	s_nop 0
	global_load_lds_dwordx4 v[174:175], off
	s_waitcnt vmcnt(6)
	s_barrier
	v_mfma_f32_16x16x32_f16 v[32:35], v[190:193], v[230:233], v[32:35]
	v_mfma_f32_16x16x32_f16 v[28:31], v[190:193], v[242:245], v[28:31]
	v_mfma_f32_16x16x32_f16 v[24:27], v[198:201], v[230:233], v[24:27]
	v_mfma_f32_16x16x32_f16 v[20:23], v[198:201], v[242:245], v[20:23]
	v_mfma_f32_16x16x32_f16 v[16:19], v[206:209], v[230:233], v[16:19]
	v_mfma_f32_16x16x32_f16 v[12:15], v[206:209], v[242:245], v[12:15]
	v_mfma_f32_16x16x32_f16 v[8:11], v[214:217], v[230:233], v[8:11]
	v_mfma_f32_16x16x32_f16 v[4:7], v[214:217], v[242:245], v[4:7]
	v_mfma_f32_16x16x32_f16 v[32:35], v[194:197], v[238:241], v[32:35]
	v_mfma_f32_16x16x32_f16 v[28:31], v[194:197], v[246:249], v[28:31]
	v_mfma_f32_16x16x32_f16 v[24:27], v[202:205], v[238:241], v[24:27]
	v_mfma_f32_16x16x32_f16 v[20:23], v[202:205], v[246:249], v[20:23]
	v_mfma_f32_16x16x32_f16 v[16:19], v[210:213], v[238:241], v[16:19]
	v_mfma_f32_16x16x32_f16 v[12:15], v[210:213], v[246:249], v[12:15]
	v_mfma_f32_16x16x32_f16 v[8:11], v[218:221], v[238:241], v[8:11]
	v_mfma_f32_16x16x32_f16 v[4:7], v[218:221], v[246:249], v[4:7]
	s_add_i32 s1, s1, 2
	s_add_u32 s14, s14, 0x100
	s_addc_u32 s15, s15, 0
	s_cmp_lt_u32 s1, 12
	s_barrier
	s_cbranch_scc1 .LBB0_242
	s_add_u32 s12, s12, 0x40780
	s_addc_u32 s13, s13, 0
	v_lshl_add_u64 v[132:133], s[12:13], 0, v[132:133]
	v_lshl_add_u64 v[0:1], v[0:1], 1, v[132:133]
	s_or_b32 m0, s100, 0xc000
	ds_read_b128 v[138:141], v171
	ds_read_b128 v[142:145], v171 offset:1024
	ds_read_b128 v[160:163], v171 offset:2048
	ds_read_b128 v[164:167], v171 offset:3072
	ds_read_b128 v[174:177], v156
	ds_read_b128 v[178:181], v156 offset:1024
	ds_read_b128 v[182:185], v154
	ds_read_b128 v[186:189], v154 offset:1024
	ds_read_b128 v[190:193], v153
	ds_read_b128 v[194:197], v153 offset:1024
	ds_read_b128 v[198:201], v152
	ds_read_b128 v[202:205], v152 offset:1024
	global_load_lds_dwordx4 v[0:1], off
	v_lshl_add_u64 v[0:1], s[12:13], 0, v[136:137]
	v_lshl_add_u64 v[0:1], v[134:135], 1, v[0:1]
	s_or_b32 m0, s100, 0xe000
	s_nop 0
	global_load_lds_dwordx4 v[0:1], off
	s_barrier
	s_waitcnt lgkmcnt(0)
	s_waitcnt lgkmcnt(0)
	v_mfma_f32_16x16x32_f16 v[128:131], v[174:177], v[138:141], v[128:131]
	v_mfma_f32_16x16x32_f16 v[124:127], v[174:177], v[160:163], v[124:127]
	v_mfma_f32_16x16x32_f16 v[120:123], v[182:185], v[138:141], v[120:123]
	v_mfma_f32_16x16x32_f16 v[112:115], v[190:193], v[138:141], v[112:115]
	v_mfma_f32_16x16x32_f16 v[128:131], v[178:181], v[142:145], v[128:131]
	v_mfma_f32_16x16x32_f16 v[124:127], v[178:181], v[164:167], v[124:127]
	v_mfma_f32_16x16x32_f16 v[120:123], v[186:189], v[142:145], v[120:123]
	v_mfma_f32_16x16x32_f16 v[116:119], v[182:185], v[160:163], v[116:119]
	v_mfma_f32_16x16x32_f16 v[112:115], v[194:197], v[142:145], v[112:115]
	v_mfma_f32_16x16x32_f16 v[108:111], v[190:193], v[160:163], v[108:111]
	v_mfma_f32_16x16x32_f16 v[104:107], v[198:201], v[138:141], v[104:107]
	v_mfma_f32_16x16x32_f16 v[100:103], v[198:201], v[160:163], v[100:103]
	v_mfma_f32_16x16x32_f16 v[132:135], v[186:189], v[164:167], v[116:119]
	v_mfma_f32_16x16x32_f16 v[170:173], v[194:197], v[164:167], v[108:111]
	v_mfma_f32_16x16x32_f16 v[206:209], v[202:205], v[142:145], v[104:107]
	v_mfma_f32_16x16x32_f16 v[210:213], v[202:205], v[164:167], v[100:103]
	s_barrier
	s_nop 1
	ds_read_b128 v[100:103], v168
	ds_read_b128 v[104:107], v168 offset:1024
	ds_read_b128 v[108:111], v168 offset:2048
	ds_read_b128 v[116:119], v168 offset:3072
	s_barrier
	s_waitcnt lgkmcnt(0)
	s_waitcnt lgkmcnt(0)
	v_mfma_f32_16x16x32_f16 v[80:83], v[190:193], v[100:103], v[80:83]
	v_mfma_f32_16x16x32_f16 v[76:79], v[190:193], v[108:111], v[76:79]
	v_mfma_f32_16x16x32_f16 v[72:75], v[198:201], v[100:103], v[72:75]
	v_mfma_f32_16x16x32_f16 v[68:71], v[198:201], v[108:111], v[68:71]
	v_mfma_f32_16x16x32_f16 v[96:99], v[174:177], v[100:103], v[96:99]
	v_mfma_f32_16x16x32_f16 v[92:95], v[174:177], v[108:111], v[92:95]
	v_mfma_f32_16x16x32_f16 v[88:91], v[182:185], v[100:103], v[88:91]
	v_mfma_f32_16x16x32_f16 v[84:87], v[182:185], v[108:111], v[84:87]
	v_mfma_f32_16x16x32_f16 v[80:83], v[194:197], v[104:107], v[80:83]
	v_mfma_f32_16x16x32_f16 v[76:79], v[194:197], v[116:119], v[76:79]
	v_mfma_f32_16x16x32_f16 v[72:75], v[202:205], v[104:107], v[72:75]
	v_mfma_f32_16x16x32_f16 v[68:71], v[202:205], v[116:119], v[68:71]
	v_mfma_f32_16x16x32_f16 v[214:217], v[178:181], v[104:107], v[96:99]
	v_mfma_f32_16x16x32_f16 v[174:177], v[178:181], v[116:119], v[92:95]
	v_mfma_f32_16x16x32_f16 v[178:181], v[186:189], v[104:107], v[88:91]
	v_mfma_f32_16x16x32_f16 v[182:185], v[186:189], v[116:119], v[84:87]
	s_barrier
; #define LDA8(dst, b, h) _Pragma("unroll") for (int m = 0; m < 4; ++m) _Pragma("unroll") for (int k = 0; k < 2; ++k) \
;     dst[m][k] = *(const bf16x8*)((const char*)SA8(b, h) + lds_byte8(wr * 64 + m * 16 + fr, k * 32 + fq * 8))
; #define LDB8(dst, b, h) _Pragma("unroll") for (int n = 0; n < 2; ++n) _Pragma("unroll") for (int k = 0; k < 2; ++k) \
;     dst[n][k] = *(const bf16x8*)((const char*)SB8(b, h) + lds_byte8(wc * 32 + n * 16 + fr, k * 32 + fq * 8))
; #define WAIT_V8(n) asm volatile("s_waitcnt vmcnt(" #n ")" ::: "memory")
; #define WAIT_L8(n) asm volatile("s_waitcnt lgkmcnt(" #n ")" ::: "memory")
; #define BAR8 __builtin_amdgcn_s_barrier()
;     ...
;     LDA8(At, 0, 1); WAIT_V8(4); BAR8; WAIT_L8(0); MMA8(1, 0, At, B0); MMA8(1, 1, At, B1); BAR8; }
;   { LDB8(B0, 1, 0); LDA8(At, 1, 0); WAIT_V8(2); BAR8; WAIT_L8(0); MMA8(0, 0, At, B0); BAR8;
	s_nop 0
	ds_read_b128 v[84:87], v156 offset:16384
	ds_read_b128 v[88:91], v156 offset:17408
	ds_read_b128 v[92:95], v154 offset:16384
	ds_read_b128 v[96:99], v154 offset:17408
	ds_read_b128 v[186:189], v153 offset:16384
	ds_read_b128 v[190:193], v153 offset:17408
	ds_read_b128 v[194:197], v152 offset:16384
	ds_read_b128 v[198:201], v152 offset:17408
	s_waitcnt vmcnt(4)
	s_barrier
	s_waitcnt lgkmcnt(0)
	s_waitcnt lgkmcnt(0)
	v_mfma_f32_16x16x32_f16 v[64:67], v[84:87], v[138:141], v[64:67]
	v_mfma_f32_16x16x32_f16 v[60:63], v[84:87], v[160:163], v[60:63]
	v_mfma_f32_16x16x32_f16 v[56:59], v[92:95], v[138:141], v[56:59]
	v_mfma_f32_16x16x32_f16 v[52:55], v[92:95], v[160:163], v[52:55]
	v_mfma_f32_16x16x32_f16 v[48:51], v[186:189], v[138:141], v[48:51]
	v_mfma_f32_16x16x32_f16 v[44:47], v[186:189], v[160:163], v[44:47]
	v_mfma_f32_16x16x32_f16 v[40:43], v[194:197], v[138:141], v[40:43]
	v_mfma_f32_16x16x32_f16 v[36:39], v[194:197], v[160:163], v[36:39]
	v_mfma_f32_16x16x32_f16 v[64:67], v[88:91], v[142:145], v[64:67]
	v_mfma_f32_16x16x32_f16 v[60:63], v[88:91], v[164:167], v[60:63]
	v_mfma_f32_16x16x32_f16 v[56:59], v[96:99], v[142:145], v[56:59]
	v_mfma_f32_16x16x32_f16 v[52:55], v[96:99], v[164:167], v[52:55]
	v_mfma_f32_16x16x32_f16 v[48:51], v[190:193], v[142:145], v[48:51]
	v_mfma_f32_16x16x32_f16 v[44:47], v[190:193], v[164:167], v[44:47]
	v_mfma_f32_16x16x32_f16 v[40:43], v[198:201], v[142:145], v[40:43]
	v_mfma_f32_16x16x32_f16 v[36:39], v[198:201], v[164:167], v[36:39]
	v_mfma_f32_16x16x32_f16 v[32:35], v[84:87], v[100:103], v[32:35]
	v_mfma_f32_16x16x32_f16 v[28:31], v[84:87], v[108:111], v[28:31]
	v_mfma_f32_16x16x32_f16 v[24:27], v[92:95], v[100:103], v[24:27]
	v_mfma_f32_16x16x32_f16 v[20:23], v[92:95], v[108:111], v[20:23]
	v_mfma_f32_16x16x32_f16 v[16:19], v[186:189], v[100:103], v[16:19]
	v_mfma_f32_16x16x32_f16 v[12:15], v[186:189], v[108:111], v[12:15]
	v_mfma_f32_16x16x32_f16 v[8:11], v[194:197], v[100:103], v[8:11]
	v_mfma_f32_16x16x32_f16 v[4:7], v[194:197], v[108:111], v[4:7]
	v_mfma_f32_16x16x32_f16 v[136:139], v[88:91], v[104:107], v[32:35]
	v_mfma_f32_16x16x32_f16 v[140:143], v[88:91], v[116:119], v[28:31]
	v_mfma_f32_16x16x32_f16 v[160:163], v[96:99], v[104:107], v[24:27]
	v_mfma_f32_16x16x32_f16 v[164:167], v[96:99], v[116:119], v[20:23]
	v_mfma_f32_16x16x32_f16 v[202:205], v[190:193], v[104:107], v[16:19]
	v_mfma_f32_16x16x32_f16 v[186:189], v[190:193], v[116:119], v[12:15]
	v_mfma_f32_16x16x32_f16 v[190:193], v[198:201], v[104:107], v[8:11]
	v_mfma_f32_16x16x32_f16 v[194:197], v[198:201], v[116:119], v[4:7]
	s_barrier
	ds_read_b128 v[198:201], v159
	ds_read_b128 v[218:221], v159 offset:1024
	ds_read_b128 v[230:233], v159 offset:2048
	ds_read_b128 v[238:241], v159 offset:3072
	ds_read_b128 v[8:11], v156 offset:32768
	ds_read_b128 v[12:15], v156 offset:33792
	ds_read_b128 v[16:19], v154 offset:32768
	ds_read_b128 v[24:27], v154 offset:33792
	ds_read_b128 v[28:31], v153 offset:32768
	ds_read_b128 v[32:35], v153 offset:33792
	ds_read_b128 v[242:245], v152 offset:32768
	ds_read_b128 v[246:249], v152 offset:33792
	s_waitcnt vmcnt(2)
	s_barrier
	s_waitcnt lgkmcnt(0)
	s_waitcnt lgkmcnt(0)
	v_mfma_f32_16x16x32_f16 v[4:7], v[8:11], v[198:201], v[128:131]
	v_mfma_f32_16x16x32_f16 v[104:107], v[12:15], v[218:221], v[4:7]
	v_mfma_f32_16x16x32_f16 v[4:7], v[8:11], v[230:233], v[124:127]
	v_mfma_f32_16x16x32_f16 v[116:119], v[12:15], v[238:241], v[4:7]
	v_mfma_f32_16x16x32_f16 v[4:7], v[16:19], v[198:201], v[120:123]
	v_mfma_f32_16x16x32_f16 v[100:103], v[24:27], v[218:221], v[4:7]
	v_mfma_f32_16x16x32_f16 v[4:7], v[16:19], v[230:233], v[132:135]
	v_mfma_f32_16x16x32_f16 v[108:111], v[24:27], v[238:241], v[4:7]
	v_mfma_f32_16x16x32_f16 v[4:7], v[28:31], v[198:201], v[112:115]
	v_mfma_f32_16x16x32_f16 v[92:95], v[32:35], v[218:221], v[4:7]
	v_mfma_f32_16x16x32_f16 v[4:7], v[28:31], v[230:233], v[170:173]
	v_mfma_f32_16x16x32_f16 v[96:99], v[32:35], v[238:241], v[4:7]
	v_mfma_f32_16x16x32_f16 v[4:7], v[242:245], v[198:201], v[206:209]
	v_mfma_f32_16x16x32_f16 v[84:87], v[246:249], v[218:221], v[4:7]
	v_mfma_f32_16x16x32_f16 v[4:7], v[242:245], v[230:233], v[210:213]
	v_mfma_f32_16x16x32_f16 v[88:91], v[246:249], v[238:241], v[4:7]
	s_barrier
; DI int tid_opaque() { int t = threadIdx.x; asm volatile("" : "+v"(t)); return t; }
; #define LDA8(dst, b, h) _Pragma("unroll") for (int m = 0; m < 4; ++m) _Pragma("unroll") for (int k = 0; k < 2; ++k) \
;     dst[m][k] = *(const bf16x8*)((const char*)SA8(b, h) + lds_byte8(wr * 64 + m * 16 + fr, k * 32 + fq * 8))
; #define LDB8(dst, b, h) _Pragma("unroll") for (int n = 0; n < 2; ++n) _Pragma("unroll") for (int k = 0; k < 2; ++k) \
;     dst[n][k] = *(const bf16x8*)((const char*)SB8(b, h) + lds_byte8(wc * 32 + n * 16 + fr, k * 32 + fq * 8))
; #define WAIT_V8(n) asm volatile("s_waitcnt vmcnt(" #n ")" ::: "memory")
; #define WAIT_L8(n) asm volatile("s_waitcnt lgkmcnt(" #n ")" ::: "memory")
; #define BAR8 __builtin_amdgcn_s_barrier()
;     ...
;     LDB8(B1, 1, 1); WAIT_V8(0); BAR8; WAIT_L8(0); MMA8(0, 1, At, B1); BAR8;
;     LDA8(At, 1, 1); BAR8; WAIT_L8(0); MMA8(1, 0, At, B0); MMA8(1, 1, At, B1); BAR8; }
;   if (wr == 0) BAR8;
;   __syncthreads();
;   if (EPI == EPI_GU && nm0 >= 0) {
;     const int t = tid_opaque();
;     STAGE8(SB8(0, 0), Bt, K, nn0, 0); STAGE8(SA8(0, 0), A, lda, nm0, 0);
;     STAGE8(SB8(0, 1), Bt, K, nn0 + 128, 0); STAGE8(SA8(0, 1), A, lda, nm0 + 128, 0);
;   }
;     ...
;   if (t < 256) {
	ds_read_b128 v[132:135], v157
	ds_read_b128 v[168:171], v157 offset:1024
	ds_read_b128 v[206:209], v157 offset:2048
	ds_read_b128 v[210:213], v157 offset:3072
	s_waitcnt vmcnt(0)
	s_barrier
	s_waitcnt lgkmcnt(0)
	s_waitcnt lgkmcnt(0)
	v_mfma_f32_16x16x32_f16 v[4:7], v[8:11], v[132:135], v[214:217]
	v_mfma_f32_16x16x32_f16 v[8:11], v[8:11], v[206:209], v[174:177]
	v_mfma_f32_16x16x32_f16 v[4:7], v[12:15], v[168:171], v[4:7]
	v_mfma_f32_16x16x32_f16 v[20:23], v[12:15], v[210:213], v[8:11]
	v_mfma_f32_16x16x32_f16 v[8:11], v[16:19], v[132:135], v[178:181]
	v_mfma_f32_16x16x32_f16 v[12:15], v[16:19], v[206:209], v[182:185]
	v_mfma_f32_16x16x32_f16 v[8:11], v[24:27], v[168:171], v[8:11]
	v_mfma_f32_16x16x32_f16 v[24:27], v[24:27], v[210:213], v[12:15]
	v_mfma_f32_16x16x32_f16 v[12:15], v[28:31], v[132:135], v[80:83]
	v_mfma_f32_16x16x32_f16 v[16:19], v[28:31], v[206:209], v[76:79]
	v_mfma_f32_16x16x32_f16 v[12:15], v[32:35], v[168:171], v[12:15]
	v_mfma_f32_16x16x32_f16 v[28:31], v[32:35], v[210:213], v[16:19]
	v_mfma_f32_16x16x32_f16 v[16:19], v[242:245], v[132:135], v[72:75]
	v_mfma_f32_16x16x32_f16 v[32:35], v[242:245], v[206:209], v[68:71]
	v_mfma_f32_16x16x32_f16 v[16:19], v[246:249], v[168:171], v[16:19]
	v_mfma_f32_16x16x32_f16 v[32:35], v[246:249], v[210:213], v[32:35]
	s_barrier
	ds_read_b128 v[172:175], v156 offset:49152
	ds_read_b128 v[156:159], v156 offset:50176
	ds_read_b128 v[176:179], v154 offset:49152
	ds_read_b128 v[180:183], v154 offset:50176
	ds_read_b128 v[214:217], v153 offset:49152
	ds_read_b128 v[242:245], v153 offset:50176
	ds_read_b128 v[246:249], v152 offset:49152
	ds_read_b128 v[150:153], v152 offset:50176
	s_barrier
	s_waitcnt lgkmcnt(0)
	s_waitcnt lgkmcnt(0)
	v_mfma_f32_16x16x32_f16 v[64:67], v[172:175], v[198:201], v[64:67]
	v_mfma_f32_16x16x32_f16 v[60:63], v[172:175], v[230:233], v[60:63]
	v_mfma_f32_16x16x32_f16 v[56:59], v[176:179], v[198:201], v[56:59]
	v_mfma_f32_16x16x32_f16 v[52:55], v[176:179], v[230:233], v[52:55]
	v_mfma_f32_16x16x32_f16 v[48:51], v[214:217], v[198:201], v[48:51]
	v_mfma_f32_16x16x32_f16 v[44:47], v[214:217], v[230:233], v[44:47]
	v_mfma_f32_16x16x32_f16 v[40:43], v[246:249], v[198:201], v[40:43]
	v_mfma_f32_16x16x32_f16 v[36:39], v[246:249], v[230:233], v[36:39]
	v_mfma_f32_16x16x32_f16 v[128:131], v[156:159], v[218:221], v[64:67]
	v_mfma_f32_16x16x32_f16 v[124:127], v[156:159], v[238:241], v[60:63]
	v_mfma_f32_16x16x32_f16 v[120:123], v[180:183], v[218:221], v[56:59]
	v_mfma_f32_16x16x32_f16 v[112:115], v[180:183], v[238:241], v[52:55]
	v_mfma_f32_16x16x32_f16 v[80:83], v[242:245], v[218:221], v[48:51]
	v_mfma_f32_16x16x32_f16 v[76:79], v[242:245], v[238:241], v[44:47]
	v_mfma_f32_16x16x32_f16 v[72:75], v[150:153], v[218:221], v[40:43]
	v_mfma_f32_16x16x32_f16 v[68:71], v[150:153], v[238:241], v[36:39]
	v_mfma_f32_16x16x32_f16 v[40:43], v[172:175], v[206:209], v[140:143]
	v_mfma_f32_16x16x32_f16 v[44:47], v[176:179], v[206:209], v[164:167]
	v_mfma_f32_16x16x32_f16 v[48:51], v[214:217], v[206:209], v[186:189]
	v_mfma_f32_16x16x32_f16 v[36:39], v[172:175], v[132:135], v[136:139]
	v_mfma_f32_16x16x32_f16 v[52:55], v[156:159], v[210:213], v[40:43]
	v_mfma_f32_16x16x32_f16 v[40:43], v[176:179], v[132:135], v[160:163]
	v_mfma_f32_16x16x32_f16 v[56:59], v[180:183], v[210:213], v[44:47]
	v_mfma_f32_16x16x32_f16 v[44:47], v[214:217], v[132:135], v[202:205]
	v_mfma_f32_16x16x32_f16 v[60:63], v[242:245], v[210:213], v[48:51]
	v_mfma_f32_16x16x32_f16 v[48:51], v[246:249], v[132:135], v[190:193]
	v_mfma_f32_16x16x32_f16 v[64:67], v[246:249], v[206:209], v[194:197]
	v_mfma_f32_16x16x32_f16 v[36:39], v[156:159], v[168:171], v[36:39]
	v_mfma_f32_16x16x32_f16 v[40:43], v[180:183], v[168:171], v[40:43]
	v_mfma_f32_16x16x32_f16 v[44:47], v[242:245], v[168:171], v[44:47]
	v_mfma_f32_16x16x32_f16 v[48:51], v[150:153], v[168:171], v[48:51]
	v_mfma_f32_16x16x32_f16 v[64:67], v[150:153], v[210:213], v[64:67]
	s_movk_i32 s1, 0x100
	v_cmp_gt_u32_e32 vcc, s1, v3
	s_barrier
	s_and_saveexec_b64 s[12:13], vcc
	s_cbranch_execz .LBB0_245
	s_barrier

; #define BAR8 __builtin_amdgcn_s_barrier()
; #define G_XF (outp())
; #define G_SS ((float*)(wsp() + OFF_SS))
;     ...
;     STAGE8(SB8(0, 0), Bt, K, bcol, 0); STAGE8(SA8(0, 0), A, lda, brow, 0);
;     STAGE8(SB8(0, 1), Bt, K, bcol + 128, 0); STAGE8(SA8(0, 1), A, lda, brow + 128, 0);
;   }
;   if (wr == 1) BAR8;
; __global__ void __launch_bounds__(512, 2) mega(Params p) {
;     ...
;     for (int item = bid; item < 4 * 64; item += nb) {
;       const int nt = item >> 6, mt = item & 63;
;       e.ss = nullptr; e.xf = G_XF; e.xb = G_XB; e.ss_out = G_SS;
;       gemm_tile<EPI_RESID, 256, false>(G_OB, DM, wb + W_OUT, DM, mt * 256, nt * 256, e);
.LBB0_905:
	s_mov_b32 s0, 24
	s_mov_b32 s0, 25
	s_ashr_i32 s1, s0, 31
	s_lshl_b64 s[0:1], s[0:1], 3
	s_add_u32 s0, s70, s0
	s_addc_u32 s1, s71, s1
	v_readlane_b32 s6, v255, 60
	v_readlane_b32 s7, v255, 61
	s_nop 4
	s_mov_b32 s0, 25
	s_ashr_i32 s1, s0, 31
	s_lshl_b64 s[0:1], s[0:1], 3
	s_add_u32 s0, s70, s0
	s_addc_u32 s1, s71, s1
	s_mov_b32 s2, 25
	v_readlane_b32 s0, v255, 60
	v_readlane_b32 s1, v255, 61
	s_nop 4
	s_ashr_i32 s3, s2, 31
	s_lshl_b64 s[2:3], s[2:3], 3
	s_add_u32 s2, s70, s2
	s_addc_u32 s3, s71, s3
	v_mov_b32_e32 v3, v224
	v_readlane_b32 s2, v255, 60
	v_readlane_b32 s3, v255, 61
	s_nop 4
	v_mov_b32_e32 v18, 1
	v_bfe_i32 v1, v3, 27, 1
	s_waitcnt vmcnt(10)
	v_lshlrev_b32_e32 v150, 4, v3
	s_nop 0
	v_readfirstlane_b32 s100, v150
	v_lshrrev_b32_e32 v1, 22, v1
	v_add_u32_e32 v1, v150, v1
	v_and_b32_e32 v1, 0xfffffc00, v1
	v_ashrrev_i32_e32 v0, 31, v3
	v_sub_u32_e32 v1, v150, v1
	v_lshrrev_b32_e32 v0, 26, v0
	v_lshrrev_b32_e32 v5, 4, v1
	v_add_u32_e32 v0, v3, v0
	v_bitop3_b32 v5, v5, v1, 32 bitop3:0x6c
	v_ashrrev_i32_e32 v1, 31, v1
	s_waitcnt lgkmcnt(0)
	s_add_u32 s29, s2, 0x6000000
	v_ashrrev_i32_e32 v0, 6, v0
	v_lshrrev_b32_e32 v1, 26, v1
	s_addc_u32 s33, s3, 0
	s_lshl_b32 s8, s24, 8
	v_lshlrev_b32_e32 v6, 3, v0
	v_add_u32_e32 v1, v5, v1
	s_and_b32 s25, s8, 0x3f00
	s_lshl_b32 s8, s24, 2
	v_and_b32_e32 v6, -16, v6
	v_ashrrev_i32_e32 v1, 6, v1
	s_and_b32 s8, s8, 0xffffff00
	v_add_u32_e32 v16, v1, v6
	v_mul_i32_i24_e32 v1, 64, v1
	s_ashr_i32 s9, s8, 31
	v_lshlrev_b32_e32 v0, 5, v0
	v_sub_u32_e32 v1, v5, v1
	s_waitcnt vmcnt(9)
	v_add_u32_e32 v152, 0x2000, v150
	s_lshl_b64 s[12:13], s[8:9], 11
	v_and_b32_e32 v0, 32, v0
	v_ashrrev_i16_sdwa v1, v18, sext(v1) dst_sel:DWORD dst_unused:UNUSED_PAD src0_sel:DWORD src1_sel:BYTE_0
	v_ashrrev_i32_e32 v5, 31, v152
	s_add_u32 s12, s14, s12
	v_add_u32_sdwa v0, v0, sext(v1) dst_sel:DWORD dst_unused:UNUSED_PAD src0_sel:DWORD src1_sel:WORD_0
	v_ashrrev_i32_e32 v17, 31, v16
	v_lshrrev_b32_e32 v5, 22, v5
	s_addc_u32 s13, s15, s13
	v_lshlrev_b64 v[6:7], 11, v[16:17]
	v_ashrrev_i32_e32 v1, 31, v0
	v_add_u32_e32 v5, v152, v5
	v_lshl_add_u64 v[10:11], s[12:13], 0, v[6:7]
	v_lshlrev_b64 v[8:9], 1, v[0:1]
	v_ashrrev_i32_e32 v5, 10, v5
	v_lshl_add_u64 v[14:15], v[10:11], 0, v[8:9]
	v_mul_i32_i24_e32 v10, 0x400, v5
	v_sub_u32_e32 v10, v152, v10
	v_lshrrev_b32_e32 v11, 4, v10
	v_bitop3_b32 v10, v11, v10, 32 bitop3:0x6c
	v_ashrrev_i32_e32 v12, 31, v10
	v_lshrrev_b32_e32 v12, 26, v12
	v_lshlrev_b32_e32 v11, 3, v5
	v_add_u32_e32 v12, v10, v12
	v_and_b32_e32 v11, -16, v11
	v_ashrrev_i32_e32 v13, 6, v12
	v_add_u32_e32 v24, v13, v11
	v_and_b32_e32 v11, 0xc0, v12
	v_lshlrev_b32_e32 v5, 5, v5
	v_sub_u32_e32 v10, v10, v11
	v_add_u32_e32 v151, 0x10000, v150
	v_and_b32_e32 v5, 32, v5
	v_ashrrev_i16_sdwa v10, v18, sext(v10) dst_sel:DWORD dst_unused:UNUSED_PAD src0_sel:DWORD src1_sel:BYTE_0
	v_ashrrev_i32_e32 v25, 31, v24
	v_add_u32_sdwa v132, v5, sext(v10) dst_sel:DWORD dst_unused:UNUSED_PAD src0_sel:DWORD src1_sel:WORD_0
	v_lshlrev_b64 v[10:11], 11, v[24:25]
	s_waitcnt vmcnt(8)
	v_add_u32_e32 v157, 0x12000, v150
	v_mov_b32_e32 v4, v2
	s_or_b32 m0, s100, 0x10000
	v_lshl_add_u64 v[18:19], s[12:13], 0, v[10:11]
	global_load_lds_dwordx4 v[14:15], off
	v_ashrrev_i32_e32 v133, 31, v132
	s_or_b32 m0, s100, 0x12000
	s_lshl_b32 s27, s25, 10
	s_lshl_b32 s12, s25, 11
	v_lshlrev_b64 v[12:13], 1, v[132:133]
	s_add_u32 s12, s29, s12
	v_lshl_add_u64 v[18:19], v[18:19], 0, v[12:13]
	s_addc_u32 s13, s33, 0
	global_load_lds_dwordx4 v[18:19], off
	v_lshl_add_u64 v[20:21], s[12:13], 0, v[6:7]
	s_mov_b32 m0, s100
	s_or_b32 s30, s8, 0x80
	v_lshl_add_u64 v[20:21], v[20:21], 0, v[8:9]
	v_lshl_add_u64 v[22:23], s[12:13], 0, v[10:11]
	s_ashr_i32 s31, s30, 31
	global_load_lds_dwordx4 v[20:21], off
	s_or_b32 m0, s100, 0x2000
	s_lshl_b64 s[12:13], s[30:31], 11
	s_add_u32 s12, s14, s12
	s_addc_u32 s13, s15, s13
	v_add_u32_e32 v159, 0x14000, v150
	v_lshl_add_u64 v[22:23], v[22:23], 0, v[12:13]
	v_lshl_add_u64 v[26:27], s[12:13], 0, v[6:7]
	v_add_u32_e32 v161, 0x16000, v150
	s_bitset1_b32 s27, 17
	global_load_lds_dwordx4 v[22:23], off
	v_lshl_add_u64 v[26:27], v[26:27], 0, v[8:9]
	s_or_b32 m0, s100, 0x14000
	v_lshl_add_u64 v[28:29], s[12:13], 0, v[10:11]
	s_lshl_b32 s27, s27, 1
	global_load_lds_dwordx4 v[26:27], off
	s_or_b32 m0, s100, 0x16000
	s_add_u32 s12, s29, s27
	s_addc_u32 s13, s33, 0
	v_add_u32_e32 v162, 0x4000, v150
	v_lshl_add_u64 v[28:29], v[28:29], 0, v[12:13]
	v_lshl_add_u64 v[30:31], s[12:13], 0, v[6:7]
	global_load_lds_dwordx4 v[28:29], off
	v_lshl_add_u64 v[30:31], v[30:31], 0, v[8:9]
	s_or_b32 m0, s100, 0x4000
	v_add_u32_e32 v163, 0x6000, v150
	global_load_lds_dwordx4 v[30:31], off
	v_lshl_add_u64 v[30:31], s[12:13], 0, v[10:11]
	v_lshl_add_u64 v[30:31], v[30:31], 0, v[12:13]
	s_or_b32 m0, s100, 0x6000
	v_ashrrev_i32_e32 v5, 8, v3
	global_load_lds_dwordx4 v[30:31], off
	v_cmp_eq_u32_e32 vcc, 1, v5
	s_and_saveexec_b64 s[12:13], vcc
	s_cbranch_execz .LBB0_907
	s_barrier
; #define WAIT_V8(n) asm volatile("s_waitcnt vmcnt(" #n ")" ::: "memory")
; #define BAR8 __builtin_amdgcn_s_barrier()
;     ...
;   f32x4 acc[2][2][4][2];
;   {
;     float zinit = 0.f;
;     asm volatile("" : "+v"(zinit));
; #pragma unroll
;     for (int a = 0; a < 2; ++a)
; #pragma unroll
;       for (int b = 0; b < 2; ++b)
; #pragma unroll
;         for (int m = 0; m < 4; ++m)
; #pragma unroll
;           for (int n = 0; n < 2; ++n)
; #pragma unroll
;             for (int j = 0; j < 4; ++j) acc[a][b][m][n][j] = zinit;
;   }
;   bf16x8 At[4][2], B0[2][2], B1[2][2];
;   const int nt = K / 64;
;   if (!pre) {
;     STAGE8(SB8(0, 0), Bt, K, bcol, 0); STAGE8(SA8(0, 0), A, lda, brow, 0);
;     STAGE8(SB8(0, 1), Bt, K, bcol + 128, 0); STAGE8(SA8(0, 1), A, lda, brow + 128, 0);
;   }
;   if (wr == 1) BAR8;
;   WAIT_V8(4); BAR8;
;   STAGE8(SB8(1, 0), Bt, K, bcol, 1); STAGE8(SA8(1, 0), A, lda, brow, 1); STAGE8(SB8(1, 1), Bt, K, bcol + 128, 1);
;   WAIT_V8(6); BAR8;
.LBB0_907:
	s_or_b64 exec, exec, s[12:13]
	s_lshl_b32 s29, s20, 11
	s_waitcnt vmcnt(0)
	v_add_u32_e32 v164, 0x18000, v150
	s_and_b32 s36, s29, 0x1f80000
	s_mov_b64 s[38:39], 0x80
	v_add_u32_e32 v165, 0x1a000, v150
	v_lshl_add_u64 v[14:15], v[14:15], 0, s[38:39]
	s_or_b32 m0, s100, 0x18000
	v_add_u32_e32 v166, 0x8000, v150
	s_waitcnt vmcnt(4)
	s_barrier
	global_load_lds_dwordx4 v[14:15], off
	v_lshl_add_u64 v[14:15], v[18:19], 0, s[38:39]
	s_or_b32 m0, s100, 0x1a000
	v_add_u32_e32 v168, 0xa000, v150
	global_load_lds_dwordx4 v[14:15], off
	v_lshl_add_u64 v[14:15], v[20:21], 0, s[38:39]
	s_or_b32 m0, s100, 0x8000
	v_add_u32_e32 v169, 0x1c000, v150
	global_load_lds_dwordx4 v[14:15], off
	v_lshl_add_u64 v[14:15], v[22:23], 0, s[38:39]
	s_or_b32 m0, s100, 0xa000
	v_add_u32_e32 v170, 0x1e000, v150
	global_load_lds_dwordx4 v[14:15], off
	v_lshl_add_u64 v[14:15], v[26:27], 0, s[38:39]
	s_or_b32 m0, s100, 0x1c000
	s_nop 0
	global_load_lds_dwordx4 v[14:15], off
	v_lshl_add_u64 v[14:15], v[28:29], 0, s[38:39]
	s_or_b32 m0, s100, 0x1e000
	v_and_b32_e32 v147, 15, v3
	global_load_lds_dwordx4 v[14:15], off
	v_bfe_u32 v148, v3, 4, 2
	v_lshlrev_b32_e32 v14, 4, v148
	v_lshlrev_b32_e32 v15, 6, v147
	v_lshlrev_b32_e32 v18, 2, v3
	v_lshlrev_b64 v[136:137], 10, v[16:17]
	v_or_b32_e32 v17, v14, v15
	v_and_b32_e32 v18, 32, v18
	s_mov_b32 s29, 0x10000
	s_and_b32 s12, s21, 0xffffff00
	v_bitop3_b32 v20, v17, s29, v18 bitop3:0xde
	s_mov_b32 s29, 0x14000
	s_ashr_i32 s13, s12, 31
	v_readlane_b32 s40, v254, 35
	v_bitop3_b32 v19, v14, v18, v15 bitop3:0x36
	v_bitop3_b32 v21, v17, s29, v18 bitop3:0xde
	s_mov_b32 s29, 0x18000
	v_lshlrev_b32_e32 v15, 6, v3
	s_lshl_b64 s[12:13], s[12:13], 11
	s_mov_b32 s37, s40
	v_bitop3_b32 v22, v17, s29, v18 bitop3:0xde
	s_mov_b32 s29, 0x1c000
	v_and_b32_e32 v15, 0x3c0, v15
	v_bitop3_b32 v17, v17, s29, v18 bitop3:0xde
	v_bitop3_b32 v18, v15, v18, v14 bitop3:0x36
	v_lshl_add_u64 v[14:15], s[12:13], 0, v[6:7]
	v_lshl_add_u64 v[6:7], s[36:37], 0, v[6:7]
	v_lshl_add_u64 v[14:15], v[14:15], 0, v[8:9]
	v_lshl_add_u64 v[6:7], v[6:7], 0, v[8:9]
	v_bfe_u32 v146, v3, 6, 2
	s_waitcnt vmcnt(6)
	v_lshlrev_b32_e32 v149, 6, v5
	v_lshlrev_b32_e32 v5, 13, v5
	v_lshl_add_u64 v[138:139], s[4:5], 0, v[14:15]
	v_lshl_add_u64 v[14:15], s[12:13], 0, v[10:11]
	v_lshl_add_u64 v[142:143], s[2:3], 0, v[6:7]
	v_lshl_add_u64 v[6:7], s[36:37], 0, v[10:11]
	v_lshlrev_b64 v[134:135], 10, v[24:25]
	v_readlane_b32 s41, v254, 36
	v_readlane_b32 s42, v254, 37
	v_readlane_b32 s43, v254, 38
	v_lshlrev_b32_e32 v16, 12, v146
	v_or_b32_e32 v23, 0x800, v5
	v_or_b32_e32 v24, 0x1000, v5
	v_or_b32_e32 v25, 0x1800, v5
	v_lshl_add_u64 v[14:15], v[14:15], 0, v[12:13]
	v_lshl_add_u64 v[6:7], v[6:7], 0, v[12:13]
	v_lshl_add_u64 v[140:141], s[4:5], 0, v[14:15]
	v_lshl_add_u64 v[144:145], s[2:3], 0, v[6:7]
	s_mov_b32 s29, -2
	s_mov_b64 s[12:13], 0
	v_add_u32_e32 v171, v20, v16
	v_add_u32_e32 v156, v19, v5
	v_add_u32_e32 v155, v18, v23
	v_add_u32_e32 v154, v18, v24
	v_add_u32_e32 v153, v18, v25
	v_add_u32_e32 v167, v21, v16
	v_add_u32_e32 v160, v22, v16
	v_add_u32_e32 v158, v17, v16
	v_mov_b32_e32 v5, v4
	v_mov_b64_e32 v[6:7], v[4:5]
	v_mov_b64_e32 v[8:9], v[4:5]
	v_mov_b64_e32 v[10:11], v[4:5]
	v_mov_b64_e32 v[12:13], v[4:5]
	v_mov_b64_e32 v[14:15], v[4:5]
	v_mov_b64_e32 v[16:17], v[4:5]
	v_mov_b64_e32 v[18:19], v[4:5]
	v_mov_b64_e32 v[20:21], v[4:5]
	v_mov_b64_e32 v[22:23], v[4:5]
	v_mov_b64_e32 v[24:25], v[4:5]
	v_mov_b64_e32 v[26:27], v[4:5]
	v_mov_b64_e32 v[28:29], v[4:5]
	v_mov_b64_e32 v[30:31], v[4:5]
	v_mov_b64_e32 v[32:33], v[4:5]
	v_mov_b64_e32 v[34:35], v[4:5]
	v_mov_b64_e32 v[36:37], v[4:5]
	v_mov_b64_e32 v[38:39], v[4:5]
	v_mov_b64_e32 v[40:41], v[4:5]
	v_mov_b64_e32 v[42:43], v[4:5]
	v_mov_b64_e32 v[44:45], v[4:5]
	v_mov_b64_e32 v[46:47], v[4:5]
	v_mov_b64_e32 v[48:49], v[4:5]
	v_mov_b64_e32 v[50:51], v[4:5]
	v_mov_b64_e32 v[52:53], v[4:5]
	v_mov_b64_e32 v[54:55], v[4:5]
	v_mov_b64_e32 v[56:57], v[4:5]
	v_mov_b64_e32 v[58:59], v[4:5]
	v_mov_b64_e32 v[60:61], v[4:5]
	v_mov_b64_e32 v[62:63], v[4:5]
	v_mov_b64_e32 v[64:65], v[4:5]
	v_mov_b64_e32 v[66:67], v[4:5]
	v_mov_b64_e32 v[68:69], v[4:5]
	v_mov_b64_e32 v[70:71], v[4:5]
	v_mov_b64_e32 v[72:73], v[4:5]
	v_mov_b64_e32 v[74:75], v[4:5]
	v_mov_b64_e32 v[76:77], v[4:5]
	v_mov_b64_e32 v[78:79], v[4:5]
	v_mov_b64_e32 v[80:81], v[4:5]
	v_mov_b64_e32 v[82:83], v[4:5]
	v_mov_b64_e32 v[84:85], v[4:5]
	v_mov_b64_e32 v[86:87], v[4:5]
	v_mov_b64_e32 v[88:89], v[4:5]
	v_mov_b64_e32 v[90:91], v[4:5]
	v_mov_b64_e32 v[92:93], v[4:5]
	v_mov_b64_e32 v[94:95], v[4:5]
	v_mov_b64_e32 v[96:97], v[4:5]
	v_mov_b64_e32 v[98:99], v[4:5]
	v_mov_b64_e32 v[100:101], v[4:5]
	v_mov_b64_e32 v[102:103], v[4:5]
	v_mov_b64_e32 v[104:105], v[4:5]
	v_mov_b64_e32 v[106:107], v[4:5]
	v_mov_b64_e32 v[108:109], v[4:5]
	v_mov_b64_e32 v[110:111], v[4:5]
	v_mov_b64_e32 v[112:113], v[4:5]
	v_mov_b64_e32 v[114:115], v[4:5]
	v_mov_b64_e32 v[116:117], v[4:5]
	v_mov_b64_e32 v[118:119], v[4:5]
	v_mov_b64_e32 v[120:121], v[4:5]
	v_mov_b64_e32 v[122:123], v[4:5]
	v_mov_b64_e32 v[124:125], v[4:5]
	v_mov_b64_e32 v[126:127], v[4:5]
	v_mov_b64_e32 v[128:129], v[4:5]
	v_mov_b64_e32 v[130:131], v[4:5]
	s_mov_b64 s[36:37], 0x6040080
	s_mov_b64 s[38:39], 0xc4a0100
	s_mov_b64 s[40:41], 0x6000100
	s_mov_b64 s[42:43], 0xc4e0100
	s_mov_b64 s[44:45], 0x6040100
	s_mov_b64 s[46:47], 0xc4a0180
	s_mov_b64 s[48:49], 0x6000180
	s_mov_b64 s[50:51], 0xc4e0180
	s_barrier
; #define LDA8(dst, b, h) _Pragma("unroll") for (int m = 0; m < 4; ++m) _Pragma("unroll") for (int k = 0; k < 2; ++k) \
;     dst[m][k] = *(const bf16x8*)((const char*)SA8(b, h) + lds_byte8(wr * 64 + m * 16 + fr, k * 32 + fq * 8))
; #define LDB8(dst, b, h) _Pragma("unroll") for (int n = 0; n < 2; ++n) _Pragma("unroll") for (int k = 0; k < 2; ++k) \
;     dst[n][k] = *(const bf16x8*)((const char*)SB8(b, h) + lds_byte8(wc * 32 + n * 16 + fr, k * 32 + fq * 8))
; #define WAIT_L8(n) asm volatile("s_waitcnt lgkmcnt(" #n ")" ::: "memory")
; #define BAR8 __builtin_amdgcn_s_barrier()
; #define SCHED8 __builtin_amdgcn_sched_barrier(0)
;     ...
;   for (int tt = 0; tt < nt - 2; tt += 2) {
;     LDB8(B0, 0, 0); SCHED8; LDA8(At, 0, 0); STAGE8(SA8(1, 1), A, lda, brow + 128, tt + 1);
;     WAIT_L8(8); BAR8; WAIT_L8(0); MMA8(0, 0, At, B0); BAR8; SCHED8;
;     LDB8(B1, 0, 1); STAGE8(SB8(0, 0), Bt, K, bcol, tt + 2);
;     BAR8; WAIT_L8(0); MMA8(0, 1, At, B1); BAR8;
;     LDA8(At, 0, 1); STAGE8(SA8(0, 0), A, lda, brow, tt + 2);
;     BAR8; WAIT_L8(0); MMA8(1, 0, At, B0); BAR8; SCHED8;
.LBB0_908:
	ds_read_b128 v[174:177], v171
	ds_read_b128 v[178:181], v171 offset:1024
	ds_read_b128 v[182:185], v171 offset:2048
	ds_read_b128 v[186:189], v171 offset:3072
	v_add_u32_e32 v172, 0xc000, v150
	v_lshl_add_u64 v[222:223], v[142:143], 0, s[12:13]
	v_lshl_add_u64 v[226:227], v[222:223], 0, s[36:37]
	s_or_b32 m0, s100, 0xc000
	v_add_u32_e32 v173, 0xe000, v150
	ds_read_b128 v[190:193], v156
	ds_read_b128 v[194:197], v156 offset:1024
	ds_read_b128 v[198:201], v155
	ds_read_b128 v[202:205], v155 offset:1024
	ds_read_b128 v[206:209], v154
	ds_read_b128 v[210:213], v154 offset:1024
	ds_read_b128 v[214:217], v153
	ds_read_b128 v[218:221], v153 offset:1024
	global_load_lds_dwordx4 v[226:227], off
	v_lshl_add_u64 v[226:227], v[144:145], 0, s[12:13]
	v_lshl_add_u64 v[228:229], v[226:227], 0, s[36:37]
	s_or_b32 m0, s100, 0xe000
	s_nop 0
	global_load_lds_dwordx4 v[228:229], off
	s_waitcnt lgkmcnt(8)
	s_barrier
	s_waitcnt lgkmcnt(0)
	s_waitcnt lgkmcnt(0)
	v_mfma_f32_16x16x32_bf16 v[128:131], v[190:193], v[174:177], v[128:131]
	v_mfma_f32_16x16x32_bf16 v[124:127], v[190:193], v[182:185], v[124:127]
	v_mfma_f32_16x16x32_bf16 v[120:123], v[198:201], v[174:177], v[120:123]
	v_mfma_f32_16x16x32_bf16 v[116:119], v[198:201], v[182:185], v[116:119]
	v_mfma_f32_16x16x32_bf16 v[112:115], v[206:209], v[174:177], v[112:115]
	v_mfma_f32_16x16x32_bf16 v[108:111], v[206:209], v[182:185], v[108:111]
	v_mfma_f32_16x16x32_bf16 v[104:107], v[214:217], v[174:177], v[104:107]
	v_mfma_f32_16x16x32_bf16 v[100:103], v[214:217], v[182:185], v[100:103]
	v_mfma_f32_16x16x32_bf16 v[128:131], v[194:197], v[178:181], v[128:131]
	v_mfma_f32_16x16x32_bf16 v[124:127], v[194:197], v[186:189], v[124:127]
	v_mfma_f32_16x16x32_bf16 v[120:123], v[202:205], v[178:181], v[120:123]
	v_mfma_f32_16x16x32_bf16 v[116:119], v[202:205], v[186:189], v[116:119]
	v_mfma_f32_16x16x32_bf16 v[112:115], v[210:213], v[178:181], v[112:115]
	v_mfma_f32_16x16x32_bf16 v[108:111], v[210:213], v[186:189], v[108:111]
	v_mfma_f32_16x16x32_bf16 v[104:107], v[218:221], v[178:181], v[104:107]
	v_mfma_f32_16x16x32_bf16 v[100:103], v[218:221], v[186:189], v[100:103]
	s_barrier
	v_lshl_add_u64 v[228:229], v[138:139], 0, s[12:13]
	v_lshl_add_u64 v[236:237], v[228:229], 0, s[38:39]
	s_or_b32 m0, s100, 0x10000
	ds_read_b128 v[230:233], v167
	ds_read_b128 v[238:241], v167 offset:1024
	ds_read_b128 v[242:245], v167 offset:2048
	ds_read_b128 v[246:249], v167 offset:3072
	global_load_lds_dwordx4 v[236:237], off
	v_lshl_add_u64 v[236:237], v[140:141], 0, s[12:13]
	v_lshl_add_u64 v[250:251], v[236:237], 0, s[38:39]
	s_or_b32 m0, s100, 0x12000
	s_nop 0
	global_load_lds_dwordx4 v[250:251], off
	s_barrier
	s_waitcnt lgkmcnt(0)
	s_waitcnt lgkmcnt(0)
	v_mfma_f32_16x16x32_bf16 v[96:99], v[190:193], v[230:233], v[96:99]
	v_mfma_f32_16x16x32_bf16 v[92:95], v[190:193], v[242:245], v[92:95]
	v_mfma_f32_16x16x32_bf16 v[88:91], v[198:201], v[230:233], v[88:91]
	v_mfma_f32_16x16x32_bf16 v[84:87], v[198:201], v[242:245], v[84:87]
	v_mfma_f32_16x16x32_bf16 v[80:83], v[206:209], v[230:233], v[80:83]
	v_mfma_f32_16x16x32_bf16 v[76:79], v[206:209], v[242:245], v[76:79]
	v_mfma_f32_16x16x32_bf16 v[72:75], v[214:217], v[230:233], v[72:75]
	v_mfma_f32_16x16x32_bf16 v[68:71], v[214:217], v[242:245], v[68:71]
	v_mfma_f32_16x16x32_bf16 v[96:99], v[194:197], v[238:241], v[96:99]
	v_mfma_f32_16x16x32_bf16 v[92:95], v[194:197], v[246:249], v[92:95]
	v_mfma_f32_16x16x32_bf16 v[88:91], v[202:205], v[238:241], v[88:91]
	v_mfma_f32_16x16x32_bf16 v[84:87], v[202:205], v[246:249], v[84:87]
	v_mfma_f32_16x16x32_bf16 v[80:83], v[210:213], v[238:241], v[80:83]
	v_mfma_f32_16x16x32_bf16 v[76:79], v[210:213], v[246:249], v[76:79]
	v_mfma_f32_16x16x32_bf16 v[72:75], v[218:221], v[238:241], v[72:75]
	v_mfma_f32_16x16x32_bf16 v[68:71], v[218:221], v[246:249], v[68:71]
	v_lshl_add_u64 v[250:251], v[222:223], 0, s[40:41]
	s_mov_b32 m0, s100
	s_barrier
	ds_read_b128 v[190:193], v156 offset:16384
	ds_read_b128 v[194:197], v156 offset:17408
	ds_read_b128 v[198:201], v155 offset:16384
	ds_read_b128 v[202:205], v155 offset:17408
	ds_read_b128 v[206:209], v154 offset:16384
	ds_read_b128 v[210:213], v154 offset:17408
	ds_read_b128 v[214:217], v153 offset:16384
	ds_read_b128 v[218:221], v153 offset:17408
	global_load_lds_dwordx4 v[250:251], off
	v_lshl_add_u64 v[250:251], v[226:227], 0, s[40:41]
	s_or_b32 m0, s100, 0x2000
	s_nop 0
	global_load_lds_dwordx4 v[250:251], off
	s_barrier
	s_waitcnt lgkmcnt(0)
	s_waitcnt lgkmcnt(0)
	v_mfma_f32_16x16x32_bf16 v[64:67], v[190:193], v[174:177], v[64:67]
	v_mfma_f32_16x16x32_bf16 v[60:63], v[190:193], v[182:185], v[60:63]
	v_mfma_f32_16x16x32_bf16 v[56:59], v[198:201], v[174:177], v[56:59]
	v_mfma_f32_16x16x32_bf16 v[52:55], v[198:201], v[182:185], v[52:55]
	v_mfma_f32_16x16x32_bf16 v[48:51], v[206:209], v[174:177], v[48:51]
	v_mfma_f32_16x16x32_bf16 v[44:47], v[206:209], v[182:185], v[44:47]
	v_mfma_f32_16x16x32_bf16 v[40:43], v[214:217], v[174:177], v[40:43]
	v_mfma_f32_16x16x32_bf16 v[36:39], v[214:217], v[182:185], v[36:39]
	v_mfma_f32_16x16x32_bf16 v[64:67], v[194:197], v[178:181], v[64:67]
	v_mfma_f32_16x16x32_bf16 v[60:63], v[194:197], v[186:189], v[60:63]
	v_mfma_f32_16x16x32_bf16 v[56:59], v[202:205], v[178:181], v[56:59]
	v_mfma_f32_16x16x32_bf16 v[52:55], v[202:205], v[186:189], v[52:55]
	v_mfma_f32_16x16x32_bf16 v[48:51], v[210:213], v[178:181], v[48:51]
	v_mfma_f32_16x16x32_bf16 v[44:47], v[210:213], v[186:189], v[44:47]
	v_mfma_f32_16x16x32_bf16 v[40:43], v[218:221], v[178:181], v[40:43]
	v_mfma_f32_16x16x32_bf16 v[36:39], v[218:221], v[186:189], v[36:39]
	s_barrier
; #define LDA8(dst, b, h) _Pragma("unroll") for (int m = 0; m < 4; ++m) _Pragma("unroll") for (int k = 0; k < 2; ++k) \
;     dst[m][k] = *(const bf16x8*)((const char*)SA8(b, h) + lds_byte8(wr * 64 + m * 16 + fr, k * 32 + fq * 8))
; #define LDB8(dst, b, h) _Pragma("unroll") for (int n = 0; n < 2; ++n) _Pragma("unroll") for (int k = 0; k < 2; ++k) \
;     dst[n][k] = *(const bf16x8*)((const char*)SB8(b, h) + lds_byte8(wc * 32 + n * 16 + fr, k * 32 + fq * 8))
; #define WAIT_V8(n) asm volatile("s_waitcnt vmcnt(" #n ")" ::: "memory")
; #define WAIT_L8(n) asm volatile("s_waitcnt lgkmcnt(" #n ")" ::: "memory")
; #define BAR8 __builtin_amdgcn_s_barrier()
; #define SCHED8 __builtin_amdgcn_sched_barrier(0)
;     ...
;     BAR8; WAIT_L8(0); MMA8(1, 0, At, B0); BAR8; SCHED8;
;     STAGE8(SB8(0, 1), Bt, K, bcol + 128, tt + 2);
;     WAIT_V8(6); BAR8; MMA8(1, 1, At, B1); BAR8;
;     LDB8(B0, 1, 0); SCHED8; LDA8(At, 1, 0); STAGE8(SA8(0, 1), A, lda, brow + 128, tt + 2);
;     WAIT_L8(8); BAR8; WAIT_L8(0); MMA8(0, 0, At, B0); BAR8; SCHED8;
;     LDB8(B1, 1, 1); STAGE8(SB8(1, 0), Bt, K, bcol, tt + 3);
;     BAR8; WAIT_L8(0); MMA8(0, 1, At, B1); BAR8;
;     LDA8(At, 1, 1); STAGE8(SA8(1, 0), A, lda, brow, tt + 3);
	v_lshl_add_u64 v[174:175], v[228:229], 0, s[42:43]
	s_or_b32 m0, s100, 0x14000
	s_nop 0
	global_load_lds_dwordx4 v[174:175], off
	v_lshl_add_u64 v[174:175], v[236:237], 0, s[42:43]
	s_or_b32 m0, s100, 0x16000
	s_nop 0
	global_load_lds_dwordx4 v[174:175], off
	s_waitcnt vmcnt(6)
	s_barrier
	v_mfma_f32_16x16x32_bf16 v[32:35], v[190:193], v[230:233], v[32:35]
	v_mfma_f32_16x16x32_bf16 v[28:31], v[190:193], v[242:245], v[28:31]
	v_mfma_f32_16x16x32_bf16 v[24:27], v[198:201], v[230:233], v[24:27]
	v_mfma_f32_16x16x32_bf16 v[20:23], v[198:201], v[242:245], v[20:23]
	v_mfma_f32_16x16x32_bf16 v[16:19], v[206:209], v[230:233], v[16:19]
	v_mfma_f32_16x16x32_bf16 v[12:15], v[206:209], v[242:245], v[12:15]
	v_mfma_f32_16x16x32_bf16 v[8:11], v[214:217], v[230:233], v[8:11]
	v_mfma_f32_16x16x32_bf16 v[4:7], v[214:217], v[242:245], v[4:7]
	v_mfma_f32_16x16x32_bf16 v[32:35], v[194:197], v[238:241], v[32:35]
	v_mfma_f32_16x16x32_bf16 v[28:31], v[194:197], v[246:249], v[28:31]
	v_mfma_f32_16x16x32_bf16 v[24:27], v[202:205], v[238:241], v[24:27]
	v_mfma_f32_16x16x32_bf16 v[20:23], v[202:205], v[246:249], v[20:23]
	v_mfma_f32_16x16x32_bf16 v[16:19], v[210:213], v[238:241], v[16:19]
	v_mfma_f32_16x16x32_bf16 v[12:15], v[210:213], v[246:249], v[12:15]
	v_mfma_f32_16x16x32_bf16 v[8:11], v[218:221], v[238:241], v[8:11]
	v_mfma_f32_16x16x32_bf16 v[4:7], v[218:221], v[246:249], v[4:7]
	s_barrier
	ds_read_b128 v[174:177], v160
	ds_read_b128 v[178:181], v160 offset:1024
	ds_read_b128 v[182:185], v160 offset:2048
	ds_read_b128 v[186:189], v160 offset:3072
	v_lshl_add_u64 v[230:231], v[222:223], 0, s[44:45]
	s_or_b32 m0, s100, 0x4000
	ds_read_b128 v[190:193], v156 offset:32768
	ds_read_b128 v[194:197], v156 offset:33792
	ds_read_b128 v[198:201], v155 offset:32768
	ds_read_b128 v[202:205], v155 offset:33792
	ds_read_b128 v[206:209], v154 offset:32768
	ds_read_b128 v[210:213], v154 offset:33792
	ds_read_b128 v[214:217], v153 offset:32768
	ds_read_b128 v[218:221], v153 offset:33792
	global_load_lds_dwordx4 v[230:231], off
	v_lshl_add_u64 v[230:231], v[226:227], 0, s[44:45]
	s_or_b32 m0, s100, 0x6000
	s_nop 0
	global_load_lds_dwordx4 v[230:231], off
	s_waitcnt lgkmcnt(8)
	s_barrier
	s_waitcnt lgkmcnt(0)
	s_waitcnt lgkmcnt(0)
	v_mfma_f32_16x16x32_bf16 v[128:131], v[190:193], v[174:177], v[128:131]
	v_mfma_f32_16x16x32_bf16 v[124:127], v[190:193], v[182:185], v[124:127]
	v_mfma_f32_16x16x32_bf16 v[120:123], v[198:201], v[174:177], v[120:123]
	v_mfma_f32_16x16x32_bf16 v[116:119], v[198:201], v[182:185], v[116:119]
	v_mfma_f32_16x16x32_bf16 v[112:115], v[206:209], v[174:177], v[112:115]
	v_mfma_f32_16x16x32_bf16 v[108:111], v[206:209], v[182:185], v[108:111]
	v_mfma_f32_16x16x32_bf16 v[104:107], v[214:217], v[174:177], v[104:107]
	v_mfma_f32_16x16x32_bf16 v[100:103], v[214:217], v[182:185], v[100:103]
	v_mfma_f32_16x16x32_bf16 v[128:131], v[194:197], v[178:181], v[128:131]
	v_mfma_f32_16x16x32_bf16 v[124:127], v[194:197], v[186:189], v[124:127]
	v_mfma_f32_16x16x32_bf16 v[120:123], v[202:205], v[178:181], v[120:123]
	v_mfma_f32_16x16x32_bf16 v[116:119], v[202:205], v[186:189], v[116:119]
	v_mfma_f32_16x16x32_bf16 v[112:115], v[210:213], v[178:181], v[112:115]
	v_mfma_f32_16x16x32_bf16 v[108:111], v[210:213], v[186:189], v[108:111]
	v_mfma_f32_16x16x32_bf16 v[104:107], v[218:221], v[178:181], v[104:107]
	v_mfma_f32_16x16x32_bf16 v[100:103], v[218:221], v[186:189], v[100:103]
	s_barrier
	v_lshl_add_u64 v[250:251], v[228:229], 0, s[46:47]
	s_or_b32 m0, s100, 0x18000
	ds_read_b128 v[230:233], v158
	ds_read_b128 v[238:241], v158 offset:1024
	ds_read_b128 v[242:245], v158 offset:2048
	ds_read_b128 v[246:249], v158 offset:3072
	global_load_lds_dwordx4 v[250:251], off
	v_lshl_add_u64 v[250:251], v[236:237], 0, s[46:47]
	s_or_b32 m0, s100, 0x1a000
	s_nop 0
	global_load_lds_dwordx4 v[250:251], off
	s_barrier
	s_waitcnt lgkmcnt(0)
	s_waitcnt lgkmcnt(0)
	v_mfma_f32_16x16x32_bf16 v[96:99], v[190:193], v[230:233], v[96:99]
	v_mfma_f32_16x16x32_bf16 v[92:95], v[190:193], v[242:245], v[92:95]
	v_mfma_f32_16x16x32_bf16 v[88:91], v[198:201], v[230:233], v[88:91]
	v_mfma_f32_16x16x32_bf16 v[84:87], v[198:201], v[242:245], v[84:87]
	v_mfma_f32_16x16x32_bf16 v[80:83], v[206:209], v[230:233], v[80:83]
	v_mfma_f32_16x16x32_bf16 v[76:79], v[206:209], v[242:245], v[76:79]
	v_mfma_f32_16x16x32_bf16 v[72:75], v[214:217], v[230:233], v[72:75]
	v_mfma_f32_16x16x32_bf16 v[68:71], v[214:217], v[242:245], v[68:71]
	v_mfma_f32_16x16x32_bf16 v[96:99], v[194:197], v[238:241], v[96:99]
	v_mfma_f32_16x16x32_bf16 v[92:95], v[194:197], v[246:249], v[92:95]
	v_mfma_f32_16x16x32_bf16 v[88:91], v[202:205], v[238:241], v[88:91]
	v_mfma_f32_16x16x32_bf16 v[84:87], v[202:205], v[246:249], v[84:87]
	v_mfma_f32_16x16x32_bf16 v[80:83], v[210:213], v[238:241], v[80:83]
	v_mfma_f32_16x16x32_bf16 v[76:79], v[210:213], v[246:249], v[76:79]
	v_mfma_f32_16x16x32_bf16 v[72:75], v[218:221], v[238:241], v[72:75]
	v_mfma_f32_16x16x32_bf16 v[68:71], v[218:221], v[246:249], v[68:71]
	v_lshl_add_u64 v[222:223], v[222:223], 0, s[48:49]
	s_or_b32 m0, s100, 0x8000
	s_barrier
	ds_read_b128 v[190:193], v156 offset:49152
	ds_read_b128 v[194:197], v156 offset:50176
	ds_read_b128 v[198:201], v155 offset:49152
	ds_read_b128 v[202:205], v155 offset:50176
	ds_read_b128 v[206:209], v154 offset:49152
	ds_read_b128 v[210:213], v154 offset:50176
	ds_read_b128 v[214:217], v153 offset:49152
	ds_read_b128 v[218:221], v153 offset:50176
	global_load_lds_dwordx4 v[222:223], off
	v_lshl_add_u64 v[222:223], v[226:227], 0, s[48:49]
	s_or_b32 m0, s100, 0xa000
	s_nop 0
	global_load_lds_dwordx4 v[222:223], off
	s_barrier
; #define LDA8(dst, b, h) _Pragma("unroll") for (int m = 0; m < 4; ++m) _Pragma("unroll") for (int k = 0; k < 2; ++k) \
;     dst[m][k] = *(const bf16x8*)((const char*)SA8(b, h) + lds_byte8(wr * 64 + m * 16 + fr, k * 32 + fq * 8))
; #define LDB8(dst, b, h) _Pragma("unroll") for (int n = 0; n < 2; ++n) _Pragma("unroll") for (int k = 0; k < 2; ++k) \
;     dst[n][k] = *(const bf16x8*)((const char*)SB8(b, h) + lds_byte8(wc * 32 + n * 16 + fr, k * 32 + fq * 8))
; #define WAIT_V8(n) asm volatile("s_waitcnt vmcnt(" #n ")" ::: "memory")
; #define WAIT_L8(n) asm volatile("s_waitcnt lgkmcnt(" #n ")" ::: "memory")
; #define BAR8 __builtin_amdgcn_s_barrier()
; #define SCHED8 __builtin_amdgcn_sched_barrier(0)
;     ...
;     BAR8; WAIT_L8(0); MMA8(1, 0, At, B0); BAR8; SCHED8;
;     STAGE8(SB8(1, 1), Bt, K, bcol + 128, tt + 3);
;     WAIT_V8(6); BAR8; MMA8(1, 1, At, B1); BAR8;
;   }
;   { LDB8(B0, 0, 0); LDA8(At, 0, 0); STAGE8(SA8(1, 1), A, lda, brow + 128, nt - 1);
;     BAR8; WAIT_L8(0); MMA8(0, 0, At, B0); BAR8;
;     LDB8(B1, 0, 1); BAR8; WAIT_L8(0); MMA8(0, 1, At, B1); BAR8;
;     LDA8(At, 0, 1); WAIT_V8(4); BAR8; WAIT_L8(0); MMA8(1, 0, At, B0); MMA8(1, 1, At, B1); BAR8; }
	s_waitcnt lgkmcnt(0)
	s_waitcnt lgkmcnt(0)
	v_mfma_f32_16x16x32_bf16 v[64:67], v[190:193], v[174:177], v[64:67]
	v_mfma_f32_16x16x32_bf16 v[60:63], v[190:193], v[182:185], v[60:63]
	v_mfma_f32_16x16x32_bf16 v[56:59], v[198:201], v[174:177], v[56:59]
	v_mfma_f32_16x16x32_bf16 v[52:55], v[198:201], v[182:185], v[52:55]
	v_mfma_f32_16x16x32_bf16 v[48:51], v[206:209], v[174:177], v[48:51]
	v_mfma_f32_16x16x32_bf16 v[44:47], v[206:209], v[182:185], v[44:47]
	v_mfma_f32_16x16x32_bf16 v[40:43], v[214:217], v[174:177], v[40:43]
	v_mfma_f32_16x16x32_bf16 v[36:39], v[214:217], v[182:185], v[36:39]
	v_mfma_f32_16x16x32_bf16 v[64:67], v[194:197], v[178:181], v[64:67]
	v_mfma_f32_16x16x32_bf16 v[60:63], v[194:197], v[186:189], v[60:63]
	v_mfma_f32_16x16x32_bf16 v[56:59], v[202:205], v[178:181], v[56:59]
	v_mfma_f32_16x16x32_bf16 v[52:55], v[202:205], v[186:189], v[52:55]
	v_mfma_f32_16x16x32_bf16 v[48:51], v[210:213], v[178:181], v[48:51]
	v_mfma_f32_16x16x32_bf16 v[44:47], v[210:213], v[186:189], v[44:47]
	v_mfma_f32_16x16x32_bf16 v[40:43], v[218:221], v[178:181], v[40:43]
	v_mfma_f32_16x16x32_bf16 v[36:39], v[218:221], v[186:189], v[36:39]
	s_barrier
	v_lshl_add_u64 v[174:175], v[228:229], 0, s[50:51]
	s_or_b32 m0, s100, 0x1c000
	s_nop 0
	global_load_lds_dwordx4 v[174:175], off
	v_lshl_add_u64 v[174:175], v[236:237], 0, s[50:51]
	s_or_b32 m0, s100, 0x1e000
	s_nop 0
	global_load_lds_dwordx4 v[174:175], off
	s_waitcnt vmcnt(6)
	s_barrier
	v_mfma_f32_16x16x32_bf16 v[32:35], v[190:193], v[230:233], v[32:35]
	v_mfma_f32_16x16x32_bf16 v[28:31], v[190:193], v[242:245], v[28:31]
	v_mfma_f32_16x16x32_bf16 v[24:27], v[198:201], v[230:233], v[24:27]
	v_mfma_f32_16x16x32_bf16 v[20:23], v[198:201], v[242:245], v[20:23]
	v_mfma_f32_16x16x32_bf16 v[16:19], v[206:209], v[230:233], v[16:19]
	v_mfma_f32_16x16x32_bf16 v[12:15], v[206:209], v[242:245], v[12:15]
	v_mfma_f32_16x16x32_bf16 v[8:11], v[214:217], v[230:233], v[8:11]
	v_mfma_f32_16x16x32_bf16 v[4:7], v[214:217], v[242:245], v[4:7]
	v_mfma_f32_16x16x32_bf16 v[32:35], v[194:197], v[238:241], v[32:35]
	v_mfma_f32_16x16x32_bf16 v[28:31], v[194:197], v[246:249], v[28:31]
	v_mfma_f32_16x16x32_bf16 v[24:27], v[202:205], v[238:241], v[24:27]
	v_mfma_f32_16x16x32_bf16 v[20:23], v[202:205], v[246:249], v[20:23]
	v_mfma_f32_16x16x32_bf16 v[16:19], v[210:213], v[238:241], v[16:19]
	v_mfma_f32_16x16x32_bf16 v[12:15], v[210:213], v[246:249], v[12:15]
	v_mfma_f32_16x16x32_bf16 v[8:11], v[218:221], v[238:241], v[8:11]
	v_mfma_f32_16x16x32_bf16 v[4:7], v[218:221], v[246:249], v[4:7]
	s_add_i32 s29, s29, 2
	s_add_u32 s12, s12, 0x100
	s_addc_u32 s13, s13, 0
	s_cmp_lt_u32 s29, 12
	s_barrier
	s_cbranch_scc1 .LBB0_908
	s_add_u32 s2, s2, s27
	s_addc_u32 s3, s3, 0
	s_add_u32 s2, s2, 0x6000780
	s_addc_u32 s3, s3, 0
	v_lshl_add_u64 v[136:137], v[136:137], 1, s[2:3]
	v_lshl_add_u64 v[0:1], v[0:1], 1, v[136:137]
	s_or_b32 m0, s100, 0xc000
	ds_read_b128 v[138:141], v171
	ds_read_b128 v[142:145], v171 offset:1024
	ds_read_b128 v[162:165], v171 offset:2048
	ds_read_b128 v[168:171], v171 offset:3072
	ds_read_b128 v[174:177], v156
	ds_read_b128 v[178:181], v156 offset:1024
	ds_read_b128 v[182:185], v155
	ds_read_b128 v[186:189], v155 offset:1024
	ds_read_b128 v[190:193], v154
	ds_read_b128 v[194:197], v154 offset:1024
	ds_read_b128 v[198:201], v153
	ds_read_b128 v[202:205], v153 offset:1024
	global_load_lds_dwordx4 v[0:1], off
	v_lshl_add_u64 v[0:1], v[134:135], 1, s[2:3]
	v_lshl_add_u64 v[0:1], v[132:133], 1, v[0:1]
	s_or_b32 m0, s100, 0xe000
	s_nop 0
	global_load_lds_dwordx4 v[0:1], off
	s_barrier
	s_waitcnt lgkmcnt(0)
	s_waitcnt lgkmcnt(0)
	v_mfma_f32_16x16x32_bf16 v[128:131], v[174:177], v[138:141], v[128:131]
	v_mfma_f32_16x16x32_bf16 v[124:127], v[174:177], v[162:165], v[124:127]
	v_mfma_f32_16x16x32_bf16 v[120:123], v[182:185], v[138:141], v[120:123]
	v_mfma_f32_16x16x32_bf16 v[112:115], v[190:193], v[138:141], v[112:115]
	v_mfma_f32_16x16x32_bf16 v[128:131], v[178:181], v[142:145], v[128:131]
	v_mfma_f32_16x16x32_bf16 v[124:127], v[178:181], v[168:171], v[124:127]
	v_mfma_f32_16x16x32_bf16 v[120:123], v[186:189], v[142:145], v[120:123]
	v_mfma_f32_16x16x32_bf16 v[116:119], v[182:185], v[162:165], v[116:119]
	v_mfma_f32_16x16x32_bf16 v[112:115], v[194:197], v[142:145], v[112:115]
	v_mfma_f32_16x16x32_bf16 v[108:111], v[190:193], v[162:165], v[108:111]
	v_mfma_f32_16x16x32_bf16 v[104:107], v[198:201], v[138:141], v[104:107]
	v_mfma_f32_16x16x32_bf16 v[100:103], v[198:201], v[162:165], v[100:103]
	v_mfma_f32_16x16x32_bf16 v[132:135], v[186:189], v[168:171], v[116:119]
	v_mfma_f32_16x16x32_bf16 v[206:209], v[194:197], v[168:171], v[108:111]
	v_mfma_f32_16x16x32_bf16 v[210:213], v[202:205], v[142:145], v[104:107]
	v_mfma_f32_16x16x32_bf16 v[214:217], v[202:205], v[168:171], v[100:103]
	s_barrier
	s_nop 1
	ds_read_b128 v[100:103], v167
	ds_read_b128 v[104:107], v167 offset:1024
	ds_read_b128 v[108:111], v167 offset:2048
	ds_read_b128 v[116:119], v167 offset:3072
	s_barrier
	s_waitcnt lgkmcnt(0)
	s_waitcnt lgkmcnt(0)
	v_mfma_f32_16x16x32_bf16 v[80:83], v[190:193], v[100:103], v[80:83]
	v_mfma_f32_16x16x32_bf16 v[76:79], v[190:193], v[108:111], v[76:79]
	v_mfma_f32_16x16x32_bf16 v[72:75], v[198:201], v[100:103], v[72:75]
	v_mfma_f32_16x16x32_bf16 v[68:71], v[198:201], v[108:111], v[68:71]
	v_mfma_f32_16x16x32_bf16 v[96:99], v[174:177], v[100:103], v[96:99]
	v_mfma_f32_16x16x32_bf16 v[92:95], v[174:177], v[108:111], v[92:95]
	v_mfma_f32_16x16x32_bf16 v[88:91], v[182:185], v[100:103], v[88:91]
	v_mfma_f32_16x16x32_bf16 v[84:87], v[182:185], v[108:111], v[84:87]
	v_mfma_f32_16x16x32_bf16 v[80:83], v[194:197], v[104:107], v[80:83]
	v_mfma_f32_16x16x32_bf16 v[76:79], v[194:197], v[116:119], v[76:79]
	v_mfma_f32_16x16x32_bf16 v[72:75], v[202:205], v[104:107], v[72:75]
	v_mfma_f32_16x16x32_bf16 v[68:71], v[202:205], v[116:119], v[68:71]
	v_mfma_f32_16x16x32_bf16 v[218:221], v[178:181], v[104:107], v[96:99]
	v_mfma_f32_16x16x32_bf16 v[172:175], v[178:181], v[116:119], v[92:95]
	v_mfma_f32_16x16x32_bf16 v[176:179], v[186:189], v[104:107], v[88:91]
	v_mfma_f32_16x16x32_bf16 v[180:183], v[186:189], v[116:119], v[84:87]
	s_barrier
; #define LDA8(dst, b, h) _Pragma("unroll") for (int m = 0; m < 4; ++m) _Pragma("unroll") for (int k = 0; k < 2; ++k) \
;     dst[m][k] = *(const bf16x8*)((const char*)SA8(b, h) + lds_byte8(wr * 64 + m * 16 + fr, k * 32 + fq * 8))
; #define LDB8(dst, b, h) _Pragma("unroll") for (int n = 0; n < 2; ++n) _Pragma("unroll") for (int k = 0; k < 2; ++k) \
;     dst[n][k] = *(const bf16x8*)((const char*)SB8(b, h) + lds_byte8(wc * 32 + n * 16 + fr, k * 32 + fq * 8))
; #define WAIT_V8(n) asm volatile("s_waitcnt vmcnt(" #n ")" ::: "memory")
; #define WAIT_L8(n) asm volatile("s_waitcnt lgkmcnt(" #n ")" ::: "memory")
; #define BAR8 __builtin_amdgcn_s_barrier()
;     ...
;     LDA8(At, 0, 1); WAIT_V8(4); BAR8; WAIT_L8(0); MMA8(1, 0, At, B0); MMA8(1, 1, At, B1); BAR8; }
;   { LDB8(B0, 1, 0); LDA8(At, 1, 0); WAIT_V8(2); BAR8; WAIT_L8(0); MMA8(0, 0, At, B0); BAR8;
	s_nop 0
	ds_read_b128 v[84:87], v156 offset:16384
	ds_read_b128 v[88:91], v156 offset:17408
	ds_read_b128 v[92:95], v155 offset:16384
	ds_read_b128 v[96:99], v155 offset:17408
	ds_read_b128 v[184:187], v154 offset:16384
	ds_read_b128 v[188:191], v154 offset:17408
	ds_read_b128 v[192:195], v153 offset:16384
	ds_read_b128 v[196:199], v153 offset:17408
	s_waitcnt vmcnt(4)
	s_barrier
	s_waitcnt lgkmcnt(0)
	s_waitcnt lgkmcnt(0)
	v_mfma_f32_16x16x32_bf16 v[64:67], v[84:87], v[138:141], v[64:67]
	v_mfma_f32_16x16x32_bf16 v[60:63], v[84:87], v[162:165], v[60:63]
	v_mfma_f32_16x16x32_bf16 v[56:59], v[92:95], v[138:141], v[56:59]
	v_mfma_f32_16x16x32_bf16 v[52:55], v[92:95], v[162:165], v[52:55]
	v_mfma_f32_16x16x32_bf16 v[48:51], v[184:187], v[138:141], v[48:51]
	v_mfma_f32_16x16x32_bf16 v[44:47], v[184:187], v[162:165], v[44:47]
	v_mfma_f32_16x16x32_bf16 v[40:43], v[192:195], v[138:141], v[40:43]
	v_mfma_f32_16x16x32_bf16 v[36:39], v[192:195], v[162:165], v[36:39]
	v_mfma_f32_16x16x32_bf16 v[64:67], v[88:91], v[142:145], v[64:67]
	v_mfma_f32_16x16x32_bf16 v[60:63], v[88:91], v[168:171], v[60:63]
	v_mfma_f32_16x16x32_bf16 v[56:59], v[96:99], v[142:145], v[56:59]
	v_mfma_f32_16x16x32_bf16 v[52:55], v[96:99], v[168:171], v[52:55]
	v_mfma_f32_16x16x32_bf16 v[48:51], v[188:191], v[142:145], v[48:51]
	v_mfma_f32_16x16x32_bf16 v[44:47], v[188:191], v[168:171], v[44:47]
	v_mfma_f32_16x16x32_bf16 v[40:43], v[196:199], v[142:145], v[40:43]
	v_mfma_f32_16x16x32_bf16 v[36:39], v[196:199], v[168:171], v[36:39]
	v_mfma_f32_16x16x32_bf16 v[32:35], v[84:87], v[100:103], v[32:35]
	v_mfma_f32_16x16x32_bf16 v[28:31], v[84:87], v[108:111], v[28:31]
	v_mfma_f32_16x16x32_bf16 v[24:27], v[92:95], v[100:103], v[24:27]
	v_mfma_f32_16x16x32_bf16 v[20:23], v[92:95], v[108:111], v[20:23]
	v_mfma_f32_16x16x32_bf16 v[16:19], v[184:187], v[100:103], v[16:19]
	v_mfma_f32_16x16x32_bf16 v[12:15], v[184:187], v[108:111], v[12:15]
	v_mfma_f32_16x16x32_bf16 v[8:11], v[192:195], v[100:103], v[8:11]
	v_mfma_f32_16x16x32_bf16 v[4:7], v[192:195], v[108:111], v[4:7]
	v_mfma_f32_16x16x32_bf16 v[136:139], v[88:91], v[104:107], v[32:35]
	v_mfma_f32_16x16x32_bf16 v[140:143], v[88:91], v[116:119], v[28:31]
	v_mfma_f32_16x16x32_bf16 v[162:165], v[96:99], v[104:107], v[24:27]
	v_mfma_f32_16x16x32_bf16 v[166:169], v[96:99], v[116:119], v[20:23]
	v_mfma_f32_16x16x32_bf16 v[200:203], v[188:191], v[104:107], v[16:19]
	v_mfma_f32_16x16x32_bf16 v[184:187], v[188:191], v[116:119], v[12:15]
	v_mfma_f32_16x16x32_bf16 v[188:191], v[196:199], v[104:107], v[8:11]
	v_mfma_f32_16x16x32_bf16 v[192:195], v[196:199], v[116:119], v[4:7]
	s_barrier
	ds_read_b128 v[196:199], v160
	ds_read_b128 v[230:233], v160 offset:1024
	ds_read_b128 v[238:241], v160 offset:2048
	ds_read_b128 v[242:245], v160 offset:3072
	ds_read_b128 v[8:11], v156 offset:32768
	ds_read_b128 v[12:15], v156 offset:33792
	ds_read_b128 v[16:19], v155 offset:32768
	ds_read_b128 v[24:27], v155 offset:33792
	ds_read_b128 v[28:31], v154 offset:32768
	ds_read_b128 v[32:35], v154 offset:33792
	ds_read_b128 v[246:249], v153 offset:32768
	ds_read_b128 v[226:229], v153 offset:33792
	s_waitcnt vmcnt(2)
	s_barrier
	s_waitcnt lgkmcnt(0)
	s_waitcnt lgkmcnt(0)
	v_mfma_f32_16x16x32_bf16 v[4:7], v[8:11], v[196:199], v[128:131]
	v_mfma_f32_16x16x32_bf16 v[104:107], v[12:15], v[230:233], v[4:7]
	v_mfma_f32_16x16x32_bf16 v[4:7], v[8:11], v[238:241], v[124:127]
	v_mfma_f32_16x16x32_bf16 v[116:119], v[12:15], v[242:245], v[4:7]
	v_mfma_f32_16x16x32_bf16 v[4:7], v[16:19], v[196:199], v[120:123]
	v_mfma_f32_16x16x32_bf16 v[100:103], v[24:27], v[230:233], v[4:7]
	v_mfma_f32_16x16x32_bf16 v[4:7], v[16:19], v[238:241], v[132:135]
	v_mfma_f32_16x16x32_bf16 v[108:111], v[24:27], v[242:245], v[4:7]
	v_mfma_f32_16x16x32_bf16 v[4:7], v[28:31], v[196:199], v[112:115]
	v_mfma_f32_16x16x32_bf16 v[92:95], v[32:35], v[230:233], v[4:7]
	v_mfma_f32_16x16x32_bf16 v[4:7], v[28:31], v[238:241], v[206:209]
	v_mfma_f32_16x16x32_bf16 v[96:99], v[32:35], v[242:245], v[4:7]
	v_mfma_f32_16x16x32_bf16 v[4:7], v[246:249], v[196:199], v[210:213]
	v_mfma_f32_16x16x32_bf16 v[84:87], v[226:229], v[230:233], v[4:7]
	v_mfma_f32_16x16x32_bf16 v[4:7], v[246:249], v[238:241], v[214:217]
	v_mfma_f32_16x16x32_bf16 v[88:91], v[226:229], v[242:245], v[4:7]
	s_barrier
; #define LDA8(dst, b, h) _Pragma("unroll") for (int m = 0; m < 4; ++m) _Pragma("unroll") for (int k = 0; k < 2; ++k) \
;     dst[m][k] = *(const bf16x8*)((const char*)SA8(b, h) + lds_byte8(wr * 64 + m * 16 + fr, k * 32 + fq * 8))
; #define LDB8(dst, b, h) _Pragma("unroll") for (int n = 0; n < 2; ++n) _Pragma("unroll") for (int k = 0; k < 2; ++k) \
;     dst[n][k] = *(const bf16x8*)((const char*)SB8(b, h) + lds_byte8(wc * 32 + n * 16 + fr, k * 32 + fq * 8))
; #define WAIT_V8(n) asm volatile("s_waitcnt vmcnt(" #n ")" ::: "memory")
; #define WAIT_L8(n) asm volatile("s_waitcnt lgkmcnt(" #n ")" ::: "memory")
; #define BAR8 __builtin_amdgcn_s_barrier()
;     ...
;     LDB8(B1, 1, 1); WAIT_V8(0); BAR8; WAIT_L8(0); MMA8(0, 1, At, B1); BAR8;
;     LDA8(At, 1, 1); BAR8; WAIT_L8(0); MMA8(1, 0, At, B0); MMA8(1, 1, At, B1); BAR8; }
;   if (wr == 0) BAR8;
;   __syncthreads();
;     ...
;   if (t < 256) {
;     float rs = 1.f;
;     if (e.ss) {
	ds_read_b128 v[132:135], v158
	ds_read_b128 v[204:207], v158 offset:1024
	ds_read_b128 v[208:211], v158 offset:2048
	ds_read_b128 v[158:161], v158 offset:3072
	s_waitcnt vmcnt(0)
	s_barrier
	s_waitcnt lgkmcnt(0)
	s_waitcnt lgkmcnt(0)
	v_mfma_f32_16x16x32_bf16 v[4:7], v[8:11], v[132:135], v[218:221]
	v_mfma_f32_16x16x32_bf16 v[8:11], v[8:11], v[208:211], v[172:175]
	v_mfma_f32_16x16x32_bf16 v[4:7], v[12:15], v[204:207], v[4:7]
	v_mfma_f32_16x16x32_bf16 v[20:23], v[12:15], v[158:161], v[8:11]
	v_mfma_f32_16x16x32_bf16 v[8:11], v[16:19], v[132:135], v[176:179]
	v_mfma_f32_16x16x32_bf16 v[12:15], v[16:19], v[208:211], v[180:183]
	v_mfma_f32_16x16x32_bf16 v[8:11], v[24:27], v[204:207], v[8:11]
	v_mfma_f32_16x16x32_bf16 v[24:27], v[24:27], v[158:161], v[12:15]
	v_mfma_f32_16x16x32_bf16 v[12:15], v[28:31], v[132:135], v[80:83]
	v_mfma_f32_16x16x32_bf16 v[16:19], v[28:31], v[208:211], v[76:79]
	v_mfma_f32_16x16x32_bf16 v[12:15], v[32:35], v[204:207], v[12:15]
	v_mfma_f32_16x16x32_bf16 v[28:31], v[32:35], v[158:161], v[16:19]
	v_mfma_f32_16x16x32_bf16 v[16:19], v[246:249], v[132:135], v[72:75]
	v_mfma_f32_16x16x32_bf16 v[32:35], v[246:249], v[208:211], v[68:71]
	v_mfma_f32_16x16x32_bf16 v[16:19], v[226:229], v[204:207], v[16:19]
	v_mfma_f32_16x16x32_bf16 v[32:35], v[226:229], v[158:161], v[32:35]
	s_barrier
	ds_read_b128 v[170:173], v156 offset:49152
	ds_read_b128 v[174:177], v156 offset:50176
	ds_read_b128 v[178:181], v155 offset:49152
	ds_read_b128 v[212:215], v155 offset:50176
	ds_read_b128 v[216:219], v154 offset:49152
	ds_read_b128 v[154:157], v154 offset:50176
	ds_read_b128 v[220:223], v153 offset:49152
	ds_read_b128 v[150:153], v153 offset:50176
	s_barrier
	s_waitcnt lgkmcnt(0)
	s_waitcnt lgkmcnt(0)
	v_mfma_f32_16x16x32_bf16 v[64:67], v[170:173], v[196:199], v[64:67]
	v_mfma_f32_16x16x32_bf16 v[60:63], v[170:173], v[238:241], v[60:63]
	v_mfma_f32_16x16x32_bf16 v[56:59], v[178:181], v[196:199], v[56:59]
	v_mfma_f32_16x16x32_bf16 v[52:55], v[178:181], v[238:241], v[52:55]
	v_mfma_f32_16x16x32_bf16 v[48:51], v[216:219], v[196:199], v[48:51]
	v_mfma_f32_16x16x32_bf16 v[44:47], v[216:219], v[238:241], v[44:47]
	v_mfma_f32_16x16x32_bf16 v[40:43], v[220:223], v[196:199], v[40:43]
	v_mfma_f32_16x16x32_bf16 v[36:39], v[220:223], v[238:241], v[36:39]
	v_mfma_f32_16x16x32_bf16 v[128:131], v[174:177], v[230:233], v[64:67]
	v_mfma_f32_16x16x32_bf16 v[124:127], v[174:177], v[242:245], v[60:63]
	v_mfma_f32_16x16x32_bf16 v[120:123], v[212:215], v[230:233], v[56:59]
	v_mfma_f32_16x16x32_bf16 v[112:115], v[212:215], v[242:245], v[52:55]
	v_mfma_f32_16x16x32_bf16 v[80:83], v[154:157], v[230:233], v[48:51]
	v_mfma_f32_16x16x32_bf16 v[76:79], v[154:157], v[242:245], v[44:47]
	v_mfma_f32_16x16x32_bf16 v[72:75], v[150:153], v[230:233], v[40:43]
	v_mfma_f32_16x16x32_bf16 v[68:71], v[150:153], v[242:245], v[36:39]
	v_mfma_f32_16x16x32_bf16 v[40:43], v[170:173], v[208:211], v[140:143]
	v_mfma_f32_16x16x32_bf16 v[44:47], v[178:181], v[208:211], v[166:169]
	v_mfma_f32_16x16x32_bf16 v[48:51], v[216:219], v[208:211], v[184:187]
	v_mfma_f32_16x16x32_bf16 v[36:39], v[170:173], v[132:135], v[136:139]
	v_mfma_f32_16x16x32_bf16 v[52:55], v[174:177], v[158:161], v[40:43]
	v_mfma_f32_16x16x32_bf16 v[40:43], v[178:181], v[132:135], v[162:165]
	v_mfma_f32_16x16x32_bf16 v[56:59], v[212:215], v[158:161], v[44:47]
	v_mfma_f32_16x16x32_bf16 v[44:47], v[216:219], v[132:135], v[200:203]
	v_mfma_f32_16x16x32_bf16 v[60:63], v[154:157], v[158:161], v[48:51]
	v_mfma_f32_16x16x32_bf16 v[48:51], v[220:223], v[132:135], v[188:191]
	v_mfma_f32_16x16x32_bf16 v[64:67], v[220:223], v[208:211], v[192:195]
	v_mfma_f32_16x16x32_bf16 v[36:39], v[174:177], v[204:207], v[36:39]
	v_mfma_f32_16x16x32_bf16 v[40:43], v[212:215], v[204:207], v[40:43]
	v_mfma_f32_16x16x32_bf16 v[44:47], v[154:157], v[204:207], v[44:47]
	v_mfma_f32_16x16x32_bf16 v[48:51], v[150:153], v[204:207], v[48:51]
	v_mfma_f32_16x16x32_bf16 v[64:67], v[150:153], v[158:161], v[64:67]
	s_movk_i32 s2, 0x100
	v_cmp_gt_u32_e32 vcc, s2, v3
	s_barrier
	s_and_saveexec_b64 s[2:3], vcc
	s_cbranch_execz .LBB0_911
	s_barrier

;     ...
;   if (!pre) {
;     STAGE8(SB8(0, 0), Bt, K, bcol, 0); STAGE8(SA8(0, 0), A, lda, brow, 0);
;     STAGE8(SB8(0, 1), Bt, K, bcol + 128, 0); STAGE8(SA8(0, 1), A, lda, brow + 128, 0);
;   }
.LBB0_1001:
	s_lshr_b32 s27, s37, 8
	s_cmpk_gt_i32 s38, 0x7f
	s_mov_b64 s[0:1], -1
	s_cbranch_scc0 .LBB0_1011
	s_mov_b32 s0, 25
	s_ashr_i32 s1, s0, 31
	s_lshl_b64 s[0:1], s[0:1], 3
	s_add_u32 s0, s70, s0
	s_addc_u32 s1, s71, s1
	v_readlane_b32 s6, v255, 60
	v_readlane_b32 s7, v255, 61
	s_nop 4
	s_mov_b32 s0, 25
	s_ashr_i32 s1, s0, 31
	s_lshl_b64 s[0:1], s[0:1], 3
	s_add_u32 s0, s70, s0
	s_addc_u32 s1, s71, s1
	v_readlane_b32 s2, v255, 60
	v_readlane_b32 s3, v255, 61
	s_nop 4
	s_mov_b32 s0, 25
	s_ashr_i32 s1, s0, 31
	s_lshl_b64 s[0:1], s[0:1], 3
	s_add_u32 s0, s70, s0
	s_addc_u32 s1, s71, s1
	v_mov_b32_e32 v3, v224
	v_readlane_b32 s12, v255, 60
	v_readlane_b32 s13, v255, 61
	s_nop 4
	s_lshl_b32 s0, s38, 8
	v_bfe_i32 v1, v3, 27, 1
	s_waitcnt vmcnt(10)
	v_lshlrev_b32_e32 v150, 4, v3
	s_nop 0
	v_readfirstlane_b32 s100, v150
	v_lshrrev_b32_e32 v1, 22, v1
	v_add_u32_e32 v1, v150, v1
	v_and_b32_e32 v1, 0xfffffc00, v1
	v_ashrrev_i32_e32 v0, 31, v3
	v_sub_u32_e32 v1, v150, v1
	v_lshrrev_b32_e32 v0, 26, v0
	v_lshrrev_b32_e32 v5, 4, v1
	v_add_u32_e32 v0, v3, v0
	v_bitop3_b32 v5, v5, v1, 32 bitop3:0x6c
	v_ashrrev_i32_e32 v1, 31, v1
	v_ashrrev_i32_e32 v0, 6, v0
	v_lshrrev_b32_e32 v1, 26, v1
	v_lshlrev_b32_e32 v6, 3, v0
	v_add_u32_e32 v1, v5, v1
	s_and_b32 s29, s0, 0x700
	s_lshl_b32 s0, s38, 5
	v_and_b32_e32 v6, -16, v6
	v_ashrrev_i32_e32 v1, 6, v1
	s_and_b32 s39, s0, 0x7fffff00
	v_add_u32_e32 v6, v1, v6
	v_mul_i32_i24_e32 v1, 64, v1
	s_add_i32 s0, s39, 0xfffff000
	v_lshlrev_b32_e32 v0, 5, v0
	v_sub_u32_e32 v1, v5, v1
	v_mov_b32_e32 v14, 1
	s_waitcnt vmcnt(9)
	v_add_u32_e32 v152, 0x2000, v150
	s_lshl_b32 s1, s0, 11
	v_and_b32_e32 v0, 32, v0
	v_ashrrev_i16_sdwa v1, v14, sext(v1) dst_sel:DWORD dst_unused:UNUSED_PAD src0_sel:DWORD src1_sel:BYTE_0
	v_ashrrev_i32_e32 v5, 31, v152
	s_add_u32 s14, s24, s1
	v_add_u32_sdwa v0, v0, sext(v1) dst_sel:DWORD dst_unused:UNUSED_PAD src0_sel:DWORD src1_sel:WORD_0
	v_ashrrev_i32_e32 v7, 31, v6
	v_lshrrev_b32_e32 v5, 22, v5
	s_addc_u32 s15, s25, 0
	v_lshlrev_b64 v[132:133], 11, v[6:7]
	v_ashrrev_i32_e32 v1, 31, v0
	v_add_u32_e32 v5, v152, v5
	v_lshl_add_u64 v[8:9], s[14:15], 0, v[132:133]
	v_lshlrev_b64 v[6:7], 1, v[0:1]
	v_ashrrev_i32_e32 v5, 10, v5
	v_lshl_add_u64 v[10:11], v[8:9], 0, v[6:7]
	v_mul_i32_i24_e32 v8, 0x400, v5
	v_sub_u32_e32 v8, v152, v8
	v_lshrrev_b32_e32 v9, 4, v8
	v_bitop3_b32 v9, v9, v8, 32 bitop3:0x6c
	v_ashrrev_i32_e32 v12, 31, v9
	v_add_u32_e32 v151, 0x10000, v150
	v_lshrrev_b32_e32 v12, 26, v12
	v_add_u32_e32 v12, v9, v12
	s_waitcnt vmcnt(8)
	v_add_u32_e32 v157, 0x12000, v150
	v_mov_b32_e32 v4, v2
	s_or_b32 m0, s100, 0x10000
	v_lshlrev_b32_e32 v8, 3, v5
	v_ashrrev_i32_e32 v13, 6, v12
	v_and_b32_e32 v12, 0xc0, v12
	global_load_lds_dwordx4 v[10:11], off
	v_and_b32_e32 v8, -16, v8
	v_lshlrev_b32_e32 v5, 5, v5
	v_sub_u32_e32 v9, v9, v12
	s_or_b32 m0, s100, 0x12000
	s_lshl_b32 s1, s29, 11
	v_add_u32_e32 v8, v13, v8
	v_and_b32_e32 v5, 32, v5
	v_ashrrev_i16_sdwa v9, v14, sext(v9) dst_sel:DWORD dst_unused:UNUSED_PAD src0_sel:DWORD src1_sel:BYTE_0
	s_waitcnt lgkmcnt(0)
	s_add_u32 s1, s12, s1
	v_add_u32_sdwa v134, v5, sext(v9) dst_sel:DWORD dst_unused:UNUSED_PAD src0_sel:DWORD src1_sel:WORD_0
	v_ashrrev_i32_e32 v9, 31, v8
	s_addc_u32 s40, s13, 0
	v_lshlrev_b64 v[136:137], 11, v[8:9]
	v_ashrrev_i32_e32 v135, 31, v134
	s_add_u32 s8, s1, 0xb800000
	v_lshl_add_u64 v[12:13], s[14:15], 0, v[136:137]
	v_lshlrev_b64 v[8:9], 1, v[134:135]
	s_addc_u32 s9, s40, 0
	v_lshl_add_u64 v[12:13], v[12:13], 0, v[8:9]
	v_lshl_add_u64 v[14:15], s[8:9], 0, v[132:133]
	global_load_lds_dwordx4 v[12:13], off
	v_lshl_add_u64 v[16:17], v[14:15], 0, v[6:7]
	s_mov_b32 m0, s100
	s_nop 0
	global_load_lds_dwordx4 v[16:17], off
	s_or_b32 m0, s100, 0x2000
	s_add_u32 s20, s14, 0x40000
	v_lshl_add_u64 v[14:15], s[8:9], 0, v[136:137]
	s_addc_u32 s21, s15, 0
	v_add_u32_e32 v159, 0x14000, v150
	v_lshl_add_u64 v[14:15], v[14:15], 0, v[8:9]
	v_lshl_add_u64 v[18:19], s[20:21], 0, v[132:133]
	global_load_lds_dwordx4 v[14:15], off
	v_lshl_add_u64 v[18:19], v[18:19], 0, v[6:7]
	s_or_b32 m0, s100, 0x14000
	v_add_u32_e32 v160, 0x16000, v150
	global_load_lds_dwordx4 v[18:19], off
	v_lshl_add_u64 v[18:19], s[20:21], 0, v[136:137]
	s_or_b32 m0, s100, 0x16000
	s_add_u32 s20, s1, 0xb840000
	v_lshl_add_u64 v[18:19], v[18:19], 0, v[8:9]
	s_addc_u32 s21, s40, 0
	v_add_u32_e32 v162, 0x4000, v150
	global_load_lds_dwordx4 v[18:19], off
	v_lshl_add_u64 v[18:19], s[20:21], 0, v[132:133]
	v_lshl_add_u64 v[18:19], v[18:19], 0, v[6:7]
	s_or_b32 m0, s100, 0x4000
	v_add_u32_e32 v163, 0x6000, v150
	global_load_lds_dwordx4 v[18:19], off
	v_lshl_add_u64 v[18:19], s[20:21], 0, v[136:137]
	v_lshl_add_u64 v[18:19], v[18:19], 0, v[8:9]
	s_or_b32 m0, s100, 0x6000
	v_ashrrev_i32_e32 v5, 8, v3
	global_load_lds_dwordx4 v[18:19], off
	v_cmp_eq_u32_e32 vcc, 1, v5
	s_and_saveexec_b64 s[20:21], vcc
	s_cbranch_execz .LBB0_1004
	s_barrier
; #define WAIT_V8(n) asm volatile("s_waitcnt vmcnt(" #n ")" ::: "memory")
; #define BAR8 __builtin_amdgcn_s_barrier()
;     ...
;   const int brow = m0, bcol = n0;
;   const int wid = t >> 6, lane = t & 63, wr = wid >> 2, wc = wid & 3, fr = lane & 15, fq = lane >> 4;
;   f32x4 acc[2][2][4][2];
;   {
;     float zinit = 0.f;
;     asm volatile("" : "+v"(zinit));
; #pragma unroll
;     for (int a = 0; a < 2; ++a)
; #pragma unroll
;       for (int b = 0; b < 2; ++b)
; #pragma unroll
;         for (int m = 0; m < 4; ++m)
; #pragma unroll
;           for (int n = 0; n < 2; ++n)
; #pragma unroll
;             for (int j = 0; j < 4; ++j) acc[a][b][m][n][j] = zinit;
;   }
;   bf16x8 At[4][2], B0[2][2], B1[2][2];
;   const int nt = K / 64;
;   if (!pre) {
;     STAGE8(SB8(0, 0), Bt, K, bcol, 0); STAGE8(SA8(0, 0), A, lda, brow, 0);
;     STAGE8(SB8(0, 1), Bt, K, bcol + 128, 0); STAGE8(SA8(0, 1), A, lda, brow + 128, 0);
;   }
;   if (wr == 1) BAR8;
;   WAIT_V8(4); BAR8;
;   STAGE8(SB8(1, 0), Bt, K, bcol, 1); STAGE8(SA8(1, 0), A, lda, brow, 1); STAGE8(SB8(1, 1), Bt, K, bcol + 128, 1);
;   WAIT_V8(6); BAR8;
.LBB0_1004:
	s_or_b64 exec, exec, s[20:21]
	v_readlane_b32 s40, v254, 35
	s_lshl_b32 s20, s36, 10
	v_readlane_b32 s42, v254, 37
	v_readlane_b32 s43, v254, 38
	s_waitcnt vmcnt(0)
	v_add_u32_e32 v164, 0x18000, v150
	s_and_b32 s20, s20, 0xfffc0000
	s_mov_b32 s21, s40
	s_mov_b64 s[42:43], 0x80
	v_add_u32_e32 v165, 0x1a000, v150
	s_and_b32 s1, s27, 7
	s_add_i32 s20, s20, 0xffc00000
	v_lshl_add_u64 v[10:11], v[10:11], 0, s[42:43]
	s_or_b32 m0, s100, 0x18000
	v_add_u32_e32 v166, 0x8000, v150
	s_lshl_b32 s1, s1, 19
	s_lshl_b64 s[20:21], s[20:21], 1
	s_waitcnt vmcnt(4)
	s_barrier
	global_load_lds_dwordx4 v[10:11], off
	v_lshl_add_u64 v[10:11], v[12:13], 0, s[42:43]
	s_or_b32 m0, s100, 0x1a000
	v_add_u32_e32 v167, 0xa000, v150
	global_load_lds_dwordx4 v[10:11], off
	v_lshl_add_u64 v[10:11], v[16:17], 0, s[42:43]
	s_or_b32 m0, s100, 0x8000
	s_add_u32 s14, s14, 0x40080
	global_load_lds_dwordx4 v[10:11], off
	v_lshl_add_u64 v[10:11], v[14:15], 0, s[42:43]
	s_addc_u32 s15, s15, 0
	s_or_b32 m0, s100, 0xa000
	v_add_u32_e32 v169, 0x1c000, v150
	global_load_lds_dwordx4 v[10:11], off
	v_lshl_add_u64 v[10:11], s[14:15], 0, v[132:133]
	v_lshl_add_u64 v[10:11], v[10:11], 0, v[6:7]
	s_or_b32 m0, s100, 0x1c000
	v_add_u32_e32 v170, 0x1e000, v150
	global_load_lds_dwordx4 v[10:11], off
	v_lshl_add_u64 v[10:11], s[14:15], 0, v[136:137]
	v_lshl_add_u64 v[10:11], v[10:11], 0, v[8:9]
	s_or_b32 m0, s100, 0x1e000
	v_and_b32_e32 v147, 15, v3
	global_load_lds_dwordx4 v[10:11], off
	v_bfe_u32 v148, v3, 4, 2
	v_lshlrev_b32_e32 v11, 4, v148
	v_lshlrev_b32_e32 v12, 6, v147
	v_lshlrev_b32_e32 v14, 2, v3
	v_or_b32_e32 v13, v11, v12
	v_and_b32_e32 v14, 32, v14
	s_mov_b32 s14, 0x10000
	v_bitop3_b32 v15, v13, s14, v14 bitop3:0xde
	s_mov_b32 s14, 0x14000
	s_add_u32 s12, s12, s1
	v_bitop3_b32 v16, v13, s14, v14 bitop3:0xde
	s_mov_b32 s14, 0x18000
	v_lshlrev_b32_e32 v18, 6, v3
	s_addc_u32 s13, s13, 0
	v_lshl_add_u64 v[8:9], v[136:137], 0, v[8:9]
	v_lshl_add_u64 v[6:7], v[132:133], 0, v[6:7]
	v_bfe_u32 v146, v3, 6, 2
	s_waitcnt vmcnt(6)
	v_lshlrev_b32_e32 v149, 6, v5
	v_bitop3_b32 v17, v13, s14, v14 bitop3:0xde
	s_mov_b32 s14, 0x1c000
	v_lshlrev_b32_e32 v5, 13, v5
	v_and_b32_e32 v18, 0x3c0, v18
	v_lshl_add_u64 v[138:139], s[12:13], 0, v[8:9]
	v_lshl_add_u64 v[140:141], s[12:13], 0, v[6:7]
	s_add_u32 s12, s4, s20
	v_readlane_b32 s41, v254, 36
	v_lshlrev_b32_e32 v10, 12, v146
	v_bitop3_b32 v12, v11, v14, v12 bitop3:0x36
	v_bitop3_b32 v13, v13, s14, v14 bitop3:0xde
	v_bitop3_b32 v11, v18, v14, v11 bitop3:0x36
	v_or_b32_e32 v14, 0x800, v5
	v_or_b32_e32 v18, 0x1000, v5
	v_or_b32_e32 v19, 0x1800, v5
	s_addc_u32 s13, s5, s21
	v_lshl_add_u64 v[142:143], s[12:13], 0, v[6:7]
	v_lshl_add_u64 v[144:145], s[12:13], 0, v[8:9]
	s_mov_b32 s1, -2
	s_mov_b64 s[12:13], 0
	v_add_u32_e32 v171, v15, v10
	v_add_u32_e32 v156, v12, v5
	v_add_u32_e32 v155, v11, v14
	v_add_u32_e32 v154, v11, v18
	v_add_u32_e32 v153, v11, v19
	v_add_u32_e32 v168, v16, v10
	v_add_u32_e32 v161, v17, v10
	v_add_u32_e32 v158, v13, v10
	v_mov_b32_e32 v5, v4
	v_mov_b64_e32 v[6:7], v[4:5]
	v_mov_b64_e32 v[8:9], v[4:5]
	v_mov_b64_e32 v[10:11], v[4:5]
	v_mov_b64_e32 v[12:13], v[4:5]
	v_mov_b64_e32 v[14:15], v[4:5]
	v_mov_b64_e32 v[16:17], v[4:5]
	v_mov_b64_e32 v[18:19], v[4:5]
	v_mov_b64_e32 v[20:21], v[4:5]
	v_mov_b64_e32 v[22:23], v[4:5]
	v_mov_b64_e32 v[24:25], v[4:5]
	v_mov_b64_e32 v[26:27], v[4:5]
	v_mov_b64_e32 v[28:29], v[4:5]
	v_mov_b64_e32 v[30:31], v[4:5]
	v_mov_b64_e32 v[32:33], v[4:5]
	v_mov_b64_e32 v[34:35], v[4:5]
	v_mov_b64_e32 v[36:37], v[4:5]
	v_mov_b64_e32 v[38:39], v[4:5]
	v_mov_b64_e32 v[40:41], v[4:5]
	v_mov_b64_e32 v[42:43], v[4:5]
	v_mov_b64_e32 v[44:45], v[4:5]
	v_mov_b64_e32 v[46:47], v[4:5]
	v_mov_b64_e32 v[48:49], v[4:5]
	v_mov_b64_e32 v[50:51], v[4:5]
	v_mov_b64_e32 v[52:53], v[4:5]
	v_mov_b64_e32 v[54:55], v[4:5]
	v_mov_b64_e32 v[56:57], v[4:5]
	v_mov_b64_e32 v[58:59], v[4:5]
	v_mov_b64_e32 v[60:61], v[4:5]
	v_mov_b64_e32 v[62:63], v[4:5]
	v_mov_b64_e32 v[64:65], v[4:5]
	v_mov_b64_e32 v[66:67], v[4:5]
	v_mov_b64_e32 v[68:69], v[4:5]
	v_mov_b64_e32 v[70:71], v[4:5]
	v_mov_b64_e32 v[72:73], v[4:5]
	v_mov_b64_e32 v[74:75], v[4:5]
	v_mov_b64_e32 v[76:77], v[4:5]
	v_mov_b64_e32 v[78:79], v[4:5]
	v_mov_b64_e32 v[80:81], v[4:5]
	v_mov_b64_e32 v[82:83], v[4:5]
	v_mov_b64_e32 v[84:85], v[4:5]
	v_mov_b64_e32 v[86:87], v[4:5]
	v_mov_b64_e32 v[88:89], v[4:5]
	v_mov_b64_e32 v[90:91], v[4:5]
	v_mov_b64_e32 v[92:93], v[4:5]
	v_mov_b64_e32 v[94:95], v[4:5]
	v_mov_b64_e32 v[96:97], v[4:5]
	v_mov_b64_e32 v[98:99], v[4:5]
	v_mov_b64_e32 v[100:101], v[4:5]
	v_mov_b64_e32 v[102:103], v[4:5]
	v_mov_b64_e32 v[104:105], v[4:5]
	v_mov_b64_e32 v[106:107], v[4:5]
	v_mov_b64_e32 v[108:109], v[4:5]
	v_mov_b64_e32 v[110:111], v[4:5]
	v_mov_b64_e32 v[112:113], v[4:5]
	v_mov_b64_e32 v[114:115], v[4:5]
	v_mov_b64_e32 v[116:117], v[4:5]
	v_mov_b64_e32 v[118:119], v[4:5]
	v_mov_b64_e32 v[120:121], v[4:5]
	v_mov_b64_e32 v[122:123], v[4:5]
	v_mov_b64_e32 v[124:125], v[4:5]
	v_mov_b64_e32 v[126:127], v[4:5]
	v_mov_b64_e32 v[128:129], v[4:5]
	v_mov_b64_e32 v[130:131], v[4:5]
	s_mov_b64 s[20:21], 0xb840080
	s_mov_b64 s[40:41], 0xc7a0100
	s_mov_b64 s[42:43], 0xb800100
	s_mov_b64 s[44:45], 0xc7e0100
	s_mov_b64 s[46:47], 0xb840100
	s_mov_b64 s[48:49], 0xc7a0180
	s_mov_b64 s[50:51], 0xb800180
	s_mov_b64 s[52:53], 0xc7e0180
	s_barrier
; #define LDA8(dst, b, h) _Pragma("unroll") for (int m = 0; m < 4; ++m) _Pragma("unroll") for (int k = 0; k < 2; ++k) \
;     dst[m][k] = *(const bf16x8*)((const char*)SA8(b, h) + lds_byte8(wr * 64 + m * 16 + fr, k * 32 + fq * 8))
; #define LDB8(dst, b, h) _Pragma("unroll") for (int n = 0; n < 2; ++n) _Pragma("unroll") for (int k = 0; k < 2; ++k) \
;     dst[n][k] = *(const bf16x8*)((const char*)SB8(b, h) + lds_byte8(wc * 32 + n * 16 + fr, k * 32 + fq * 8))
; #define WAIT_L8(n) asm volatile("s_waitcnt lgkmcnt(" #n ")" ::: "memory")
; #define BAR8 __builtin_amdgcn_s_barrier()
; #define SCHED8 __builtin_amdgcn_sched_barrier(0)
;     ...
;   for (int tt = 0; tt < nt - 2; tt += 2) {
;     LDB8(B0, 0, 0); SCHED8; LDA8(At, 0, 0); STAGE8(SA8(1, 1), A, lda, brow + 128, tt + 1);
;     WAIT_L8(8); BAR8; WAIT_L8(0); MMA8(0, 0, At, B0); BAR8; SCHED8;
;     LDB8(B1, 0, 1); STAGE8(SB8(0, 0), Bt, K, bcol, tt + 2);
;     BAR8; WAIT_L8(0); MMA8(0, 1, At, B1); BAR8;
;     LDA8(At, 0, 1); STAGE8(SA8(0, 0), A, lda, brow, tt + 2);
;     BAR8; WAIT_L8(0); MMA8(1, 0, At, B0); BAR8; SCHED8;
.LBB0_1005:
	ds_read_b128 v[174:177], v171
	ds_read_b128 v[178:181], v171 offset:1024
	ds_read_b128 v[182:185], v171 offset:2048
	ds_read_b128 v[186:189], v171 offset:3072
	v_add_u32_e32 v172, 0xc000, v150
	v_lshl_add_u64 v[222:223], v[140:141], 0, s[12:13]
	v_add_u32_e32 v173, 0xe000, v150
	v_lshl_add_u64 v[226:227], v[222:223], 0, s[20:21]
	s_or_b32 m0, s100, 0xc000
	v_lshl_add_u64 v[236:237], v[138:139], 0, s[12:13]
	ds_read_b128 v[190:193], v156
	ds_read_b128 v[194:197], v156 offset:1024
	ds_read_b128 v[198:201], v155
	ds_read_b128 v[202:205], v155 offset:1024
	ds_read_b128 v[206:209], v154
	ds_read_b128 v[210:213], v154 offset:1024
	ds_read_b128 v[214:217], v153
	ds_read_b128 v[218:221], v153 offset:1024
	global_load_lds_dwordx4 v[226:227], off
	v_lshl_add_u64 v[226:227], v[236:237], 0, s[20:21]
	s_or_b32 m0, s100, 0xe000
	s_nop 0
	global_load_lds_dwordx4 v[226:227], off
	s_waitcnt lgkmcnt(8)
	s_barrier
	s_waitcnt lgkmcnt(0)
	s_waitcnt lgkmcnt(0)
	v_mfma_f32_16x16x32_bf16 v[128:131], v[190:193], v[174:177], v[128:131]
	v_mfma_f32_16x16x32_bf16 v[124:127], v[190:193], v[182:185], v[124:127]
	v_mfma_f32_16x16x32_bf16 v[120:123], v[198:201], v[174:177], v[120:123]
	v_mfma_f32_16x16x32_bf16 v[116:119], v[198:201], v[182:185], v[116:119]
	v_mfma_f32_16x16x32_bf16 v[112:115], v[206:209], v[174:177], v[112:115]
	v_mfma_f32_16x16x32_bf16 v[108:111], v[206:209], v[182:185], v[108:111]
	v_mfma_f32_16x16x32_bf16 v[104:107], v[214:217], v[174:177], v[104:107]
	v_mfma_f32_16x16x32_bf16 v[100:103], v[214:217], v[182:185], v[100:103]
	v_mfma_f32_16x16x32_bf16 v[128:131], v[194:197], v[178:181], v[128:131]
	v_mfma_f32_16x16x32_bf16 v[124:127], v[194:197], v[186:189], v[124:127]
	v_mfma_f32_16x16x32_bf16 v[120:123], v[202:205], v[178:181], v[120:123]
	v_mfma_f32_16x16x32_bf16 v[116:119], v[202:205], v[186:189], v[116:119]
	v_mfma_f32_16x16x32_bf16 v[112:115], v[210:213], v[178:181], v[112:115]
	v_mfma_f32_16x16x32_bf16 v[108:111], v[210:213], v[186:189], v[108:111]
	v_mfma_f32_16x16x32_bf16 v[104:107], v[218:221], v[178:181], v[104:107]
	v_mfma_f32_16x16x32_bf16 v[100:103], v[218:221], v[186:189], v[100:103]
	s_barrier
	v_lshl_add_u64 v[246:247], v[142:143], 0, s[12:13]
	v_lshl_add_u64 v[248:249], v[246:247], 0, s[40:41]
	s_or_b32 m0, s100, 0x10000
	ds_read_b128 v[226:229], v168
	ds_read_b128 v[230:233], v168 offset:1024
	ds_read_b128 v[238:241], v168 offset:2048
	ds_read_b128 v[242:245], v168 offset:3072
	global_load_lds_dwordx4 v[248:249], off
	v_lshl_add_u64 v[248:249], v[144:145], 0, s[12:13]
	v_lshl_add_u64 v[250:251], v[248:249], 0, s[40:41]
	s_or_b32 m0, s100, 0x12000
	s_nop 0
	global_load_lds_dwordx4 v[250:251], off
	s_barrier
	s_waitcnt lgkmcnt(0)
	s_waitcnt lgkmcnt(0)
	v_mfma_f32_16x16x32_bf16 v[96:99], v[190:193], v[226:229], v[96:99]
	v_mfma_f32_16x16x32_bf16 v[92:95], v[190:193], v[238:241], v[92:95]
	v_mfma_f32_16x16x32_bf16 v[88:91], v[198:201], v[226:229], v[88:91]
	v_mfma_f32_16x16x32_bf16 v[84:87], v[198:201], v[238:241], v[84:87]
	v_mfma_f32_16x16x32_bf16 v[80:83], v[206:209], v[226:229], v[80:83]
	v_mfma_f32_16x16x32_bf16 v[76:79], v[206:209], v[238:241], v[76:79]
	v_mfma_f32_16x16x32_bf16 v[72:75], v[214:217], v[226:229], v[72:75]
	v_mfma_f32_16x16x32_bf16 v[68:71], v[214:217], v[238:241], v[68:71]
	v_mfma_f32_16x16x32_bf16 v[96:99], v[194:197], v[230:233], v[96:99]
	v_mfma_f32_16x16x32_bf16 v[92:95], v[194:197], v[242:245], v[92:95]
	v_mfma_f32_16x16x32_bf16 v[88:91], v[202:205], v[230:233], v[88:91]
	v_mfma_f32_16x16x32_bf16 v[84:87], v[202:205], v[242:245], v[84:87]
	v_mfma_f32_16x16x32_bf16 v[80:83], v[210:213], v[230:233], v[80:83]
	v_mfma_f32_16x16x32_bf16 v[76:79], v[210:213], v[242:245], v[76:79]
	v_mfma_f32_16x16x32_bf16 v[72:75], v[218:221], v[230:233], v[72:75]
	v_mfma_f32_16x16x32_bf16 v[68:71], v[218:221], v[242:245], v[68:71]
	v_lshl_add_u64 v[250:251], v[222:223], 0, s[42:43]
	s_mov_b32 m0, s100
	s_barrier
	ds_read_b128 v[190:193], v156 offset:16384
	ds_read_b128 v[194:197], v156 offset:17408
	ds_read_b128 v[198:201], v155 offset:16384
	ds_read_b128 v[202:205], v155 offset:17408
	ds_read_b128 v[206:209], v154 offset:16384
	ds_read_b128 v[210:213], v154 offset:17408
	ds_read_b128 v[214:217], v153 offset:16384
	ds_read_b128 v[218:221], v153 offset:17408
	global_load_lds_dwordx4 v[250:251], off
	v_lshl_add_u64 v[250:251], v[236:237], 0, s[42:43]
	s_or_b32 m0, s100, 0x2000
	s_nop 0
	global_load_lds_dwordx4 v[250:251], off
	s_barrier
	s_waitcnt lgkmcnt(0)
	s_waitcnt lgkmcnt(0)
	v_mfma_f32_16x16x32_bf16 v[64:67], v[190:193], v[174:177], v[64:67]
	v_mfma_f32_16x16x32_bf16 v[60:63], v[190:193], v[182:185], v[60:63]
	v_mfma_f32_16x16x32_bf16 v[56:59], v[198:201], v[174:177], v[56:59]
	v_mfma_f32_16x16x32_bf16 v[52:55], v[198:201], v[182:185], v[52:55]
	v_mfma_f32_16x16x32_bf16 v[48:51], v[206:209], v[174:177], v[48:51]
	v_mfma_f32_16x16x32_bf16 v[44:47], v[206:209], v[182:185], v[44:47]
	v_mfma_f32_16x16x32_bf16 v[40:43], v[214:217], v[174:177], v[40:43]
	v_mfma_f32_16x16x32_bf16 v[36:39], v[214:217], v[182:185], v[36:39]
	v_mfma_f32_16x16x32_bf16 v[64:67], v[194:197], v[178:181], v[64:67]
	v_mfma_f32_16x16x32_bf16 v[60:63], v[194:197], v[186:189], v[60:63]
	v_mfma_f32_16x16x32_bf16 v[56:59], v[202:205], v[178:181], v[56:59]
	v_mfma_f32_16x16x32_bf16 v[52:55], v[202:205], v[186:189], v[52:55]
	v_mfma_f32_16x16x32_bf16 v[48:51], v[210:213], v[178:181], v[48:51]
	v_mfma_f32_16x16x32_bf16 v[44:47], v[210:213], v[186:189], v[44:47]
	v_mfma_f32_16x16x32_bf16 v[40:43], v[218:221], v[178:181], v[40:43]
	v_mfma_f32_16x16x32_bf16 v[36:39], v[218:221], v[186:189], v[36:39]
	s_barrier
; #define LDA8(dst, b, h) _Pragma("unroll") for (int m = 0; m < 4; ++m) _Pragma("unroll") for (int k = 0; k < 2; ++k) \
;     dst[m][k] = *(const bf16x8*)((const char*)SA8(b, h) + lds_byte8(wr * 64 + m * 16 + fr, k * 32 + fq * 8))
; #define LDB8(dst, b, h) _Pragma("unroll") for (int n = 0; n < 2; ++n) _Pragma("unroll") for (int k = 0; k < 2; ++k) \
;     dst[n][k] = *(const bf16x8*)((const char*)SB8(b, h) + lds_byte8(wc * 32 + n * 16 + fr, k * 32 + fq * 8))
; #define WAIT_V8(n) asm volatile("s_waitcnt vmcnt(" #n ")" ::: "memory")
; #define WAIT_L8(n) asm volatile("s_waitcnt lgkmcnt(" #n ")" ::: "memory")
; #define BAR8 __builtin_amdgcn_s_barrier()
; #define SCHED8 __builtin_amdgcn_sched_barrier(0)
;     ...
;     BAR8; WAIT_L8(0); MMA8(1, 0, At, B0); BAR8; SCHED8;
;     STAGE8(SB8(0, 1), Bt, K, bcol + 128, tt + 2);
;     WAIT_V8(6); BAR8; MMA8(1, 1, At, B1); BAR8;
;     LDB8(B0, 1, 0); SCHED8; LDA8(At, 1, 0); STAGE8(SA8(0, 1), A, lda, brow + 128, tt + 2);
;     WAIT_L8(8); BAR8; WAIT_L8(0); MMA8(0, 0, At, B0); BAR8; SCHED8;
;     LDB8(B1, 1, 1); STAGE8(SB8(1, 0), Bt, K, bcol, tt + 3);
;     BAR8; WAIT_L8(0); MMA8(0, 1, At, B1); BAR8;
;     LDA8(At, 1, 1); STAGE8(SA8(1, 0), A, lda, brow, tt + 3);
	v_lshl_add_u64 v[174:175], v[246:247], 0, s[44:45]
	s_or_b32 m0, s100, 0x14000
	s_nop 0
	global_load_lds_dwordx4 v[174:175], off
	v_lshl_add_u64 v[174:175], v[248:249], 0, s[44:45]
	s_or_b32 m0, s100, 0x16000
	s_nop 0
	global_load_lds_dwordx4 v[174:175], off
	s_waitcnt vmcnt(6)
	s_barrier
	v_mfma_f32_16x16x32_bf16 v[32:35], v[190:193], v[226:229], v[32:35]
	v_mfma_f32_16x16x32_bf16 v[28:31], v[190:193], v[238:241], v[28:31]
	v_mfma_f32_16x16x32_bf16 v[24:27], v[198:201], v[226:229], v[24:27]
	v_mfma_f32_16x16x32_bf16 v[20:23], v[198:201], v[238:241], v[20:23]
	v_mfma_f32_16x16x32_bf16 v[16:19], v[206:209], v[226:229], v[16:19]
	v_mfma_f32_16x16x32_bf16 v[12:15], v[206:209], v[238:241], v[12:15]
	v_mfma_f32_16x16x32_bf16 v[8:11], v[214:217], v[226:229], v[8:11]
	v_mfma_f32_16x16x32_bf16 v[4:7], v[214:217], v[238:241], v[4:7]
	v_mfma_f32_16x16x32_bf16 v[32:35], v[194:197], v[230:233], v[32:35]
	v_mfma_f32_16x16x32_bf16 v[28:31], v[194:197], v[242:245], v[28:31]
	v_mfma_f32_16x16x32_bf16 v[24:27], v[202:205], v[230:233], v[24:27]
	v_mfma_f32_16x16x32_bf16 v[20:23], v[202:205], v[242:245], v[20:23]
	v_mfma_f32_16x16x32_bf16 v[16:19], v[210:213], v[230:233], v[16:19]
	v_mfma_f32_16x16x32_bf16 v[12:15], v[210:213], v[242:245], v[12:15]
	v_mfma_f32_16x16x32_bf16 v[8:11], v[218:221], v[230:233], v[8:11]
	v_mfma_f32_16x16x32_bf16 v[4:7], v[218:221], v[242:245], v[4:7]
	s_barrier
	ds_read_b128 v[174:177], v161
	ds_read_b128 v[178:181], v161 offset:1024
	ds_read_b128 v[182:185], v161 offset:2048
	ds_read_b128 v[186:189], v161 offset:3072
	v_lshl_add_u64 v[226:227], v[222:223], 0, s[46:47]
	s_or_b32 m0, s100, 0x4000
	ds_read_b128 v[190:193], v156 offset:32768
	ds_read_b128 v[194:197], v156 offset:33792
	ds_read_b128 v[198:201], v155 offset:32768
	ds_read_b128 v[202:205], v155 offset:33792
	ds_read_b128 v[206:209], v154 offset:32768
	ds_read_b128 v[210:213], v154 offset:33792
	ds_read_b128 v[214:217], v153 offset:32768
	ds_read_b128 v[218:221], v153 offset:33792
	global_load_lds_dwordx4 v[226:227], off
	v_lshl_add_u64 v[226:227], v[236:237], 0, s[46:47]
	s_or_b32 m0, s100, 0x6000
	s_nop 0
	global_load_lds_dwordx4 v[226:227], off
	s_waitcnt lgkmcnt(8)
	s_barrier
	s_waitcnt lgkmcnt(0)
	s_waitcnt lgkmcnt(0)
	v_mfma_f32_16x16x32_bf16 v[128:131], v[190:193], v[174:177], v[128:131]
	v_mfma_f32_16x16x32_bf16 v[124:127], v[190:193], v[182:185], v[124:127]
	v_mfma_f32_16x16x32_bf16 v[120:123], v[198:201], v[174:177], v[120:123]
	v_mfma_f32_16x16x32_bf16 v[116:119], v[198:201], v[182:185], v[116:119]
	v_mfma_f32_16x16x32_bf16 v[112:115], v[206:209], v[174:177], v[112:115]
	v_mfma_f32_16x16x32_bf16 v[108:111], v[206:209], v[182:185], v[108:111]
	v_mfma_f32_16x16x32_bf16 v[104:107], v[214:217], v[174:177], v[104:107]
	v_mfma_f32_16x16x32_bf16 v[100:103], v[214:217], v[182:185], v[100:103]
	v_mfma_f32_16x16x32_bf16 v[128:131], v[194:197], v[178:181], v[128:131]
	v_mfma_f32_16x16x32_bf16 v[124:127], v[194:197], v[186:189], v[124:127]
	v_mfma_f32_16x16x32_bf16 v[120:123], v[202:205], v[178:181], v[120:123]
	v_mfma_f32_16x16x32_bf16 v[116:119], v[202:205], v[186:189], v[116:119]
	v_mfma_f32_16x16x32_bf16 v[112:115], v[210:213], v[178:181], v[112:115]
	v_mfma_f32_16x16x32_bf16 v[108:111], v[210:213], v[186:189], v[108:111]
	v_mfma_f32_16x16x32_bf16 v[104:107], v[218:221], v[178:181], v[104:107]
	v_mfma_f32_16x16x32_bf16 v[100:103], v[218:221], v[186:189], v[100:103]
	s_barrier
	v_lshl_add_u64 v[250:251], v[246:247], 0, s[48:49]
	s_or_b32 m0, s100, 0x18000
	ds_read_b128 v[226:229], v158
	ds_read_b128 v[230:233], v158 offset:1024
	ds_read_b128 v[238:241], v158 offset:2048
	ds_read_b128 v[242:245], v158 offset:3072
	global_load_lds_dwordx4 v[250:251], off
	v_lshl_add_u64 v[250:251], v[248:249], 0, s[48:49]
	s_or_b32 m0, s100, 0x1a000
	s_nop 0
	global_load_lds_dwordx4 v[250:251], off
	s_barrier
	s_waitcnt lgkmcnt(0)
	s_waitcnt lgkmcnt(0)
	v_mfma_f32_16x16x32_bf16 v[96:99], v[190:193], v[226:229], v[96:99]
	v_mfma_f32_16x16x32_bf16 v[92:95], v[190:193], v[238:241], v[92:95]
	v_mfma_f32_16x16x32_bf16 v[88:91], v[198:201], v[226:229], v[88:91]
	v_mfma_f32_16x16x32_bf16 v[84:87], v[198:201], v[238:241], v[84:87]
	v_mfma_f32_16x16x32_bf16 v[80:83], v[206:209], v[226:229], v[80:83]
	v_mfma_f32_16x16x32_bf16 v[76:79], v[206:209], v[238:241], v[76:79]
	v_mfma_f32_16x16x32_bf16 v[72:75], v[214:217], v[226:229], v[72:75]
	v_mfma_f32_16x16x32_bf16 v[68:71], v[214:217], v[238:241], v[68:71]
	v_mfma_f32_16x16x32_bf16 v[96:99], v[194:197], v[230:233], v[96:99]
	v_mfma_f32_16x16x32_bf16 v[92:95], v[194:197], v[242:245], v[92:95]
	v_mfma_f32_16x16x32_bf16 v[88:91], v[202:205], v[230:233], v[88:91]
	v_mfma_f32_16x16x32_bf16 v[84:87], v[202:205], v[242:245], v[84:87]
	v_mfma_f32_16x16x32_bf16 v[80:83], v[210:213], v[230:233], v[80:83]
	v_mfma_f32_16x16x32_bf16 v[76:79], v[210:213], v[242:245], v[76:79]
	v_mfma_f32_16x16x32_bf16 v[72:75], v[218:221], v[230:233], v[72:75]
	v_mfma_f32_16x16x32_bf16 v[68:71], v[218:221], v[242:245], v[68:71]
	v_lshl_add_u64 v[222:223], v[222:223], 0, s[50:51]
	s_or_b32 m0, s100, 0x8000
	s_barrier
	ds_read_b128 v[190:193], v156 offset:49152
	ds_read_b128 v[194:197], v156 offset:50176
	ds_read_b128 v[198:201], v155 offset:49152
	ds_read_b128 v[202:205], v155 offset:50176
	ds_read_b128 v[206:209], v154 offset:49152
	ds_read_b128 v[210:213], v154 offset:50176
	ds_read_b128 v[214:217], v153 offset:49152
	ds_read_b128 v[218:221], v153 offset:50176
	global_load_lds_dwordx4 v[222:223], off
	v_lshl_add_u64 v[222:223], v[236:237], 0, s[50:51]
	s_or_b32 m0, s100, 0xa000
	s_nop 0
	global_load_lds_dwordx4 v[222:223], off
	s_barrier
; #define LDA8(dst, b, h) _Pragma("unroll") for (int m = 0; m < 4; ++m) _Pragma("unroll") for (int k = 0; k < 2; ++k) \
;     dst[m][k] = *(const bf16x8*)((const char*)SA8(b, h) + lds_byte8(wr * 64 + m * 16 + fr, k * 32 + fq * 8))
; #define LDB8(dst, b, h) _Pragma("unroll") for (int n = 0; n < 2; ++n) _Pragma("unroll") for (int k = 0; k < 2; ++k) \
;     dst[n][k] = *(const bf16x8*)((const char*)SB8(b, h) + lds_byte8(wc * 32 + n * 16 + fr, k * 32 + fq * 8))
; #define WAIT_V8(n) asm volatile("s_waitcnt vmcnt(" #n ")" ::: "memory")
; #define WAIT_L8(n) asm volatile("s_waitcnt lgkmcnt(" #n ")" ::: "memory")
; #define BAR8 __builtin_amdgcn_s_barrier()
; #define SCHED8 __builtin_amdgcn_sched_barrier(0)
;     ...
;     BAR8; WAIT_L8(0); MMA8(1, 0, At, B0); BAR8; SCHED8;
;     STAGE8(SB8(1, 1), Bt, K, bcol + 128, tt + 3);
;     WAIT_V8(6); BAR8; MMA8(1, 1, At, B1); BAR8;
;   }
;   { LDB8(B0, 0, 0); LDA8(At, 0, 0); STAGE8(SA8(1, 1), A, lda, brow + 128, nt - 1);
;     BAR8; WAIT_L8(0); MMA8(0, 0, At, B0); BAR8;
;     LDB8(B1, 0, 1); BAR8; WAIT_L8(0); MMA8(0, 1, At, B1); BAR8;
;     LDA8(At, 0, 1); WAIT_V8(4); BAR8; WAIT_L8(0); MMA8(1, 0, At, B0); MMA8(1, 1, At, B1); BAR8; }
	s_waitcnt lgkmcnt(0)
	s_waitcnt lgkmcnt(0)
	v_mfma_f32_16x16x32_bf16 v[64:67], v[190:193], v[174:177], v[64:67]
	v_mfma_f32_16x16x32_bf16 v[60:63], v[190:193], v[182:185], v[60:63]
	v_mfma_f32_16x16x32_bf16 v[56:59], v[198:201], v[174:177], v[56:59]
	v_mfma_f32_16x16x32_bf16 v[52:55], v[198:201], v[182:185], v[52:55]
	v_mfma_f32_16x16x32_bf16 v[48:51], v[206:209], v[174:177], v[48:51]
	v_mfma_f32_16x16x32_bf16 v[44:47], v[206:209], v[182:185], v[44:47]
	v_mfma_f32_16x16x32_bf16 v[40:43], v[214:217], v[174:177], v[40:43]
	v_mfma_f32_16x16x32_bf16 v[36:39], v[214:217], v[182:185], v[36:39]
	v_mfma_f32_16x16x32_bf16 v[64:67], v[194:197], v[178:181], v[64:67]
	v_mfma_f32_16x16x32_bf16 v[60:63], v[194:197], v[186:189], v[60:63]
	v_mfma_f32_16x16x32_bf16 v[56:59], v[202:205], v[178:181], v[56:59]
	v_mfma_f32_16x16x32_bf16 v[52:55], v[202:205], v[186:189], v[52:55]
	v_mfma_f32_16x16x32_bf16 v[48:51], v[210:213], v[178:181], v[48:51]
	v_mfma_f32_16x16x32_bf16 v[44:47], v[210:213], v[186:189], v[44:47]
	v_mfma_f32_16x16x32_bf16 v[40:43], v[218:221], v[178:181], v[40:43]
	v_mfma_f32_16x16x32_bf16 v[36:39], v[218:221], v[186:189], v[36:39]
	s_barrier
	v_lshl_add_u64 v[174:175], v[246:247], 0, s[52:53]
	s_or_b32 m0, s100, 0x1c000
	s_nop 0
	global_load_lds_dwordx4 v[174:175], off
	v_lshl_add_u64 v[174:175], v[248:249], 0, s[52:53]
	s_or_b32 m0, s100, 0x1e000
	s_nop 0
	global_load_lds_dwordx4 v[174:175], off
	s_waitcnt vmcnt(6)
	s_barrier
	v_mfma_f32_16x16x32_bf16 v[32:35], v[190:193], v[226:229], v[32:35]
	v_mfma_f32_16x16x32_bf16 v[28:31], v[190:193], v[238:241], v[28:31]
	v_mfma_f32_16x16x32_bf16 v[24:27], v[198:201], v[226:229], v[24:27]
	v_mfma_f32_16x16x32_bf16 v[20:23], v[198:201], v[238:241], v[20:23]
	v_mfma_f32_16x16x32_bf16 v[16:19], v[206:209], v[226:229], v[16:19]
	v_mfma_f32_16x16x32_bf16 v[12:15], v[206:209], v[238:241], v[12:15]
	v_mfma_f32_16x16x32_bf16 v[8:11], v[214:217], v[226:229], v[8:11]
	v_mfma_f32_16x16x32_bf16 v[4:7], v[214:217], v[238:241], v[4:7]
	v_mfma_f32_16x16x32_bf16 v[32:35], v[194:197], v[230:233], v[32:35]
	v_mfma_f32_16x16x32_bf16 v[28:31], v[194:197], v[242:245], v[28:31]
	v_mfma_f32_16x16x32_bf16 v[24:27], v[202:205], v[230:233], v[24:27]
	v_mfma_f32_16x16x32_bf16 v[20:23], v[202:205], v[242:245], v[20:23]
	v_mfma_f32_16x16x32_bf16 v[16:19], v[210:213], v[230:233], v[16:19]
	v_mfma_f32_16x16x32_bf16 v[12:15], v[210:213], v[242:245], v[12:15]
	v_mfma_f32_16x16x32_bf16 v[8:11], v[218:221], v[230:233], v[8:11]
	v_mfma_f32_16x16x32_bf16 v[4:7], v[218:221], v[242:245], v[4:7]
	s_add_i32 s1, s1, 2
	s_add_u32 s12, s12, 0x100
	s_addc_u32 s13, s13, 0
	s_cmp_lt_u32 s1, 12
	s_barrier
	s_cbranch_scc1 .LBB0_1005
	s_add_u32 s8, s8, 0x40780
	s_addc_u32 s9, s9, 0
	v_lshl_add_u64 v[132:133], s[8:9], 0, v[132:133]
	v_lshl_add_u64 v[0:1], v[0:1], 1, v[132:133]
	s_or_b32 m0, s100, 0xc000
	ds_read_b128 v[138:141], v171
	ds_read_b128 v[142:145], v171 offset:1024
	ds_read_b128 v[162:165], v171 offset:2048
	ds_read_b128 v[174:177], v171 offset:3072
	ds_read_b128 v[178:181], v156
	ds_read_b128 v[182:185], v156 offset:1024
	ds_read_b128 v[186:189], v155
	ds_read_b128 v[190:193], v155 offset:1024
	ds_read_b128 v[194:197], v154
	ds_read_b128 v[198:201], v154 offset:1024
	ds_read_b128 v[202:205], v153
	ds_read_b128 v[206:209], v153 offset:1024
	global_load_lds_dwordx4 v[0:1], off
	v_lshl_add_u64 v[0:1], s[8:9], 0, v[136:137]
	v_lshl_add_u64 v[0:1], v[134:135], 1, v[0:1]
	s_or_b32 m0, s100, 0xe000
	s_nop 0
	global_load_lds_dwordx4 v[0:1], off
	s_barrier
	s_waitcnt lgkmcnt(0)
	s_waitcnt lgkmcnt(0)
	v_mfma_f32_16x16x32_bf16 v[128:131], v[178:181], v[138:141], v[128:131]
	v_mfma_f32_16x16x32_bf16 v[124:127], v[178:181], v[162:165], v[124:127]
	v_mfma_f32_16x16x32_bf16 v[120:123], v[186:189], v[138:141], v[120:123]
	v_mfma_f32_16x16x32_bf16 v[112:115], v[194:197], v[138:141], v[112:115]
	v_mfma_f32_16x16x32_bf16 v[128:131], v[182:185], v[142:145], v[128:131]
	v_mfma_f32_16x16x32_bf16 v[124:127], v[182:185], v[174:177], v[124:127]
	v_mfma_f32_16x16x32_bf16 v[120:123], v[190:193], v[142:145], v[120:123]
	v_mfma_f32_16x16x32_bf16 v[116:119], v[186:189], v[162:165], v[116:119]
	v_mfma_f32_16x16x32_bf16 v[112:115], v[198:201], v[142:145], v[112:115]
	v_mfma_f32_16x16x32_bf16 v[108:111], v[194:197], v[162:165], v[108:111]
	v_mfma_f32_16x16x32_bf16 v[104:107], v[202:205], v[138:141], v[104:107]
	v_mfma_f32_16x16x32_bf16 v[100:103], v[202:205], v[162:165], v[100:103]
	v_mfma_f32_16x16x32_bf16 v[132:135], v[190:193], v[174:177], v[116:119]
	v_mfma_f32_16x16x32_bf16 v[170:173], v[198:201], v[174:177], v[108:111]
	v_mfma_f32_16x16x32_bf16 v[210:213], v[206:209], v[142:145], v[104:107]
	v_mfma_f32_16x16x32_bf16 v[214:217], v[206:209], v[174:177], v[100:103]
	s_barrier
	s_nop 1
	ds_read_b128 v[100:103], v168
	ds_read_b128 v[104:107], v168 offset:1024
	ds_read_b128 v[108:111], v168 offset:2048
	ds_read_b128 v[116:119], v168 offset:3072
	s_barrier
	s_waitcnt lgkmcnt(0)
	s_waitcnt lgkmcnt(0)
	v_mfma_f32_16x16x32_bf16 v[80:83], v[194:197], v[100:103], v[80:83]
	v_mfma_f32_16x16x32_bf16 v[76:79], v[194:197], v[108:111], v[76:79]
	v_mfma_f32_16x16x32_bf16 v[72:75], v[202:205], v[100:103], v[72:75]
	v_mfma_f32_16x16x32_bf16 v[68:71], v[202:205], v[108:111], v[68:71]
	v_mfma_f32_16x16x32_bf16 v[96:99], v[178:181], v[100:103], v[96:99]
	v_mfma_f32_16x16x32_bf16 v[92:95], v[178:181], v[108:111], v[92:95]
	v_mfma_f32_16x16x32_bf16 v[88:91], v[186:189], v[100:103], v[88:91]
	v_mfma_f32_16x16x32_bf16 v[84:87], v[186:189], v[108:111], v[84:87]
	v_mfma_f32_16x16x32_bf16 v[80:83], v[198:201], v[104:107], v[80:83]
	v_mfma_f32_16x16x32_bf16 v[76:79], v[198:201], v[116:119], v[76:79]
	v_mfma_f32_16x16x32_bf16 v[72:75], v[206:209], v[104:107], v[72:75]
	v_mfma_f32_16x16x32_bf16 v[68:71], v[206:209], v[116:119], v[68:71]
	v_mfma_f32_16x16x32_bf16 v[166:169], v[182:185], v[104:107], v[96:99]
	v_mfma_f32_16x16x32_bf16 v[178:181], v[182:185], v[116:119], v[92:95]
	v_mfma_f32_16x16x32_bf16 v[182:185], v[190:193], v[104:107], v[88:91]
	v_mfma_f32_16x16x32_bf16 v[186:189], v[190:193], v[116:119], v[84:87]
	s_barrier
; #define LDA8(dst, b, h) _Pragma("unroll") for (int m = 0; m < 4; ++m) _Pragma("unroll") for (int k = 0; k < 2; ++k) \
;     dst[m][k] = *(const bf16x8*)((const char*)SA8(b, h) + lds_byte8(wr * 64 + m * 16 + fr, k * 32 + fq * 8))
; #define LDB8(dst, b, h) _Pragma("unroll") for (int n = 0; n < 2; ++n) _Pragma("unroll") for (int k = 0; k < 2; ++k) \
;     dst[n][k] = *(const bf16x8*)((const char*)SB8(b, h) + lds_byte8(wc * 32 + n * 16 + fr, k * 32 + fq * 8))
; #define WAIT_V8(n) asm volatile("s_waitcnt vmcnt(" #n ")" ::: "memory")
; #define WAIT_L8(n) asm volatile("s_waitcnt lgkmcnt(" #n ")" ::: "memory")
; #define BAR8 __builtin_amdgcn_s_barrier()
;     ...
;     LDA8(At, 0, 1); WAIT_V8(4); BAR8; WAIT_L8(0); MMA8(1, 0, At, B0); MMA8(1, 1, At, B1); BAR8; }
;   { LDB8(B0, 1, 0); LDA8(At, 1, 0); WAIT_V8(2); BAR8; WAIT_L8(0); MMA8(0, 0, At, B0); BAR8;
	s_nop 0
	ds_read_b128 v[84:87], v156 offset:16384
	ds_read_b128 v[88:91], v156 offset:17408
	ds_read_b128 v[92:95], v155 offset:16384
	ds_read_b128 v[96:99], v155 offset:17408
	ds_read_b128 v[190:193], v154 offset:16384
	ds_read_b128 v[194:197], v154 offset:17408
	ds_read_b128 v[198:201], v153 offset:16384
	ds_read_b128 v[202:205], v153 offset:17408
	s_waitcnt vmcnt(4)
	s_barrier
	s_waitcnt lgkmcnt(0)
	s_waitcnt lgkmcnt(0)
	v_mfma_f32_16x16x32_bf16 v[64:67], v[84:87], v[138:141], v[64:67]
	v_mfma_f32_16x16x32_bf16 v[60:63], v[84:87], v[162:165], v[60:63]
	v_mfma_f32_16x16x32_bf16 v[56:59], v[92:95], v[138:141], v[56:59]
	v_mfma_f32_16x16x32_bf16 v[52:55], v[92:95], v[162:165], v[52:55]
	v_mfma_f32_16x16x32_bf16 v[48:51], v[190:193], v[138:141], v[48:51]
	v_mfma_f32_16x16x32_bf16 v[44:47], v[190:193], v[162:165], v[44:47]
	v_mfma_f32_16x16x32_bf16 v[40:43], v[198:201], v[138:141], v[40:43]
	v_mfma_f32_16x16x32_bf16 v[36:39], v[198:201], v[162:165], v[36:39]
	v_mfma_f32_16x16x32_bf16 v[64:67], v[88:91], v[142:145], v[64:67]
	v_mfma_f32_16x16x32_bf16 v[60:63], v[88:91], v[174:177], v[60:63]
	v_mfma_f32_16x16x32_bf16 v[56:59], v[96:99], v[142:145], v[56:59]
	v_mfma_f32_16x16x32_bf16 v[52:55], v[96:99], v[174:177], v[52:55]
	v_mfma_f32_16x16x32_bf16 v[48:51], v[194:197], v[142:145], v[48:51]
	v_mfma_f32_16x16x32_bf16 v[44:47], v[194:197], v[174:177], v[44:47]
	v_mfma_f32_16x16x32_bf16 v[40:43], v[202:205], v[142:145], v[40:43]
	v_mfma_f32_16x16x32_bf16 v[36:39], v[202:205], v[174:177], v[36:39]
	v_mfma_f32_16x16x32_bf16 v[32:35], v[84:87], v[100:103], v[32:35]
	v_mfma_f32_16x16x32_bf16 v[28:31], v[84:87], v[108:111], v[28:31]
	v_mfma_f32_16x16x32_bf16 v[24:27], v[92:95], v[100:103], v[24:27]
	v_mfma_f32_16x16x32_bf16 v[20:23], v[92:95], v[108:111], v[20:23]
	v_mfma_f32_16x16x32_bf16 v[16:19], v[190:193], v[100:103], v[16:19]
	v_mfma_f32_16x16x32_bf16 v[12:15], v[190:193], v[108:111], v[12:15]
	v_mfma_f32_16x16x32_bf16 v[8:11], v[198:201], v[100:103], v[8:11]
	v_mfma_f32_16x16x32_bf16 v[4:7], v[198:201], v[108:111], v[4:7]
	v_mfma_f32_16x16x32_bf16 v[136:139], v[88:91], v[104:107], v[32:35]
	v_mfma_f32_16x16x32_bf16 v[140:143], v[88:91], v[116:119], v[28:31]
	v_mfma_f32_16x16x32_bf16 v[162:165], v[96:99], v[104:107], v[24:27]
	v_mfma_f32_16x16x32_bf16 v[174:177], v[96:99], v[116:119], v[20:23]
	v_mfma_f32_16x16x32_bf16 v[206:209], v[194:197], v[104:107], v[16:19]
	v_mfma_f32_16x16x32_bf16 v[190:193], v[194:197], v[116:119], v[12:15]
	v_mfma_f32_16x16x32_bf16 v[194:197], v[202:205], v[104:107], v[8:11]
	v_mfma_f32_16x16x32_bf16 v[198:201], v[202:205], v[116:119], v[4:7]
	s_barrier
	ds_read_b128 v[202:205], v161
	ds_read_b128 v[218:221], v161 offset:1024
	ds_read_b128 v[226:229], v161 offset:2048
	ds_read_b128 v[230:233], v161 offset:3072
	ds_read_b128 v[8:11], v156 offset:32768
	ds_read_b128 v[12:15], v156 offset:33792
	ds_read_b128 v[16:19], v155 offset:32768
	ds_read_b128 v[24:27], v155 offset:33792
	ds_read_b128 v[28:31], v154 offset:32768
	ds_read_b128 v[32:35], v154 offset:33792
	ds_read_b128 v[238:241], v153 offset:32768
	ds_read_b128 v[242:245], v153 offset:33792
	s_waitcnt vmcnt(2)
	s_barrier
	s_waitcnt lgkmcnt(0)
	s_waitcnt lgkmcnt(0)
	v_mfma_f32_16x16x32_bf16 v[4:7], v[8:11], v[202:205], v[128:131]
	v_mfma_f32_16x16x32_bf16 v[104:107], v[12:15], v[218:221], v[4:7]
	v_mfma_f32_16x16x32_bf16 v[4:7], v[8:11], v[226:229], v[124:127]
	v_mfma_f32_16x16x32_bf16 v[116:119], v[12:15], v[230:233], v[4:7]
	v_mfma_f32_16x16x32_bf16 v[4:7], v[16:19], v[202:205], v[120:123]
	v_mfma_f32_16x16x32_bf16 v[100:103], v[24:27], v[218:221], v[4:7]
	v_mfma_f32_16x16x32_bf16 v[4:7], v[16:19], v[226:229], v[132:135]
	v_mfma_f32_16x16x32_bf16 v[108:111], v[24:27], v[230:233], v[4:7]
	v_mfma_f32_16x16x32_bf16 v[4:7], v[28:31], v[202:205], v[112:115]
	v_mfma_f32_16x16x32_bf16 v[92:95], v[32:35], v[218:221], v[4:7]
	v_mfma_f32_16x16x32_bf16 v[4:7], v[28:31], v[226:229], v[170:173]
	v_mfma_f32_16x16x32_bf16 v[96:99], v[32:35], v[230:233], v[4:7]
	v_mfma_f32_16x16x32_bf16 v[4:7], v[238:241], v[202:205], v[210:213]
	v_mfma_f32_16x16x32_bf16 v[84:87], v[242:245], v[218:221], v[4:7]
	v_mfma_f32_16x16x32_bf16 v[4:7], v[238:241], v[226:229], v[214:217]
	v_mfma_f32_16x16x32_bf16 v[88:91], v[242:245], v[230:233], v[4:7]
	s_barrier
; #define LDA8(dst, b, h) _Pragma("unroll") for (int m = 0; m < 4; ++m) _Pragma("unroll") for (int k = 0; k < 2; ++k) \
;     dst[m][k] = *(const bf16x8*)((const char*)SA8(b, h) + lds_byte8(wr * 64 + m * 16 + fr, k * 32 + fq * 8))
; #define LDB8(dst, b, h) _Pragma("unroll") for (int n = 0; n < 2; ++n) _Pragma("unroll") for (int k = 0; k < 2; ++k) \
;     dst[n][k] = *(const bf16x8*)((const char*)SB8(b, h) + lds_byte8(wc * 32 + n * 16 + fr, k * 32 + fq * 8))
; #define WAIT_V8(n) asm volatile("s_waitcnt vmcnt(" #n ")" ::: "memory")
; #define WAIT_L8(n) asm volatile("s_waitcnt lgkmcnt(" #n ")" ::: "memory")
; #define BAR8 __builtin_amdgcn_s_barrier()
;     ...
;     LDB8(B1, 1, 1); WAIT_V8(0); BAR8; WAIT_L8(0); MMA8(0, 1, At, B1); BAR8;
;     LDA8(At, 1, 1); BAR8; WAIT_L8(0); MMA8(1, 0, At, B0); MMA8(1, 1, At, B1); BAR8; }
;   if (wr == 0) BAR8;
;   __syncthreads();
;     ...
;   if (t < 256) {
;     float rs = 1.f;
;     if (e.ss) {
	ds_read_b128 v[132:135], v158
	ds_read_b128 v[170:173], v158 offset:1024
	ds_read_b128 v[210:213], v158 offset:2048
	ds_read_b128 v[158:161], v158 offset:3072
	s_waitcnt vmcnt(0)
	s_barrier
	s_waitcnt lgkmcnt(0)
	s_waitcnt lgkmcnt(0)
	v_mfma_f32_16x16x32_bf16 v[4:7], v[8:11], v[132:135], v[166:169]
	v_mfma_f32_16x16x32_bf16 v[8:11], v[8:11], v[210:213], v[178:181]
	v_mfma_f32_16x16x32_bf16 v[4:7], v[12:15], v[170:173], v[4:7]
	v_mfma_f32_16x16x32_bf16 v[20:23], v[12:15], v[158:161], v[8:11]
	v_mfma_f32_16x16x32_bf16 v[8:11], v[16:19], v[132:135], v[182:185]
	v_mfma_f32_16x16x32_bf16 v[12:15], v[16:19], v[210:213], v[186:189]
	v_mfma_f32_16x16x32_bf16 v[8:11], v[24:27], v[170:173], v[8:11]
	v_mfma_f32_16x16x32_bf16 v[24:27], v[24:27], v[158:161], v[12:15]
	v_mfma_f32_16x16x32_bf16 v[12:15], v[28:31], v[132:135], v[80:83]
	v_mfma_f32_16x16x32_bf16 v[16:19], v[28:31], v[210:213], v[76:79]
	v_mfma_f32_16x16x32_bf16 v[12:15], v[32:35], v[170:173], v[12:15]
	v_mfma_f32_16x16x32_bf16 v[28:31], v[32:35], v[158:161], v[16:19]
	v_mfma_f32_16x16x32_bf16 v[16:19], v[238:241], v[132:135], v[72:75]
	v_mfma_f32_16x16x32_bf16 v[32:35], v[238:241], v[210:213], v[68:71]
	v_mfma_f32_16x16x32_bf16 v[16:19], v[242:245], v[170:173], v[16:19]
	v_mfma_f32_16x16x32_bf16 v[32:35], v[242:245], v[158:161], v[32:35]
	s_barrier
	ds_read_b128 v[166:169], v156 offset:49152
	ds_read_b128 v[178:181], v156 offset:50176
	ds_read_b128 v[182:185], v155 offset:49152
	ds_read_b128 v[186:189], v155 offset:50176
	ds_read_b128 v[214:217], v154 offset:49152
	ds_read_b128 v[154:157], v154 offset:50176
	ds_read_b128 v[238:241], v153 offset:49152
	ds_read_b128 v[150:153], v153 offset:50176
	s_barrier
	s_waitcnt lgkmcnt(0)
	s_waitcnt lgkmcnt(0)
	v_mfma_f32_16x16x32_bf16 v[64:67], v[166:169], v[202:205], v[64:67]
	v_mfma_f32_16x16x32_bf16 v[60:63], v[166:169], v[226:229], v[60:63]
	v_mfma_f32_16x16x32_bf16 v[56:59], v[182:185], v[202:205], v[56:59]
	v_mfma_f32_16x16x32_bf16 v[52:55], v[182:185], v[226:229], v[52:55]
	v_mfma_f32_16x16x32_bf16 v[48:51], v[214:217], v[202:205], v[48:51]
	v_mfma_f32_16x16x32_bf16 v[44:47], v[214:217], v[226:229], v[44:47]
	v_mfma_f32_16x16x32_bf16 v[40:43], v[238:241], v[202:205], v[40:43]
	v_mfma_f32_16x16x32_bf16 v[36:39], v[238:241], v[226:229], v[36:39]
	v_mfma_f32_16x16x32_bf16 v[128:131], v[178:181], v[218:221], v[64:67]
	v_mfma_f32_16x16x32_bf16 v[124:127], v[178:181], v[230:233], v[60:63]
	v_mfma_f32_16x16x32_bf16 v[120:123], v[186:189], v[218:221], v[56:59]
	v_mfma_f32_16x16x32_bf16 v[112:115], v[186:189], v[230:233], v[52:55]
	v_mfma_f32_16x16x32_bf16 v[80:83], v[154:157], v[218:221], v[48:51]
	v_mfma_f32_16x16x32_bf16 v[76:79], v[154:157], v[230:233], v[44:47]
	v_mfma_f32_16x16x32_bf16 v[72:75], v[150:153], v[218:221], v[40:43]
	v_mfma_f32_16x16x32_bf16 v[68:71], v[150:153], v[230:233], v[36:39]
	v_mfma_f32_16x16x32_bf16 v[36:39], v[166:169], v[132:135], v[136:139]
	v_mfma_f32_16x16x32_bf16 v[64:67], v[178:181], v[170:173], v[36:39]
	v_mfma_f32_16x16x32_bf16 v[36:39], v[166:169], v[210:213], v[140:143]
	v_mfma_f32_16x16x32_bf16 v[60:63], v[178:181], v[158:161], v[36:39]
	v_mfma_f32_16x16x32_bf16 v[36:39], v[182:185], v[132:135], v[162:165]
	v_mfma_f32_16x16x32_bf16 v[56:59], v[186:189], v[170:173], v[36:39]
	v_mfma_f32_16x16x32_bf16 v[36:39], v[182:185], v[210:213], v[174:177]
	v_mfma_f32_16x16x32_bf16 v[52:55], v[186:189], v[158:161], v[36:39]
	v_mfma_f32_16x16x32_bf16 v[36:39], v[214:217], v[132:135], v[206:209]
	v_mfma_f32_16x16x32_bf16 v[48:51], v[154:157], v[170:173], v[36:39]
	v_mfma_f32_16x16x32_bf16 v[36:39], v[214:217], v[210:213], v[190:193]
	v_mfma_f32_16x16x32_bf16 v[44:47], v[154:157], v[158:161], v[36:39]
	v_mfma_f32_16x16x32_bf16 v[36:39], v[238:241], v[132:135], v[194:197]
	v_mfma_f32_16x16x32_bf16 v[40:43], v[150:153], v[170:173], v[36:39]
	v_mfma_f32_16x16x32_bf16 v[36:39], v[238:241], v[210:213], v[198:201]
	v_mfma_f32_16x16x32_bf16 v[36:39], v[150:153], v[158:161], v[36:39]
	s_movk_i32 s1, 0x100
	v_cmp_gt_u32_e32 vcc, s1, v3
	s_barrier
	s_and_saveexec_b64 s[8:9], vcc
	s_cbranch_execz .LBB0_1008
	s_barrier

;     ...
;   if (!pre) {
;     STAGE8(SB8(0, 0), Bt, K, bcol, 0); STAGE8(SA8(0, 0), A, lda, brow, 0);
;     STAGE8(SB8(0, 1), Bt, K, bcol + 128, 0); STAGE8(SA8(0, 1), A, lda, brow + 128, 0);
;   }
.LBB0_1011:
	s_and_b64 vcc, exec, s[0:1]
	s_cbranch_vccz .LBB0_1000
	s_mov_b32 s0, 25
	s_ashr_i32 s1, s0, 31
	s_lshl_b64 s[0:1], s[0:1], 3
	s_add_u32 s0, s70, s0
	s_addc_u32 s1, s71, s1
	v_readlane_b32 s6, v255, 60
	v_readlane_b32 s7, v255, 61
	s_nop 4
	s_mov_b32 s0, 25
	s_ashr_i32 s1, s0, 31
	s_lshl_b64 s[0:1], s[0:1], 3
	s_add_u32 s0, s70, s0
	s_addc_u32 s1, s71, s1
	v_readlane_b32 s2, v255, 60
	v_readlane_b32 s3, v255, 61
	s_nop 4
	s_mov_b32 s0, 25
	s_ashr_i32 s1, s0, 31
	s_lshl_b64 s[0:1], s[0:1], 3
	s_add_u32 s0, s70, s0
	s_addc_u32 s1, s71, s1
	v_mov_b32_e32 v3, v224
	v_readlane_b32 s12, v255, 60
	v_readlane_b32 s13, v255, 61
	s_nop 4
	s_lshl_b32 s0, s38, 8
	v_bfe_i32 v1, v3, 27, 1
	s_waitcnt vmcnt(10)
	v_lshlrev_b32_e32 v150, 4, v3
	s_nop 0
	v_readfirstlane_b32 s100, v150
	v_lshrrev_b32_e32 v1, 22, v1
	v_add_u32_e32 v1, v150, v1
	v_and_b32_e32 v1, 0xfffffc00, v1
	v_ashrrev_i32_e32 v0, 31, v3
	v_sub_u32_e32 v1, v150, v1
	v_lshrrev_b32_e32 v0, 26, v0
	v_lshrrev_b32_e32 v5, 4, v1
	v_add_u32_e32 v0, v3, v0
	v_bitop3_b32 v5, v5, v1, 32 bitop3:0x6c
	v_ashrrev_i32_e32 v1, 31, v1
	v_ashrrev_i32_e32 v0, 6, v0
	v_lshrrev_b32_e32 v1, 26, v1
	v_lshlrev_b32_e32 v6, 3, v0
	v_add_u32_e32 v1, v5, v1
	s_and_b32 s20, s0, 0x3f00
	s_lshl_b32 s0, s38, 2
	v_and_b32_e32 v6, -16, v6
	v_ashrrev_i32_e32 v1, 6, v1
	s_and_b32 s0, s0, 0xffffff00
	v_add_u32_e32 v6, v1, v6
	v_mul_i32_i24_e32 v1, 64, v1
	s_ashr_i32 s1, s0, 31
	v_lshlrev_b32_e32 v0, 5, v0
	v_sub_u32_e32 v1, v5, v1
	v_mov_b32_e32 v14, 1
	s_waitcnt vmcnt(9)
	v_add_u32_e32 v152, 0x2000, v150
	s_lshl_b64 s[8:9], s[0:1], 11
	v_and_b32_e32 v0, 32, v0
	v_ashrrev_i16_sdwa v1, v14, sext(v1) dst_sel:DWORD dst_unused:UNUSED_PAD src0_sel:DWORD src1_sel:BYTE_0
	v_ashrrev_i32_e32 v5, 31, v152
	s_add_u32 s8, s30, s8
	v_add_u32_sdwa v0, v0, sext(v1) dst_sel:DWORD dst_unused:UNUSED_PAD src0_sel:DWORD src1_sel:WORD_0
	v_ashrrev_i32_e32 v7, 31, v6
	v_lshrrev_b32_e32 v5, 22, v5
	s_addc_u32 s9, s31, s9
	v_lshlrev_b64 v[132:133], 11, v[6:7]
	v_ashrrev_i32_e32 v1, 31, v0
	v_add_u32_e32 v5, v152, v5
	v_lshl_add_u64 v[8:9], s[8:9], 0, v[132:133]
	v_lshlrev_b64 v[6:7], 1, v[0:1]
	v_ashrrev_i32_e32 v5, 10, v5
	v_lshl_add_u64 v[10:11], v[8:9], 0, v[6:7]
	v_mul_i32_i24_e32 v8, 0x400, v5
	v_sub_u32_e32 v8, v152, v8
	v_lshrrev_b32_e32 v9, 4, v8
	v_bitop3_b32 v9, v9, v8, 32 bitop3:0x6c
	v_ashrrev_i32_e32 v12, 31, v9
	v_lshrrev_b32_e32 v12, 26, v12
	v_add_u32_e32 v12, v9, v12
	v_lshlrev_b32_e32 v8, 3, v5
	v_ashrrev_i32_e32 v13, 6, v12
	v_and_b32_e32 v12, 0xc0, v12
	v_and_b32_e32 v8, -16, v8
	v_lshlrev_b32_e32 v5, 5, v5
	v_sub_u32_e32 v9, v9, v12
	v_add_u32_e32 v8, v13, v8
	v_and_b32_e32 v5, 32, v5
	v_ashrrev_i16_sdwa v9, v14, sext(v9) dst_sel:DWORD dst_unused:UNUSED_PAD src0_sel:DWORD src1_sel:BYTE_0
	v_add_u32_e32 v151, 0x10000, v150
	v_add_u32_sdwa v134, v5, sext(v9) dst_sel:DWORD dst_unused:UNUSED_PAD src0_sel:DWORD src1_sel:WORD_0
	v_ashrrev_i32_e32 v9, 31, v8
	v_lshlrev_b64 v[136:137], 11, v[8:9]
	s_waitcnt vmcnt(8)
	v_add_u32_e32 v157, 0x12000, v150
	v_mov_b32_e32 v4, v2
	s_or_b32 m0, s100, 0x10000
	v_lshl_add_u64 v[12:13], s[8:9], 0, v[136:137]
	global_load_lds_dwordx4 v[10:11], off
	s_or_b32 m0, s100, 0x12000
	s_lshl_b32 s8, s20, 11
	v_ashrrev_i32_e32 v135, 31, v134
	s_waitcnt lgkmcnt(0)
	s_add_u32 s8, s12, s8
	v_lshlrev_b64 v[8:9], 1, v[134:135]
	s_addc_u32 s9, s13, 0
	v_lshl_add_u64 v[12:13], v[12:13], 0, v[8:9]
	v_lshl_add_u64 v[14:15], s[8:9], 0, v[132:133]
	global_load_lds_dwordx4 v[12:13], off
	v_lshl_add_u64 v[14:15], v[14:15], 0, v[6:7]
	s_mov_b32 m0, s100
	s_nop 0
	global_load_lds_dwordx4 v[14:15], off
	s_or_b32 m0, s100, 0x2000
	s_or_b32 s14, s0, 0x80
	s_ashr_i32 s15, s14, 31
	s_lshl_b64 s[14:15], s[14:15], 11
	s_add_u32 s14, s30, s14
	v_lshl_add_u64 v[16:17], s[8:9], 0, v[136:137]
	s_addc_u32 s15, s31, s15
	v_add_u32_e32 v159, 0x14000, v150
	v_lshl_add_u64 v[16:17], v[16:17], 0, v[8:9]
	v_lshl_add_u64 v[18:19], s[14:15], 0, v[132:133]
	v_add_u32_e32 v160, 0x16000, v150
	global_load_lds_dwordx4 v[16:17], off
	v_lshl_add_u64 v[18:19], v[18:19], 0, v[6:7]
	s_or_b32 m0, s100, 0x14000
	v_lshl_add_u64 v[20:21], s[14:15], 0, v[136:137]
	global_load_lds_dwordx4 v[18:19], off
	s_or_b32 m0, s100, 0x16000
	s_add_u32 s14, s8, 0x40000
	s_addc_u32 s15, s9, 0
	v_add_u32_e32 v162, 0x4000, v150
	v_lshl_add_u64 v[20:21], v[20:21], 0, v[8:9]
	v_lshl_add_u64 v[22:23], s[14:15], 0, v[132:133]
	global_load_lds_dwordx4 v[20:21], off
	v_lshl_add_u64 v[22:23], v[22:23], 0, v[6:7]
	s_or_b32 m0, s100, 0x4000
	v_add_u32_e32 v163, 0x6000, v150
	global_load_lds_dwordx4 v[22:23], off
	v_lshl_add_u64 v[22:23], s[14:15], 0, v[136:137]
	v_lshl_add_u64 v[22:23], v[22:23], 0, v[8:9]
	s_or_b32 m0, s100, 0x6000
	v_ashrrev_i32_e32 v5, 8, v3
	global_load_lds_dwordx4 v[22:23], off
	v_cmp_eq_u32_e32 vcc, 1, v5
	s_and_saveexec_b64 s[14:15], vcc
	s_cbranch_execz .LBB0_1014
	s_barrier
; #define WAIT_V8(n) asm volatile("s_waitcnt vmcnt(" #n ")" ::: "memory")
; #define BAR8 __builtin_amdgcn_s_barrier()
;     ...
;   const int brow = m0, bcol = n0;
;   const int wid = t >> 6, lane = t & 63, wr = wid >> 2, wc = wid & 3, fr = lane & 15, fq = lane >> 4;
;   f32x4 acc[2][2][4][2];
;   {
;     float zinit = 0.f;
;     asm volatile("" : "+v"(zinit));
; #pragma unroll
;     for (int a = 0; a < 2; ++a)
; #pragma unroll
;       for (int b = 0; b < 2; ++b)
; #pragma unroll
;         for (int m = 0; m < 4; ++m)
; #pragma unroll
;           for (int n = 0; n < 2; ++n)
; #pragma unroll
;             for (int j = 0; j < 4; ++j) acc[a][b][m][n][j] = zinit;
;   }
;   bf16x8 At[4][2], B0[2][2], B1[2][2];
;   const int nt = K / 64;
;   if (!pre) {
;     STAGE8(SB8(0, 0), Bt, K, bcol, 0); STAGE8(SA8(0, 0), A, lda, brow, 0);
;     STAGE8(SB8(0, 1), Bt, K, bcol + 128, 0); STAGE8(SA8(0, 1), A, lda, brow + 128, 0);
;   }
;   if (wr == 1) BAR8;
;   WAIT_V8(4); BAR8;
;   STAGE8(SB8(1, 0), Bt, K, bcol, 1); STAGE8(SA8(1, 0), A, lda, brow, 1); STAGE8(SB8(1, 1), Bt, K, bcol + 128, 1);
;   WAIT_V8(6); BAR8;
.LBB0_1014:
	s_or_b64 exec, exec, s[14:15]
	v_readlane_b32 s40, v254, 35
	v_readlane_b32 s42, v254, 37
	v_readlane_b32 s43, v254, 38
	s_waitcnt vmcnt(0)
	v_add_u32_e32 v164, 0x18000, v150
	s_mov_b64 s[42:43], 0x80
	v_add_u32_e32 v165, 0x1a000, v150
	v_lshl_add_u64 v[10:11], v[10:11], 0, s[42:43]
	s_or_b32 m0, s100, 0x18000
	v_add_u32_e32 v166, 0x8000, v150
	s_waitcnt vmcnt(4)
	s_barrier
	global_load_lds_dwordx4 v[10:11], off
	v_lshl_add_u64 v[10:11], v[12:13], 0, s[42:43]
	s_or_b32 m0, s100, 0x1a000
	v_add_u32_e32 v167, 0xa000, v150
	global_load_lds_dwordx4 v[10:11], off
	v_lshl_add_u64 v[10:11], v[14:15], 0, s[42:43]
	s_or_b32 m0, s100, 0x8000
	v_add_u32_e32 v169, 0x1c000, v150
	global_load_lds_dwordx4 v[10:11], off
	v_lshl_add_u64 v[10:11], v[16:17], 0, s[42:43]
	s_or_b32 m0, s100, 0xa000
	v_add_u32_e32 v170, 0x1e000, v150
	global_load_lds_dwordx4 v[10:11], off
	v_lshl_add_u64 v[10:11], v[18:19], 0, s[42:43]
	s_or_b32 m0, s100, 0x1c000
	s_nop 0
	global_load_lds_dwordx4 v[10:11], off
	v_lshl_add_u64 v[10:11], v[20:21], 0, s[42:43]
	s_or_b32 m0, s100, 0x1e000
	v_and_b32_e32 v147, 15, v3
	global_load_lds_dwordx4 v[10:11], off
	v_bfe_u32 v148, v3, 4, 2
	v_lshlrev_b32_e32 v10, 4, v148
	v_lshlrev_b32_e32 v11, 6, v147
	v_lshlrev_b32_e32 v14, 2, v3
	v_or_b32_e32 v13, v10, v11
	v_and_b32_e32 v14, 32, v14
	s_mov_b32 s21, 0x10000
	v_bitop3_b32 v16, v13, s21, v14 bitop3:0xde
	s_mov_b32 s21, 0x14000
	s_and_b32 s14, s27, 63
	v_bitop3_b32 v15, v10, v14, v11 bitop3:0x36
	v_bitop3_b32 v17, v13, s21, v14 bitop3:0xde
	s_mov_b32 s21, 0x18000
	v_lshlrev_b32_e32 v11, 6, v3
	s_lshl_b32 s14, s14, 19
	s_mov_b32 s15, s40
	v_bitop3_b32 v18, v13, s21, v14 bitop3:0xde
	s_mov_b32 s21, 0x1c000
	v_and_b32_e32 v11, 0x3c0, v11
	v_bitop3_b32 v13, v13, s21, v14 bitop3:0xde
	v_bitop3_b32 v14, v11, v14, v10 bitop3:0x36
	v_lshl_add_u64 v[10:11], s[14:15], 0, v[136:137]
	v_readlane_b32 s41, v254, 36
	s_and_b32 s40, s33, 0xffffff00
	v_lshl_add_u64 v[10:11], v[10:11], 0, v[8:9]
	s_ashr_i32 s41, s40, 31
	v_lshl_add_u64 v[138:139], s[12:13], 0, v[10:11]
	v_lshl_add_u64 v[10:11], s[14:15], 0, v[132:133]
	s_lshl_b64 s[40:41], s[40:41], 11
	v_lshl_add_u64 v[10:11], v[10:11], 0, v[6:7]
	v_lshl_add_u64 v[140:141], s[12:13], 0, v[10:11]
	v_lshl_add_u64 v[10:11], s[40:41], 0, v[132:133]
	v_lshl_add_u64 v[6:7], v[10:11], 0, v[6:7]
	v_bfe_u32 v146, v3, 6, 2
	s_waitcnt vmcnt(6)
	v_lshlrev_b32_e32 v149, 6, v5
	v_lshlrev_b32_e32 v5, 13, v5
	v_lshl_add_u64 v[142:143], s[4:5], 0, v[6:7]
	v_lshl_add_u64 v[6:7], s[40:41], 0, v[136:137]
	v_lshlrev_b32_e32 v12, 12, v146
	v_or_b32_e32 v19, 0x800, v5
	v_or_b32_e32 v20, 0x1000, v5
	v_or_b32_e32 v21, 0x1800, v5
	v_lshl_add_u64 v[6:7], v[6:7], 0, v[8:9]
	v_lshl_add_u64 v[144:145], s[4:5], 0, v[6:7]
	s_mov_b32 s14, -2
	s_mov_b64 s[12:13], 0
	v_add_u32_e32 v171, v16, v12
	v_add_u32_e32 v156, v15, v5
	v_add_u32_e32 v155, v14, v19
	v_add_u32_e32 v154, v14, v20
	v_add_u32_e32 v153, v14, v21
	v_add_u32_e32 v168, v17, v12
	v_add_u32_e32 v161, v18, v12
	v_add_u32_e32 v158, v13, v12
	v_mov_b32_e32 v5, v4
	v_mov_b64_e32 v[6:7], v[4:5]
	v_mov_b64_e32 v[8:9], v[4:5]
	v_mov_b64_e32 v[10:11], v[4:5]
	v_mov_b64_e32 v[12:13], v[4:5]
	v_mov_b64_e32 v[14:15], v[4:5]
	v_mov_b64_e32 v[16:17], v[4:5]
	v_mov_b64_e32 v[18:19], v[4:5]
	v_mov_b64_e32 v[20:21], v[4:5]
	v_mov_b64_e32 v[22:23], v[4:5]
	v_mov_b64_e32 v[24:25], v[4:5]
	v_mov_b64_e32 v[26:27], v[4:5]
	v_mov_b64_e32 v[28:29], v[4:5]
	v_mov_b64_e32 v[30:31], v[4:5]
	v_mov_b64_e32 v[32:33], v[4:5]
	v_mov_b64_e32 v[34:35], v[4:5]
	v_mov_b64_e32 v[36:37], v[4:5]
	v_mov_b64_e32 v[38:39], v[4:5]
	v_mov_b64_e32 v[40:41], v[4:5]
	v_mov_b64_e32 v[42:43], v[4:5]
	v_mov_b64_e32 v[44:45], v[4:5]
	v_mov_b64_e32 v[46:47], v[4:5]
	v_mov_b64_e32 v[48:49], v[4:5]
	v_mov_b64_e32 v[50:51], v[4:5]
	v_mov_b64_e32 v[52:53], v[4:5]
	v_mov_b64_e32 v[54:55], v[4:5]
	v_mov_b64_e32 v[56:57], v[4:5]
	v_mov_b64_e32 v[58:59], v[4:5]
	v_mov_b64_e32 v[60:61], v[4:5]
	v_mov_b64_e32 v[62:63], v[4:5]
	v_mov_b64_e32 v[64:65], v[4:5]
	v_mov_b64_e32 v[66:67], v[4:5]
	v_mov_b64_e32 v[68:69], v[4:5]
	v_mov_b64_e32 v[70:71], v[4:5]
	v_mov_b64_e32 v[72:73], v[4:5]
	v_mov_b64_e32 v[74:75], v[4:5]
	v_mov_b64_e32 v[76:77], v[4:5]
	v_mov_b64_e32 v[78:79], v[4:5]
	v_mov_b64_e32 v[80:81], v[4:5]
	v_mov_b64_e32 v[82:83], v[4:5]
	v_mov_b64_e32 v[84:85], v[4:5]
	v_mov_b64_e32 v[86:87], v[4:5]
	v_mov_b64_e32 v[88:89], v[4:5]
	v_mov_b64_e32 v[90:91], v[4:5]
	v_mov_b64_e32 v[92:93], v[4:5]
	v_mov_b64_e32 v[94:95], v[4:5]
	v_mov_b64_e32 v[96:97], v[4:5]
	v_mov_b64_e32 v[98:99], v[4:5]
	v_mov_b64_e32 v[100:101], v[4:5]
	v_mov_b64_e32 v[102:103], v[4:5]
	v_mov_b64_e32 v[104:105], v[4:5]
	v_mov_b64_e32 v[106:107], v[4:5]
	v_mov_b64_e32 v[108:109], v[4:5]
	v_mov_b64_e32 v[110:111], v[4:5]
	v_mov_b64_e32 v[112:113], v[4:5]
	v_mov_b64_e32 v[114:115], v[4:5]
	v_mov_b64_e32 v[116:117], v[4:5]
	v_mov_b64_e32 v[118:119], v[4:5]
	v_mov_b64_e32 v[120:121], v[4:5]
	v_mov_b64_e32 v[122:123], v[4:5]
	v_mov_b64_e32 v[124:125], v[4:5]
	v_mov_b64_e32 v[126:127], v[4:5]
	v_mov_b64_e32 v[128:129], v[4:5]
	v_mov_b64_e32 v[130:131], v[4:5]
	s_mov_b64 s[40:41], 0xc6a0100
	s_mov_b64 s[42:43], 0xc6e0100
	s_mov_b64 s[44:45], 0xc6a0180
	s_mov_b64 s[46:47], 0xc6e0180
	s_barrier
; #define LDA8(dst, b, h) _Pragma("unroll") for (int m = 0; m < 4; ++m) _Pragma("unroll") for (int k = 0; k < 2; ++k) \
;     dst[m][k] = *(const bf16x8*)((const char*)SA8(b, h) + lds_byte8(wr * 64 + m * 16 + fr, k * 32 + fq * 8))
; #define LDB8(dst, b, h) _Pragma("unroll") for (int n = 0; n < 2; ++n) _Pragma("unroll") for (int k = 0; k < 2; ++k) \
;     dst[n][k] = *(const bf16x8*)((const char*)SB8(b, h) + lds_byte8(wc * 32 + n * 16 + fr, k * 32 + fq * 8))
; #define WAIT_L8(n) asm volatile("s_waitcnt lgkmcnt(" #n ")" ::: "memory")
; #define BAR8 __builtin_amdgcn_s_barrier()
; #define SCHED8 __builtin_amdgcn_sched_barrier(0)
;     ...
;   for (int tt = 0; tt < nt - 2; tt += 2) {
;     LDB8(B0, 0, 0); SCHED8; LDA8(At, 0, 0); STAGE8(SA8(1, 1), A, lda, brow + 128, tt + 1);
;     WAIT_L8(8); BAR8; WAIT_L8(0); MMA8(0, 0, At, B0); BAR8; SCHED8;
;     LDB8(B1, 0, 1); STAGE8(SB8(0, 0), Bt, K, bcol, tt + 2);
;     BAR8; WAIT_L8(0); MMA8(0, 1, At, B1); BAR8;
;     LDA8(At, 0, 1); STAGE8(SA8(0, 0), A, lda, brow, tt + 2);
;     BAR8; WAIT_L8(0); MMA8(1, 0, At, B0); BAR8; SCHED8;
.LBB0_1015:
	ds_read_b128 v[174:177], v171
	ds_read_b128 v[178:181], v171 offset:1024
	ds_read_b128 v[182:185], v171 offset:2048
	ds_read_b128 v[186:189], v171 offset:3072
	v_add_u32_e32 v172, 0xc000, v150
	v_lshl_add_u64 v[222:223], v[140:141], 0, s[12:13]
	v_add_u32_e32 v173, 0xe000, v150
	v_lshl_add_u64 v[226:227], v[222:223], 0, s[34:35]
	s_or_b32 m0, s100, 0xc000
	v_lshl_add_u64 v[236:237], v[138:139], 0, s[12:13]
	ds_read_b128 v[190:193], v156
	ds_read_b128 v[194:197], v156 offset:1024
	ds_read_b128 v[198:201], v155
	ds_read_b128 v[202:205], v155 offset:1024
	ds_read_b128 v[206:209], v154
	ds_read_b128 v[210:213], v154 offset:1024
	ds_read_b128 v[214:217], v153
	ds_read_b128 v[218:221], v153 offset:1024
	global_load_lds_dwordx4 v[226:227], off
	v_lshl_add_u64 v[226:227], v[236:237], 0, s[34:35]
	s_or_b32 m0, s100, 0xe000
	s_nop 0
	global_load_lds_dwordx4 v[226:227], off
	s_waitcnt lgkmcnt(8)
	s_barrier
	s_waitcnt lgkmcnt(0)
	s_waitcnt lgkmcnt(0)
	v_mfma_f32_16x16x32_f16 v[128:131], v[190:193], v[174:177], v[128:131]
	v_mfma_f32_16x16x32_f16 v[124:127], v[190:193], v[182:185], v[124:127]
	v_mfma_f32_16x16x32_f16 v[120:123], v[198:201], v[174:177], v[120:123]
	v_mfma_f32_16x16x32_f16 v[116:119], v[198:201], v[182:185], v[116:119]
	v_mfma_f32_16x16x32_f16 v[112:115], v[206:209], v[174:177], v[112:115]
	v_mfma_f32_16x16x32_f16 v[108:111], v[206:209], v[182:185], v[108:111]
	v_mfma_f32_16x16x32_f16 v[104:107], v[214:217], v[174:177], v[104:107]
	v_mfma_f32_16x16x32_f16 v[100:103], v[214:217], v[182:185], v[100:103]
	v_mfma_f32_16x16x32_f16 v[128:131], v[194:197], v[178:181], v[128:131]
	v_mfma_f32_16x16x32_f16 v[124:127], v[194:197], v[186:189], v[124:127]
	v_mfma_f32_16x16x32_f16 v[120:123], v[202:205], v[178:181], v[120:123]
	v_mfma_f32_16x16x32_f16 v[116:119], v[202:205], v[186:189], v[116:119]
	v_mfma_f32_16x16x32_f16 v[112:115], v[210:213], v[178:181], v[112:115]
	v_mfma_f32_16x16x32_f16 v[108:111], v[210:213], v[186:189], v[108:111]
	v_mfma_f32_16x16x32_f16 v[104:107], v[218:221], v[178:181], v[104:107]
	v_mfma_f32_16x16x32_f16 v[100:103], v[218:221], v[186:189], v[100:103]
	s_barrier
	v_lshl_add_u64 v[246:247], v[142:143], 0, s[12:13]
	v_lshl_add_u64 v[248:249], v[246:247], 0, s[40:41]
	s_or_b32 m0, s100, 0x10000
	ds_read_b128 v[226:229], v168
	ds_read_b128 v[230:233], v168 offset:1024
	ds_read_b128 v[238:241], v168 offset:2048
	ds_read_b128 v[242:245], v168 offset:3072
	global_load_lds_dwordx4 v[248:249], off
	v_lshl_add_u64 v[248:249], v[144:145], 0, s[12:13]
	v_lshl_add_u64 v[250:251], v[248:249], 0, s[40:41]
	s_or_b32 m0, s100, 0x12000
	s_nop 0
	global_load_lds_dwordx4 v[250:251], off
	s_barrier
	s_waitcnt lgkmcnt(0)
	s_waitcnt lgkmcnt(0)
	v_mfma_f32_16x16x32_f16 v[96:99], v[190:193], v[226:229], v[96:99]
	v_mfma_f32_16x16x32_f16 v[92:95], v[190:193], v[238:241], v[92:95]
	v_mfma_f32_16x16x32_f16 v[88:91], v[198:201], v[226:229], v[88:91]
	v_mfma_f32_16x16x32_f16 v[84:87], v[198:201], v[238:241], v[84:87]
	v_mfma_f32_16x16x32_f16 v[80:83], v[206:209], v[226:229], v[80:83]
	v_mfma_f32_16x16x32_f16 v[76:79], v[206:209], v[238:241], v[76:79]
	v_mfma_f32_16x16x32_f16 v[72:75], v[214:217], v[226:229], v[72:75]
	v_mfma_f32_16x16x32_f16 v[68:71], v[214:217], v[238:241], v[68:71]
	v_mfma_f32_16x16x32_f16 v[96:99], v[194:197], v[230:233], v[96:99]
	v_mfma_f32_16x16x32_f16 v[92:95], v[194:197], v[242:245], v[92:95]
	v_mfma_f32_16x16x32_f16 v[88:91], v[202:205], v[230:233], v[88:91]
	v_mfma_f32_16x16x32_f16 v[84:87], v[202:205], v[242:245], v[84:87]
	v_mfma_f32_16x16x32_f16 v[80:83], v[210:213], v[230:233], v[80:83]
	v_mfma_f32_16x16x32_f16 v[76:79], v[210:213], v[242:245], v[76:79]
	v_mfma_f32_16x16x32_f16 v[72:75], v[218:221], v[230:233], v[72:75]
	v_mfma_f32_16x16x32_f16 v[68:71], v[218:221], v[242:245], v[68:71]
	v_lshl_add_u64 v[250:251], v[222:223], 0, s[10:11]
	s_mov_b32 m0, s100
	s_barrier
	ds_read_b128 v[190:193], v156 offset:16384
	ds_read_b128 v[194:197], v156 offset:17408
	ds_read_b128 v[198:201], v155 offset:16384
	ds_read_b128 v[202:205], v155 offset:17408
	ds_read_b128 v[206:209], v154 offset:16384
	ds_read_b128 v[210:213], v154 offset:17408
	ds_read_b128 v[214:217], v153 offset:16384
	ds_read_b128 v[218:221], v153 offset:17408
	global_load_lds_dwordx4 v[250:251], off
	v_lshl_add_u64 v[250:251], v[236:237], 0, s[10:11]
	s_or_b32 m0, s100, 0x2000
	s_nop 0
	global_load_lds_dwordx4 v[250:251], off
	s_barrier
	s_waitcnt lgkmcnt(0)
	s_waitcnt lgkmcnt(0)
	v_mfma_f32_16x16x32_f16 v[64:67], v[190:193], v[174:177], v[64:67]
	v_mfma_f32_16x16x32_f16 v[60:63], v[190:193], v[182:185], v[60:63]
	v_mfma_f32_16x16x32_f16 v[56:59], v[198:201], v[174:177], v[56:59]
	v_mfma_f32_16x16x32_f16 v[52:55], v[198:201], v[182:185], v[52:55]
	v_mfma_f32_16x16x32_f16 v[48:51], v[206:209], v[174:177], v[48:51]
	v_mfma_f32_16x16x32_f16 v[44:47], v[206:209], v[182:185], v[44:47]
	v_mfma_f32_16x16x32_f16 v[40:43], v[214:217], v[174:177], v[40:43]
	v_mfma_f32_16x16x32_f16 v[36:39], v[214:217], v[182:185], v[36:39]
	v_mfma_f32_16x16x32_f16 v[64:67], v[194:197], v[178:181], v[64:67]
	v_mfma_f32_16x16x32_f16 v[60:63], v[194:197], v[186:189], v[60:63]
	v_mfma_f32_16x16x32_f16 v[56:59], v[202:205], v[178:181], v[56:59]
	v_mfma_f32_16x16x32_f16 v[52:55], v[202:205], v[186:189], v[52:55]
	v_mfma_f32_16x16x32_f16 v[48:51], v[210:213], v[178:181], v[48:51]
	v_mfma_f32_16x16x32_f16 v[44:47], v[210:213], v[186:189], v[44:47]
	v_mfma_f32_16x16x32_f16 v[40:43], v[218:221], v[178:181], v[40:43]
	v_mfma_f32_16x16x32_f16 v[36:39], v[218:221], v[186:189], v[36:39]
	s_barrier
; #define LDA8(dst, b, h) _Pragma("unroll") for (int m = 0; m < 4; ++m) _Pragma("unroll") for (int k = 0; k < 2; ++k) \
;     dst[m][k] = *(const bf16x8*)((const char*)SA8(b, h) + lds_byte8(wr * 64 + m * 16 + fr, k * 32 + fq * 8))
; #define LDB8(dst, b, h) _Pragma("unroll") for (int n = 0; n < 2; ++n) _Pragma("unroll") for (int k = 0; k < 2; ++k) \
;     dst[n][k] = *(const bf16x8*)((const char*)SB8(b, h) + lds_byte8(wc * 32 + n * 16 + fr, k * 32 + fq * 8))
; #define WAIT_V8(n) asm volatile("s_waitcnt vmcnt(" #n ")" ::: "memory")
; #define WAIT_L8(n) asm volatile("s_waitcnt lgkmcnt(" #n ")" ::: "memory")
; #define BAR8 __builtin_amdgcn_s_barrier()
; #define SCHED8 __builtin_amdgcn_sched_barrier(0)
;     ...
;     BAR8; WAIT_L8(0); MMA8(1, 0, At, B0); BAR8; SCHED8;
;     STAGE8(SB8(0, 1), Bt, K, bcol + 128, tt + 2);
;     WAIT_V8(6); BAR8; MMA8(1, 1, At, B1); BAR8;
;     LDB8(B0, 1, 0); SCHED8; LDA8(At, 1, 0); STAGE8(SA8(0, 1), A, lda, brow + 128, tt + 2);
;     WAIT_L8(8); BAR8; WAIT_L8(0); MMA8(0, 0, At, B0); BAR8; SCHED8;
;     LDB8(B1, 1, 1); STAGE8(SB8(1, 0), Bt, K, bcol, tt + 3);
;     BAR8; WAIT_L8(0); MMA8(0, 1, At, B1); BAR8;
;     LDA8(At, 1, 1); STAGE8(SA8(1, 0), A, lda, brow, tt + 3);
	v_lshl_add_u64 v[174:175], v[246:247], 0, s[42:43]
	s_or_b32 m0, s100, 0x14000
	s_nop 0
	global_load_lds_dwordx4 v[174:175], off
	v_lshl_add_u64 v[174:175], v[248:249], 0, s[42:43]
	s_or_b32 m0, s100, 0x16000
	s_nop 0
	global_load_lds_dwordx4 v[174:175], off
	s_waitcnt vmcnt(6)
	s_barrier
	v_mfma_f32_16x16x32_f16 v[32:35], v[190:193], v[226:229], v[32:35]
	v_mfma_f32_16x16x32_f16 v[28:31], v[190:193], v[238:241], v[28:31]
	v_mfma_f32_16x16x32_f16 v[24:27], v[198:201], v[226:229], v[24:27]
	v_mfma_f32_16x16x32_f16 v[20:23], v[198:201], v[238:241], v[20:23]
	v_mfma_f32_16x16x32_f16 v[16:19], v[206:209], v[226:229], v[16:19]
	v_mfma_f32_16x16x32_f16 v[12:15], v[206:209], v[238:241], v[12:15]
	v_mfma_f32_16x16x32_f16 v[8:11], v[214:217], v[226:229], v[8:11]
	v_mfma_f32_16x16x32_f16 v[4:7], v[214:217], v[238:241], v[4:7]
	v_mfma_f32_16x16x32_f16 v[32:35], v[194:197], v[230:233], v[32:35]
	v_mfma_f32_16x16x32_f16 v[28:31], v[194:197], v[242:245], v[28:31]
	v_mfma_f32_16x16x32_f16 v[24:27], v[202:205], v[230:233], v[24:27]
	v_mfma_f32_16x16x32_f16 v[20:23], v[202:205], v[242:245], v[20:23]
	v_mfma_f32_16x16x32_f16 v[16:19], v[210:213], v[230:233], v[16:19]
	v_mfma_f32_16x16x32_f16 v[12:15], v[210:213], v[242:245], v[12:15]
	v_mfma_f32_16x16x32_f16 v[8:11], v[218:221], v[230:233], v[8:11]
	v_mfma_f32_16x16x32_f16 v[4:7], v[218:221], v[242:245], v[4:7]
	s_barrier
	ds_read_b128 v[174:177], v161
	ds_read_b128 v[178:181], v161 offset:1024
	ds_read_b128 v[182:185], v161 offset:2048
	ds_read_b128 v[186:189], v161 offset:3072
	v_lshl_add_u64 v[226:227], v[222:223], 0, s[18:19]
	s_or_b32 m0, s100, 0x4000
	ds_read_b128 v[190:193], v156 offset:32768
	ds_read_b128 v[194:197], v156 offset:33792
	ds_read_b128 v[198:201], v155 offset:32768
	ds_read_b128 v[202:205], v155 offset:33792
	ds_read_b128 v[206:209], v154 offset:32768
	ds_read_b128 v[210:213], v154 offset:33792
	ds_read_b128 v[214:217], v153 offset:32768
	ds_read_b128 v[218:221], v153 offset:33792
	global_load_lds_dwordx4 v[226:227], off
	v_lshl_add_u64 v[226:227], v[236:237], 0, s[18:19]
	s_or_b32 m0, s100, 0x6000
	s_nop 0
	global_load_lds_dwordx4 v[226:227], off
	s_waitcnt lgkmcnt(8)
	s_barrier
	s_waitcnt lgkmcnt(0)
	s_waitcnt lgkmcnt(0)
	v_mfma_f32_16x16x32_f16 v[128:131], v[190:193], v[174:177], v[128:131]
	v_mfma_f32_16x16x32_f16 v[124:127], v[190:193], v[182:185], v[124:127]
	v_mfma_f32_16x16x32_f16 v[120:123], v[198:201], v[174:177], v[120:123]
	v_mfma_f32_16x16x32_f16 v[116:119], v[198:201], v[182:185], v[116:119]
	v_mfma_f32_16x16x32_f16 v[112:115], v[206:209], v[174:177], v[112:115]
	v_mfma_f32_16x16x32_f16 v[108:111], v[206:209], v[182:185], v[108:111]
	v_mfma_f32_16x16x32_f16 v[104:107], v[214:217], v[174:177], v[104:107]
	v_mfma_f32_16x16x32_f16 v[100:103], v[214:217], v[182:185], v[100:103]
	v_mfma_f32_16x16x32_f16 v[128:131], v[194:197], v[178:181], v[128:131]
	v_mfma_f32_16x16x32_f16 v[124:127], v[194:197], v[186:189], v[124:127]
	v_mfma_f32_16x16x32_f16 v[120:123], v[202:205], v[178:181], v[120:123]
	v_mfma_f32_16x16x32_f16 v[116:119], v[202:205], v[186:189], v[116:119]
	v_mfma_f32_16x16x32_f16 v[112:115], v[210:213], v[178:181], v[112:115]
	v_mfma_f32_16x16x32_f16 v[108:111], v[210:213], v[186:189], v[108:111]
	v_mfma_f32_16x16x32_f16 v[104:107], v[218:221], v[178:181], v[104:107]
	v_mfma_f32_16x16x32_f16 v[100:103], v[218:221], v[186:189], v[100:103]
	s_barrier
	v_lshl_add_u64 v[250:251], v[246:247], 0, s[44:45]
	s_or_b32 m0, s100, 0x18000
	ds_read_b128 v[226:229], v158
	ds_read_b128 v[230:233], v158 offset:1024
	ds_read_b128 v[238:241], v158 offset:2048
	ds_read_b128 v[242:245], v158 offset:3072
	global_load_lds_dwordx4 v[250:251], off
	v_lshl_add_u64 v[250:251], v[248:249], 0, s[44:45]
	s_or_b32 m0, s100, 0x1a000
	s_nop 0
	global_load_lds_dwordx4 v[250:251], off
	s_barrier
	s_waitcnt lgkmcnt(0)
	s_waitcnt lgkmcnt(0)
	v_mfma_f32_16x16x32_f16 v[96:99], v[190:193], v[226:229], v[96:99]
	v_mfma_f32_16x16x32_f16 v[92:95], v[190:193], v[238:241], v[92:95]
	v_mfma_f32_16x16x32_f16 v[88:91], v[198:201], v[226:229], v[88:91]
	v_mfma_f32_16x16x32_f16 v[84:87], v[198:201], v[238:241], v[84:87]
	v_mfma_f32_16x16x32_f16 v[80:83], v[206:209], v[226:229], v[80:83]
	v_mfma_f32_16x16x32_f16 v[76:79], v[206:209], v[238:241], v[76:79]
	v_mfma_f32_16x16x32_f16 v[72:75], v[214:217], v[226:229], v[72:75]
	v_mfma_f32_16x16x32_f16 v[68:71], v[214:217], v[238:241], v[68:71]
	v_mfma_f32_16x16x32_f16 v[96:99], v[194:197], v[230:233], v[96:99]
	v_mfma_f32_16x16x32_f16 v[92:95], v[194:197], v[242:245], v[92:95]
	v_mfma_f32_16x16x32_f16 v[88:91], v[202:205], v[230:233], v[88:91]
	v_mfma_f32_16x16x32_f16 v[84:87], v[202:205], v[242:245], v[84:87]
	v_mfma_f32_16x16x32_f16 v[80:83], v[210:213], v[230:233], v[80:83]
	v_mfma_f32_16x16x32_f16 v[76:79], v[210:213], v[242:245], v[76:79]
	v_mfma_f32_16x16x32_f16 v[72:75], v[218:221], v[230:233], v[72:75]
	v_mfma_f32_16x16x32_f16 v[68:71], v[218:221], v[242:245], v[68:71]
	v_lshl_add_u64 v[222:223], v[222:223], 0, s[22:23]
	s_or_b32 m0, s100, 0x8000
	s_barrier
	ds_read_b128 v[190:193], v156 offset:49152
	ds_read_b128 v[194:197], v156 offset:50176
	ds_read_b128 v[198:201], v155 offset:49152
	ds_read_b128 v[202:205], v155 offset:50176
	ds_read_b128 v[206:209], v154 offset:49152
	ds_read_b128 v[210:213], v154 offset:50176
	ds_read_b128 v[214:217], v153 offset:49152
	ds_read_b128 v[218:221], v153 offset:50176
	global_load_lds_dwordx4 v[222:223], off
	v_lshl_add_u64 v[222:223], v[236:237], 0, s[22:23]
	s_or_b32 m0, s100, 0xa000
	s_nop 0
	global_load_lds_dwordx4 v[222:223], off
	s_barrier
; #define LDA8(dst, b, h) _Pragma("unroll") for (int m = 0; m < 4; ++m) _Pragma("unroll") for (int k = 0; k < 2; ++k) \
;     dst[m][k] = *(const bf16x8*)((const char*)SA8(b, h) + lds_byte8(wr * 64 + m * 16 + fr, k * 32 + fq * 8))
; #define LDB8(dst, b, h) _Pragma("unroll") for (int n = 0; n < 2; ++n) _Pragma("unroll") for (int k = 0; k < 2; ++k) \
;     dst[n][k] = *(const bf16x8*)((const char*)SB8(b, h) + lds_byte8(wc * 32 + n * 16 + fr, k * 32 + fq * 8))
; #define WAIT_V8(n) asm volatile("s_waitcnt vmcnt(" #n ")" ::: "memory")
; #define WAIT_L8(n) asm volatile("s_waitcnt lgkmcnt(" #n ")" ::: "memory")
; #define BAR8 __builtin_amdgcn_s_barrier()
; #define SCHED8 __builtin_amdgcn_sched_barrier(0)
;     ...
;     BAR8; WAIT_L8(0); MMA8(1, 0, At, B0); BAR8; SCHED8;
;     STAGE8(SB8(1, 1), Bt, K, bcol + 128, tt + 3);
;     WAIT_V8(6); BAR8; MMA8(1, 1, At, B1); BAR8;
;   }
;   { LDB8(B0, 0, 0); LDA8(At, 0, 0); STAGE8(SA8(1, 1), A, lda, brow + 128, nt - 1);
;     BAR8; WAIT_L8(0); MMA8(0, 0, At, B0); BAR8;
;     LDB8(B1, 0, 1); BAR8; WAIT_L8(0); MMA8(0, 1, At, B1); BAR8;
;     LDA8(At, 0, 1); WAIT_V8(4); BAR8; WAIT_L8(0); MMA8(1, 0, At, B0); MMA8(1, 1, At, B1); BAR8; }
	s_waitcnt lgkmcnt(0)
	s_waitcnt lgkmcnt(0)
	v_mfma_f32_16x16x32_f16 v[64:67], v[190:193], v[174:177], v[64:67]
	v_mfma_f32_16x16x32_f16 v[60:63], v[190:193], v[182:185], v[60:63]
	v_mfma_f32_16x16x32_f16 v[56:59], v[198:201], v[174:177], v[56:59]
	v_mfma_f32_16x16x32_f16 v[52:55], v[198:201], v[182:185], v[52:55]
	v_mfma_f32_16x16x32_f16 v[48:51], v[206:209], v[174:177], v[48:51]
	v_mfma_f32_16x16x32_f16 v[44:47], v[206:209], v[182:185], v[44:47]
	v_mfma_f32_16x16x32_f16 v[40:43], v[214:217], v[174:177], v[40:43]
	v_mfma_f32_16x16x32_f16 v[36:39], v[214:217], v[182:185], v[36:39]
	v_mfma_f32_16x16x32_f16 v[64:67], v[194:197], v[178:181], v[64:67]
	v_mfma_f32_16x16x32_f16 v[60:63], v[194:197], v[186:189], v[60:63]
	v_mfma_f32_16x16x32_f16 v[56:59], v[202:205], v[178:181], v[56:59]
	v_mfma_f32_16x16x32_f16 v[52:55], v[202:205], v[186:189], v[52:55]
	v_mfma_f32_16x16x32_f16 v[48:51], v[210:213], v[178:181], v[48:51]
	v_mfma_f32_16x16x32_f16 v[44:47], v[210:213], v[186:189], v[44:47]
	v_mfma_f32_16x16x32_f16 v[40:43], v[218:221], v[178:181], v[40:43]
	v_mfma_f32_16x16x32_f16 v[36:39], v[218:221], v[186:189], v[36:39]
	s_barrier
	v_lshl_add_u64 v[174:175], v[246:247], 0, s[46:47]
	s_or_b32 m0, s100, 0x1c000
	s_nop 0
	global_load_lds_dwordx4 v[174:175], off
	v_lshl_add_u64 v[174:175], v[248:249], 0, s[46:47]
	s_or_b32 m0, s100, 0x1e000
	s_nop 0
	global_load_lds_dwordx4 v[174:175], off
	s_waitcnt vmcnt(6)
	s_barrier
	v_mfma_f32_16x16x32_f16 v[32:35], v[190:193], v[226:229], v[32:35]
	v_mfma_f32_16x16x32_f16 v[28:31], v[190:193], v[238:241], v[28:31]
	v_mfma_f32_16x16x32_f16 v[24:27], v[198:201], v[226:229], v[24:27]
	v_mfma_f32_16x16x32_f16 v[20:23], v[198:201], v[238:241], v[20:23]
	v_mfma_f32_16x16x32_f16 v[16:19], v[206:209], v[226:229], v[16:19]
	v_mfma_f32_16x16x32_f16 v[12:15], v[206:209], v[238:241], v[12:15]
	v_mfma_f32_16x16x32_f16 v[8:11], v[214:217], v[226:229], v[8:11]
	v_mfma_f32_16x16x32_f16 v[4:7], v[214:217], v[238:241], v[4:7]
	v_mfma_f32_16x16x32_f16 v[32:35], v[194:197], v[230:233], v[32:35]
	v_mfma_f32_16x16x32_f16 v[28:31], v[194:197], v[242:245], v[28:31]
	v_mfma_f32_16x16x32_f16 v[24:27], v[202:205], v[230:233], v[24:27]
	v_mfma_f32_16x16x32_f16 v[20:23], v[202:205], v[242:245], v[20:23]
	v_mfma_f32_16x16x32_f16 v[16:19], v[210:213], v[230:233], v[16:19]
	v_mfma_f32_16x16x32_f16 v[12:15], v[210:213], v[242:245], v[12:15]
	v_mfma_f32_16x16x32_f16 v[8:11], v[218:221], v[230:233], v[8:11]
	v_mfma_f32_16x16x32_f16 v[4:7], v[218:221], v[242:245], v[4:7]
	s_add_i32 s14, s14, 2
	s_add_u32 s12, s12, 0x100
	s_addc_u32 s13, s13, 0
	s_cmp_lt_u32 s14, 12
	s_barrier
	s_cbranch_scc1 .LBB0_1015
	s_add_u32 s8, s8, 0x40780
	s_addc_u32 s9, s9, 0
	v_lshl_add_u64 v[132:133], s[8:9], 0, v[132:133]
	v_lshl_add_u64 v[0:1], v[0:1], 1, v[132:133]
	s_or_b32 m0, s100, 0xc000
	ds_read_b128 v[138:141], v171
	ds_read_b128 v[142:145], v171 offset:1024
	ds_read_b128 v[162:165], v171 offset:2048
	ds_read_b128 v[174:177], v171 offset:3072
	ds_read_b128 v[178:181], v156
	ds_read_b128 v[182:185], v156 offset:1024
	ds_read_b128 v[186:189], v155
	ds_read_b128 v[190:193], v155 offset:1024
	ds_read_b128 v[194:197], v154
	ds_read_b128 v[198:201], v154 offset:1024
	ds_read_b128 v[202:205], v153
	ds_read_b128 v[206:209], v153 offset:1024
	global_load_lds_dwordx4 v[0:1], off
	v_lshl_add_u64 v[0:1], s[8:9], 0, v[136:137]
	v_lshl_add_u64 v[0:1], v[134:135], 1, v[0:1]
	s_or_b32 m0, s100, 0xe000
	s_nop 0
	global_load_lds_dwordx4 v[0:1], off
	s_barrier
	s_waitcnt lgkmcnt(0)
	s_waitcnt lgkmcnt(0)
	v_mfma_f32_16x16x32_f16 v[128:131], v[178:181], v[138:141], v[128:131]
	v_mfma_f32_16x16x32_f16 v[124:127], v[178:181], v[162:165], v[124:127]
	v_mfma_f32_16x16x32_f16 v[120:123], v[186:189], v[138:141], v[120:123]
	v_mfma_f32_16x16x32_f16 v[112:115], v[194:197], v[138:141], v[112:115]
	v_mfma_f32_16x16x32_f16 v[128:131], v[182:185], v[142:145], v[128:131]
	v_mfma_f32_16x16x32_f16 v[124:127], v[182:185], v[174:177], v[124:127]
	v_mfma_f32_16x16x32_f16 v[120:123], v[190:193], v[142:145], v[120:123]
	v_mfma_f32_16x16x32_f16 v[116:119], v[186:189], v[162:165], v[116:119]
	v_mfma_f32_16x16x32_f16 v[112:115], v[198:201], v[142:145], v[112:115]
	v_mfma_f32_16x16x32_f16 v[108:111], v[194:197], v[162:165], v[108:111]
	v_mfma_f32_16x16x32_f16 v[104:107], v[202:205], v[138:141], v[104:107]
	v_mfma_f32_16x16x32_f16 v[100:103], v[202:205], v[162:165], v[100:103]
	v_mfma_f32_16x16x32_f16 v[132:135], v[190:193], v[174:177], v[116:119]
	v_mfma_f32_16x16x32_f16 v[170:173], v[198:201], v[174:177], v[108:111]
	v_mfma_f32_16x16x32_f16 v[210:213], v[206:209], v[142:145], v[104:107]
	v_mfma_f32_16x16x32_f16 v[214:217], v[206:209], v[174:177], v[100:103]
	s_barrier
	s_nop 1
	ds_read_b128 v[100:103], v168
	ds_read_b128 v[104:107], v168 offset:1024
	ds_read_b128 v[108:111], v168 offset:2048
	ds_read_b128 v[116:119], v168 offset:3072
	s_barrier
	s_waitcnt lgkmcnt(0)
	s_waitcnt lgkmcnt(0)
	v_mfma_f32_16x16x32_f16 v[80:83], v[194:197], v[100:103], v[80:83]
	v_mfma_f32_16x16x32_f16 v[76:79], v[194:197], v[108:111], v[76:79]
	v_mfma_f32_16x16x32_f16 v[72:75], v[202:205], v[100:103], v[72:75]
	v_mfma_f32_16x16x32_f16 v[68:71], v[202:205], v[108:111], v[68:71]
	v_mfma_f32_16x16x32_f16 v[96:99], v[178:181], v[100:103], v[96:99]
	v_mfma_f32_16x16x32_f16 v[92:95], v[178:181], v[108:111], v[92:95]
	v_mfma_f32_16x16x32_f16 v[88:91], v[186:189], v[100:103], v[88:91]
	v_mfma_f32_16x16x32_f16 v[84:87], v[186:189], v[108:111], v[84:87]
	v_mfma_f32_16x16x32_f16 v[80:83], v[198:201], v[104:107], v[80:83]
	v_mfma_f32_16x16x32_f16 v[76:79], v[198:201], v[116:119], v[76:79]
	v_mfma_f32_16x16x32_f16 v[72:75], v[206:209], v[104:107], v[72:75]
	v_mfma_f32_16x16x32_f16 v[68:71], v[206:209], v[116:119], v[68:71]
	v_mfma_f32_16x16x32_f16 v[166:169], v[182:185], v[104:107], v[96:99]
	v_mfma_f32_16x16x32_f16 v[178:181], v[182:185], v[116:119], v[92:95]
	v_mfma_f32_16x16x32_f16 v[182:185], v[190:193], v[104:107], v[88:91]
	v_mfma_f32_16x16x32_f16 v[186:189], v[190:193], v[116:119], v[84:87]
	s_barrier
; #define LDA8(dst, b, h) _Pragma("unroll") for (int m = 0; m < 4; ++m) _Pragma("unroll") for (int k = 0; k < 2; ++k) \
;     dst[m][k] = *(const bf16x8*)((const char*)SA8(b, h) + lds_byte8(wr * 64 + m * 16 + fr, k * 32 + fq * 8))
; #define LDB8(dst, b, h) _Pragma("unroll") for (int n = 0; n < 2; ++n) _Pragma("unroll") for (int k = 0; k < 2; ++k) \
;     dst[n][k] = *(const bf16x8*)((const char*)SB8(b, h) + lds_byte8(wc * 32 + n * 16 + fr, k * 32 + fq * 8))
; #define WAIT_V8(n) asm volatile("s_waitcnt vmcnt(" #n ")" ::: "memory")
; #define WAIT_L8(n) asm volatile("s_waitcnt lgkmcnt(" #n ")" ::: "memory")
; #define BAR8 __builtin_amdgcn_s_barrier()
;     ...
;     LDA8(At, 0, 1); WAIT_V8(4); BAR8; WAIT_L8(0); MMA8(1, 0, At, B0); MMA8(1, 1, At, B1); BAR8; }
;   { LDB8(B0, 1, 0); LDA8(At, 1, 0); WAIT_V8(2); BAR8; WAIT_L8(0); MMA8(0, 0, At, B0); BAR8;
	s_nop 0
	ds_read_b128 v[84:87], v156 offset:16384
	ds_read_b128 v[88:91], v156 offset:17408
	ds_read_b128 v[92:95], v155 offset:16384
	ds_read_b128 v[96:99], v155 offset:17408
	ds_read_b128 v[190:193], v154 offset:16384
	ds_read_b128 v[194:197], v154 offset:17408
	ds_read_b128 v[198:201], v153 offset:16384
	ds_read_b128 v[202:205], v153 offset:17408
	s_waitcnt vmcnt(4)
	s_barrier
	s_waitcnt lgkmcnt(0)
	s_waitcnt lgkmcnt(0)
	v_mfma_f32_16x16x32_f16 v[64:67], v[84:87], v[138:141], v[64:67]
	v_mfma_f32_16x16x32_f16 v[60:63], v[84:87], v[162:165], v[60:63]
	v_mfma_f32_16x16x32_f16 v[56:59], v[92:95], v[138:141], v[56:59]
	v_mfma_f32_16x16x32_f16 v[52:55], v[92:95], v[162:165], v[52:55]
	v_mfma_f32_16x16x32_f16 v[48:51], v[190:193], v[138:141], v[48:51]
	v_mfma_f32_16x16x32_f16 v[44:47], v[190:193], v[162:165], v[44:47]
	v_mfma_f32_16x16x32_f16 v[40:43], v[198:201], v[138:141], v[40:43]
	v_mfma_f32_16x16x32_f16 v[36:39], v[198:201], v[162:165], v[36:39]
	v_mfma_f32_16x16x32_f16 v[64:67], v[88:91], v[142:145], v[64:67]
	v_mfma_f32_16x16x32_f16 v[60:63], v[88:91], v[174:177], v[60:63]
	v_mfma_f32_16x16x32_f16 v[56:59], v[96:99], v[142:145], v[56:59]
	v_mfma_f32_16x16x32_f16 v[52:55], v[96:99], v[174:177], v[52:55]
	v_mfma_f32_16x16x32_f16 v[48:51], v[194:197], v[142:145], v[48:51]
	v_mfma_f32_16x16x32_f16 v[44:47], v[194:197], v[174:177], v[44:47]
	v_mfma_f32_16x16x32_f16 v[40:43], v[202:205], v[142:145], v[40:43]
	v_mfma_f32_16x16x32_f16 v[36:39], v[202:205], v[174:177], v[36:39]
	v_mfma_f32_16x16x32_f16 v[32:35], v[84:87], v[100:103], v[32:35]
	v_mfma_f32_16x16x32_f16 v[28:31], v[84:87], v[108:111], v[28:31]
	v_mfma_f32_16x16x32_f16 v[24:27], v[92:95], v[100:103], v[24:27]
	v_mfma_f32_16x16x32_f16 v[20:23], v[92:95], v[108:111], v[20:23]
	v_mfma_f32_16x16x32_f16 v[16:19], v[190:193], v[100:103], v[16:19]
	v_mfma_f32_16x16x32_f16 v[12:15], v[190:193], v[108:111], v[12:15]
	v_mfma_f32_16x16x32_f16 v[8:11], v[198:201], v[100:103], v[8:11]
	v_mfma_f32_16x16x32_f16 v[4:7], v[198:201], v[108:111], v[4:7]
	v_mfma_f32_16x16x32_f16 v[136:139], v[88:91], v[104:107], v[32:35]
	v_mfma_f32_16x16x32_f16 v[140:143], v[88:91], v[116:119], v[28:31]
	v_mfma_f32_16x16x32_f16 v[162:165], v[96:99], v[104:107], v[24:27]
	v_mfma_f32_16x16x32_f16 v[174:177], v[96:99], v[116:119], v[20:23]
	v_mfma_f32_16x16x32_f16 v[206:209], v[194:197], v[104:107], v[16:19]
	v_mfma_f32_16x16x32_f16 v[190:193], v[194:197], v[116:119], v[12:15]
	v_mfma_f32_16x16x32_f16 v[194:197], v[202:205], v[104:107], v[8:11]
	v_mfma_f32_16x16x32_f16 v[198:201], v[202:205], v[116:119], v[4:7]
	s_barrier
	ds_read_b128 v[202:205], v161
	ds_read_b128 v[218:221], v161 offset:1024
	ds_read_b128 v[226:229], v161 offset:2048
	ds_read_b128 v[230:233], v161 offset:3072
	ds_read_b128 v[8:11], v156 offset:32768
	ds_read_b128 v[12:15], v156 offset:33792
	ds_read_b128 v[16:19], v155 offset:32768
	ds_read_b128 v[24:27], v155 offset:33792
	ds_read_b128 v[28:31], v154 offset:32768
	ds_read_b128 v[32:35], v154 offset:33792
	ds_read_b128 v[238:241], v153 offset:32768
	ds_read_b128 v[242:245], v153 offset:33792
	s_waitcnt vmcnt(2)
	s_barrier
	s_waitcnt lgkmcnt(0)
	s_waitcnt lgkmcnt(0)
	v_mfma_f32_16x16x32_f16 v[4:7], v[8:11], v[202:205], v[128:131]
	v_mfma_f32_16x16x32_f16 v[104:107], v[12:15], v[218:221], v[4:7]
	v_mfma_f32_16x16x32_f16 v[4:7], v[8:11], v[226:229], v[124:127]
	v_mfma_f32_16x16x32_f16 v[116:119], v[12:15], v[230:233], v[4:7]
	v_mfma_f32_16x16x32_f16 v[4:7], v[16:19], v[202:205], v[120:123]
	v_mfma_f32_16x16x32_f16 v[100:103], v[24:27], v[218:221], v[4:7]
	v_mfma_f32_16x16x32_f16 v[4:7], v[16:19], v[226:229], v[132:135]
	v_mfma_f32_16x16x32_f16 v[108:111], v[24:27], v[230:233], v[4:7]
	v_mfma_f32_16x16x32_f16 v[4:7], v[28:31], v[202:205], v[112:115]
	v_mfma_f32_16x16x32_f16 v[92:95], v[32:35], v[218:221], v[4:7]
	v_mfma_f32_16x16x32_f16 v[4:7], v[28:31], v[226:229], v[170:173]
	v_mfma_f32_16x16x32_f16 v[96:99], v[32:35], v[230:233], v[4:7]
	v_mfma_f32_16x16x32_f16 v[4:7], v[238:241], v[202:205], v[210:213]
	v_mfma_f32_16x16x32_f16 v[84:87], v[242:245], v[218:221], v[4:7]
	v_mfma_f32_16x16x32_f16 v[4:7], v[238:241], v[226:229], v[214:217]
	v_mfma_f32_16x16x32_f16 v[88:91], v[242:245], v[230:233], v[4:7]
	s_barrier
; #define LDA8(dst, b, h) _Pragma("unroll") for (int m = 0; m < 4; ++m) _Pragma("unroll") for (int k = 0; k < 2; ++k) \
;     dst[m][k] = *(const bf16x8*)((const char*)SA8(b, h) + lds_byte8(wr * 64 + m * 16 + fr, k * 32 + fq * 8))
; #define LDB8(dst, b, h) _Pragma("unroll") for (int n = 0; n < 2; ++n) _Pragma("unroll") for (int k = 0; k < 2; ++k) \
;     dst[n][k] = *(const bf16x8*)((const char*)SB8(b, h) + lds_byte8(wc * 32 + n * 16 + fr, k * 32 + fq * 8))
; #define WAIT_V8(n) asm volatile("s_waitcnt vmcnt(" #n ")" ::: "memory")
; #define WAIT_L8(n) asm volatile("s_waitcnt lgkmcnt(" #n ")" ::: "memory")
; #define BAR8 __builtin_amdgcn_s_barrier()
;     ...
;     LDB8(B1, 1, 1); WAIT_V8(0); BAR8; WAIT_L8(0); MMA8(0, 1, At, B1); BAR8;
;     LDA8(At, 1, 1); BAR8; WAIT_L8(0); MMA8(1, 0, At, B0); MMA8(1, 1, At, B1); BAR8; }
;   if (wr == 0) BAR8;
;   __syncthreads();
;     ...
;   if (t < 256) {
;     float rs = 1.f;
;     if (e.ss) {
	ds_read_b128 v[132:135], v158
	ds_read_b128 v[170:173], v158 offset:1024
	ds_read_b128 v[210:213], v158 offset:2048
	ds_read_b128 v[158:161], v158 offset:3072
	s_waitcnt vmcnt(0)
	s_barrier
	s_waitcnt lgkmcnt(0)
	s_waitcnt lgkmcnt(0)
	v_mfma_f32_16x16x32_f16 v[4:7], v[8:11], v[132:135], v[166:169]
	v_mfma_f32_16x16x32_f16 v[8:11], v[8:11], v[210:213], v[178:181]
	v_mfma_f32_16x16x32_f16 v[4:7], v[12:15], v[170:173], v[4:7]
	v_mfma_f32_16x16x32_f16 v[20:23], v[12:15], v[158:161], v[8:11]
	v_mfma_f32_16x16x32_f16 v[8:11], v[16:19], v[132:135], v[182:185]
	v_mfma_f32_16x16x32_f16 v[12:15], v[16:19], v[210:213], v[186:189]
	v_mfma_f32_16x16x32_f16 v[8:11], v[24:27], v[170:173], v[8:11]
	v_mfma_f32_16x16x32_f16 v[24:27], v[24:27], v[158:161], v[12:15]
	v_mfma_f32_16x16x32_f16 v[12:15], v[28:31], v[132:135], v[80:83]
	v_mfma_f32_16x16x32_f16 v[16:19], v[28:31], v[210:213], v[76:79]
	v_mfma_f32_16x16x32_f16 v[12:15], v[32:35], v[170:173], v[12:15]
	v_mfma_f32_16x16x32_f16 v[28:31], v[32:35], v[158:161], v[16:19]
	v_mfma_f32_16x16x32_f16 v[16:19], v[238:241], v[132:135], v[72:75]
	v_mfma_f32_16x16x32_f16 v[32:35], v[238:241], v[210:213], v[68:71]
	v_mfma_f32_16x16x32_f16 v[16:19], v[242:245], v[170:173], v[16:19]
	v_mfma_f32_16x16x32_f16 v[32:35], v[242:245], v[158:161], v[32:35]
	s_barrier
	ds_read_b128 v[166:169], v156 offset:49152
	ds_read_b128 v[178:181], v156 offset:50176
	ds_read_b128 v[182:185], v155 offset:49152
	ds_read_b128 v[186:189], v155 offset:50176
	ds_read_b128 v[214:217], v154 offset:49152
	ds_read_b128 v[154:157], v154 offset:50176
	ds_read_b128 v[238:241], v153 offset:49152
	ds_read_b128 v[150:153], v153 offset:50176
	s_barrier
	s_waitcnt lgkmcnt(0)
	s_waitcnt lgkmcnt(0)
	v_mfma_f32_16x16x32_f16 v[64:67], v[166:169], v[202:205], v[64:67]
	v_mfma_f32_16x16x32_f16 v[60:63], v[166:169], v[226:229], v[60:63]
	v_mfma_f32_16x16x32_f16 v[56:59], v[182:185], v[202:205], v[56:59]
	v_mfma_f32_16x16x32_f16 v[52:55], v[182:185], v[226:229], v[52:55]
	v_mfma_f32_16x16x32_f16 v[48:51], v[214:217], v[202:205], v[48:51]
	v_mfma_f32_16x16x32_f16 v[44:47], v[214:217], v[226:229], v[44:47]
	v_mfma_f32_16x16x32_f16 v[40:43], v[238:241], v[202:205], v[40:43]
	v_mfma_f32_16x16x32_f16 v[36:39], v[238:241], v[226:229], v[36:39]
	v_mfma_f32_16x16x32_f16 v[128:131], v[178:181], v[218:221], v[64:67]
	v_mfma_f32_16x16x32_f16 v[124:127], v[178:181], v[230:233], v[60:63]
	v_mfma_f32_16x16x32_f16 v[120:123], v[186:189], v[218:221], v[56:59]
	v_mfma_f32_16x16x32_f16 v[112:115], v[186:189], v[230:233], v[52:55]
	v_mfma_f32_16x16x32_f16 v[80:83], v[154:157], v[218:221], v[48:51]
	v_mfma_f32_16x16x32_f16 v[76:79], v[154:157], v[230:233], v[44:47]
	v_mfma_f32_16x16x32_f16 v[72:75], v[150:153], v[218:221], v[40:43]
	v_mfma_f32_16x16x32_f16 v[68:71], v[150:153], v[230:233], v[36:39]
	v_mfma_f32_16x16x32_f16 v[36:39], v[166:169], v[132:135], v[136:139]
	v_mfma_f32_16x16x32_f16 v[64:67], v[178:181], v[170:173], v[36:39]
	v_mfma_f32_16x16x32_f16 v[36:39], v[166:169], v[210:213], v[140:143]
	v_mfma_f32_16x16x32_f16 v[60:63], v[178:181], v[158:161], v[36:39]
	v_mfma_f32_16x16x32_f16 v[36:39], v[182:185], v[132:135], v[162:165]
	v_mfma_f32_16x16x32_f16 v[56:59], v[186:189], v[170:173], v[36:39]
	v_mfma_f32_16x16x32_f16 v[36:39], v[182:185], v[210:213], v[174:177]
	v_mfma_f32_16x16x32_f16 v[52:55], v[186:189], v[158:161], v[36:39]
	v_mfma_f32_16x16x32_f16 v[36:39], v[214:217], v[132:135], v[206:209]
	v_mfma_f32_16x16x32_f16 v[48:51], v[154:157], v[170:173], v[36:39]
	v_mfma_f32_16x16x32_f16 v[36:39], v[214:217], v[210:213], v[190:193]
	v_mfma_f32_16x16x32_f16 v[44:47], v[154:157], v[158:161], v[36:39]
	v_mfma_f32_16x16x32_f16 v[36:39], v[238:241], v[132:135], v[194:197]
	v_mfma_f32_16x16x32_f16 v[40:43], v[150:153], v[170:173], v[36:39]
	v_mfma_f32_16x16x32_f16 v[36:39], v[238:241], v[210:213], v[198:201]
	v_mfma_f32_16x16x32_f16 v[36:39], v[150:153], v[158:161], v[36:39]
	s_movk_i32 s8, 0x100
	v_cmp_gt_u32_e32 vcc, s8, v3
	s_barrier
	s_and_saveexec_b64 s[8:9], vcc
	s_cbranch_execz .LBB0_1018
	s_barrier

;     ...
;   if (!pre) {
;     STAGE8(SB8(0, 0), Bt, K, bcol, 0); STAGE8(SA8(0, 0), A, lda, brow, 0);
;     STAGE8(SB8(0, 1), Bt, K, bcol + 128, 0); STAGE8(SA8(0, 1), A, lda, brow + 128, 0);
;   }
.LBB0_1149:
	s_mov_b32 s0, 24
	s_mov_b32 s0, 25
	s_ashr_i32 s1, s0, 31
	s_lshl_b64 s[0:1], s[0:1], 3
	s_add_u32 s0, s70, s0
	s_addc_u32 s1, s71, s1
	v_readlane_b32 s6, v255, 60
	v_readlane_b32 s7, v255, 61
	s_nop 4
	s_mov_b32 s0, 25
	s_ashr_i32 s1, s0, 31
	s_lshl_b64 s[0:1], s[0:1], 3
	s_add_u32 s0, s70, s0
	s_addc_u32 s1, s71, s1
	s_mov_b32 s2, 25
	v_readlane_b32 s0, v255, 60
	v_readlane_b32 s1, v255, 61
	s_nop 4
	s_ashr_i32 s3, s2, 31
	s_lshl_b64 s[2:3], s[2:3], 3
	s_add_u32 s2, s70, s2
	s_addc_u32 s3, s71, s3
	v_mov_b32_e32 v3, v224
	v_readlane_b32 s2, v255, 60
	v_readlane_b32 s3, v255, 61
	s_nop 4
	v_mov_b32_e32 v18, 1
	v_bfe_i32 v1, v3, 27, 1
	s_waitcnt vmcnt(10)
	v_lshlrev_b32_e32 v150, 4, v3
	s_nop 0
	v_readfirstlane_b32 s100, v150
	v_lshrrev_b32_e32 v1, 22, v1
	v_add_u32_e32 v1, v150, v1
	v_and_b32_e32 v1, 0xfffffc00, v1
	v_ashrrev_i32_e32 v0, 31, v3
	v_sub_u32_e32 v1, v150, v1
	v_lshrrev_b32_e32 v0, 26, v0
	v_lshrrev_b32_e32 v5, 4, v1
	v_add_u32_e32 v0, v3, v0
	v_bitop3_b32 v5, v5, v1, 32 bitop3:0x6c
	v_ashrrev_i32_e32 v1, 31, v1
	s_waitcnt lgkmcnt(0)
	s_add_u32 s29, s2, 0x3000000
	v_ashrrev_i32_e32 v0, 6, v0
	v_lshrrev_b32_e32 v1, 26, v1
	s_addc_u32 s33, s3, 0
	s_lshl_b32 s8, s24, 8
	v_lshlrev_b32_e32 v6, 3, v0
	v_add_u32_e32 v1, v5, v1
	s_and_b32 s25, s8, 0x3f00
	s_lshl_b32 s8, s24, 2
	v_and_b32_e32 v6, -16, v6
	v_ashrrev_i32_e32 v1, 6, v1
	s_and_b32 s8, s8, 0xffffff00
	v_add_u32_e32 v16, v1, v6
	v_mul_i32_i24_e32 v1, 64, v1
	s_ashr_i32 s9, s8, 31
	v_lshlrev_b32_e32 v0, 5, v0
	v_sub_u32_e32 v1, v5, v1
	s_waitcnt vmcnt(9)
	v_add_u32_e32 v152, 0x2000, v150
	s_lshl_b64 s[12:13], s[8:9], 10
	v_and_b32_e32 v0, 32, v0
	v_ashrrev_i16_sdwa v1, v18, sext(v1) dst_sel:DWORD dst_unused:UNUSED_PAD src0_sel:DWORD src1_sel:BYTE_0
	v_ashrrev_i32_e32 v5, 31, v152
	s_add_u32 s12, s14, s12
	v_add_u32_sdwa v0, v0, sext(v1) dst_sel:DWORD dst_unused:UNUSED_PAD src0_sel:DWORD src1_sel:WORD_0
	v_ashrrev_i32_e32 v17, 31, v16
	v_lshrrev_b32_e32 v5, 22, v5
	s_addc_u32 s13, s15, s13
	v_lshlrev_b64 v[6:7], 10, v[16:17]
	v_ashrrev_i32_e32 v1, 31, v0
	v_add_u32_e32 v5, v152, v5
	v_lshl_add_u64 v[10:11], s[12:13], 0, v[6:7]
	v_lshlrev_b64 v[8:9], 1, v[0:1]
	v_ashrrev_i32_e32 v5, 10, v5
	v_lshl_add_u64 v[14:15], v[10:11], 0, v[8:9]
	v_mul_i32_i24_e32 v10, 0x400, v5
	v_sub_u32_e32 v10, v152, v10
	v_lshrrev_b32_e32 v11, 4, v10
	v_bitop3_b32 v10, v11, v10, 32 bitop3:0x6c
	v_ashrrev_i32_e32 v12, 31, v10
	v_lshrrev_b32_e32 v12, 26, v12
	v_lshlrev_b32_e32 v11, 3, v5
	v_add_u32_e32 v12, v10, v12
	v_and_b32_e32 v11, -16, v11
	v_ashrrev_i32_e32 v13, 6, v12
	v_add_u32_e32 v24, v13, v11
	v_and_b32_e32 v11, 0xc0, v12
	v_lshlrev_b32_e32 v5, 5, v5
	v_sub_u32_e32 v10, v10, v11
	v_add_u32_e32 v151, 0x10000, v150
	v_and_b32_e32 v5, 32, v5
	v_ashrrev_i16_sdwa v10, v18, sext(v10) dst_sel:DWORD dst_unused:UNUSED_PAD src0_sel:DWORD src1_sel:BYTE_0
	v_ashrrev_i32_e32 v25, 31, v24
	v_add_u32_sdwa v132, v5, sext(v10) dst_sel:DWORD dst_unused:UNUSED_PAD src0_sel:DWORD src1_sel:WORD_0
	v_lshlrev_b64 v[10:11], 10, v[24:25]
	s_waitcnt vmcnt(8)
	v_add_u32_e32 v157, 0x12000, v150
	v_mov_b32_e32 v4, v2
	s_or_b32 m0, s100, 0x10000
	v_lshl_add_u64 v[18:19], s[12:13], 0, v[10:11]
	global_load_lds_dwordx4 v[14:15], off
	v_ashrrev_i32_e32 v133, 31, v132
	s_or_b32 m0, s100, 0x12000
	s_lshl_b32 s27, s25, 9
	s_lshl_b32 s12, s25, 10
	v_lshlrev_b64 v[12:13], 1, v[132:133]
	s_add_u32 s12, s29, s12
	v_lshl_add_u64 v[18:19], v[18:19], 0, v[12:13]
	s_addc_u32 s13, s33, 0
	global_load_lds_dwordx4 v[18:19], off
	v_lshl_add_u64 v[20:21], s[12:13], 0, v[6:7]
	s_mov_b32 m0, s100
	s_or_b32 s30, s8, 0x80
	v_lshl_add_u64 v[20:21], v[20:21], 0, v[8:9]
	v_lshl_add_u64 v[22:23], s[12:13], 0, v[10:11]
	s_ashr_i32 s31, s30, 31
	global_load_lds_dwordx4 v[20:21], off
	s_or_b32 m0, s100, 0x2000
	s_lshl_b64 s[12:13], s[30:31], 10
	s_add_u32 s12, s14, s12
	s_addc_u32 s13, s15, s13
	v_add_u32_e32 v159, 0x14000, v150
	v_lshl_add_u64 v[22:23], v[22:23], 0, v[12:13]
	v_lshl_add_u64 v[26:27], s[12:13], 0, v[6:7]
	v_add_u32_e32 v161, 0x16000, v150
	s_bitset1_b32 s27, 16
	global_load_lds_dwordx4 v[22:23], off
	v_lshl_add_u64 v[26:27], v[26:27], 0, v[8:9]
	s_or_b32 m0, s100, 0x14000
	v_lshl_add_u64 v[28:29], s[12:13], 0, v[10:11]
	s_lshl_b32 s27, s27, 1
	global_load_lds_dwordx4 v[26:27], off
	s_or_b32 m0, s100, 0x16000
	s_add_u32 s12, s29, s27
	s_addc_u32 s13, s33, 0
	v_add_u32_e32 v162, 0x4000, v150
	v_lshl_add_u64 v[28:29], v[28:29], 0, v[12:13]
	v_lshl_add_u64 v[30:31], s[12:13], 0, v[6:7]
	global_load_lds_dwordx4 v[28:29], off
	v_lshl_add_u64 v[30:31], v[30:31], 0, v[8:9]
	s_or_b32 m0, s100, 0x4000
	v_add_u32_e32 v163, 0x6000, v150
	global_load_lds_dwordx4 v[30:31], off
	v_lshl_add_u64 v[30:31], s[12:13], 0, v[10:11]
	v_lshl_add_u64 v[30:31], v[30:31], 0, v[12:13]
	s_or_b32 m0, s100, 0x6000
	v_ashrrev_i32_e32 v5, 8, v3
	global_load_lds_dwordx4 v[30:31], off
	v_cmp_eq_u32_e32 vcc, 1, v5
	s_and_saveexec_b64 s[12:13], vcc
	s_cbranch_execz .LBB0_1151
	s_barrier
; #define WAIT_V8(n) asm volatile("s_waitcnt vmcnt(" #n ")" ::: "memory")
; #define BAR8 __builtin_amdgcn_s_barrier()
;     ...
;   const int brow = m0, bcol = n0;
;   const int wid = t >> 6, lane = t & 63, wr = wid >> 2, wc = wid & 3, fr = lane & 15, fq = lane >> 4;
;   f32x4 acc[2][2][4][2];
;   {
;     float zinit = 0.f;
;     asm volatile("" : "+v"(zinit));
; #pragma unroll
;     for (int a = 0; a < 2; ++a)
; #pragma unroll
;       for (int b = 0; b < 2; ++b)
; #pragma unroll
;         for (int m = 0; m < 4; ++m)
; #pragma unroll
;           for (int n = 0; n < 2; ++n)
; #pragma unroll
;             for (int j = 0; j < 4; ++j) acc[a][b][m][n][j] = zinit;
;   }
;   bf16x8 At[4][2], B0[2][2], B1[2][2];
;   const int nt = K / 64;
;   if (!pre) {
;     STAGE8(SB8(0, 0), Bt, K, bcol, 0); STAGE8(SA8(0, 0), A, lda, brow, 0);
;     STAGE8(SB8(0, 1), Bt, K, bcol + 128, 0); STAGE8(SA8(0, 1), A, lda, brow + 128, 0);
;   }
;   if (wr == 1) BAR8;
;   WAIT_V8(4); BAR8;
;   STAGE8(SB8(1, 0), Bt, K, bcol, 1); STAGE8(SA8(1, 0), A, lda, brow, 1); STAGE8(SB8(1, 1), Bt, K, bcol + 128, 1);
;   WAIT_V8(6); BAR8;
.LBB0_1151:
	s_or_b64 exec, exec, s[12:13]
	s_lshl_b32 s29, s20, 10
	v_add_u32_e32 v164, 0x18000, v150
	s_and_b32 s36, s29, 0xfc0000
	s_mov_b64 s[38:39], 0x80
	v_add_u32_e32 v165, 0x1a000, v150
	v_lshl_add_u64 v[14:15], v[14:15], 0, s[38:39]
	s_or_b32 m0, s100, 0x18000
	v_add_u32_e32 v166, 0x8000, v150
	s_waitcnt vmcnt(4)
	s_barrier
	global_load_lds_dwordx4 v[14:15], off
	v_lshl_add_u64 v[14:15], v[18:19], 0, s[38:39]
	s_or_b32 m0, s100, 0x1a000
	v_add_u32_e32 v168, 0xa000, v150
	global_load_lds_dwordx4 v[14:15], off
	v_lshl_add_u64 v[14:15], v[20:21], 0, s[38:39]
	s_or_b32 m0, s100, 0x8000
	v_add_u32_e32 v169, 0x1c000, v150
	global_load_lds_dwordx4 v[14:15], off
	v_lshl_add_u64 v[14:15], v[22:23], 0, s[38:39]
	s_or_b32 m0, s100, 0xa000
	v_add_u32_e32 v170, 0x1e000, v150
	global_load_lds_dwordx4 v[14:15], off
	v_lshl_add_u64 v[14:15], v[26:27], 0, s[38:39]
	s_or_b32 m0, s100, 0x1c000
	s_nop 0
	global_load_lds_dwordx4 v[14:15], off
	v_lshl_add_u64 v[14:15], v[28:29], 0, s[38:39]
	s_or_b32 m0, s100, 0x1e000
	v_and_b32_e32 v147, 15, v3
	global_load_lds_dwordx4 v[14:15], off
	v_bfe_u32 v148, v3, 4, 2
	v_lshlrev_b32_e32 v14, 4, v148
	v_lshlrev_b32_e32 v15, 6, v147
	v_lshlrev_b32_e32 v18, 2, v3
	v_lshlrev_b64 v[136:137], 9, v[16:17]
	v_or_b32_e32 v17, v14, v15
	v_and_b32_e32 v18, 32, v18
	s_mov_b32 s29, 0x10000
	s_and_b32 s12, s21, 0xffffff00
	v_bitop3_b32 v20, v17, s29, v18 bitop3:0xde
	s_mov_b32 s29, 0x14000
	s_ashr_i32 s13, s12, 31
	v_readlane_b32 s40, v254, 35
	v_bitop3_b32 v19, v14, v18, v15 bitop3:0x36
	v_bitop3_b32 v21, v17, s29, v18 bitop3:0xde
	s_mov_b32 s29, 0x18000
	v_lshlrev_b32_e32 v15, 6, v3
	s_lshl_b64 s[12:13], s[12:13], 10
	s_mov_b32 s37, s40
	v_bitop3_b32 v22, v17, s29, v18 bitop3:0xde
	s_mov_b32 s29, 0x1c000
	v_and_b32_e32 v15, 0x3c0, v15
	v_bitop3_b32 v17, v17, s29, v18 bitop3:0xde
	v_bitop3_b32 v18, v15, v18, v14 bitop3:0x36
	v_lshl_add_u64 v[14:15], s[12:13], 0, v[6:7]
	v_lshl_add_u64 v[6:7], s[36:37], 0, v[6:7]
	v_lshl_add_u64 v[14:15], v[14:15], 0, v[8:9]
	v_lshl_add_u64 v[6:7], v[6:7], 0, v[8:9]
	v_bfe_u32 v146, v3, 6, 2
	s_waitcnt vmcnt(6)
	v_lshlrev_b32_e32 v149, 6, v5
	v_lshlrev_b32_e32 v5, 13, v5
	v_lshl_add_u64 v[138:139], s[4:5], 0, v[14:15]
	v_lshl_add_u64 v[14:15], s[12:13], 0, v[10:11]
	v_lshl_add_u64 v[142:143], s[2:3], 0, v[6:7]
	v_lshl_add_u64 v[6:7], s[36:37], 0, v[10:11]
	v_lshlrev_b64 v[134:135], 9, v[24:25]
	v_readlane_b32 s41, v254, 36
	v_readlane_b32 s42, v254, 37
	v_readlane_b32 s43, v254, 38
	v_lshlrev_b32_e32 v16, 12, v146
	v_or_b32_e32 v23, 0x800, v5
	v_or_b32_e32 v24, 0x1000, v5
	v_or_b32_e32 v25, 0x1800, v5
	v_lshl_add_u64 v[14:15], v[14:15], 0, v[12:13]
	v_lshl_add_u64 v[6:7], v[6:7], 0, v[12:13]
	v_lshl_add_u64 v[140:141], s[4:5], 0, v[14:15]
	v_lshl_add_u64 v[144:145], s[2:3], 0, v[6:7]
	s_mov_b32 s29, -2
	s_mov_b64 s[12:13], 0
	v_add_u32_e32 v171, v20, v16
	v_add_u32_e32 v156, v19, v5
	v_add_u32_e32 v155, v18, v23
	v_add_u32_e32 v154, v18, v24
	v_add_u32_e32 v153, v18, v25
	v_add_u32_e32 v167, v21, v16
	v_add_u32_e32 v160, v22, v16
	v_add_u32_e32 v158, v17, v16
	v_mov_b32_e32 v5, v4
	v_mov_b64_e32 v[6:7], v[4:5]
	v_mov_b64_e32 v[8:9], v[4:5]
	v_mov_b64_e32 v[10:11], v[4:5]
	v_mov_b64_e32 v[12:13], v[4:5]
	v_mov_b64_e32 v[14:15], v[4:5]
	v_mov_b64_e32 v[16:17], v[4:5]
	v_mov_b64_e32 v[18:19], v[4:5]
	v_mov_b64_e32 v[20:21], v[4:5]
	v_mov_b64_e32 v[22:23], v[4:5]
	v_mov_b64_e32 v[24:25], v[4:5]
	v_mov_b64_e32 v[26:27], v[4:5]
	v_mov_b64_e32 v[28:29], v[4:5]
	v_mov_b64_e32 v[30:31], v[4:5]
	v_mov_b64_e32 v[32:33], v[4:5]
	v_mov_b64_e32 v[34:35], v[4:5]
	v_mov_b64_e32 v[36:37], v[4:5]
	v_mov_b64_e32 v[38:39], v[4:5]
	v_mov_b64_e32 v[40:41], v[4:5]
	v_mov_b64_e32 v[42:43], v[4:5]
	v_mov_b64_e32 v[44:45], v[4:5]
	v_mov_b64_e32 v[46:47], v[4:5]
	v_mov_b64_e32 v[48:49], v[4:5]
	v_mov_b64_e32 v[50:51], v[4:5]
	v_mov_b64_e32 v[52:53], v[4:5]
	v_mov_b64_e32 v[54:55], v[4:5]
	v_mov_b64_e32 v[56:57], v[4:5]
	v_mov_b64_e32 v[58:59], v[4:5]
	v_mov_b64_e32 v[60:61], v[4:5]
	v_mov_b64_e32 v[62:63], v[4:5]
	v_mov_b64_e32 v[64:65], v[4:5]
	v_mov_b64_e32 v[66:67], v[4:5]
	v_mov_b64_e32 v[68:69], v[4:5]
	v_mov_b64_e32 v[70:71], v[4:5]
	v_mov_b64_e32 v[72:73], v[4:5]
	v_mov_b64_e32 v[74:75], v[4:5]
	v_mov_b64_e32 v[76:77], v[4:5]
	v_mov_b64_e32 v[78:79], v[4:5]
	v_mov_b64_e32 v[80:81], v[4:5]
	v_mov_b64_e32 v[82:83], v[4:5]
	v_mov_b64_e32 v[84:85], v[4:5]
	v_mov_b64_e32 v[86:87], v[4:5]
	v_mov_b64_e32 v[88:89], v[4:5]
	v_mov_b64_e32 v[90:91], v[4:5]
	v_mov_b64_e32 v[92:93], v[4:5]
	v_mov_b64_e32 v[94:95], v[4:5]
	v_mov_b64_e32 v[96:97], v[4:5]
	v_mov_b64_e32 v[98:99], v[4:5]
	v_mov_b64_e32 v[100:101], v[4:5]
	v_mov_b64_e32 v[102:103], v[4:5]
	v_mov_b64_e32 v[104:105], v[4:5]
	v_mov_b64_e32 v[106:107], v[4:5]
	v_mov_b64_e32 v[108:109], v[4:5]
	v_mov_b64_e32 v[110:111], v[4:5]
	v_mov_b64_e32 v[112:113], v[4:5]
	v_mov_b64_e32 v[114:115], v[4:5]
	v_mov_b64_e32 v[116:117], v[4:5]
	v_mov_b64_e32 v[118:119], v[4:5]
	v_mov_b64_e32 v[120:121], v[4:5]
	v_mov_b64_e32 v[122:123], v[4:5]
	v_mov_b64_e32 v[124:125], v[4:5]
	v_mov_b64_e32 v[126:127], v[4:5]
	v_mov_b64_e32 v[128:129], v[4:5]
	v_mov_b64_e32 v[130:131], v[4:5]
	s_mov_b64 s[36:37], 0x3020080
	s_mov_b64 s[38:39], 0xc9a0100
	s_mov_b64 s[40:41], 0x3000100
	s_mov_b64 s[42:43], 0xc9c0100
	s_mov_b64 s[44:45], 0x3020100
	s_mov_b64 s[46:47], 0xc9a0180
	s_mov_b64 s[48:49], 0x3000180
	s_mov_b64 s[50:51], 0xc9c0180
	s_barrier
; #define LDA8(dst, b, h) _Pragma("unroll") for (int m = 0; m < 4; ++m) _Pragma("unroll") for (int k = 0; k < 2; ++k) \
;     dst[m][k] = *(const bf16x8*)((const char*)SA8(b, h) + lds_byte8(wr * 64 + m * 16 + fr, k * 32 + fq * 8))
; #define LDB8(dst, b, h) _Pragma("unroll") for (int n = 0; n < 2; ++n) _Pragma("unroll") for (int k = 0; k < 2; ++k) \
;     dst[n][k] = *(const bf16x8*)((const char*)SB8(b, h) + lds_byte8(wc * 32 + n * 16 + fr, k * 32 + fq * 8))
; #define WAIT_L8(n) asm volatile("s_waitcnt lgkmcnt(" #n ")" ::: "memory")
; #define BAR8 __builtin_amdgcn_s_barrier()
; #define SCHED8 __builtin_amdgcn_sched_barrier(0)
;     ...
;   for (int tt = 0; tt < nt - 2; tt += 2) {
;     LDB8(B0, 0, 0); SCHED8; LDA8(At, 0, 0); STAGE8(SA8(1, 1), A, lda, brow + 128, tt + 1);
;     WAIT_L8(8); BAR8; WAIT_L8(0); MMA8(0, 0, At, B0); BAR8; SCHED8;
;     LDB8(B1, 0, 1); STAGE8(SB8(0, 0), Bt, K, bcol, tt + 2);
;     BAR8; WAIT_L8(0); MMA8(0, 1, At, B1); BAR8;
;     LDA8(At, 0, 1); STAGE8(SA8(0, 0), A, lda, brow, tt + 2);
;     BAR8; WAIT_L8(0); MMA8(1, 0, At, B0); BAR8; SCHED8;
.LBB0_1152:
	ds_read_b128 v[174:177], v171
	ds_read_b128 v[178:181], v171 offset:1024
	ds_read_b128 v[182:185], v171 offset:2048
	ds_read_b128 v[186:189], v171 offset:3072
	v_add_u32_e32 v172, 0xc000, v150
	v_lshl_add_u64 v[222:223], v[142:143], 0, s[12:13]
	v_add_u32_e32 v173, 0xe000, v150
	v_lshl_add_u64 v[226:227], v[222:223], 0, s[36:37]
	s_or_b32 m0, s100, 0xc000
	v_lshl_add_u64 v[236:237], v[144:145], 0, s[12:13]
	ds_read_b128 v[190:193], v156
	ds_read_b128 v[194:197], v156 offset:1024
	ds_read_b128 v[198:201], v155
	ds_read_b128 v[202:205], v155 offset:1024
	ds_read_b128 v[206:209], v154
	ds_read_b128 v[210:213], v154 offset:1024
	ds_read_b128 v[214:217], v153
	ds_read_b128 v[218:221], v153 offset:1024
	global_load_lds_dwordx4 v[226:227], off
	v_lshl_add_u64 v[226:227], v[236:237], 0, s[36:37]
	s_or_b32 m0, s100, 0xe000
	s_nop 0
	global_load_lds_dwordx4 v[226:227], off
	s_waitcnt lgkmcnt(8)
	s_barrier
	s_waitcnt lgkmcnt(0)
	s_waitcnt lgkmcnt(0)
	v_mfma_f32_16x16x32_bf16 v[128:131], v[190:193], v[174:177], v[128:131]
	v_mfma_f32_16x16x32_bf16 v[124:127], v[190:193], v[182:185], v[124:127]
	v_mfma_f32_16x16x32_bf16 v[120:123], v[198:201], v[174:177], v[120:123]
	v_mfma_f32_16x16x32_bf16 v[116:119], v[198:201], v[182:185], v[116:119]
	v_mfma_f32_16x16x32_bf16 v[112:115], v[206:209], v[174:177], v[112:115]
	v_mfma_f32_16x16x32_bf16 v[108:111], v[206:209], v[182:185], v[108:111]
	v_mfma_f32_16x16x32_bf16 v[104:107], v[214:217], v[174:177], v[104:107]
	v_mfma_f32_16x16x32_bf16 v[100:103], v[214:217], v[182:185], v[100:103]
	v_mfma_f32_16x16x32_bf16 v[128:131], v[194:197], v[178:181], v[128:131]
	v_mfma_f32_16x16x32_bf16 v[124:127], v[194:197], v[186:189], v[124:127]
	v_mfma_f32_16x16x32_bf16 v[120:123], v[202:205], v[178:181], v[120:123]
	v_mfma_f32_16x16x32_bf16 v[116:119], v[202:205], v[186:189], v[116:119]
	v_mfma_f32_16x16x32_bf16 v[112:115], v[210:213], v[178:181], v[112:115]
	v_mfma_f32_16x16x32_bf16 v[108:111], v[210:213], v[186:189], v[108:111]
	v_mfma_f32_16x16x32_bf16 v[104:107], v[218:221], v[178:181], v[104:107]
	v_mfma_f32_16x16x32_bf16 v[100:103], v[218:221], v[186:189], v[100:103]
	s_barrier
	v_lshl_add_u64 v[246:247], v[138:139], 0, s[12:13]
	v_lshl_add_u64 v[248:249], v[246:247], 0, s[38:39]
	s_or_b32 m0, s100, 0x10000
	ds_read_b128 v[226:229], v167
	ds_read_b128 v[230:233], v167 offset:1024
	ds_read_b128 v[238:241], v167 offset:2048
	ds_read_b128 v[242:245], v167 offset:3072
	global_load_lds_dwordx4 v[248:249], off
	v_lshl_add_u64 v[248:249], v[140:141], 0, s[12:13]
	v_lshl_add_u64 v[250:251], v[248:249], 0, s[38:39]
	s_or_b32 m0, s100, 0x12000
	s_nop 0
	global_load_lds_dwordx4 v[250:251], off
	s_barrier
	s_waitcnt lgkmcnt(0)
	s_waitcnt lgkmcnt(0)
	v_mfma_f32_16x16x32_bf16 v[96:99], v[190:193], v[226:229], v[96:99]
	v_mfma_f32_16x16x32_bf16 v[92:95], v[190:193], v[238:241], v[92:95]
	v_mfma_f32_16x16x32_bf16 v[88:91], v[198:201], v[226:229], v[88:91]
	v_mfma_f32_16x16x32_bf16 v[84:87], v[198:201], v[238:241], v[84:87]
	v_mfma_f32_16x16x32_bf16 v[80:83], v[206:209], v[226:229], v[80:83]
	v_mfma_f32_16x16x32_bf16 v[76:79], v[206:209], v[238:241], v[76:79]
	v_mfma_f32_16x16x32_bf16 v[72:75], v[214:217], v[226:229], v[72:75]
	v_mfma_f32_16x16x32_bf16 v[68:71], v[214:217], v[238:241], v[68:71]
	v_mfma_f32_16x16x32_bf16 v[96:99], v[194:197], v[230:233], v[96:99]
	v_mfma_f32_16x16x32_bf16 v[92:95], v[194:197], v[242:245], v[92:95]
	v_mfma_f32_16x16x32_bf16 v[88:91], v[202:205], v[230:233], v[88:91]
	v_mfma_f32_16x16x32_bf16 v[84:87], v[202:205], v[242:245], v[84:87]
	v_mfma_f32_16x16x32_bf16 v[80:83], v[210:213], v[230:233], v[80:83]
	v_mfma_f32_16x16x32_bf16 v[76:79], v[210:213], v[242:245], v[76:79]
	v_mfma_f32_16x16x32_bf16 v[72:75], v[218:221], v[230:233], v[72:75]
	v_mfma_f32_16x16x32_bf16 v[68:71], v[218:221], v[242:245], v[68:71]
	v_lshl_add_u64 v[250:251], v[222:223], 0, s[40:41]
	s_mov_b32 m0, s100
	s_barrier
	ds_read_b128 v[190:193], v156 offset:16384
	ds_read_b128 v[194:197], v156 offset:17408
	ds_read_b128 v[198:201], v155 offset:16384
	ds_read_b128 v[202:205], v155 offset:17408
	ds_read_b128 v[206:209], v154 offset:16384
	ds_read_b128 v[210:213], v154 offset:17408
	ds_read_b128 v[214:217], v153 offset:16384
	ds_read_b128 v[218:221], v153 offset:17408
	global_load_lds_dwordx4 v[250:251], off
	v_lshl_add_u64 v[250:251], v[236:237], 0, s[40:41]
	s_or_b32 m0, s100, 0x2000
	s_nop 0
	global_load_lds_dwordx4 v[250:251], off
	s_barrier
	s_waitcnt lgkmcnt(0)
	s_waitcnt lgkmcnt(0)
	v_mfma_f32_16x16x32_bf16 v[64:67], v[190:193], v[174:177], v[64:67]
	v_mfma_f32_16x16x32_bf16 v[60:63], v[190:193], v[182:185], v[60:63]
	v_mfma_f32_16x16x32_bf16 v[56:59], v[198:201], v[174:177], v[56:59]
	v_mfma_f32_16x16x32_bf16 v[52:55], v[198:201], v[182:185], v[52:55]
	v_mfma_f32_16x16x32_bf16 v[48:51], v[206:209], v[174:177], v[48:51]
	v_mfma_f32_16x16x32_bf16 v[44:47], v[206:209], v[182:185], v[44:47]
	v_mfma_f32_16x16x32_bf16 v[40:43], v[214:217], v[174:177], v[40:43]
	v_mfma_f32_16x16x32_bf16 v[36:39], v[214:217], v[182:185], v[36:39]
	v_mfma_f32_16x16x32_bf16 v[64:67], v[194:197], v[178:181], v[64:67]
	v_mfma_f32_16x16x32_bf16 v[60:63], v[194:197], v[186:189], v[60:63]
	v_mfma_f32_16x16x32_bf16 v[56:59], v[202:205], v[178:181], v[56:59]
	v_mfma_f32_16x16x32_bf16 v[52:55], v[202:205], v[186:189], v[52:55]
	v_mfma_f32_16x16x32_bf16 v[48:51], v[210:213], v[178:181], v[48:51]
	v_mfma_f32_16x16x32_bf16 v[44:47], v[210:213], v[186:189], v[44:47]
	v_mfma_f32_16x16x32_bf16 v[40:43], v[218:221], v[178:181], v[40:43]
	v_mfma_f32_16x16x32_bf16 v[36:39], v[218:221], v[186:189], v[36:39]
	s_barrier
; #define LDA8(dst, b, h) _Pragma("unroll") for (int m = 0; m < 4; ++m) _Pragma("unroll") for (int k = 0; k < 2; ++k) \
;     dst[m][k] = *(const bf16x8*)((const char*)SA8(b, h) + lds_byte8(wr * 64 + m * 16 + fr, k * 32 + fq * 8))
; #define LDB8(dst, b, h) _Pragma("unroll") for (int n = 0; n < 2; ++n) _Pragma("unroll") for (int k = 0; k < 2; ++k) \
;     dst[n][k] = *(const bf16x8*)((const char*)SB8(b, h) + lds_byte8(wc * 32 + n * 16 + fr, k * 32 + fq * 8))
; #define WAIT_V8(n) asm volatile("s_waitcnt vmcnt(" #n ")" ::: "memory")
; #define WAIT_L8(n) asm volatile("s_waitcnt lgkmcnt(" #n ")" ::: "memory")
; #define BAR8 __builtin_amdgcn_s_barrier()
; #define SCHED8 __builtin_amdgcn_sched_barrier(0)
;     ...
;     STAGE8(SB8(0, 1), Bt, K, bcol + 128, tt + 2);
;     WAIT_V8(6); BAR8; MMA8(1, 1, At, B1); BAR8;
;     LDB8(B0, 1, 0); SCHED8; LDA8(At, 1, 0); STAGE8(SA8(0, 1), A, lda, brow + 128, tt + 2);
;     WAIT_L8(8); BAR8; WAIT_L8(0); MMA8(0, 0, At, B0); BAR8; SCHED8;
;     LDB8(B1, 1, 1); STAGE8(SB8(1, 0), Bt, K, bcol, tt + 3);
;     BAR8; WAIT_L8(0); MMA8(0, 1, At, B1); BAR8;
;     LDA8(At, 1, 1); STAGE8(SA8(1, 0), A, lda, brow, tt + 3);
;     BAR8; WAIT_L8(0); MMA8(1, 0, At, B0); BAR8; SCHED8;
	v_lshl_add_u64 v[174:175], v[246:247], 0, s[42:43]
	s_or_b32 m0, s100, 0x14000
	s_nop 0
	global_load_lds_dwordx4 v[174:175], off
	v_lshl_add_u64 v[174:175], v[248:249], 0, s[42:43]
	s_or_b32 m0, s100, 0x16000
	s_nop 0
	global_load_lds_dwordx4 v[174:175], off
	s_waitcnt vmcnt(6)
	s_barrier
	v_mfma_f32_16x16x32_bf16 v[32:35], v[190:193], v[226:229], v[32:35]
	v_mfma_f32_16x16x32_bf16 v[28:31], v[190:193], v[238:241], v[28:31]
	v_mfma_f32_16x16x32_bf16 v[24:27], v[198:201], v[226:229], v[24:27]
	v_mfma_f32_16x16x32_bf16 v[20:23], v[198:201], v[238:241], v[20:23]
	v_mfma_f32_16x16x32_bf16 v[16:19], v[206:209], v[226:229], v[16:19]
	v_mfma_f32_16x16x32_bf16 v[12:15], v[206:209], v[238:241], v[12:15]
	v_mfma_f32_16x16x32_bf16 v[8:11], v[214:217], v[226:229], v[8:11]
	v_mfma_f32_16x16x32_bf16 v[4:7], v[214:217], v[238:241], v[4:7]
	v_mfma_f32_16x16x32_bf16 v[32:35], v[194:197], v[230:233], v[32:35]
	v_mfma_f32_16x16x32_bf16 v[28:31], v[194:197], v[242:245], v[28:31]
	v_mfma_f32_16x16x32_bf16 v[24:27], v[202:205], v[230:233], v[24:27]
	v_mfma_f32_16x16x32_bf16 v[20:23], v[202:205], v[242:245], v[20:23]
	v_mfma_f32_16x16x32_bf16 v[16:19], v[210:213], v[230:233], v[16:19]
	v_mfma_f32_16x16x32_bf16 v[12:15], v[210:213], v[242:245], v[12:15]
	v_mfma_f32_16x16x32_bf16 v[8:11], v[218:221], v[230:233], v[8:11]
	v_mfma_f32_16x16x32_bf16 v[4:7], v[218:221], v[242:245], v[4:7]
	s_barrier
	ds_read_b128 v[174:177], v160
	ds_read_b128 v[178:181], v160 offset:1024
	ds_read_b128 v[182:185], v160 offset:2048
	ds_read_b128 v[186:189], v160 offset:3072
	v_lshl_add_u64 v[226:227], v[222:223], 0, s[44:45]
	s_or_b32 m0, s100, 0x4000
	ds_read_b128 v[190:193], v156 offset:32768
	ds_read_b128 v[194:197], v156 offset:33792
	ds_read_b128 v[198:201], v155 offset:32768
	ds_read_b128 v[202:205], v155 offset:33792
	ds_read_b128 v[206:209], v154 offset:32768
	ds_read_b128 v[210:213], v154 offset:33792
	ds_read_b128 v[214:217], v153 offset:32768
	ds_read_b128 v[218:221], v153 offset:33792
	global_load_lds_dwordx4 v[226:227], off
	v_lshl_add_u64 v[226:227], v[236:237], 0, s[44:45]
	s_or_b32 m0, s100, 0x6000
	s_nop 0
	global_load_lds_dwordx4 v[226:227], off
	s_waitcnt lgkmcnt(8)
	s_barrier
	s_waitcnt lgkmcnt(0)
	s_waitcnt lgkmcnt(0)
	v_mfma_f32_16x16x32_bf16 v[128:131], v[190:193], v[174:177], v[128:131]
	v_mfma_f32_16x16x32_bf16 v[124:127], v[190:193], v[182:185], v[124:127]
	v_mfma_f32_16x16x32_bf16 v[120:123], v[198:201], v[174:177], v[120:123]
	v_mfma_f32_16x16x32_bf16 v[116:119], v[198:201], v[182:185], v[116:119]
	v_mfma_f32_16x16x32_bf16 v[112:115], v[206:209], v[174:177], v[112:115]
	v_mfma_f32_16x16x32_bf16 v[108:111], v[206:209], v[182:185], v[108:111]
	v_mfma_f32_16x16x32_bf16 v[104:107], v[214:217], v[174:177], v[104:107]
	v_mfma_f32_16x16x32_bf16 v[100:103], v[214:217], v[182:185], v[100:103]
	v_mfma_f32_16x16x32_bf16 v[128:131], v[194:197], v[178:181], v[128:131]
	v_mfma_f32_16x16x32_bf16 v[124:127], v[194:197], v[186:189], v[124:127]
	v_mfma_f32_16x16x32_bf16 v[120:123], v[202:205], v[178:181], v[120:123]
	v_mfma_f32_16x16x32_bf16 v[116:119], v[202:205], v[186:189], v[116:119]
	v_mfma_f32_16x16x32_bf16 v[112:115], v[210:213], v[178:181], v[112:115]
	v_mfma_f32_16x16x32_bf16 v[108:111], v[210:213], v[186:189], v[108:111]
	v_mfma_f32_16x16x32_bf16 v[104:107], v[218:221], v[178:181], v[104:107]
	v_mfma_f32_16x16x32_bf16 v[100:103], v[218:221], v[186:189], v[100:103]
	s_barrier
	v_lshl_add_u64 v[250:251], v[246:247], 0, s[46:47]
	s_or_b32 m0, s100, 0x18000
	ds_read_b128 v[226:229], v158
	ds_read_b128 v[230:233], v158 offset:1024
	ds_read_b128 v[238:241], v158 offset:2048
	ds_read_b128 v[242:245], v158 offset:3072
	global_load_lds_dwordx4 v[250:251], off
	v_lshl_add_u64 v[250:251], v[248:249], 0, s[46:47]
	s_or_b32 m0, s100, 0x1a000
	s_nop 0
	global_load_lds_dwordx4 v[250:251], off
	s_barrier
	s_waitcnt lgkmcnt(0)
	s_waitcnt lgkmcnt(0)
	v_mfma_f32_16x16x32_bf16 v[96:99], v[190:193], v[226:229], v[96:99]
	v_mfma_f32_16x16x32_bf16 v[92:95], v[190:193], v[238:241], v[92:95]
	v_mfma_f32_16x16x32_bf16 v[88:91], v[198:201], v[226:229], v[88:91]
	v_mfma_f32_16x16x32_bf16 v[84:87], v[198:201], v[238:241], v[84:87]
	v_mfma_f32_16x16x32_bf16 v[80:83], v[206:209], v[226:229], v[80:83]
	v_mfma_f32_16x16x32_bf16 v[76:79], v[206:209], v[238:241], v[76:79]
	v_mfma_f32_16x16x32_bf16 v[72:75], v[214:217], v[226:229], v[72:75]
	v_mfma_f32_16x16x32_bf16 v[68:71], v[214:217], v[238:241], v[68:71]
	v_mfma_f32_16x16x32_bf16 v[96:99], v[194:197], v[230:233], v[96:99]
	v_mfma_f32_16x16x32_bf16 v[92:95], v[194:197], v[242:245], v[92:95]
	v_mfma_f32_16x16x32_bf16 v[88:91], v[202:205], v[230:233], v[88:91]
	v_mfma_f32_16x16x32_bf16 v[84:87], v[202:205], v[242:245], v[84:87]
	v_mfma_f32_16x16x32_bf16 v[80:83], v[210:213], v[230:233], v[80:83]
	v_mfma_f32_16x16x32_bf16 v[76:79], v[210:213], v[242:245], v[76:79]
	v_mfma_f32_16x16x32_bf16 v[72:75], v[218:221], v[230:233], v[72:75]
	v_mfma_f32_16x16x32_bf16 v[68:71], v[218:221], v[242:245], v[68:71]
	v_lshl_add_u64 v[222:223], v[222:223], 0, s[48:49]
	s_or_b32 m0, s100, 0x8000
	s_barrier
	ds_read_b128 v[190:193], v156 offset:49152
	ds_read_b128 v[194:197], v156 offset:50176
	ds_read_b128 v[198:201], v155 offset:49152
	ds_read_b128 v[202:205], v155 offset:50176
	ds_read_b128 v[206:209], v154 offset:49152
	ds_read_b128 v[210:213], v154 offset:50176
	ds_read_b128 v[214:217], v153 offset:49152
	ds_read_b128 v[218:221], v153 offset:50176
	global_load_lds_dwordx4 v[222:223], off
	v_lshl_add_u64 v[222:223], v[236:237], 0, s[48:49]
	s_or_b32 m0, s100, 0xa000
	s_nop 0
	global_load_lds_dwordx4 v[222:223], off
	s_barrier
; #define LDA8(dst, b, h) _Pragma("unroll") for (int m = 0; m < 4; ++m) _Pragma("unroll") for (int k = 0; k < 2; ++k) \
;     dst[m][k] = *(const bf16x8*)((const char*)SA8(b, h) + lds_byte8(wr * 64 + m * 16 + fr, k * 32 + fq * 8))
; #define LDB8(dst, b, h) _Pragma("unroll") for (int n = 0; n < 2; ++n) _Pragma("unroll") for (int k = 0; k < 2; ++k) \
;     dst[n][k] = *(const bf16x8*)((const char*)SB8(b, h) + lds_byte8(wc * 32 + n * 16 + fr, k * 32 + fq * 8))
; #define WAIT_V8(n) asm volatile("s_waitcnt vmcnt(" #n ")" ::: "memory")
; #define WAIT_L8(n) asm volatile("s_waitcnt lgkmcnt(" #n ")" ::: "memory")
; #define BAR8 __builtin_amdgcn_s_barrier()
; #define SCHED8 __builtin_amdgcn_sched_barrier(0)
;     ...
;     BAR8; WAIT_L8(0); MMA8(1, 0, At, B0); BAR8; SCHED8;
;     STAGE8(SB8(1, 1), Bt, K, bcol + 128, tt + 3);
;     WAIT_V8(6); BAR8; MMA8(1, 1, At, B1); BAR8;
;   }
;   { LDB8(B0, 0, 0); LDA8(At, 0, 0); STAGE8(SA8(1, 1), A, lda, brow + 128, nt - 1);
;     BAR8; WAIT_L8(0); MMA8(0, 0, At, B0); BAR8;
;     LDB8(B1, 0, 1); BAR8; WAIT_L8(0); MMA8(0, 1, At, B1); BAR8;
	s_waitcnt lgkmcnt(0)
	s_waitcnt lgkmcnt(0)
	v_mfma_f32_16x16x32_bf16 v[64:67], v[190:193], v[174:177], v[64:67]
	v_mfma_f32_16x16x32_bf16 v[60:63], v[190:193], v[182:185], v[60:63]
	v_mfma_f32_16x16x32_bf16 v[56:59], v[198:201], v[174:177], v[56:59]
	v_mfma_f32_16x16x32_bf16 v[52:55], v[198:201], v[182:185], v[52:55]
	v_mfma_f32_16x16x32_bf16 v[48:51], v[206:209], v[174:177], v[48:51]
	v_mfma_f32_16x16x32_bf16 v[44:47], v[206:209], v[182:185], v[44:47]
	v_mfma_f32_16x16x32_bf16 v[40:43], v[214:217], v[174:177], v[40:43]
	v_mfma_f32_16x16x32_bf16 v[36:39], v[214:217], v[182:185], v[36:39]
	v_mfma_f32_16x16x32_bf16 v[64:67], v[194:197], v[178:181], v[64:67]
	v_mfma_f32_16x16x32_bf16 v[60:63], v[194:197], v[186:189], v[60:63]
	v_mfma_f32_16x16x32_bf16 v[56:59], v[202:205], v[178:181], v[56:59]
	v_mfma_f32_16x16x32_bf16 v[52:55], v[202:205], v[186:189], v[52:55]
	v_mfma_f32_16x16x32_bf16 v[48:51], v[210:213], v[178:181], v[48:51]
	v_mfma_f32_16x16x32_bf16 v[44:47], v[210:213], v[186:189], v[44:47]
	v_mfma_f32_16x16x32_bf16 v[40:43], v[218:221], v[178:181], v[40:43]
	v_mfma_f32_16x16x32_bf16 v[36:39], v[218:221], v[186:189], v[36:39]
	s_barrier
	v_lshl_add_u64 v[174:175], v[246:247], 0, s[50:51]
	s_or_b32 m0, s100, 0x1c000
	s_nop 0
	global_load_lds_dwordx4 v[174:175], off
	v_lshl_add_u64 v[174:175], v[248:249], 0, s[50:51]
	s_or_b32 m0, s100, 0x1e000
	s_nop 0
	global_load_lds_dwordx4 v[174:175], off
	s_waitcnt vmcnt(6)
	s_barrier
	v_mfma_f32_16x16x32_bf16 v[32:35], v[190:193], v[226:229], v[32:35]
	v_mfma_f32_16x16x32_bf16 v[28:31], v[190:193], v[238:241], v[28:31]
	v_mfma_f32_16x16x32_bf16 v[24:27], v[198:201], v[226:229], v[24:27]
	v_mfma_f32_16x16x32_bf16 v[20:23], v[198:201], v[238:241], v[20:23]
	v_mfma_f32_16x16x32_bf16 v[16:19], v[206:209], v[226:229], v[16:19]
	v_mfma_f32_16x16x32_bf16 v[12:15], v[206:209], v[238:241], v[12:15]
	v_mfma_f32_16x16x32_bf16 v[8:11], v[214:217], v[226:229], v[8:11]
	v_mfma_f32_16x16x32_bf16 v[4:7], v[214:217], v[238:241], v[4:7]
	v_mfma_f32_16x16x32_bf16 v[32:35], v[194:197], v[230:233], v[32:35]
	v_mfma_f32_16x16x32_bf16 v[28:31], v[194:197], v[242:245], v[28:31]
	v_mfma_f32_16x16x32_bf16 v[24:27], v[202:205], v[230:233], v[24:27]
	v_mfma_f32_16x16x32_bf16 v[20:23], v[202:205], v[242:245], v[20:23]
	v_mfma_f32_16x16x32_bf16 v[16:19], v[210:213], v[230:233], v[16:19]
	v_mfma_f32_16x16x32_bf16 v[12:15], v[210:213], v[242:245], v[12:15]
	v_mfma_f32_16x16x32_bf16 v[8:11], v[218:221], v[230:233], v[8:11]
	v_mfma_f32_16x16x32_bf16 v[4:7], v[218:221], v[242:245], v[4:7]
	s_add_i32 s29, s29, 2
	s_add_u32 s12, s12, 0x100
	s_addc_u32 s13, s13, 0
	s_cmp_lt_u32 s29, 4
	s_barrier
	s_cbranch_scc1 .LBB0_1152
	s_add_u32 s2, s2, s27
	s_addc_u32 s3, s3, 0
	s_add_u32 s2, s2, 0x3000380
	s_addc_u32 s3, s3, 0
	v_lshl_add_u64 v[136:137], v[136:137], 1, s[2:3]
	v_lshl_add_u64 v[0:1], v[0:1], 1, v[136:137]
	s_or_b32 m0, s100, 0xc000
	ds_read_b128 v[138:141], v171
	ds_read_b128 v[142:145], v171 offset:1024
	ds_read_b128 v[162:165], v171 offset:2048
	ds_read_b128 v[168:171], v171 offset:3072
	ds_read_b128 v[174:177], v156
	ds_read_b128 v[178:181], v156 offset:1024
	ds_read_b128 v[182:185], v155
	ds_read_b128 v[186:189], v155 offset:1024
	ds_read_b128 v[190:193], v154
	ds_read_b128 v[194:197], v154 offset:1024
	ds_read_b128 v[198:201], v153
	ds_read_b128 v[202:205], v153 offset:1024
	global_load_lds_dwordx4 v[0:1], off
	v_lshl_add_u64 v[0:1], v[134:135], 1, s[2:3]
	v_lshl_add_u64 v[0:1], v[132:133], 1, v[0:1]
	s_or_b32 m0, s100, 0xe000
	s_nop 0
	global_load_lds_dwordx4 v[0:1], off
	s_barrier
	s_waitcnt lgkmcnt(0)
	s_waitcnt lgkmcnt(0)
	v_mfma_f32_16x16x32_bf16 v[128:131], v[174:177], v[138:141], v[128:131]
	v_mfma_f32_16x16x32_bf16 v[124:127], v[174:177], v[162:165], v[124:127]
	v_mfma_f32_16x16x32_bf16 v[120:123], v[182:185], v[138:141], v[120:123]
	v_mfma_f32_16x16x32_bf16 v[112:115], v[190:193], v[138:141], v[112:115]
	v_mfma_f32_16x16x32_bf16 v[128:131], v[178:181], v[142:145], v[128:131]
	v_mfma_f32_16x16x32_bf16 v[124:127], v[178:181], v[168:171], v[124:127]
	v_mfma_f32_16x16x32_bf16 v[120:123], v[186:189], v[142:145], v[120:123]
	v_mfma_f32_16x16x32_bf16 v[116:119], v[182:185], v[162:165], v[116:119]
	v_mfma_f32_16x16x32_bf16 v[112:115], v[194:197], v[142:145], v[112:115]
	v_mfma_f32_16x16x32_bf16 v[108:111], v[190:193], v[162:165], v[108:111]
	v_mfma_f32_16x16x32_bf16 v[104:107], v[198:201], v[138:141], v[104:107]
	v_mfma_f32_16x16x32_bf16 v[100:103], v[198:201], v[162:165], v[100:103]
	v_mfma_f32_16x16x32_bf16 v[132:135], v[186:189], v[168:171], v[116:119]
	v_mfma_f32_16x16x32_bf16 v[206:209], v[194:197], v[168:171], v[108:111]
	v_mfma_f32_16x16x32_bf16 v[210:213], v[202:205], v[142:145], v[104:107]
	v_mfma_f32_16x16x32_bf16 v[214:217], v[202:205], v[168:171], v[100:103]
	s_barrier
	s_nop 1
	ds_read_b128 v[100:103], v167
	ds_read_b128 v[104:107], v167 offset:1024
	ds_read_b128 v[108:111], v167 offset:2048
	ds_read_b128 v[116:119], v167 offset:3072
	s_barrier
	s_waitcnt lgkmcnt(0)
	s_waitcnt lgkmcnt(0)
	v_mfma_f32_16x16x32_bf16 v[80:83], v[190:193], v[100:103], v[80:83]
	v_mfma_f32_16x16x32_bf16 v[76:79], v[190:193], v[108:111], v[76:79]
	v_mfma_f32_16x16x32_bf16 v[72:75], v[198:201], v[100:103], v[72:75]
	v_mfma_f32_16x16x32_bf16 v[68:71], v[198:201], v[108:111], v[68:71]
	v_mfma_f32_16x16x32_bf16 v[96:99], v[174:177], v[100:103], v[96:99]
	v_mfma_f32_16x16x32_bf16 v[92:95], v[174:177], v[108:111], v[92:95]
	v_mfma_f32_16x16x32_bf16 v[88:91], v[182:185], v[100:103], v[88:91]
	v_mfma_f32_16x16x32_bf16 v[84:87], v[182:185], v[108:111], v[84:87]
	v_mfma_f32_16x16x32_bf16 v[80:83], v[194:197], v[104:107], v[80:83]
	v_mfma_f32_16x16x32_bf16 v[76:79], v[194:197], v[116:119], v[76:79]
	v_mfma_f32_16x16x32_bf16 v[72:75], v[202:205], v[104:107], v[72:75]
	v_mfma_f32_16x16x32_bf16 v[68:71], v[202:205], v[116:119], v[68:71]
	v_mfma_f32_16x16x32_bf16 v[218:221], v[178:181], v[104:107], v[96:99]
	v_mfma_f32_16x16x32_bf16 v[172:175], v[178:181], v[116:119], v[92:95]
	v_mfma_f32_16x16x32_bf16 v[176:179], v[186:189], v[104:107], v[88:91]
	v_mfma_f32_16x16x32_bf16 v[180:183], v[186:189], v[116:119], v[84:87]
	s_barrier
; #define LDA8(dst, b, h) _Pragma("unroll") for (int m = 0; m < 4; ++m) _Pragma("unroll") for (int k = 0; k < 2; ++k) \
;     dst[m][k] = *(const bf16x8*)((const char*)SA8(b, h) + lds_byte8(wr * 64 + m * 16 + fr, k * 32 + fq * 8))
; #define LDB8(dst, b, h) _Pragma("unroll") for (int n = 0; n < 2; ++n) _Pragma("unroll") for (int k = 0; k < 2; ++k) \
;     dst[n][k] = *(const bf16x8*)((const char*)SB8(b, h) + lds_byte8(wc * 32 + n * 16 + fr, k * 32 + fq * 8))
; #define WAIT_V8(n) asm volatile("s_waitcnt vmcnt(" #n ")" ::: "memory")
; #define WAIT_L8(n) asm volatile("s_waitcnt lgkmcnt(" #n ")" ::: "memory")
; #define BAR8 __builtin_amdgcn_s_barrier()
;     ...
;     LDA8(At, 0, 1); WAIT_V8(4); BAR8; WAIT_L8(0); MMA8(1, 0, At, B0); MMA8(1, 1, At, B1); BAR8; }
;   { LDB8(B0, 1, 0); LDA8(At, 1, 0); WAIT_V8(2); BAR8; WAIT_L8(0); MMA8(0, 0, At, B0); BAR8;
	s_nop 0
	ds_read_b128 v[84:87], v156 offset:16384
	ds_read_b128 v[88:91], v156 offset:17408
	ds_read_b128 v[92:95], v155 offset:16384
	ds_read_b128 v[96:99], v155 offset:17408
	ds_read_b128 v[184:187], v154 offset:16384
	ds_read_b128 v[188:191], v154 offset:17408
	ds_read_b128 v[192:195], v153 offset:16384
	ds_read_b128 v[196:199], v153 offset:17408
	s_waitcnt vmcnt(4)
	s_barrier
	s_waitcnt lgkmcnt(0)
	s_waitcnt lgkmcnt(0)
	v_mfma_f32_16x16x32_bf16 v[64:67], v[84:87], v[138:141], v[64:67]
	v_mfma_f32_16x16x32_bf16 v[60:63], v[84:87], v[162:165], v[60:63]
	v_mfma_f32_16x16x32_bf16 v[56:59], v[92:95], v[138:141], v[56:59]
	v_mfma_f32_16x16x32_bf16 v[52:55], v[92:95], v[162:165], v[52:55]
	v_mfma_f32_16x16x32_bf16 v[48:51], v[184:187], v[138:141], v[48:51]
	v_mfma_f32_16x16x32_bf16 v[44:47], v[184:187], v[162:165], v[44:47]
	v_mfma_f32_16x16x32_bf16 v[40:43], v[192:195], v[138:141], v[40:43]
	v_mfma_f32_16x16x32_bf16 v[36:39], v[192:195], v[162:165], v[36:39]
	v_mfma_f32_16x16x32_bf16 v[64:67], v[88:91], v[142:145], v[64:67]
	v_mfma_f32_16x16x32_bf16 v[60:63], v[88:91], v[168:171], v[60:63]
	v_mfma_f32_16x16x32_bf16 v[56:59], v[96:99], v[142:145], v[56:59]
	v_mfma_f32_16x16x32_bf16 v[52:55], v[96:99], v[168:171], v[52:55]
	v_mfma_f32_16x16x32_bf16 v[48:51], v[188:191], v[142:145], v[48:51]
	v_mfma_f32_16x16x32_bf16 v[44:47], v[188:191], v[168:171], v[44:47]
	v_mfma_f32_16x16x32_bf16 v[40:43], v[196:199], v[142:145], v[40:43]
	v_mfma_f32_16x16x32_bf16 v[36:39], v[196:199], v[168:171], v[36:39]
	v_mfma_f32_16x16x32_bf16 v[32:35], v[84:87], v[100:103], v[32:35]
	v_mfma_f32_16x16x32_bf16 v[28:31], v[84:87], v[108:111], v[28:31]
	v_mfma_f32_16x16x32_bf16 v[24:27], v[92:95], v[100:103], v[24:27]
	v_mfma_f32_16x16x32_bf16 v[20:23], v[92:95], v[108:111], v[20:23]
	v_mfma_f32_16x16x32_bf16 v[16:19], v[184:187], v[100:103], v[16:19]
	v_mfma_f32_16x16x32_bf16 v[12:15], v[184:187], v[108:111], v[12:15]
	v_mfma_f32_16x16x32_bf16 v[8:11], v[192:195], v[100:103], v[8:11]
	v_mfma_f32_16x16x32_bf16 v[4:7], v[192:195], v[108:111], v[4:7]
	v_mfma_f32_16x16x32_bf16 v[136:139], v[88:91], v[104:107], v[32:35]
	v_mfma_f32_16x16x32_bf16 v[140:143], v[88:91], v[116:119], v[28:31]
	v_mfma_f32_16x16x32_bf16 v[162:165], v[96:99], v[104:107], v[24:27]
	v_mfma_f32_16x16x32_bf16 v[166:169], v[96:99], v[116:119], v[20:23]
	v_mfma_f32_16x16x32_bf16 v[200:203], v[188:191], v[104:107], v[16:19]
	v_mfma_f32_16x16x32_bf16 v[184:187], v[188:191], v[116:119], v[12:15]
	v_mfma_f32_16x16x32_bf16 v[188:191], v[196:199], v[104:107], v[8:11]
	v_mfma_f32_16x16x32_bf16 v[192:195], v[196:199], v[116:119], v[4:7]
	s_barrier
	ds_read_b128 v[196:199], v160
	ds_read_b128 v[226:229], v160 offset:1024
	ds_read_b128 v[230:233], v160 offset:2048
	ds_read_b128 v[238:241], v160 offset:3072
	ds_read_b128 v[8:11], v156 offset:32768
	ds_read_b128 v[12:15], v156 offset:33792
	ds_read_b128 v[16:19], v155 offset:32768
	ds_read_b128 v[24:27], v155 offset:33792
	ds_read_b128 v[28:31], v154 offset:32768
	ds_read_b128 v[32:35], v154 offset:33792
	ds_read_b128 v[242:245], v153 offset:32768
	ds_read_b128 v[246:249], v153 offset:33792
	s_waitcnt vmcnt(2)
	s_barrier
	s_waitcnt lgkmcnt(0)
	s_waitcnt lgkmcnt(0)
	v_mfma_f32_16x16x32_bf16 v[4:7], v[8:11], v[196:199], v[128:131]
	v_mfma_f32_16x16x32_bf16 v[104:107], v[12:15], v[226:229], v[4:7]
	v_mfma_f32_16x16x32_bf16 v[4:7], v[8:11], v[230:233], v[124:127]
	v_mfma_f32_16x16x32_bf16 v[116:119], v[12:15], v[238:241], v[4:7]
	v_mfma_f32_16x16x32_bf16 v[4:7], v[16:19], v[196:199], v[120:123]
	v_mfma_f32_16x16x32_bf16 v[100:103], v[24:27], v[226:229], v[4:7]
	v_mfma_f32_16x16x32_bf16 v[4:7], v[16:19], v[230:233], v[132:135]
	v_mfma_f32_16x16x32_bf16 v[108:111], v[24:27], v[238:241], v[4:7]
	v_mfma_f32_16x16x32_bf16 v[4:7], v[28:31], v[196:199], v[112:115]
	v_mfma_f32_16x16x32_bf16 v[92:95], v[32:35], v[226:229], v[4:7]
	v_mfma_f32_16x16x32_bf16 v[4:7], v[28:31], v[230:233], v[206:209]
	v_mfma_f32_16x16x32_bf16 v[96:99], v[32:35], v[238:241], v[4:7]
	v_mfma_f32_16x16x32_bf16 v[4:7], v[242:245], v[196:199], v[210:213]
	v_mfma_f32_16x16x32_bf16 v[84:87], v[246:249], v[226:229], v[4:7]
	v_mfma_f32_16x16x32_bf16 v[4:7], v[242:245], v[230:233], v[214:217]
	v_mfma_f32_16x16x32_bf16 v[88:91], v[246:249], v[238:241], v[4:7]
	s_barrier
; #define LDA8(dst, b, h) _Pragma("unroll") for (int m = 0; m < 4; ++m) _Pragma("unroll") for (int k = 0; k < 2; ++k) \
;     dst[m][k] = *(const bf16x8*)((const char*)SA8(b, h) + lds_byte8(wr * 64 + m * 16 + fr, k * 32 + fq * 8))
; #define LDB8(dst, b, h) _Pragma("unroll") for (int n = 0; n < 2; ++n) _Pragma("unroll") for (int k = 0; k < 2; ++k) \
;     dst[n][k] = *(const bf16x8*)((const char*)SB8(b, h) + lds_byte8(wc * 32 + n * 16 + fr, k * 32 + fq * 8))
; #define WAIT_V8(n) asm volatile("s_waitcnt vmcnt(" #n ")" ::: "memory")
; #define WAIT_L8(n) asm volatile("s_waitcnt lgkmcnt(" #n ")" ::: "memory")
; #define BAR8 __builtin_amdgcn_s_barrier()
;     ...
;     LDB8(B1, 1, 1); WAIT_V8(0); BAR8; WAIT_L8(0); MMA8(0, 1, At, B1); BAR8;
;     LDA8(At, 1, 1); BAR8; WAIT_L8(0); MMA8(1, 0, At, B0); MMA8(1, 1, At, B1); BAR8; }
;   if (wr == 0) BAR8;
;   __syncthreads();
	ds_read_b128 v[132:135], v158
	ds_read_b128 v[204:207], v158 offset:1024
	ds_read_b128 v[208:211], v158 offset:2048
	ds_read_b128 v[158:161], v158 offset:3072
	s_waitcnt vmcnt(0)
	s_barrier
	s_waitcnt lgkmcnt(0)
	s_waitcnt lgkmcnt(0)
	v_mfma_f32_16x16x32_bf16 v[4:7], v[8:11], v[132:135], v[218:221]
	v_mfma_f32_16x16x32_bf16 v[8:11], v[8:11], v[208:211], v[172:175]
	v_mfma_f32_16x16x32_bf16 v[4:7], v[12:15], v[204:207], v[4:7]
	v_mfma_f32_16x16x32_bf16 v[20:23], v[12:15], v[158:161], v[8:11]
	v_mfma_f32_16x16x32_bf16 v[8:11], v[16:19], v[132:135], v[176:179]
	v_mfma_f32_16x16x32_bf16 v[12:15], v[16:19], v[208:211], v[180:183]
	v_mfma_f32_16x16x32_bf16 v[8:11], v[24:27], v[204:207], v[8:11]
	v_mfma_f32_16x16x32_bf16 v[24:27], v[24:27], v[158:161], v[12:15]
	v_mfma_f32_16x16x32_bf16 v[12:15], v[28:31], v[132:135], v[80:83]
	v_mfma_f32_16x16x32_bf16 v[16:19], v[28:31], v[208:211], v[76:79]
	v_mfma_f32_16x16x32_bf16 v[12:15], v[32:35], v[204:207], v[12:15]
	v_mfma_f32_16x16x32_bf16 v[28:31], v[32:35], v[158:161], v[16:19]
	v_mfma_f32_16x16x32_bf16 v[16:19], v[242:245], v[132:135], v[72:75]
	v_mfma_f32_16x16x32_bf16 v[32:35], v[242:245], v[208:211], v[68:71]
	v_mfma_f32_16x16x32_bf16 v[16:19], v[246:249], v[204:207], v[16:19]
	v_mfma_f32_16x16x32_bf16 v[32:35], v[246:249], v[158:161], v[32:35]
	s_barrier
	ds_read_b128 v[170:173], v156 offset:49152
	ds_read_b128 v[174:177], v156 offset:50176
	ds_read_b128 v[178:181], v155 offset:49152
	ds_read_b128 v[212:215], v155 offset:50176
	ds_read_b128 v[216:219], v154 offset:49152
	ds_read_b128 v[154:157], v154 offset:50176
	ds_read_b128 v[220:223], v153 offset:49152
	ds_read_b128 v[150:153], v153 offset:50176
	s_barrier
	s_waitcnt lgkmcnt(0)
	s_waitcnt lgkmcnt(0)
	v_mfma_f32_16x16x32_bf16 v[64:67], v[170:173], v[196:199], v[64:67]
	v_mfma_f32_16x16x32_bf16 v[60:63], v[170:173], v[230:233], v[60:63]
	v_mfma_f32_16x16x32_bf16 v[56:59], v[178:181], v[196:199], v[56:59]
	v_mfma_f32_16x16x32_bf16 v[52:55], v[178:181], v[230:233], v[52:55]
	v_mfma_f32_16x16x32_bf16 v[48:51], v[216:219], v[196:199], v[48:51]
	v_mfma_f32_16x16x32_bf16 v[44:47], v[216:219], v[230:233], v[44:47]
	v_mfma_f32_16x16x32_bf16 v[40:43], v[220:223], v[196:199], v[40:43]
	v_mfma_f32_16x16x32_bf16 v[36:39], v[220:223], v[230:233], v[36:39]
	v_mfma_f32_16x16x32_bf16 v[128:131], v[174:177], v[226:229], v[64:67]
	v_mfma_f32_16x16x32_bf16 v[124:127], v[174:177], v[238:241], v[60:63]
	v_mfma_f32_16x16x32_bf16 v[120:123], v[212:215], v[226:229], v[56:59]
	v_mfma_f32_16x16x32_bf16 v[112:115], v[212:215], v[238:241], v[52:55]
	v_mfma_f32_16x16x32_bf16 v[80:83], v[154:157], v[226:229], v[48:51]
	v_mfma_f32_16x16x32_bf16 v[76:79], v[154:157], v[238:241], v[44:47]
	v_mfma_f32_16x16x32_bf16 v[72:75], v[150:153], v[226:229], v[40:43]
	v_mfma_f32_16x16x32_bf16 v[68:71], v[150:153], v[238:241], v[36:39]
	v_mfma_f32_16x16x32_bf16 v[40:43], v[170:173], v[208:211], v[140:143]
	v_mfma_f32_16x16x32_bf16 v[44:47], v[178:181], v[208:211], v[166:169]
	v_mfma_f32_16x16x32_bf16 v[48:51], v[216:219], v[208:211], v[184:187]
	v_mfma_f32_16x16x32_bf16 v[36:39], v[170:173], v[132:135], v[136:139]
	v_mfma_f32_16x16x32_bf16 v[52:55], v[174:177], v[158:161], v[40:43]
	v_mfma_f32_16x16x32_bf16 v[40:43], v[178:181], v[132:135], v[162:165]
	v_mfma_f32_16x16x32_bf16 v[56:59], v[212:215], v[158:161], v[44:47]
	v_mfma_f32_16x16x32_bf16 v[44:47], v[216:219], v[132:135], v[200:203]
	v_mfma_f32_16x16x32_bf16 v[60:63], v[154:157], v[158:161], v[48:51]
	v_mfma_f32_16x16x32_bf16 v[48:51], v[220:223], v[132:135], v[188:191]
	v_mfma_f32_16x16x32_bf16 v[64:67], v[220:223], v[208:211], v[192:195]
	v_mfma_f32_16x16x32_bf16 v[36:39], v[174:177], v[204:207], v[36:39]
	v_mfma_f32_16x16x32_bf16 v[40:43], v[212:215], v[204:207], v[40:43]
	v_mfma_f32_16x16x32_bf16 v[44:47], v[154:157], v[204:207], v[44:47]
	v_mfma_f32_16x16x32_bf16 v[48:51], v[150:153], v[204:207], v[48:51]
	v_mfma_f32_16x16x32_bf16 v[64:67], v[150:153], v[158:161], v[64:67]
	s_movk_i32 s2, 0x100
	v_cmp_gt_u32_e32 vcc, s2, v3
	s_barrier
	s_and_saveexec_b64 s[2:3], vcc
	s_cbranch_execz .LBB0_1155
	s_barrier

;     ...
;   if (!pre) {
;     STAGE8(SB8(0, 0), Bt, K, bcol, 0); STAGE8(SA8(0, 0), A, lda, brow, 0);
;     STAGE8(SB8(0, 1), Bt, K, bcol + 128, 0); STAGE8(SA8(0, 1), A, lda, brow + 128, 0);
;   }
.LBB0_1253:
	s_and_b64 vcc, exec, s[0:1]
	s_cbranch_vccz .LBB0_1266
	s_mov_b32 s0, 25
	s_ashr_i32 s1, s0, 31
	s_xor_b64 s[8:9], s[8:9], -1
	s_lshl_b64 s[0:1], s[0:1], 3
	s_add_u32 s0, s70, s0
	s_addc_u32 s1, s71, s1
	v_readlane_b32 s2, v255, 60
	v_readlane_b32 s3, v255, 61
	s_nop 4
	s_lshl_b32 s0, s25, 8
	v_mov_b32_e32 v3, v224
	s_and_b32 s27, s0, 0x3f00
	s_lshl_b32 s0, s25, 2
	s_and_b32 s0, s0, 0xffffff00
	s_waitcnt vmcnt(10)
	v_lshlrev_b32_e32 v150, 4, v3
	s_nop 0
	v_readfirstlane_b32 s100, v150
	v_ashrrev_i32_e32 v0, 31, v3
	v_bfe_i32 v5, v3, 27, 1
	v_mov_b32_e32 v4, v2
	s_andn2_b64 vcc, exec, s[8:9]
	v_lshrrev_b32_e32 v1, 26, v0
	v_lshrrev_b32_e32 v0, 22, v5
	v_add_u32_e32 v151, 0x10000, v150
	s_waitcnt vmcnt(9)
	v_add_u32_e32 v152, 0x2000, v150
	v_add_u32_e32 v153, 0x12000, v150
	v_add_u32_e32 v154, 0x14000, v150
	v_add_u32_e32 v155, 0x16000, v150
	s_waitcnt vmcnt(8)
	v_add_u32_e32 v156, 0x4000, v150
	v_add_u32_e32 v157, 0x6000, v150
	s_cbranch_vccnz .LBB0_1256
	v_add_u32_e32 v6, v150, v0
	v_and_b32_e32 v6, 0xfffffc00, v6
	v_sub_u32_e32 v6, v150, v6
	v_lshrrev_b32_e32 v7, 4, v6
	v_add_u32_e32 v5, v3, v1
	v_bitop3_b32 v7, v7, v6, 32 bitop3:0x6c
	v_ashrrev_i32_e32 v6, 31, v6
	v_ashrrev_i32_e32 v5, 6, v5
	v_lshrrev_b32_e32 v6, 26, v6
	v_lshlrev_b32_e32 v8, 3, v5
	v_add_u32_e32 v6, v7, v6
	v_and_b32_e32 v8, -16, v8
	v_ashrrev_i32_e32 v9, 6, v6
	v_add_u32_e32 v6, v9, v8
	v_mul_i32_i24_e32 v8, 64, v9
	s_ashr_i32 s1, s0, 31
	v_lshlrev_b32_e32 v5, 5, v5
	v_sub_u32_e32 v7, v7, v8
	v_mov_b32_e32 v14, 1
	s_lshl_b64 s[8:9], s[0:1], 11
	v_and_b32_e32 v5, 32, v5
	v_ashrrev_i16_sdwa v7, v14, sext(v7) dst_sel:DWORD dst_unused:UNUSED_PAD src0_sel:DWORD src1_sel:BYTE_0
	s_add_u32 s8, s4, s8
	v_add_u32_sdwa v8, v5, sext(v7) dst_sel:DWORD dst_unused:UNUSED_PAD src0_sel:DWORD src1_sel:WORD_0
	v_ashrrev_i32_e32 v7, 31, v6
	v_ashrrev_i32_e32 v5, 31, v152
	s_addc_u32 s9, s5, s9
	v_lshlrev_b64 v[6:7], 11, v[6:7]
	v_ashrrev_i32_e32 v9, 31, v8
	v_lshrrev_b32_e32 v5, 22, v5
	v_lshl_add_u64 v[10:11], s[8:9], 0, v[6:7]
	v_lshlrev_b64 v[8:9], 1, v[8:9]
	v_add_u32_e32 v5, v152, v5
	v_lshl_add_u64 v[10:11], v[10:11], 0, v[8:9]
	s_or_b32 m0, s100, 0x10000
	v_ashrrev_i32_e32 v5, 10, v5
	global_load_lds_dwordx4 v[10:11], off
	v_mul_i32_i24_e32 v10, 0x400, v5
	v_sub_u32_e32 v10, v152, v10
	v_lshrrev_b32_e32 v11, 4, v10
	v_bitop3_b32 v11, v11, v10, 32 bitop3:0x6c
	v_ashrrev_i32_e32 v12, 31, v11
	v_lshrrev_b32_e32 v12, 26, v12
	v_add_u32_e32 v12, v11, v12
	v_lshlrev_b32_e32 v10, 3, v5
	v_ashrrev_i32_e32 v13, 6, v12
	v_and_b32_e32 v12, 0xc0, v12
	v_and_b32_e32 v10, -16, v10
	v_lshlrev_b32_e32 v5, 5, v5
	v_sub_u32_e32 v11, v11, v12
	v_add_u32_e32 v10, v13, v10
	v_and_b32_e32 v5, 32, v5
	v_ashrrev_i16_sdwa v11, v14, sext(v11) dst_sel:DWORD dst_unused:UNUSED_PAD src0_sel:DWORD src1_sel:BYTE_0
	v_add_u32_sdwa v12, v5, sext(v11) dst_sel:DWORD dst_unused:UNUSED_PAD src0_sel:DWORD src1_sel:WORD_0
	v_ashrrev_i32_e32 v11, 31, v10
	v_lshlrev_b64 v[10:11], 11, v[10:11]
	v_ashrrev_i32_e32 v13, 31, v12
	s_or_b32 m0, s100, 0x12000
	s_lshl_b32 s1, s27, 11
	v_lshl_add_u64 v[14:15], s[8:9], 0, v[10:11]
	v_lshlrev_b64 v[12:13], 1, v[12:13]
	s_waitcnt lgkmcnt(0)
	s_add_u32 s8, s2, s1
	v_lshl_add_u64 v[14:15], v[14:15], 0, v[12:13]
	s_addc_u32 s9, s3, 0
	s_or_b32 s14, s0, 0x80
	global_load_lds_dwordx4 v[14:15], off
	v_lshl_add_u64 v[14:15], s[8:9], 0, v[6:7]
	s_ashr_i32 s15, s14, 31
	v_lshl_add_u64 v[14:15], v[14:15], 0, v[8:9]
	s_mov_b32 m0, s100
	s_lshl_b64 s[14:15], s[14:15], 11
	global_load_lds_dwordx4 v[14:15], off
	v_lshl_add_u64 v[14:15], s[8:9], 0, v[10:11]
	s_add_u32 s14, s4, s14
	v_lshl_add_u64 v[14:15], v[14:15], 0, v[12:13]
	s_addc_u32 s15, s5, s15
	s_or_b32 m0, s100, 0x2000
	global_load_lds_dwordx4 v[14:15], off
	v_lshl_add_u64 v[14:15], s[14:15], 0, v[6:7]
	v_lshl_add_u64 v[14:15], v[14:15], 0, v[8:9]
	s_or_b32 m0, s100, 0x14000
	s_add_u32 s8, s8, 0x40000
	global_load_lds_dwordx4 v[14:15], off
	v_lshl_add_u64 v[14:15], s[14:15], 0, v[10:11]
	s_addc_u32 s9, s9, 0
	v_lshl_add_u64 v[14:15], v[14:15], 0, v[12:13]
	s_or_b32 m0, s100, 0x16000
	v_lshl_add_u64 v[6:7], s[8:9], 0, v[6:7]
	global_load_lds_dwordx4 v[14:15], off
	v_lshl_add_u64 v[6:7], v[6:7], 0, v[8:9]
	s_or_b32 m0, s100, 0x4000
	s_nop 0
	global_load_lds_dwordx4 v[6:7], off
	v_lshl_add_u64 v[6:7], s[8:9], 0, v[10:11]
	v_lshl_add_u64 v[6:7], v[6:7], 0, v[12:13]
	s_or_b32 m0, s100, 0x6000
	s_nop 0
	global_load_lds_dwordx4 v[6:7], off

; #define WAIT_V8(n) asm volatile("s_waitcnt vmcnt(" #n ")" ::: "memory")
; #define BAR8 __builtin_amdgcn_s_barrier()
;     ...
;   if (wr == 1) BAR8;
;   WAIT_V8(4); BAR8;
;   STAGE8(SB8(1, 0), Bt, K, bcol, 1); STAGE8(SA8(1, 0), A, lda, brow, 1); STAGE8(SB8(1, 1), Bt, K, bcol + 128, 1);
;   WAIT_V8(6); BAR8;
.LBB0_1258:
	s_or_b64 exec, exec, s[8:9]
	v_add_u32_e32 v0, v150, v0
	v_and_b32_e32 v0, 0xfffffc00, v0
	v_sub_u32_e32 v0, v150, v0
	v_lshrrev_b32_e32 v6, 4, v0
	v_add_u32_e32 v1, v3, v1
	v_bitop3_b32 v7, v6, v0, 32 bitop3:0x6c
	v_ashrrev_i32_e32 v0, 31, v0
	v_ashrrev_i32_e32 v1, 6, v1
	v_lshrrev_b32_e32 v0, 26, v0
	v_lshlrev_b32_e32 v6, 3, v1
	v_add_u32_e32 v0, v7, v0
	v_and_b32_e32 v6, -16, v6
	v_ashrrev_i32_e32 v0, 6, v0
	s_and_b32 s1, s12, 63
	s_and_b32 s8, s20, 0xffffff00
	v_add_u32_e32 v6, v0, v6
	v_mul_i32_i24_e32 v0, 64, v0
	s_lshl_b32 s12, s1, 19
	s_ashr_i32 s9, s8, 31
	s_ashr_i32 s1, s0, 31
	v_lshlrev_b32_e32 v1, 5, v1
	v_sub_u32_e32 v0, v7, v0
	v_mov_b32_e32 v13, 1
	s_lshl_b64 s[14:15], s[8:9], 11
	s_lshl_b64 s[8:9], s[0:1], 11
	v_and_b32_e32 v1, 32, v1
	v_ashrrev_i16_sdwa v0, v13, sext(v0) dst_sel:DWORD dst_unused:UNUSED_PAD src0_sel:DWORD src1_sel:BYTE_0
	s_add_u32 s8, s4, s8
	v_add_u32_sdwa v0, v1, sext(v0) dst_sel:DWORD dst_unused:UNUSED_PAD src0_sel:DWORD src1_sel:WORD_0
	v_ashrrev_i32_e32 v7, 31, v6
	v_readlane_b32 s40, v254, 35
	s_addc_u32 s9, s5, s9
	v_lshlrev_b64 v[132:133], 11, v[6:7]
	v_ashrrev_i32_e32 v1, 31, v0
	v_readlane_b32 s41, v254, 36
	v_lshl_add_u64 v[6:7], s[8:9], 0, v[132:133]
	v_lshlrev_b64 v[8:9], 1, v[0:1]
	v_add_u32_e32 v164, 0x18000, v150
	s_mov_b32 s13, s40
	v_lshl_add_u64 v[6:7], v[6:7], 0, v[8:9]
	s_mov_b64 s[40:41], 0x80
	v_lshl_add_u64 v[6:7], v[6:7], 0, s[40:41]
	s_or_b32 m0, s100, 0x18000
	s_waitcnt vmcnt(4)
	s_barrier
	global_load_lds_dwordx4 v[6:7], off
	v_ashrrev_i32_e32 v6, 31, v152
	v_lshrrev_b32_e32 v6, 22, v6
	v_add_u32_e32 v6, v152, v6
	v_ashrrev_i32_e32 v7, 10, v6
	v_mul_i32_i24_e32 v6, 0x400, v7
	v_sub_u32_e32 v6, v152, v6
	v_lshrrev_b32_e32 v10, 4, v6
	v_bitop3_b32 v10, v10, v6, 32 bitop3:0x6c
	v_ashrrev_i32_e32 v11, 31, v10
	v_lshrrev_b32_e32 v11, 26, v11
	v_add_u32_e32 v11, v10, v11
	v_lshlrev_b32_e32 v6, 3, v7
	v_ashrrev_i32_e32 v12, 6, v11
	v_and_b32_e32 v11, 0xc0, v11
	v_and_b32_e32 v6, -16, v6
	v_lshlrev_b32_e32 v7, 5, v7
	v_sub_u32_e32 v10, v10, v11
	v_add_u32_e32 v6, v12, v6
	v_and_b32_e32 v7, 32, v7
	v_ashrrev_i16_sdwa v10, v13, sext(v10) dst_sel:DWORD dst_unused:UNUSED_PAD src0_sel:DWORD src1_sel:BYTE_0
	v_add_u32_sdwa v134, v7, sext(v10) dst_sel:DWORD dst_unused:UNUSED_PAD src0_sel:DWORD src1_sel:WORD_0
	v_ashrrev_i32_e32 v7, 31, v6
	v_add_u32_e32 v165, 0x1a000, v150
	v_lshlrev_b64 v[136:137], 11, v[6:7]
	v_ashrrev_i32_e32 v135, 31, v134
	v_lshl_add_u64 v[6:7], s[8:9], 0, v[136:137]
	v_lshlrev_b64 v[10:11], 1, v[134:135]
	s_or_b32 m0, s100, 0x1a000
	s_lshl_b32 s1, s27, 11
	v_lshl_add_u64 v[6:7], v[6:7], 0, v[10:11]
	s_waitcnt lgkmcnt(0)
	s_add_u32 s8, s2, s1
	v_lshl_add_u64 v[6:7], v[6:7], 0, s[40:41]
	s_addc_u32 s9, s3, 0
	global_load_lds_dwordx4 v[6:7], off
	v_lshl_add_u64 v[6:7], s[8:9], 0, v[132:133]
	v_add_u32_e32 v166, 0x8000, v150
	v_lshl_add_u64 v[6:7], v[6:7], 0, v[8:9]
	s_or_b32 s36, s0, 0x80
	v_lshl_add_u64 v[6:7], v[6:7], 0, s[40:41]
	s_or_b32 m0, s100, 0x8000
	s_ashr_i32 s37, s36, 31
	global_load_lds_dwordx4 v[6:7], off
	v_lshl_add_u64 v[6:7], s[8:9], 0, v[136:137]
	v_add_u32_e32 v167, 0xa000, v150
	s_lshl_b64 s[36:37], s[36:37], 11
	v_lshl_add_u64 v[6:7], v[6:7], 0, v[10:11]
	s_add_u32 s36, s4, s36
	v_lshl_add_u64 v[6:7], v[6:7], 0, s[40:41]
	s_addc_u32 s37, s5, s37
	s_or_b32 m0, s100, 0xa000
	global_load_lds_dwordx4 v[6:7], off
	v_lshl_add_u64 v[6:7], s[36:37], 0, v[132:133]
	v_add_u32_e32 v168, 0x1c000, v150
	v_lshl_add_u64 v[6:7], v[6:7], 0, v[8:9]
	v_lshl_add_u64 v[6:7], v[6:7], 0, s[40:41]
	s_or_b32 m0, s100, 0x1c000
	v_add_u32_e32 v170, 0x1e000, v150
	global_load_lds_dwordx4 v[6:7], off
	v_lshl_add_u64 v[6:7], s[36:37], 0, v[136:137]
	v_lshl_add_u64 v[6:7], v[6:7], 0, v[10:11]
	v_lshl_add_u64 v[6:7], v[6:7], 0, s[40:41]
	s_or_b32 m0, s100, 0x1e000
	v_and_b32_e32 v147, 15, v3
	global_load_lds_dwordx4 v[6:7], off
	v_bfe_u32 v148, v3, 4, 2
	v_lshlrev_b32_e32 v6, 4, v148
	v_lshlrev_b32_e32 v7, 6, v147
	v_lshlrev_b32_e32 v14, 2, v3
	v_or_b32_e32 v13, v6, v7
	v_and_b32_e32 v14, 32, v14
	s_mov_b32 s1, 0x10000
	v_bitop3_b32 v16, v13, s1, v14 bitop3:0xde
	s_mov_b32 s1, 0x14000
	v_bitop3_b32 v15, v6, v14, v7 bitop3:0x36
	v_bitop3_b32 v17, v13, s1, v14 bitop3:0xde
	s_mov_b32 s1, 0x18000
	v_lshlrev_b32_e32 v7, 6, v3
	v_bitop3_b32 v18, v13, s1, v14 bitop3:0xde
	s_mov_b32 s1, 0x1c000
	v_and_b32_e32 v7, 0x3c0, v7
	v_bitop3_b32 v13, v13, s1, v14 bitop3:0xde
	v_bitop3_b32 v14, v7, v14, v6 bitop3:0x36
	v_lshl_add_u64 v[6:7], s[12:13], 0, v[132:133]
	v_lshl_add_u64 v[6:7], v[6:7], 0, v[8:9]
	v_lshl_add_u64 v[138:139], s[2:3], 0, v[6:7]
	v_lshl_add_u64 v[6:7], s[12:13], 0, v[136:137]
	v_lshl_add_u64 v[6:7], v[6:7], 0, v[10:11]
	v_lshl_add_u64 v[140:141], s[2:3], 0, v[6:7]
	v_lshl_add_u64 v[6:7], s[14:15], 0, v[132:133]
	v_lshl_add_u64 v[6:7], v[6:7], 0, v[8:9]
	v_bfe_u32 v146, v3, 6, 2
	s_waitcnt vmcnt(6)
; #define LDA8(dst, b, h) _Pragma("unroll") for (int m = 0; m < 4; ++m) _Pragma("unroll") for (int k = 0; k < 2; ++k) \
;     dst[m][k] = *(const bf16x8*)((const char*)SA8(b, h) + lds_byte8(wr * 64 + m * 16 + fr, k * 32 + fq * 8))
; #define LDB8(dst, b, h) _Pragma("unroll") for (int n = 0; n < 2; ++n) _Pragma("unroll") for (int k = 0; k < 2; ++k) \
;     dst[n][k] = *(const bf16x8*)((const char*)SB8(b, h) + lds_byte8(wc * 32 + n * 16 + fr, k * 32 + fq * 8))
; #define WAIT_V8(n) asm volatile("s_waitcnt vmcnt(" #n ")" ::: "memory")
; #define WAIT_L8(n) asm volatile("s_waitcnt lgkmcnt(" #n ")" ::: "memory")
; #define BAR8 __builtin_amdgcn_s_barrier()
; #define SCHED8 __builtin_amdgcn_sched_barrier(0)
;     ...
;   f32x4 acc[2][2][4][2];
;   {
;     float zinit = 0.f;
;     asm volatile("" : "+v"(zinit));
; #pragma unroll
;     for (int a = 0; a < 2; ++a)
; #pragma unroll
;       for (int b = 0; b < 2; ++b)
; #pragma unroll
;         for (int m = 0; m < 4; ++m)
; #pragma unroll
;           for (int n = 0; n < 2; ++n)
; #pragma unroll
;             for (int j = 0; j < 4; ++j) acc[a][b][m][n][j] = zinit;
;   }
;   bf16x8 At[4][2], B0[2][2], B1[2][2];
;   const int nt = K / 64;
;   if (!pre) {
;     STAGE8(SB8(0, 0), Bt, K, bcol, 0); STAGE8(SA8(0, 0), A, lda, brow, 0);
;     STAGE8(SB8(0, 1), Bt, K, bcol + 128, 0); STAGE8(SA8(0, 1), A, lda, brow + 128, 0);
;   }
;   if (wr == 1) BAR8;
;   WAIT_V8(4); BAR8;
;   STAGE8(SB8(1, 0), Bt, K, bcol, 1); STAGE8(SA8(1, 0), A, lda, brow, 1); STAGE8(SB8(1, 1), Bt, K, bcol + 128, 1);
;   WAIT_V8(6); BAR8;
;   for (int tt = 0; tt < nt - 2; tt += 2) {
;     LDB8(B0, 0, 0); SCHED8; LDA8(At, 0, 0); STAGE8(SA8(1, 1), A, lda, brow + 128, tt + 1);
;     WAIT_L8(8); BAR8; WAIT_L8(0); MMA8(0, 0, At, B0); BAR8; SCHED8;
;     LDB8(B1, 0, 1); STAGE8(SB8(0, 0), Bt, K, bcol, tt + 2);
	v_lshlrev_b32_e32 v149, 6, v5
	v_lshlrev_b32_e32 v5, 13, v5
	v_lshl_add_u64 v[142:143], s[6:7], 0, v[6:7]
	v_lshl_add_u64 v[6:7], s[14:15], 0, v[136:137]
	v_readlane_b32 s42, v254, 37
	v_readlane_b32 s43, v254, 38
	v_lshlrev_b32_e32 v12, 12, v146
	v_or_b32_e32 v19, 0x800, v5
	v_or_b32_e32 v20, 0x1000, v5
	v_or_b32_e32 v21, 0x1800, v5
	v_lshl_add_u64 v[6:7], v[6:7], 0, v[10:11]
	v_lshl_add_u64 v[144:145], s[6:7], 0, v[6:7]
	s_mov_b32 s1, -2
	s_mov_b64 s[12:13], 0
	v_add_u32_e32 v171, v16, v12
	v_add_u32_e32 v161, v15, v5
	v_add_u32_e32 v160, v14, v19
	v_add_u32_e32 v159, v14, v20
	v_add_u32_e32 v158, v14, v21
	v_add_u32_e32 v169, v17, v12
	v_add_u32_e32 v163, v18, v12
	v_add_u32_e32 v162, v13, v12
	v_mov_b32_e32 v5, v4
	v_mov_b64_e32 v[6:7], v[4:5]
	v_mov_b64_e32 v[8:9], v[4:5]
	v_mov_b64_e32 v[10:11], v[4:5]
	v_mov_b64_e32 v[12:13], v[4:5]
	v_mov_b64_e32 v[14:15], v[4:5]
	v_mov_b64_e32 v[16:17], v[4:5]
	v_mov_b64_e32 v[18:19], v[4:5]
	v_mov_b64_e32 v[20:21], v[4:5]
	v_mov_b64_e32 v[22:23], v[4:5]
	v_mov_b64_e32 v[24:25], v[4:5]
	v_mov_b64_e32 v[26:27], v[4:5]
	v_mov_b64_e32 v[28:29], v[4:5]
	v_mov_b64_e32 v[30:31], v[4:5]
	v_mov_b64_e32 v[32:33], v[4:5]
	v_mov_b64_e32 v[34:35], v[4:5]
	v_mov_b64_e32 v[36:37], v[4:5]
	v_mov_b64_e32 v[38:39], v[4:5]
	v_mov_b64_e32 v[40:41], v[4:5]
	v_mov_b64_e32 v[42:43], v[4:5]
	v_mov_b64_e32 v[44:45], v[4:5]
	v_mov_b64_e32 v[46:47], v[4:5]
	v_mov_b64_e32 v[48:49], v[4:5]
	v_mov_b64_e32 v[50:51], v[4:5]
	v_mov_b64_e32 v[52:53], v[4:5]
	v_mov_b64_e32 v[54:55], v[4:5]
	v_mov_b64_e32 v[56:57], v[4:5]
	v_mov_b64_e32 v[58:59], v[4:5]
	v_mov_b64_e32 v[60:61], v[4:5]
	v_mov_b64_e32 v[62:63], v[4:5]
	v_mov_b64_e32 v[64:65], v[4:5]
	v_mov_b64_e32 v[66:67], v[4:5]
	v_mov_b64_e32 v[68:69], v[4:5]
	v_mov_b64_e32 v[70:71], v[4:5]
	v_mov_b64_e32 v[72:73], v[4:5]
	v_mov_b64_e32 v[74:75], v[4:5]
	v_mov_b64_e32 v[76:77], v[4:5]
	v_mov_b64_e32 v[78:79], v[4:5]
	v_mov_b64_e32 v[80:81], v[4:5]
	v_mov_b64_e32 v[82:83], v[4:5]
	v_mov_b64_e32 v[84:85], v[4:5]
	v_mov_b64_e32 v[86:87], v[4:5]
	v_mov_b64_e32 v[88:89], v[4:5]
	v_mov_b64_e32 v[90:91], v[4:5]
	v_mov_b64_e32 v[92:93], v[4:5]
	v_mov_b64_e32 v[94:95], v[4:5]
	v_mov_b64_e32 v[96:97], v[4:5]
	v_mov_b64_e32 v[98:99], v[4:5]
	v_mov_b64_e32 v[100:101], v[4:5]
	v_mov_b64_e32 v[102:103], v[4:5]
	v_mov_b64_e32 v[104:105], v[4:5]
	v_mov_b64_e32 v[106:107], v[4:5]
	v_mov_b64_e32 v[108:109], v[4:5]
	v_mov_b64_e32 v[110:111], v[4:5]
	v_mov_b64_e32 v[112:113], v[4:5]
	v_mov_b64_e32 v[114:115], v[4:5]
	v_mov_b64_e32 v[116:117], v[4:5]
	v_mov_b64_e32 v[118:119], v[4:5]
	v_mov_b64_e32 v[120:121], v[4:5]
	v_mov_b64_e32 v[122:123], v[4:5]
	v_mov_b64_e32 v[124:125], v[4:5]
	v_mov_b64_e32 v[126:127], v[4:5]
	v_mov_b64_e32 v[128:129], v[4:5]
	v_mov_b64_e32 v[130:131], v[4:5]
	s_mov_b64 s[36:37], 0xcaa0100
	s_mov_b64 s[40:41], 0xcae0100
	s_mov_b64 s[42:43], 0xcaa0180
	s_mov_b64 s[44:45], 0xcae0180
	s_barrier
.LBB0_1259:
	ds_read_b128 v[174:177], v171
	ds_read_b128 v[178:181], v171 offset:1024
	ds_read_b128 v[182:185], v171 offset:2048
	ds_read_b128 v[186:189], v171 offset:3072
	v_add_u32_e32 v172, 0xc000, v150
	v_lshl_add_u64 v[222:223], v[138:139], 0, s[12:13]
	v_add_u32_e32 v173, 0xe000, v150
	v_lshl_add_u64 v[226:227], v[222:223], 0, s[34:35]
	s_or_b32 m0, s100, 0xc000
	v_lshl_add_u64 v[236:237], v[140:141], 0, s[12:13]
	ds_read_b128 v[190:193], v161
	ds_read_b128 v[194:197], v161 offset:1024
	ds_read_b128 v[198:201], v160
	ds_read_b128 v[202:205], v160 offset:1024
	ds_read_b128 v[206:209], v159
	ds_read_b128 v[210:213], v159 offset:1024
	ds_read_b128 v[214:217], v158
	ds_read_b128 v[218:221], v158 offset:1024
	global_load_lds_dwordx4 v[226:227], off
	v_lshl_add_u64 v[226:227], v[236:237], 0, s[34:35]
	s_or_b32 m0, s100, 0xe000
	s_nop 0
	global_load_lds_dwordx4 v[226:227], off
	s_waitcnt lgkmcnt(8)
	s_barrier
	s_waitcnt lgkmcnt(0)
	s_waitcnt lgkmcnt(0)
	v_mfma_f32_16x16x32_f16 v[128:131], v[190:193], v[174:177], v[128:131]
	v_mfma_f32_16x16x32_f16 v[124:127], v[190:193], v[182:185], v[124:127]
	v_mfma_f32_16x16x32_f16 v[120:123], v[198:201], v[174:177], v[120:123]
	v_mfma_f32_16x16x32_f16 v[116:119], v[198:201], v[182:185], v[116:119]
	v_mfma_f32_16x16x32_f16 v[112:115], v[206:209], v[174:177], v[112:115]
	v_mfma_f32_16x16x32_f16 v[108:111], v[206:209], v[182:185], v[108:111]
	v_mfma_f32_16x16x32_f16 v[104:107], v[214:217], v[174:177], v[104:107]
	v_mfma_f32_16x16x32_f16 v[100:103], v[214:217], v[182:185], v[100:103]
	v_mfma_f32_16x16x32_f16 v[128:131], v[194:197], v[178:181], v[128:131]
	v_mfma_f32_16x16x32_f16 v[124:127], v[194:197], v[186:189], v[124:127]
	v_mfma_f32_16x16x32_f16 v[120:123], v[202:205], v[178:181], v[120:123]
	v_mfma_f32_16x16x32_f16 v[116:119], v[202:205], v[186:189], v[116:119]
	v_mfma_f32_16x16x32_f16 v[112:115], v[210:213], v[178:181], v[112:115]
	v_mfma_f32_16x16x32_f16 v[108:111], v[210:213], v[186:189], v[108:111]
	v_mfma_f32_16x16x32_f16 v[104:107], v[218:221], v[178:181], v[104:107]
	v_mfma_f32_16x16x32_f16 v[100:103], v[218:221], v[186:189], v[100:103]
	s_barrier
	v_lshl_add_u64 v[246:247], v[142:143], 0, s[12:13]
	v_lshl_add_u64 v[248:249], v[246:247], 0, s[36:37]
	s_or_b32 m0, s100, 0x10000
	ds_read_b128 v[226:229], v169
	ds_read_b128 v[230:233], v169 offset:1024
	ds_read_b128 v[238:241], v169 offset:2048
	ds_read_b128 v[242:245], v169 offset:3072
	global_load_lds_dwordx4 v[248:249], off
	v_lshl_add_u64 v[248:249], v[144:145], 0, s[12:13]
	v_lshl_add_u64 v[250:251], v[248:249], 0, s[36:37]
	s_or_b32 m0, s100, 0x12000
	s_nop 0
	global_load_lds_dwordx4 v[250:251], off
	s_barrier
; #define LDA8(dst, b, h) _Pragma("unroll") for (int m = 0; m < 4; ++m) _Pragma("unroll") for (int k = 0; k < 2; ++k) \
;     dst[m][k] = *(const bf16x8*)((const char*)SA8(b, h) + lds_byte8(wr * 64 + m * 16 + fr, k * 32 + fq * 8))
; #define LDB8(dst, b, h) _Pragma("unroll") for (int n = 0; n < 2; ++n) _Pragma("unroll") for (int k = 0; k < 2; ++k) \
;     dst[n][k] = *(const bf16x8*)((const char*)SB8(b, h) + lds_byte8(wc * 32 + n * 16 + fr, k * 32 + fq * 8))
; #define WAIT_V8(n) asm volatile("s_waitcnt vmcnt(" #n ")" ::: "memory")
; #define WAIT_L8(n) asm volatile("s_waitcnt lgkmcnt(" #n ")" ::: "memory")
; #define BAR8 __builtin_amdgcn_s_barrier()
; #define SCHED8 __builtin_amdgcn_sched_barrier(0)
;     ...
;     LDB8(B1, 0, 1); STAGE8(SB8(0, 0), Bt, K, bcol, tt + 2);
;     BAR8; WAIT_L8(0); MMA8(0, 1, At, B1); BAR8;
;     LDA8(At, 0, 1); STAGE8(SA8(0, 0), A, lda, brow, tt + 2);
;     BAR8; WAIT_L8(0); MMA8(1, 0, At, B0); BAR8; SCHED8;
;     STAGE8(SB8(0, 1), Bt, K, bcol + 128, tt + 2);
;     WAIT_V8(6); BAR8; MMA8(1, 1, At, B1); BAR8;
;     LDB8(B0, 1, 0); SCHED8; LDA8(At, 1, 0); STAGE8(SA8(0, 1), A, lda, brow + 128, tt + 2);
	s_waitcnt lgkmcnt(0)
	s_waitcnt lgkmcnt(0)
	v_mfma_f32_16x16x32_f16 v[96:99], v[190:193], v[226:229], v[96:99]
	v_mfma_f32_16x16x32_f16 v[92:95], v[190:193], v[238:241], v[92:95]
	v_mfma_f32_16x16x32_f16 v[88:91], v[198:201], v[226:229], v[88:91]
	v_mfma_f32_16x16x32_f16 v[84:87], v[198:201], v[238:241], v[84:87]
	v_mfma_f32_16x16x32_f16 v[80:83], v[206:209], v[226:229], v[80:83]
	v_mfma_f32_16x16x32_f16 v[76:79], v[206:209], v[238:241], v[76:79]
	v_mfma_f32_16x16x32_f16 v[72:75], v[214:217], v[226:229], v[72:75]
	v_mfma_f32_16x16x32_f16 v[68:71], v[214:217], v[238:241], v[68:71]
	v_mfma_f32_16x16x32_f16 v[96:99], v[194:197], v[230:233], v[96:99]
	v_mfma_f32_16x16x32_f16 v[92:95], v[194:197], v[242:245], v[92:95]
	v_mfma_f32_16x16x32_f16 v[88:91], v[202:205], v[230:233], v[88:91]
	v_mfma_f32_16x16x32_f16 v[84:87], v[202:205], v[242:245], v[84:87]
	v_mfma_f32_16x16x32_f16 v[80:83], v[210:213], v[230:233], v[80:83]
	v_mfma_f32_16x16x32_f16 v[76:79], v[210:213], v[242:245], v[76:79]
	v_mfma_f32_16x16x32_f16 v[72:75], v[218:221], v[230:233], v[72:75]
	v_mfma_f32_16x16x32_f16 v[68:71], v[218:221], v[242:245], v[68:71]
	v_lshl_add_u64 v[250:251], v[222:223], 0, s[10:11]
	s_mov_b32 m0, s100
	s_barrier
	ds_read_b128 v[190:193], v161 offset:16384
	ds_read_b128 v[194:197], v161 offset:17408
	ds_read_b128 v[198:201], v160 offset:16384
	ds_read_b128 v[202:205], v160 offset:17408
	ds_read_b128 v[206:209], v159 offset:16384
	ds_read_b128 v[210:213], v159 offset:17408
	ds_read_b128 v[214:217], v158 offset:16384
	ds_read_b128 v[218:221], v158 offset:17408
	global_load_lds_dwordx4 v[250:251], off
	v_lshl_add_u64 v[250:251], v[236:237], 0, s[10:11]
	s_or_b32 m0, s100, 0x2000
	s_nop 0
	global_load_lds_dwordx4 v[250:251], off
	s_barrier
	s_waitcnt lgkmcnt(0)
	s_waitcnt lgkmcnt(0)
	v_mfma_f32_16x16x32_f16 v[64:67], v[190:193], v[174:177], v[64:67]
	v_mfma_f32_16x16x32_f16 v[60:63], v[190:193], v[182:185], v[60:63]
	v_mfma_f32_16x16x32_f16 v[56:59], v[198:201], v[174:177], v[56:59]
	v_mfma_f32_16x16x32_f16 v[52:55], v[198:201], v[182:185], v[52:55]
	v_mfma_f32_16x16x32_f16 v[48:51], v[206:209], v[174:177], v[48:51]
	v_mfma_f32_16x16x32_f16 v[44:47], v[206:209], v[182:185], v[44:47]
	v_mfma_f32_16x16x32_f16 v[40:43], v[214:217], v[174:177], v[40:43]
	v_mfma_f32_16x16x32_f16 v[36:39], v[214:217], v[182:185], v[36:39]
	v_mfma_f32_16x16x32_f16 v[64:67], v[194:197], v[178:181], v[64:67]
	v_mfma_f32_16x16x32_f16 v[60:63], v[194:197], v[186:189], v[60:63]
	v_mfma_f32_16x16x32_f16 v[56:59], v[202:205], v[178:181], v[56:59]
	v_mfma_f32_16x16x32_f16 v[52:55], v[202:205], v[186:189], v[52:55]
	v_mfma_f32_16x16x32_f16 v[48:51], v[210:213], v[178:181], v[48:51]
	v_mfma_f32_16x16x32_f16 v[44:47], v[210:213], v[186:189], v[44:47]
	v_mfma_f32_16x16x32_f16 v[40:43], v[218:221], v[178:181], v[40:43]
	v_mfma_f32_16x16x32_f16 v[36:39], v[218:221], v[186:189], v[36:39]
	s_barrier
	v_lshl_add_u64 v[174:175], v[246:247], 0, s[40:41]
	s_or_b32 m0, s100, 0x14000
	s_nop 0
	global_load_lds_dwordx4 v[174:175], off
	v_lshl_add_u64 v[174:175], v[248:249], 0, s[40:41]
	s_or_b32 m0, s100, 0x16000
	s_nop 0
	global_load_lds_dwordx4 v[174:175], off
	s_waitcnt vmcnt(6)
	s_barrier
	v_mfma_f32_16x16x32_f16 v[32:35], v[190:193], v[226:229], v[32:35]
	v_mfma_f32_16x16x32_f16 v[28:31], v[190:193], v[238:241], v[28:31]
	v_mfma_f32_16x16x32_f16 v[24:27], v[198:201], v[226:229], v[24:27]
	v_mfma_f32_16x16x32_f16 v[20:23], v[198:201], v[238:241], v[20:23]
	v_mfma_f32_16x16x32_f16 v[16:19], v[206:209], v[226:229], v[16:19]
	v_mfma_f32_16x16x32_f16 v[12:15], v[206:209], v[238:241], v[12:15]
	v_mfma_f32_16x16x32_f16 v[8:11], v[214:217], v[226:229], v[8:11]
	v_mfma_f32_16x16x32_f16 v[4:7], v[214:217], v[238:241], v[4:7]
	v_mfma_f32_16x16x32_f16 v[32:35], v[194:197], v[230:233], v[32:35]
	v_mfma_f32_16x16x32_f16 v[28:31], v[194:197], v[242:245], v[28:31]
	v_mfma_f32_16x16x32_f16 v[24:27], v[202:205], v[230:233], v[24:27]
	v_mfma_f32_16x16x32_f16 v[20:23], v[202:205], v[242:245], v[20:23]
	v_mfma_f32_16x16x32_f16 v[16:19], v[210:213], v[230:233], v[16:19]
	v_mfma_f32_16x16x32_f16 v[12:15], v[210:213], v[242:245], v[12:15]
	v_mfma_f32_16x16x32_f16 v[8:11], v[218:221], v[230:233], v[8:11]
	v_mfma_f32_16x16x32_f16 v[4:7], v[218:221], v[242:245], v[4:7]
	s_barrier
	ds_read_b128 v[174:177], v163
	ds_read_b128 v[178:181], v163 offset:1024
	ds_read_b128 v[182:185], v163 offset:2048
	ds_read_b128 v[186:189], v163 offset:3072
	v_lshl_add_u64 v[226:227], v[222:223], 0, s[18:19]
	s_or_b32 m0, s100, 0x4000
	ds_read_b128 v[190:193], v161 offset:32768
	ds_read_b128 v[194:197], v161 offset:33792
	ds_read_b128 v[198:201], v160 offset:32768
	ds_read_b128 v[202:205], v160 offset:33792
	ds_read_b128 v[206:209], v159 offset:32768
	ds_read_b128 v[210:213], v159 offset:33792
	ds_read_b128 v[214:217], v158 offset:32768
	ds_read_b128 v[218:221], v158 offset:33792
	global_load_lds_dwordx4 v[226:227], off
	v_lshl_add_u64 v[226:227], v[236:237], 0, s[18:19]
	s_or_b32 m0, s100, 0x6000
	s_nop 0
	global_load_lds_dwordx4 v[226:227], off
	s_waitcnt lgkmcnt(8)
	s_barrier
; #define LDA8(dst, b, h) _Pragma("unroll") for (int m = 0; m < 4; ++m) _Pragma("unroll") for (int k = 0; k < 2; ++k) \
;     dst[m][k] = *(const bf16x8*)((const char*)SA8(b, h) + lds_byte8(wr * 64 + m * 16 + fr, k * 32 + fq * 8))
; #define LDB8(dst, b, h) _Pragma("unroll") for (int n = 0; n < 2; ++n) _Pragma("unroll") for (int k = 0; k < 2; ++k) \
;     dst[n][k] = *(const bf16x8*)((const char*)SB8(b, h) + lds_byte8(wc * 32 + n * 16 + fr, k * 32 + fq * 8))
; #define WAIT_V8(n) asm volatile("s_waitcnt vmcnt(" #n ")" ::: "memory")
; #define WAIT_L8(n) asm volatile("s_waitcnt lgkmcnt(" #n ")" ::: "memory")
; #define BAR8 __builtin_amdgcn_s_barrier()
; #define SCHED8 __builtin_amdgcn_sched_barrier(0)
;     ...
;     LDB8(B0, 1, 0); SCHED8; LDA8(At, 1, 0); STAGE8(SA8(0, 1), A, lda, brow + 128, tt + 2);
;     WAIT_L8(8); BAR8; WAIT_L8(0); MMA8(0, 0, At, B0); BAR8; SCHED8;
;     LDB8(B1, 1, 1); STAGE8(SB8(1, 0), Bt, K, bcol, tt + 3);
;     BAR8; WAIT_L8(0); MMA8(0, 1, At, B1); BAR8;
;     LDA8(At, 1, 1); STAGE8(SA8(1, 0), A, lda, brow, tt + 3);
;     BAR8; WAIT_L8(0); MMA8(1, 0, At, B0); BAR8; SCHED8;
;     STAGE8(SB8(1, 1), Bt, K, bcol + 128, tt + 3);
;     WAIT_V8(6); BAR8; MMA8(1, 1, At, B1); BAR8;
	s_waitcnt lgkmcnt(0)
	s_waitcnt lgkmcnt(0)
	v_mfma_f32_16x16x32_f16 v[128:131], v[190:193], v[174:177], v[128:131]
	v_mfma_f32_16x16x32_f16 v[124:127], v[190:193], v[182:185], v[124:127]
	v_mfma_f32_16x16x32_f16 v[120:123], v[198:201], v[174:177], v[120:123]
	v_mfma_f32_16x16x32_f16 v[116:119], v[198:201], v[182:185], v[116:119]
	v_mfma_f32_16x16x32_f16 v[112:115], v[206:209], v[174:177], v[112:115]
	v_mfma_f32_16x16x32_f16 v[108:111], v[206:209], v[182:185], v[108:111]
	v_mfma_f32_16x16x32_f16 v[104:107], v[214:217], v[174:177], v[104:107]
	v_mfma_f32_16x16x32_f16 v[100:103], v[214:217], v[182:185], v[100:103]
	v_mfma_f32_16x16x32_f16 v[128:131], v[194:197], v[178:181], v[128:131]
	v_mfma_f32_16x16x32_f16 v[124:127], v[194:197], v[186:189], v[124:127]
	v_mfma_f32_16x16x32_f16 v[120:123], v[202:205], v[178:181], v[120:123]
	v_mfma_f32_16x16x32_f16 v[116:119], v[202:205], v[186:189], v[116:119]
	v_mfma_f32_16x16x32_f16 v[112:115], v[210:213], v[178:181], v[112:115]
	v_mfma_f32_16x16x32_f16 v[108:111], v[210:213], v[186:189], v[108:111]
	v_mfma_f32_16x16x32_f16 v[104:107], v[218:221], v[178:181], v[104:107]
	v_mfma_f32_16x16x32_f16 v[100:103], v[218:221], v[186:189], v[100:103]
	s_barrier
	v_lshl_add_u64 v[250:251], v[246:247], 0, s[42:43]
	s_or_b32 m0, s100, 0x18000
	ds_read_b128 v[226:229], v162
	ds_read_b128 v[230:233], v162 offset:1024
	ds_read_b128 v[238:241], v162 offset:2048
	ds_read_b128 v[242:245], v162 offset:3072
	global_load_lds_dwordx4 v[250:251], off
	v_lshl_add_u64 v[250:251], v[248:249], 0, s[42:43]
	s_or_b32 m0, s100, 0x1a000
	s_nop 0
	global_load_lds_dwordx4 v[250:251], off
	s_barrier
	s_waitcnt lgkmcnt(0)
	s_waitcnt lgkmcnt(0)
	v_mfma_f32_16x16x32_f16 v[96:99], v[190:193], v[226:229], v[96:99]
	v_mfma_f32_16x16x32_f16 v[92:95], v[190:193], v[238:241], v[92:95]
	v_mfma_f32_16x16x32_f16 v[88:91], v[198:201], v[226:229], v[88:91]
	v_mfma_f32_16x16x32_f16 v[84:87], v[198:201], v[238:241], v[84:87]
	v_mfma_f32_16x16x32_f16 v[80:83], v[206:209], v[226:229], v[80:83]
	v_mfma_f32_16x16x32_f16 v[76:79], v[206:209], v[238:241], v[76:79]
	v_mfma_f32_16x16x32_f16 v[72:75], v[214:217], v[226:229], v[72:75]
	v_mfma_f32_16x16x32_f16 v[68:71], v[214:217], v[238:241], v[68:71]
	v_mfma_f32_16x16x32_f16 v[96:99], v[194:197], v[230:233], v[96:99]
	v_mfma_f32_16x16x32_f16 v[92:95], v[194:197], v[242:245], v[92:95]
	v_mfma_f32_16x16x32_f16 v[88:91], v[202:205], v[230:233], v[88:91]
	v_mfma_f32_16x16x32_f16 v[84:87], v[202:205], v[242:245], v[84:87]
	v_mfma_f32_16x16x32_f16 v[80:83], v[210:213], v[230:233], v[80:83]
	v_mfma_f32_16x16x32_f16 v[76:79], v[210:213], v[242:245], v[76:79]
	v_mfma_f32_16x16x32_f16 v[72:75], v[218:221], v[230:233], v[72:75]
	v_mfma_f32_16x16x32_f16 v[68:71], v[218:221], v[242:245], v[68:71]
	v_lshl_add_u64 v[222:223], v[222:223], 0, s[22:23]
	s_or_b32 m0, s100, 0x8000
	s_barrier
	ds_read_b128 v[190:193], v161 offset:49152
	ds_read_b128 v[194:197], v161 offset:50176
	ds_read_b128 v[198:201], v160 offset:49152
	ds_read_b128 v[202:205], v160 offset:50176
	ds_read_b128 v[206:209], v159 offset:49152
	ds_read_b128 v[210:213], v159 offset:50176
	ds_read_b128 v[214:217], v158 offset:49152
	ds_read_b128 v[218:221], v158 offset:50176
	global_load_lds_dwordx4 v[222:223], off
	v_lshl_add_u64 v[222:223], v[236:237], 0, s[22:23]
	s_or_b32 m0, s100, 0xa000
	s_nop 0
	global_load_lds_dwordx4 v[222:223], off
	s_barrier
	s_waitcnt lgkmcnt(0)
	s_waitcnt lgkmcnt(0)
	v_mfma_f32_16x16x32_f16 v[64:67], v[190:193], v[174:177], v[64:67]
	v_mfma_f32_16x16x32_f16 v[60:63], v[190:193], v[182:185], v[60:63]
	v_mfma_f32_16x16x32_f16 v[56:59], v[198:201], v[174:177], v[56:59]
	v_mfma_f32_16x16x32_f16 v[52:55], v[198:201], v[182:185], v[52:55]
	v_mfma_f32_16x16x32_f16 v[48:51], v[206:209], v[174:177], v[48:51]
	v_mfma_f32_16x16x32_f16 v[44:47], v[206:209], v[182:185], v[44:47]
	v_mfma_f32_16x16x32_f16 v[40:43], v[214:217], v[174:177], v[40:43]
	v_mfma_f32_16x16x32_f16 v[36:39], v[214:217], v[182:185], v[36:39]
	v_mfma_f32_16x16x32_f16 v[64:67], v[194:197], v[178:181], v[64:67]
	v_mfma_f32_16x16x32_f16 v[60:63], v[194:197], v[186:189], v[60:63]
	v_mfma_f32_16x16x32_f16 v[56:59], v[202:205], v[178:181], v[56:59]
	v_mfma_f32_16x16x32_f16 v[52:55], v[202:205], v[186:189], v[52:55]
	v_mfma_f32_16x16x32_f16 v[48:51], v[210:213], v[178:181], v[48:51]
	v_mfma_f32_16x16x32_f16 v[44:47], v[210:213], v[186:189], v[44:47]
	v_mfma_f32_16x16x32_f16 v[40:43], v[218:221], v[178:181], v[40:43]
	v_mfma_f32_16x16x32_f16 v[36:39], v[218:221], v[186:189], v[36:39]
	s_barrier
	v_lshl_add_u64 v[174:175], v[246:247], 0, s[44:45]
	s_or_b32 m0, s100, 0x1c000
	s_nop 0
	global_load_lds_dwordx4 v[174:175], off
	v_lshl_add_u64 v[174:175], v[248:249], 0, s[44:45]
	s_or_b32 m0, s100, 0x1e000
	s_nop 0
	global_load_lds_dwordx4 v[174:175], off
	s_waitcnt vmcnt(6)
	s_barrier
	v_mfma_f32_16x16x32_f16 v[32:35], v[190:193], v[226:229], v[32:35]
	v_mfma_f32_16x16x32_f16 v[28:31], v[190:193], v[238:241], v[28:31]
	v_mfma_f32_16x16x32_f16 v[24:27], v[198:201], v[226:229], v[24:27]
	v_mfma_f32_16x16x32_f16 v[20:23], v[198:201], v[238:241], v[20:23]
	v_mfma_f32_16x16x32_f16 v[16:19], v[206:209], v[226:229], v[16:19]
	v_mfma_f32_16x16x32_f16 v[12:15], v[206:209], v[238:241], v[12:15]
	v_mfma_f32_16x16x32_f16 v[8:11], v[214:217], v[226:229], v[8:11]
	v_mfma_f32_16x16x32_f16 v[4:7], v[214:217], v[238:241], v[4:7]
	v_mfma_f32_16x16x32_f16 v[32:35], v[194:197], v[230:233], v[32:35]
	v_mfma_f32_16x16x32_f16 v[28:31], v[194:197], v[242:245], v[28:31]
	v_mfma_f32_16x16x32_f16 v[24:27], v[202:205], v[230:233], v[24:27]
	v_mfma_f32_16x16x32_f16 v[20:23], v[202:205], v[242:245], v[20:23]
	v_mfma_f32_16x16x32_f16 v[16:19], v[210:213], v[230:233], v[16:19]
	v_mfma_f32_16x16x32_f16 v[12:15], v[210:213], v[242:245], v[12:15]
	v_mfma_f32_16x16x32_f16 v[8:11], v[218:221], v[230:233], v[8:11]
	v_mfma_f32_16x16x32_f16 v[4:7], v[218:221], v[242:245], v[4:7]
	s_add_i32 s1, s1, 2
	s_add_u32 s12, s12, 0x100
	s_addc_u32 s13, s13, 0
	s_cmp_lt_u32 s1, 12
	s_barrier
; #define LDA8(dst, b, h) _Pragma("unroll") for (int m = 0; m < 4; ++m) _Pragma("unroll") for (int k = 0; k < 2; ++k) \
;     dst[m][k] = *(const bf16x8*)((const char*)SA8(b, h) + lds_byte8(wr * 64 + m * 16 + fr, k * 32 + fq * 8))
; #define LDB8(dst, b, h) _Pragma("unroll") for (int n = 0; n < 2; ++n) _Pragma("unroll") for (int k = 0; k < 2; ++k) \
;     dst[n][k] = *(const bf16x8*)((const char*)SB8(b, h) + lds_byte8(wc * 32 + n * 16 + fr, k * 32 + fq * 8))
; #define WAIT_V8(n) asm volatile("s_waitcnt vmcnt(" #n ")" ::: "memory")
; #define WAIT_L8(n) asm volatile("s_waitcnt lgkmcnt(" #n ")" ::: "memory")
; #define BAR8 __builtin_amdgcn_s_barrier()
;     ...
;     WAIT_V8(6); BAR8; MMA8(1, 1, At, B1); BAR8;
;   }
;   { LDB8(B0, 0, 0); LDA8(At, 0, 0); STAGE8(SA8(1, 1), A, lda, brow + 128, nt - 1);
;     BAR8; WAIT_L8(0); MMA8(0, 0, At, B0); BAR8;
;     LDB8(B1, 0, 1); BAR8; WAIT_L8(0); MMA8(0, 1, At, B1); BAR8;
;     LDA8(At, 0, 1); WAIT_V8(4); BAR8; WAIT_L8(0); MMA8(1, 0, At, B0); MMA8(1, 1, At, B1); BAR8; }
	s_cbranch_scc1 .LBB0_1259
	s_add_u32 s8, s8, 0x40780
	s_addc_u32 s9, s9, 0
	v_lshl_add_u64 v[132:133], s[8:9], 0, v[132:133]
	v_lshl_add_u64 v[0:1], v[0:1], 1, v[132:133]
	s_or_b32 m0, s100, 0xc000
	ds_read_b128 v[138:141], v171
	ds_read_b128 v[142:145], v171 offset:1024
	ds_read_b128 v[150:153], v171 offset:2048
	ds_read_b128 v[154:157], v171 offset:3072
	ds_read_b128 v[164:167], v161
	ds_read_b128 v[174:177], v161 offset:1024
	ds_read_b128 v[178:181], v160
	ds_read_b128 v[182:185], v160 offset:1024
	ds_read_b128 v[186:189], v159
	ds_read_b128 v[190:193], v159 offset:1024
	ds_read_b128 v[194:197], v158
	ds_read_b128 v[198:201], v158 offset:1024
	global_load_lds_dwordx4 v[0:1], off
	v_lshl_add_u64 v[0:1], s[8:9], 0, v[136:137]
	v_lshl_add_u64 v[0:1], v[134:135], 1, v[0:1]
	s_or_b32 m0, s100, 0xe000
	s_nop 0
	global_load_lds_dwordx4 v[0:1], off
	s_barrier
	s_waitcnt lgkmcnt(0)
	s_waitcnt lgkmcnt(0)
	v_mfma_f32_16x16x32_f16 v[128:131], v[164:167], v[138:141], v[128:131]
	v_mfma_f32_16x16x32_f16 v[124:127], v[164:167], v[150:153], v[124:127]
	v_mfma_f32_16x16x32_f16 v[120:123], v[178:181], v[138:141], v[120:123]
	v_mfma_f32_16x16x32_f16 v[116:119], v[178:181], v[150:153], v[116:119]
	v_mfma_f32_16x16x32_f16 v[104:107], v[194:197], v[138:141], v[104:107]
	v_mfma_f32_16x16x32_f16 v[100:103], v[194:197], v[150:153], v[100:103]
	v_mfma_f32_16x16x32_f16 v[128:131], v[174:177], v[142:145], v[128:131]
	v_mfma_f32_16x16x32_f16 v[124:127], v[174:177], v[154:157], v[124:127]
	v_mfma_f32_16x16x32_f16 v[120:123], v[182:185], v[142:145], v[120:123]
	v_mfma_f32_16x16x32_f16 v[116:119], v[182:185], v[154:157], v[116:119]
	v_mfma_f32_16x16x32_f16 v[112:115], v[186:189], v[138:141], v[112:115]
	v_mfma_f32_16x16x32_f16 v[108:111], v[186:189], v[150:153], v[108:111]
	v_mfma_f32_16x16x32_f16 v[104:107], v[198:201], v[142:145], v[104:107]
	v_mfma_f32_16x16x32_f16 v[100:103], v[198:201], v[154:157], v[100:103]
	v_mfma_f32_16x16x32_f16 v[132:135], v[190:193], v[142:145], v[112:115]
	v_mfma_f32_16x16x32_f16 v[170:173], v[190:193], v[154:157], v[108:111]
	s_barrier
	s_nop 1
	ds_read_b128 v[108:111], v169
	ds_read_b128 v[112:115], v169 offset:1024
	ds_read_b128 v[202:205], v169 offset:2048
	ds_read_b128 v[206:209], v169 offset:3072
	s_barrier
	s_waitcnt lgkmcnt(0)
	s_waitcnt lgkmcnt(0)
	v_mfma_f32_16x16x32_f16 v[88:91], v[178:181], v[108:111], v[88:91]
	v_mfma_f32_16x16x32_f16 v[84:87], v[178:181], v[202:205], v[84:87]
	v_mfma_f32_16x16x32_f16 v[72:75], v[194:197], v[108:111], v[72:75]
	v_mfma_f32_16x16x32_f16 v[68:71], v[194:197], v[202:205], v[68:71]
	v_mfma_f32_16x16x32_f16 v[96:99], v[164:167], v[108:111], v[96:99]
	v_mfma_f32_16x16x32_f16 v[92:95], v[164:167], v[202:205], v[92:95]
	v_mfma_f32_16x16x32_f16 v[88:91], v[182:185], v[112:115], v[88:91]
	v_mfma_f32_16x16x32_f16 v[84:87], v[182:185], v[206:209], v[84:87]
	v_mfma_f32_16x16x32_f16 v[80:83], v[186:189], v[108:111], v[80:83]
	v_mfma_f32_16x16x32_f16 v[76:79], v[186:189], v[202:205], v[76:79]
	v_mfma_f32_16x16x32_f16 v[72:75], v[198:201], v[112:115], v[72:75]
	v_mfma_f32_16x16x32_f16 v[68:71], v[198:201], v[206:209], v[68:71]
	v_mfma_f32_16x16x32_f16 v[210:213], v[174:177], v[112:115], v[96:99]
	v_mfma_f32_16x16x32_f16 v[164:167], v[174:177], v[206:209], v[92:95]
	v_mfma_f32_16x16x32_f16 v[174:177], v[190:193], v[112:115], v[80:83]
	v_mfma_f32_16x16x32_f16 v[178:181], v[190:193], v[206:209], v[76:79]
	s_barrier
	s_nop 0
	ds_read_b128 v[76:79], v161 offset:16384
	ds_read_b128 v[80:83], v161 offset:17408
	ds_read_b128 v[92:95], v160 offset:16384
	ds_read_b128 v[96:99], v160 offset:17408
	ds_read_b128 v[182:185], v159 offset:16384
	ds_read_b128 v[186:189], v159 offset:17408
	ds_read_b128 v[190:193], v158 offset:16384
	ds_read_b128 v[194:197], v158 offset:17408
	s_waitcnt vmcnt(4)
	s_barrier
	s_waitcnt lgkmcnt(0)
	s_waitcnt lgkmcnt(0)
	v_mfma_f32_16x16x32_f16 v[64:67], v[76:79], v[138:141], v[64:67]
	v_mfma_f32_16x16x32_f16 v[60:63], v[76:79], v[150:153], v[60:63]
	v_mfma_f32_16x16x32_f16 v[56:59], v[92:95], v[138:141], v[56:59]
	v_mfma_f32_16x16x32_f16 v[52:55], v[92:95], v[150:153], v[52:55]
	v_mfma_f32_16x16x32_f16 v[40:43], v[190:193], v[138:141], v[40:43]
	v_mfma_f32_16x16x32_f16 v[36:39], v[190:193], v[150:153], v[36:39]
	v_mfma_f32_16x16x32_f16 v[64:67], v[80:83], v[142:145], v[64:67]
	v_mfma_f32_16x16x32_f16 v[60:63], v[80:83], v[154:157], v[60:63]
	v_mfma_f32_16x16x32_f16 v[56:59], v[96:99], v[142:145], v[56:59]
	v_mfma_f32_16x16x32_f16 v[52:55], v[96:99], v[154:157], v[52:55]
	v_mfma_f32_16x16x32_f16 v[48:51], v[182:185], v[138:141], v[48:51]
	v_mfma_f32_16x16x32_f16 v[44:47], v[182:185], v[150:153], v[44:47]
	v_mfma_f32_16x16x32_f16 v[40:43], v[194:197], v[142:145], v[40:43]
	v_mfma_f32_16x16x32_f16 v[36:39], v[194:197], v[154:157], v[36:39]
	v_mfma_f32_16x16x32_f16 v[198:201], v[186:189], v[142:145], v[48:51]
	v_mfma_f32_16x16x32_f16 v[214:217], v[186:189], v[154:157], v[44:47]
	v_mfma_f32_16x16x32_f16 v[24:27], v[92:95], v[108:111], v[24:27]
	v_mfma_f32_16x16x32_f16 v[20:23], v[92:95], v[202:205], v[20:23]
	v_mfma_f32_16x16x32_f16 v[8:11], v[190:193], v[108:111], v[8:11]
	v_mfma_f32_16x16x32_f16 v[4:7], v[190:193], v[202:205], v[4:7]
	v_mfma_f32_16x16x32_f16 v[32:35], v[76:79], v[108:111], v[32:35]
	v_mfma_f32_16x16x32_f16 v[28:31], v[76:79], v[202:205], v[28:31]
	v_mfma_f32_16x16x32_f16 v[24:27], v[96:99], v[112:115], v[24:27]
	v_mfma_f32_16x16x32_f16 v[20:23], v[96:99], v[206:209], v[20:23]
	v_mfma_f32_16x16x32_f16 v[16:19], v[182:185], v[108:111], v[16:19]
	v_mfma_f32_16x16x32_f16 v[12:15], v[182:185], v[202:205], v[12:15]
	v_mfma_f32_16x16x32_f16 v[8:11], v[194:197], v[112:115], v[8:11]
	v_mfma_f32_16x16x32_f16 v[4:7], v[194:197], v[206:209], v[4:7]
	v_mfma_f32_16x16x32_f16 v[136:139], v[80:83], v[112:115], v[32:35]
	v_mfma_f32_16x16x32_f16 v[140:143], v[80:83], v[206:209], v[28:31]
	v_mfma_f32_16x16x32_f16 v[150:153], v[186:189], v[112:115], v[16:19]
	v_mfma_f32_16x16x32_f16 v[154:157], v[186:189], v[206:209], v[12:15]
	s_barrier
; #define LDA8(dst, b, h) _Pragma("unroll") for (int m = 0; m < 4; ++m) _Pragma("unroll") for (int k = 0; k < 2; ++k) \
;     dst[m][k] = *(const bf16x8*)((const char*)SA8(b, h) + lds_byte8(wr * 64 + m * 16 + fr, k * 32 + fq * 8))
; #define LDB8(dst, b, h) _Pragma("unroll") for (int n = 0; n < 2; ++n) _Pragma("unroll") for (int k = 0; k < 2; ++k) \
;     dst[n][k] = *(const bf16x8*)((const char*)SB8(b, h) + lds_byte8(wc * 32 + n * 16 + fr, k * 32 + fq * 8))
; #define WAIT_V8(n) asm volatile("s_waitcnt vmcnt(" #n ")" ::: "memory")
; #define WAIT_L8(n) asm volatile("s_waitcnt lgkmcnt(" #n ")" ::: "memory")
; #define BAR8 __builtin_amdgcn_s_barrier()
;     ...
;     LDA8(At, 0, 1); WAIT_V8(4); BAR8; WAIT_L8(0); MMA8(1, 0, At, B0); MMA8(1, 1, At, B1); BAR8; }
;   { LDB8(B0, 1, 0); LDA8(At, 1, 0); WAIT_V8(2); BAR8; WAIT_L8(0); MMA8(0, 0, At, B0); BAR8;
;     LDB8(B1, 1, 1); WAIT_V8(0); BAR8; WAIT_L8(0); MMA8(0, 1, At, B1); BAR8;
;     LDA8(At, 1, 1); BAR8; WAIT_L8(0); MMA8(1, 0, At, B0); MMA8(1, 1, At, B1); BAR8; }
;   if (wr == 0) BAR8;
;   __syncthreads();
	s_nop 0
	ds_read_b128 v[12:15], v163
	ds_read_b128 v[16:19], v163 offset:1024
	ds_read_b128 v[182:185], v163 offset:2048
	ds_read_b128 v[186:189], v163 offset:3072
	ds_read_b128 v[28:31], v161 offset:32768
	ds_read_b128 v[32:35], v161 offset:33792
	ds_read_b128 v[44:47], v160 offset:32768
	ds_read_b128 v[48:51], v160 offset:33792
	ds_read_b128 v[190:193], v159 offset:32768
	ds_read_b128 v[194:197], v159 offset:33792
	ds_read_b128 v[202:205], v158 offset:32768
	ds_read_b128 v[206:209], v158 offset:33792
	s_waitcnt vmcnt(2)
	s_barrier
	s_waitcnt lgkmcnt(0)
	s_waitcnt lgkmcnt(0)
	v_mfma_f32_16x16x32_f16 v[76:79], v[28:31], v[12:15], v[128:131]
	v_mfma_f32_16x16x32_f16 v[128:131], v[32:35], v[16:19], v[76:79]
	v_mfma_f32_16x16x32_f16 v[76:79], v[28:31], v[182:185], v[124:127]
	v_mfma_f32_16x16x32_f16 v[124:127], v[32:35], v[186:189], v[76:79]
	v_mfma_f32_16x16x32_f16 v[76:79], v[44:47], v[12:15], v[120:123]
	v_mfma_f32_16x16x32_f16 v[112:115], v[48:51], v[16:19], v[76:79]
	v_mfma_f32_16x16x32_f16 v[76:79], v[44:47], v[182:185], v[116:119]
	v_mfma_f32_16x16x32_f16 v[108:111], v[48:51], v[186:189], v[76:79]
	v_mfma_f32_16x16x32_f16 v[76:79], v[190:193], v[12:15], v[132:135]
	v_mfma_f32_16x16x32_f16 v[96:99], v[194:197], v[16:19], v[76:79]
	v_mfma_f32_16x16x32_f16 v[76:79], v[190:193], v[182:185], v[170:173]
	v_mfma_f32_16x16x32_f16 v[92:95], v[194:197], v[186:189], v[76:79]
	v_mfma_f32_16x16x32_f16 v[76:79], v[202:205], v[12:15], v[104:107]
	v_mfma_f32_16x16x32_f16 v[80:83], v[206:209], v[16:19], v[76:79]
	v_mfma_f32_16x16x32_f16 v[76:79], v[202:205], v[182:185], v[100:103]
	v_mfma_f32_16x16x32_f16 v[76:79], v[206:209], v[186:189], v[76:79]
	s_barrier
	ds_read_b128 v[132:135], v162
	ds_read_b128 v[168:171], v162 offset:1024
	ds_read_b128 v[218:221], v162 offset:2048
	ds_read_b128 v[226:229], v162 offset:3072
	s_waitcnt vmcnt(0)
	s_barrier
	s_waitcnt lgkmcnt(0)
	s_waitcnt lgkmcnt(0)
	v_mfma_f32_16x16x32_f16 v[100:103], v[28:31], v[132:135], v[210:213]
	v_mfma_f32_16x16x32_f16 v[28:31], v[28:31], v[218:221], v[164:167]
	v_mfma_f32_16x16x32_f16 v[116:119], v[32:35], v[226:229], v[28:31]
	v_mfma_f32_16x16x32_f16 v[28:31], v[44:47], v[132:135], v[88:91]
	v_mfma_f32_16x16x32_f16 v[104:107], v[48:51], v[168:171], v[28:31]
	v_mfma_f32_16x16x32_f16 v[28:31], v[44:47], v[218:221], v[84:87]
	v_mfma_f32_16x16x32_f16 v[120:123], v[32:35], v[168:171], v[100:103]
	v_mfma_f32_16x16x32_f16 v[100:103], v[48:51], v[226:229], v[28:31]
	v_mfma_f32_16x16x32_f16 v[28:31], v[190:193], v[132:135], v[174:177]
	v_mfma_f32_16x16x32_f16 v[88:91], v[194:197], v[168:171], v[28:31]
	v_mfma_f32_16x16x32_f16 v[28:31], v[190:193], v[218:221], v[178:181]
	v_mfma_f32_16x16x32_f16 v[84:87], v[194:197], v[226:229], v[28:31]
	v_mfma_f32_16x16x32_f16 v[28:31], v[202:205], v[132:135], v[72:75]
	v_mfma_f32_16x16x32_f16 v[72:75], v[206:209], v[168:171], v[28:31]
	v_mfma_f32_16x16x32_f16 v[28:31], v[202:205], v[218:221], v[68:71]
	v_mfma_f32_16x16x32_f16 v[68:71], v[206:209], v[226:229], v[28:31]
	s_barrier
	ds_read_b128 v[162:165], v161 offset:49152
	ds_read_b128 v[172:175], v161 offset:50176
	ds_read_b128 v[176:179], v160 offset:49152
	ds_read_b128 v[190:193], v160 offset:50176
	ds_read_b128 v[194:197], v159 offset:49152
	ds_read_b128 v[202:205], v159 offset:50176
	ds_read_b128 v[206:209], v158 offset:49152
	ds_read_b128 v[158:161], v158 offset:50176
	s_barrier
	s_waitcnt lgkmcnt(0)
	s_waitcnt lgkmcnt(0)
	v_mfma_f32_16x16x32_f16 v[28:31], v[162:165], v[12:15], v[64:67]
	v_mfma_f32_16x16x32_f16 v[64:67], v[172:175], v[16:19], v[28:31]
	v_mfma_f32_16x16x32_f16 v[28:31], v[162:165], v[182:185], v[60:63]
	v_mfma_f32_16x16x32_f16 v[60:63], v[172:175], v[186:189], v[28:31]
	v_mfma_f32_16x16x32_f16 v[28:31], v[176:179], v[12:15], v[56:59]
	v_mfma_f32_16x16x32_f16 v[48:51], v[190:193], v[16:19], v[28:31]
	v_mfma_f32_16x16x32_f16 v[28:31], v[176:179], v[182:185], v[52:55]
	v_mfma_f32_16x16x32_f16 v[44:47], v[190:193], v[186:189], v[28:31]
	v_mfma_f32_16x16x32_f16 v[28:31], v[194:197], v[12:15], v[198:201]
	v_mfma_f32_16x16x32_f16 v[12:15], v[206:209], v[12:15], v[40:43]
	v_mfma_f32_16x16x32_f16 v[32:35], v[202:205], v[16:19], v[28:31]
	v_mfma_f32_16x16x32_f16 v[28:31], v[194:197], v[182:185], v[214:217]
	v_mfma_f32_16x16x32_f16 v[16:19], v[158:161], v[16:19], v[12:15]
	v_mfma_f32_16x16x32_f16 v[12:15], v[206:209], v[182:185], v[36:39]
	v_mfma_f32_16x16x32_f16 v[28:31], v[202:205], v[186:189], v[28:31]
	v_mfma_f32_16x16x32_f16 v[12:15], v[158:161], v[186:189], v[12:15]
	v_mfma_f32_16x16x32_f16 v[36:39], v[162:165], v[132:135], v[136:139]
	v_mfma_f32_16x16x32_f16 v[56:59], v[172:175], v[168:171], v[36:39]
	v_mfma_f32_16x16x32_f16 v[36:39], v[162:165], v[218:221], v[140:143]
	v_mfma_f32_16x16x32_f16 v[20:23], v[176:179], v[218:221], v[20:23]
	v_mfma_f32_16x16x32_f16 v[52:55], v[172:175], v[226:229], v[36:39]
	v_mfma_f32_16x16x32_f16 v[24:27], v[176:179], v[132:135], v[24:27]
	v_mfma_f32_16x16x32_f16 v[36:39], v[190:193], v[226:229], v[20:23]
	v_mfma_f32_16x16x32_f16 v[20:23], v[194:197], v[132:135], v[150:153]
	v_mfma_f32_16x16x32_f16 v[40:43], v[190:193], v[168:171], v[24:27]
	v_mfma_f32_16x16x32_f16 v[24:27], v[202:205], v[168:171], v[20:23]
	v_mfma_f32_16x16x32_f16 v[20:23], v[194:197], v[218:221], v[154:157]
	v_mfma_f32_16x16x32_f16 v[8:11], v[206:209], v[132:135], v[8:11]
	v_mfma_f32_16x16x32_f16 v[4:7], v[206:209], v[218:221], v[4:7]
	v_mfma_f32_16x16x32_f16 v[20:23], v[202:205], v[226:229], v[20:23]
	v_mfma_f32_16x16x32_f16 v[8:11], v[158:161], v[168:171], v[8:11]
	v_mfma_f32_16x16x32_f16 v[4:7], v[158:161], v[226:229], v[4:7]
	s_movk_i32 s1, 0x100
	v_cmp_gt_u32_e32 vcc, s1, v3
	s_barrier
	s_and_saveexec_b64 s[8:9], vcc
	s_cbranch_execz .LBB0_1262
	s_barrier

; #define BAR8 __builtin_amdgcn_s_barrier()
;     ...
;   if (!pre) {
;     STAGE8(SB8(0, 0), Bt, K, bcol, 0); STAGE8(SA8(0, 0), A, lda, brow, 0);
;     STAGE8(SB8(0, 1), Bt, K, bcol + 128, 0); STAGE8(SA8(0, 1), A, lda, brow + 128, 0);
;   }
;   if (wr == 1) BAR8;
.LBB0_1322:
	s_mov_b32 s0, 24
	s_mov_b32 s0, 25
	s_ashr_i32 s1, s0, 31
	s_lshl_b64 s[0:1], s[0:1], 3
	s_add_u32 s0, s70, s0
	s_addc_u32 s1, s71, s1
	v_readlane_b32 s6, v255, 60
	v_readlane_b32 s7, v255, 61
	s_nop 4
	s_mov_b32 s0, 25
	s_ashr_i32 s1, s0, 31
	s_lshl_b64 s[0:1], s[0:1], 3
	s_add_u32 s0, s70, s0
	s_addc_u32 s1, s71, s1
	s_mov_b32 s2, 25
	v_readlane_b32 s0, v255, 60
	v_readlane_b32 s1, v255, 61
	s_nop 4
	s_ashr_i32 s3, s2, 31
	s_lshl_b64 s[2:3], s[2:3], 3
	s_add_u32 s2, s70, s2
	s_addc_u32 s3, s71, s3
	v_mov_b32_e32 v3, v224
	v_readlane_b32 s2, v255, 60
	v_readlane_b32 s3, v255, 61
	s_nop 4
	s_lshl_b32 s8, s24, 8
	v_bfe_i32 v1, v3, 27, 1
	s_waitcnt vmcnt(10)
	v_lshlrev_b32_e32 v150, 4, v3
	s_nop 0
	v_readfirstlane_b32 s100, v150
	v_lshrrev_b32_e32 v1, 22, v1
	v_add_u32_e32 v1, v150, v1
	v_and_b32_e32 v1, 0xfffffc00, v1
	v_ashrrev_i32_e32 v0, 31, v3
	v_sub_u32_e32 v1, v150, v1
	v_lshrrev_b32_e32 v0, 26, v0
	v_lshrrev_b32_e32 v5, 4, v1
	v_add_u32_e32 v0, v3, v0
	v_bitop3_b32 v6, v5, v1, 32 bitop3:0x6c
	v_ashrrev_i32_e32 v1, 31, v1
	v_ashrrev_i32_e32 v0, 6, v0
	v_lshrrev_b32_e32 v1, 26, v1
	v_lshlrev_b32_e32 v5, 3, v0
	v_add_u32_e32 v1, v6, v1
	v_and_b32_e32 v5, -16, v5
	v_ashrrev_i32_e32 v1, 6, v1
	s_and_b32 s25, s8, 0x3f00
	s_lshl_b32 s8, s24, 2
	v_add_u32_e32 v5, v1, v5
	v_mul_i32_i24_e32 v1, 64, v1
	s_and_b32 s8, s8, 0xffffff00
	v_lshlrev_b32_e32 v0, 5, v0
	v_sub_u32_e32 v1, v6, v1
	v_mov_b32_e32 v15, 1
	s_mul_i32 s12, s8, 0x1600
	v_and_b32_e32 v0, 32, v0
	v_ashrrev_i16_sdwa v1, v15, sext(v1) dst_sel:DWORD dst_unused:UNUSED_PAD src0_sel:DWORD src1_sel:BYTE_0
	s_movk_i32 s27, 0xb00
	s_mul_hi_i32 s9, s8, 0x1600
	s_add_u32 s12, s14, s12
	v_add_u32_sdwa v0, v0, sext(v1) dst_sel:DWORD dst_unused:UNUSED_PAD src0_sel:DWORD src1_sel:WORD_0
	v_mad_i64_i32 v[132:133], s[30:31], v5, s27, 0
	s_addc_u32 s13, s15, s9
	v_lshlrev_b64 v[24:25], 1, v[132:133]
	v_ashrrev_i32_e32 v1, 31, v0
	v_lshl_add_u64 v[8:9], s[12:13], 0, v[24:25]
	v_lshlrev_b64 v[6:7], 1, v[0:1]
	s_waitcnt vmcnt(9)
	v_add_u32_e32 v152, 0x2000, v150
	v_lshl_add_u64 v[10:11], v[8:9], 0, v[6:7]
	v_ashrrev_i32_e32 v8, 31, v152
	v_lshrrev_b32_e32 v8, 22, v8
	v_add_u32_e32 v8, v152, v8
	v_ashrrev_i32_e32 v8, 10, v8
	v_mul_i32_i24_e32 v9, 0x400, v8
	v_sub_u32_e32 v9, v152, v9
	v_lshrrev_b32_e32 v12, 4, v9
	v_bitop3_b32 v9, v12, v9, 32 bitop3:0x6c
	v_ashrrev_i32_e32 v13, 31, v9
	v_add_u32_e32 v151, 0x10000, v150
	v_lshrrev_b32_e32 v13, 26, v13
	v_lshlrev_b32_e32 v12, 3, v8
	v_add_u32_e32 v13, v9, v13
	s_waitcnt vmcnt(8)
	v_add_u32_e32 v157, 0x12000, v150
	v_mov_b32_e32 v4, v2
	s_or_b32 m0, s100, 0x10000
	v_and_b32_e32 v12, -16, v12
	v_ashrrev_i32_e32 v14, 6, v13
	global_load_lds_dwordx4 v[10:11], off
	v_add_u32_e32 v22, v14, v12
	v_and_b32_e32 v12, 0xc0, v13
	s_or_b32 m0, s100, 0x12000
	s_mul_i32 s9, s25, 0xb00
	v_lshlrev_b32_e32 v8, 5, v8
	v_sub_u32_e32 v9, v9, v12
	v_mad_i64_i32 v[136:137], s[30:31], v22, s27, 0
	s_lshl_b32 s27, s9, 1
	v_and_b32_e32 v8, 32, v8
	v_ashrrev_i16_sdwa v9, v15, sext(v9) dst_sel:DWORD dst_unused:UNUSED_PAD src0_sel:DWORD src1_sel:BYTE_0
	s_waitcnt lgkmcnt(0)
	s_add_u32 s9, s2, s27
	v_add_u32_sdwa v134, v8, sext(v9) dst_sel:DWORD dst_unused:UNUSED_PAD src0_sel:DWORD src1_sel:WORD_0
	v_lshlrev_b64 v[26:27], 1, v[136:137]
	s_addc_u32 s29, s3, 0
	v_lshl_add_u64 v[12:13], s[12:13], 0, v[26:27]
	v_ashrrev_i32_e32 v135, 31, v134
	s_add_u32 s12, s9, 0x2000000
	v_lshlrev_b64 v[8:9], 1, v[134:135]
	s_addc_u32 s13, s29, 0
	v_lshl_add_u64 v[12:13], v[12:13], 0, v[8:9]
	v_lshl_add_u64 v[14:15], s[12:13], 0, v[24:25]
	global_load_lds_dwordx4 v[12:13], off
	v_lshl_add_u64 v[14:15], v[14:15], 0, v[6:7]
	s_mov_b32 m0, s100
	v_lshl_add_u64 v[16:17], s[12:13], 0, v[26:27]
	s_or_b32 s30, s8, 0x80
	global_load_lds_dwordx4 v[14:15], off
	s_or_b32 m0, s100, 0x2000
	s_mul_i32 s12, s30, 0x1600
	s_mul_hi_i32 s13, s30, 0x1600
	s_add_u32 s12, s14, s12
	s_addc_u32 s13, s15, s13
	v_add_u32_e32 v160, 0x14000, v150
	v_lshl_add_u64 v[16:17], v[16:17], 0, v[8:9]
	v_lshl_add_u64 v[18:19], s[12:13], 0, v[24:25]
	v_add_u32_e32 v161, 0x16000, v150
	global_load_lds_dwordx4 v[16:17], off
	v_lshl_add_u64 v[18:19], v[18:19], 0, v[6:7]
	s_or_b32 m0, s100, 0x14000
	v_lshl_add_u64 v[20:21], s[12:13], 0, v[26:27]
	global_load_lds_dwordx4 v[18:19], off
	s_or_b32 m0, s100, 0x16000
	s_add_u32 s12, s9, 0x20b0000
	s_addc_u32 s13, s29, 0
	v_add_u32_e32 v162, 0x4000, v150
	v_lshl_add_u64 v[20:21], v[20:21], 0, v[8:9]
	v_lshl_add_u64 v[24:25], s[12:13], 0, v[24:25]
	global_load_lds_dwordx4 v[20:21], off
	v_lshl_add_u64 v[24:25], v[24:25], 0, v[6:7]
	s_or_b32 m0, s100, 0x4000
	v_add_u32_e32 v163, 0x6000, v150
	global_load_lds_dwordx4 v[24:25], off
	v_lshl_add_u64 v[24:25], s[12:13], 0, v[26:27]
	v_lshl_add_u64 v[24:25], v[24:25], 0, v[8:9]
	s_or_b32 m0, s100, 0x6000
	v_ashrrev_i32_e32 v23, 8, v3
	global_load_lds_dwordx4 v[24:25], off
	v_cmp_eq_u32_e32 vcc, 1, v23
	s_and_saveexec_b64 s[12:13], vcc
	s_cbranch_execz .LBB0_1324
	s_barrier
; #define WAIT_V8(n) asm volatile("s_waitcnt vmcnt(" #n ")" ::: "memory")
; #define BAR8 __builtin_amdgcn_s_barrier()
;     ...
;   {
;     float zinit = 0.f;
;     asm volatile("" : "+v"(zinit));
; #pragma unroll
;     for (int a = 0; a < 2; ++a)
; #pragma unroll
;       for (int b = 0; b < 2; ++b)
; #pragma unroll
;         for (int m = 0; m < 4; ++m)
; #pragma unroll
;           for (int n = 0; n < 2; ++n)
; #pragma unroll
;             for (int j = 0; j < 4; ++j) acc[a][b][m][n][j] = zinit;
;   }
;   bf16x8 At[4][2], B0[2][2], B1[2][2];
;   const int nt = K / 64;
;   if (!pre) {
;     STAGE8(SB8(0, 0), Bt, K, bcol, 0); STAGE8(SA8(0, 0), A, lda, brow, 0);
;     STAGE8(SB8(0, 1), Bt, K, bcol + 128, 0); STAGE8(SA8(0, 1), A, lda, brow + 128, 0);
;   }
;   if (wr == 1) BAR8;
;   WAIT_V8(4); BAR8;
;   STAGE8(SB8(1, 0), Bt, K, bcol, 1); STAGE8(SA8(1, 0), A, lda, brow, 1); STAGE8(SB8(1, 1), Bt, K, bcol + 128, 1);
;   WAIT_V8(6); BAR8;
.LBB0_1324:
	s_or_b64 exec, exec, s[12:13]
	v_add_u32_e32 v164, 0x18000, v150
	s_mov_b64 s[36:37], 0x80
	v_add_u32_e32 v165, 0x1a000, v150
	v_lshl_add_u64 v[10:11], v[10:11], 0, s[36:37]
	s_or_b32 m0, s100, 0x18000
	v_add_u32_e32 v166, 0x8000, v150
	s_waitcnt vmcnt(4)
	s_barrier
	global_load_lds_dwordx4 v[10:11], off
	v_lshl_add_u64 v[10:11], v[12:13], 0, s[36:37]
	s_or_b32 m0, s100, 0x1a000
	v_add_u32_e32 v167, 0xa000, v150
	global_load_lds_dwordx4 v[10:11], off
	v_lshl_add_u64 v[10:11], v[14:15], 0, s[36:37]
	s_or_b32 m0, s100, 0x8000
	v_add_u32_e32 v168, 0x1c000, v150
	global_load_lds_dwordx4 v[10:11], off
	v_lshl_add_u64 v[10:11], v[16:17], 0, s[36:37]
	s_or_b32 m0, s100, 0xa000
	v_add_u32_e32 v170, 0x1e000, v150
	global_load_lds_dwordx4 v[10:11], off
	v_lshl_add_u64 v[10:11], v[18:19], 0, s[36:37]
	s_or_b32 m0, s100, 0x1c000
	s_nop 0
	global_load_lds_dwordx4 v[10:11], off
	v_lshl_add_u64 v[10:11], v[20:21], 0, s[36:37]
	s_or_b32 m0, s100, 0x1e000
	v_and_b32_e32 v147, 15, v3
	global_load_lds_dwordx4 v[10:11], off
	v_bfe_u32 v148, v3, 4, 2
	v_lshlrev_b32_e32 v10, 4, v148
	v_lshlrev_b32_e32 v11, 6, v147
	v_lshlrev_b32_e32 v13, 2, v3
	v_or_b32_e32 v12, v10, v11
	v_and_b32_e32 v13, 32, v13
	s_mov_b32 s12, 0x10000
	v_bitop3_b32 v18, v12, s12, v13 bitop3:0xde
	s_mov_b32 s12, 0x14000
	v_bitop3_b32 v17, v10, v13, v11 bitop3:0x36
	v_bitop3_b32 v19, v12, s12, v13 bitop3:0xde
	s_mov_b32 s12, 0x18000
	v_lshlrev_b32_e32 v11, 6, v3
	v_bitop3_b32 v20, v12, s12, v13 bitop3:0xde
	s_mov_b32 s12, 0x1c000
	v_and_b32_e32 v11, 0x3c0, v11
	s_movk_i32 s31, 0x1600
	s_and_b32 s29, s21, 0xffffff00
	v_bitop3_b32 v21, v12, s12, v13 bitop3:0xde
	v_bitop3_b32 v24, v11, v13, v10 bitop3:0x36
	v_mad_i64_i32 v[10:11], s[12:13], v5, s31, 0
	v_mov_b32_e32 v5, 0x1600
	v_mad_i64_i32 v[12:13], s[12:13], s29, v5, v[10:11]
	v_lshl_add_u64 v[12:13], v[12:13], 0, v[6:7]
	v_lshl_add_u64 v[138:139], s[4:5], 0, v[12:13]
	v_mad_i64_i32 v[12:13], s[12:13], v22, s31, 0
	v_mad_i64_i32 v[14:15], s[12:13], s29, v5, v[12:13]
	s_bfe_u32 s29, s20, 0x60008
	v_mov_b32_e32 v5, 0x160000
	v_mad_u64_u32 v[10:11], s[12:13], s29, v5, v[10:11]
	v_lshl_add_u64 v[6:7], v[10:11], 0, v[6:7]
	v_bfe_u32 v146, v3, 6, 2
	s_waitcnt vmcnt(6)
	v_lshlrev_b32_e32 v149, 6, v23
	v_lshlrev_b32_e32 v23, 13, v23
	v_lshl_add_u64 v[142:143], s[2:3], 0, v[6:7]
	v_mad_u64_u32 v[6:7], s[12:13], s29, v5, v[12:13]
	v_lshlrev_b32_e32 v16, 12, v146
	v_or_b32_e32 v25, 0x800, v23
	v_or_b32_e32 v26, 0x1000, v23
	v_or_b32_e32 v27, 0x1800, v23
	v_lshl_add_u64 v[14:15], v[14:15], 0, v[8:9]
	v_lshl_add_u64 v[6:7], v[6:7], 0, v[8:9]
	s_ashr_i32 s9, s8, 31
	v_lshl_add_u64 v[140:141], s[4:5], 0, v[14:15]
	v_lshl_add_u64 v[144:145], s[2:3], 0, v[6:7]
	s_mov_b32 s29, -2
	s_mov_b64 s[12:13], 0
	v_add_u32_e32 v171, v18, v16
	v_add_u32_e32 v156, v17, v23
	v_add_u32_e32 v155, v24, v25
	v_add_u32_e32 v154, v24, v26
	v_add_u32_e32 v153, v24, v27
	v_add_u32_e32 v169, v19, v16
	v_add_u32_e32 v159, v20, v16
	v_add_u32_e32 v158, v21, v16
	v_mov_b32_e32 v5, v4
	v_mov_b64_e32 v[6:7], v[4:5]
	v_mov_b64_e32 v[8:9], v[4:5]
	v_mov_b64_e32 v[10:11], v[4:5]
	v_mov_b64_e32 v[12:13], v[4:5]
	v_mov_b64_e32 v[14:15], v[4:5]
	v_mov_b64_e32 v[16:17], v[4:5]
	v_mov_b64_e32 v[18:19], v[4:5]
	v_mov_b64_e32 v[20:21], v[4:5]
	v_mov_b64_e32 v[22:23], v[4:5]
	v_mov_b64_e32 v[24:25], v[4:5]
	v_mov_b64_e32 v[26:27], v[4:5]
	v_mov_b64_e32 v[28:29], v[4:5]
	v_mov_b64_e32 v[30:31], v[4:5]
	v_mov_b64_e32 v[32:33], v[4:5]
	v_mov_b64_e32 v[34:35], v[4:5]
	v_mov_b64_e32 v[36:37], v[4:5]
	v_mov_b64_e32 v[38:39], v[4:5]
	v_mov_b64_e32 v[40:41], v[4:5]
	v_mov_b64_e32 v[42:43], v[4:5]
	v_mov_b64_e32 v[44:45], v[4:5]
	v_mov_b64_e32 v[46:47], v[4:5]
	v_mov_b64_e32 v[48:49], v[4:5]
	v_mov_b64_e32 v[50:51], v[4:5]
	v_mov_b64_e32 v[52:53], v[4:5]
	v_mov_b64_e32 v[54:55], v[4:5]
	v_mov_b64_e32 v[56:57], v[4:5]
	v_mov_b64_e32 v[58:59], v[4:5]
	v_mov_b64_e32 v[60:61], v[4:5]
	v_mov_b64_e32 v[62:63], v[4:5]
	v_mov_b64_e32 v[64:65], v[4:5]
	v_mov_b64_e32 v[66:67], v[4:5]
	v_mov_b64_e32 v[68:69], v[4:5]
	v_mov_b64_e32 v[70:71], v[4:5]
	v_mov_b64_e32 v[72:73], v[4:5]
	v_mov_b64_e32 v[74:75], v[4:5]
	v_mov_b64_e32 v[76:77], v[4:5]
	v_mov_b64_e32 v[78:79], v[4:5]
	v_mov_b64_e32 v[80:81], v[4:5]
	v_mov_b64_e32 v[82:83], v[4:5]
	v_mov_b64_e32 v[84:85], v[4:5]
	v_mov_b64_e32 v[86:87], v[4:5]
	v_mov_b64_e32 v[88:89], v[4:5]
	v_mov_b64_e32 v[90:91], v[4:5]
	v_mov_b64_e32 v[92:93], v[4:5]
	v_mov_b64_e32 v[94:95], v[4:5]
	v_mov_b64_e32 v[96:97], v[4:5]
	v_mov_b64_e32 v[98:99], v[4:5]
	v_mov_b64_e32 v[100:101], v[4:5]
	v_mov_b64_e32 v[102:103], v[4:5]
	v_mov_b64_e32 v[104:105], v[4:5]
	v_mov_b64_e32 v[106:107], v[4:5]
	v_mov_b64_e32 v[108:109], v[4:5]
	v_mov_b64_e32 v[110:111], v[4:5]
	v_mov_b64_e32 v[112:113], v[4:5]
	v_mov_b64_e32 v[114:115], v[4:5]
	v_mov_b64_e32 v[116:117], v[4:5]
	v_mov_b64_e32 v[118:119], v[4:5]
	v_mov_b64_e32 v[120:121], v[4:5]
	v_mov_b64_e32 v[122:123], v[4:5]
	v_mov_b64_e32 v[124:125], v[4:5]
	v_mov_b64_e32 v[126:127], v[4:5]
	v_mov_b64_e32 v[128:129], v[4:5]
	v_mov_b64_e32 v[130:131], v[4:5]
	s_mov_b64 s[36:37], 0x20b0080
	s_mov_b64 s[38:39], 0xd5a0100
	s_mov_b64 s[40:41], 0x2000100
	s_mov_b64 s[42:43], 0xd650100
	s_mov_b64 s[44:45], 0x20b0100
	s_mov_b64 s[46:47], 0xd5a0180
	s_mov_b64 s[48:49], 0x2000180
	s_mov_b64 s[50:51], 0xd650180
	s_barrier
; #define LDA8(dst, b, h) _Pragma("unroll") for (int m = 0; m < 4; ++m) _Pragma("unroll") for (int k = 0; k < 2; ++k) \
;     dst[m][k] = *(const bf16x8*)((const char*)SA8(b, h) + lds_byte8(wr * 64 + m * 16 + fr, k * 32 + fq * 8))
; #define LDB8(dst, b, h) _Pragma("unroll") for (int n = 0; n < 2; ++n) _Pragma("unroll") for (int k = 0; k < 2; ++k) \
;     dst[n][k] = *(const bf16x8*)((const char*)SB8(b, h) + lds_byte8(wc * 32 + n * 16 + fr, k * 32 + fq * 8))
; #define WAIT_L8(n) asm volatile("s_waitcnt lgkmcnt(" #n ")" ::: "memory")
; #define BAR8 __builtin_amdgcn_s_barrier()
; #define SCHED8 __builtin_amdgcn_sched_barrier(0)
;     ...
;   for (int tt = 0; tt < nt - 2; tt += 2) {
;     LDB8(B0, 0, 0); SCHED8; LDA8(At, 0, 0); STAGE8(SA8(1, 1), A, lda, brow + 128, tt + 1);
;     WAIT_L8(8); BAR8; WAIT_L8(0); MMA8(0, 0, At, B0); BAR8; SCHED8;
;     LDB8(B1, 0, 1); STAGE8(SB8(0, 0), Bt, K, bcol, tt + 2);
;     BAR8; WAIT_L8(0); MMA8(0, 1, At, B1); BAR8;
;     LDA8(At, 0, 1); STAGE8(SA8(0, 0), A, lda, brow, tt + 2);
;     BAR8; WAIT_L8(0); MMA8(1, 0, At, B0); BAR8; SCHED8;
.LBB0_1325:
	ds_read_b128 v[174:177], v171
	ds_read_b128 v[178:181], v171 offset:1024
	ds_read_b128 v[182:185], v171 offset:2048
	ds_read_b128 v[186:189], v171 offset:3072
	v_add_u32_e32 v172, 0xc000, v150
	v_lshl_add_u64 v[222:223], v[142:143], 0, s[12:13]
	v_add_u32_e32 v173, 0xe000, v150
	v_lshl_add_u64 v[226:227], v[222:223], 0, s[36:37]
	s_or_b32 m0, s100, 0xc000
	v_lshl_add_u64 v[236:237], v[144:145], 0, s[12:13]
	ds_read_b128 v[190:193], v156
	ds_read_b128 v[194:197], v156 offset:1024
	ds_read_b128 v[198:201], v155
	ds_read_b128 v[202:205], v155 offset:1024
	ds_read_b128 v[206:209], v154
	ds_read_b128 v[210:213], v154 offset:1024
	ds_read_b128 v[214:217], v153
	ds_read_b128 v[218:221], v153 offset:1024
	global_load_lds_dwordx4 v[226:227], off
	v_lshl_add_u64 v[226:227], v[236:237], 0, s[36:37]
	s_or_b32 m0, s100, 0xe000
	s_nop 0
	global_load_lds_dwordx4 v[226:227], off
	s_waitcnt lgkmcnt(8)
	s_barrier
	s_waitcnt lgkmcnt(0)
	s_waitcnt lgkmcnt(0)
	v_mfma_f32_16x16x32_bf16 v[128:131], v[190:193], v[174:177], v[128:131]
	v_mfma_f32_16x16x32_bf16 v[124:127], v[190:193], v[182:185], v[124:127]
	v_mfma_f32_16x16x32_bf16 v[120:123], v[198:201], v[174:177], v[120:123]
	v_mfma_f32_16x16x32_bf16 v[116:119], v[198:201], v[182:185], v[116:119]
	v_mfma_f32_16x16x32_bf16 v[112:115], v[206:209], v[174:177], v[112:115]
	v_mfma_f32_16x16x32_bf16 v[108:111], v[206:209], v[182:185], v[108:111]
	v_mfma_f32_16x16x32_bf16 v[104:107], v[214:217], v[174:177], v[104:107]
	v_mfma_f32_16x16x32_bf16 v[100:103], v[214:217], v[182:185], v[100:103]
	v_mfma_f32_16x16x32_bf16 v[128:131], v[194:197], v[178:181], v[128:131]
	v_mfma_f32_16x16x32_bf16 v[124:127], v[194:197], v[186:189], v[124:127]
	v_mfma_f32_16x16x32_bf16 v[120:123], v[202:205], v[178:181], v[120:123]
	v_mfma_f32_16x16x32_bf16 v[116:119], v[202:205], v[186:189], v[116:119]
	v_mfma_f32_16x16x32_bf16 v[112:115], v[210:213], v[178:181], v[112:115]
	v_mfma_f32_16x16x32_bf16 v[108:111], v[210:213], v[186:189], v[108:111]
	v_mfma_f32_16x16x32_bf16 v[104:107], v[218:221], v[178:181], v[104:107]
	v_mfma_f32_16x16x32_bf16 v[100:103], v[218:221], v[186:189], v[100:103]
	s_barrier
	v_lshl_add_u64 v[246:247], v[138:139], 0, s[12:13]
	v_lshl_add_u64 v[248:249], v[246:247], 0, s[38:39]
	s_or_b32 m0, s100, 0x10000
	ds_read_b128 v[226:229], v169
	ds_read_b128 v[230:233], v169 offset:1024
	ds_read_b128 v[238:241], v169 offset:2048
	ds_read_b128 v[242:245], v169 offset:3072
	global_load_lds_dwordx4 v[248:249], off
	v_lshl_add_u64 v[248:249], v[140:141], 0, s[12:13]
	v_lshl_add_u64 v[250:251], v[248:249], 0, s[38:39]
	s_or_b32 m0, s100, 0x12000
	s_nop 0
	global_load_lds_dwordx4 v[250:251], off
	s_barrier
	s_waitcnt lgkmcnt(0)
	s_waitcnt lgkmcnt(0)
	v_mfma_f32_16x16x32_bf16 v[96:99], v[190:193], v[226:229], v[96:99]
	v_mfma_f32_16x16x32_bf16 v[92:95], v[190:193], v[238:241], v[92:95]
	v_mfma_f32_16x16x32_bf16 v[88:91], v[198:201], v[226:229], v[88:91]
	v_mfma_f32_16x16x32_bf16 v[84:87], v[198:201], v[238:241], v[84:87]
	v_mfma_f32_16x16x32_bf16 v[80:83], v[206:209], v[226:229], v[80:83]
	v_mfma_f32_16x16x32_bf16 v[76:79], v[206:209], v[238:241], v[76:79]
	v_mfma_f32_16x16x32_bf16 v[72:75], v[214:217], v[226:229], v[72:75]
	v_mfma_f32_16x16x32_bf16 v[68:71], v[214:217], v[238:241], v[68:71]
	v_mfma_f32_16x16x32_bf16 v[96:99], v[194:197], v[230:233], v[96:99]
	v_mfma_f32_16x16x32_bf16 v[92:95], v[194:197], v[242:245], v[92:95]
	v_mfma_f32_16x16x32_bf16 v[88:91], v[202:205], v[230:233], v[88:91]
	v_mfma_f32_16x16x32_bf16 v[84:87], v[202:205], v[242:245], v[84:87]
	v_mfma_f32_16x16x32_bf16 v[80:83], v[210:213], v[230:233], v[80:83]
	v_mfma_f32_16x16x32_bf16 v[76:79], v[210:213], v[242:245], v[76:79]
	v_mfma_f32_16x16x32_bf16 v[72:75], v[218:221], v[230:233], v[72:75]
	v_mfma_f32_16x16x32_bf16 v[68:71], v[218:221], v[242:245], v[68:71]
	v_lshl_add_u64 v[250:251], v[222:223], 0, s[40:41]
	s_mov_b32 m0, s100
	s_barrier
	ds_read_b128 v[190:193], v156 offset:16384
	ds_read_b128 v[194:197], v156 offset:17408
	ds_read_b128 v[198:201], v155 offset:16384
	ds_read_b128 v[202:205], v155 offset:17408
	ds_read_b128 v[206:209], v154 offset:16384
	ds_read_b128 v[210:213], v154 offset:17408
	ds_read_b128 v[214:217], v153 offset:16384
	ds_read_b128 v[218:221], v153 offset:17408
	global_load_lds_dwordx4 v[250:251], off
	v_lshl_add_u64 v[250:251], v[236:237], 0, s[40:41]
	s_or_b32 m0, s100, 0x2000
	s_nop 0
	global_load_lds_dwordx4 v[250:251], off
	s_barrier
	s_waitcnt lgkmcnt(0)
	s_waitcnt lgkmcnt(0)
	v_mfma_f32_16x16x32_bf16 v[64:67], v[190:193], v[174:177], v[64:67]
	v_mfma_f32_16x16x32_bf16 v[60:63], v[190:193], v[182:185], v[60:63]
	v_mfma_f32_16x16x32_bf16 v[56:59], v[198:201], v[174:177], v[56:59]
	v_mfma_f32_16x16x32_bf16 v[52:55], v[198:201], v[182:185], v[52:55]
	v_mfma_f32_16x16x32_bf16 v[48:51], v[206:209], v[174:177], v[48:51]
	v_mfma_f32_16x16x32_bf16 v[44:47], v[206:209], v[182:185], v[44:47]
	v_mfma_f32_16x16x32_bf16 v[40:43], v[214:217], v[174:177], v[40:43]
	v_mfma_f32_16x16x32_bf16 v[36:39], v[214:217], v[182:185], v[36:39]
	v_mfma_f32_16x16x32_bf16 v[64:67], v[194:197], v[178:181], v[64:67]
	v_mfma_f32_16x16x32_bf16 v[60:63], v[194:197], v[186:189], v[60:63]
	v_mfma_f32_16x16x32_bf16 v[56:59], v[202:205], v[178:181], v[56:59]
	v_mfma_f32_16x16x32_bf16 v[52:55], v[202:205], v[186:189], v[52:55]
	v_mfma_f32_16x16x32_bf16 v[48:51], v[210:213], v[178:181], v[48:51]
	v_mfma_f32_16x16x32_bf16 v[44:47], v[210:213], v[186:189], v[44:47]
	v_mfma_f32_16x16x32_bf16 v[40:43], v[218:221], v[178:181], v[40:43]
	v_mfma_f32_16x16x32_bf16 v[36:39], v[218:221], v[186:189], v[36:39]
	s_barrier
; #define LDA8(dst, b, h) _Pragma("unroll") for (int m = 0; m < 4; ++m) _Pragma("unroll") for (int k = 0; k < 2; ++k) \
;     dst[m][k] = *(const bf16x8*)((const char*)SA8(b, h) + lds_byte8(wr * 64 + m * 16 + fr, k * 32 + fq * 8))
; #define LDB8(dst, b, h) _Pragma("unroll") for (int n = 0; n < 2; ++n) _Pragma("unroll") for (int k = 0; k < 2; ++k) \
;     dst[n][k] = *(const bf16x8*)((const char*)SB8(b, h) + lds_byte8(wc * 32 + n * 16 + fr, k * 32 + fq * 8))
; #define WAIT_V8(n) asm volatile("s_waitcnt vmcnt(" #n ")" ::: "memory")
; #define WAIT_L8(n) asm volatile("s_waitcnt lgkmcnt(" #n ")" ::: "memory")
; #define BAR8 __builtin_amdgcn_s_barrier()
; #define SCHED8 __builtin_amdgcn_sched_barrier(0)
;     ...
;     STAGE8(SB8(0, 1), Bt, K, bcol + 128, tt + 2);
;     WAIT_V8(6); BAR8; MMA8(1, 1, At, B1); BAR8;
;     LDB8(B0, 1, 0); SCHED8; LDA8(At, 1, 0); STAGE8(SA8(0, 1), A, lda, brow + 128, tt + 2);
;     WAIT_L8(8); BAR8; WAIT_L8(0); MMA8(0, 0, At, B0); BAR8; SCHED8;
;     LDB8(B1, 1, 1); STAGE8(SB8(1, 0), Bt, K, bcol, tt + 3);
;     BAR8; WAIT_L8(0); MMA8(0, 1, At, B1); BAR8;
;     LDA8(At, 1, 1); STAGE8(SA8(1, 0), A, lda, brow, tt + 3);
;     BAR8; WAIT_L8(0); MMA8(1, 0, At, B0); BAR8; SCHED8;
	v_lshl_add_u64 v[174:175], v[246:247], 0, s[42:43]
	s_or_b32 m0, s100, 0x14000
	s_nop 0
	global_load_lds_dwordx4 v[174:175], off
	v_lshl_add_u64 v[174:175], v[248:249], 0, s[42:43]
	s_or_b32 m0, s100, 0x16000
	s_nop 0
	global_load_lds_dwordx4 v[174:175], off
	s_waitcnt vmcnt(6)
	s_barrier
	v_mfma_f32_16x16x32_bf16 v[32:35], v[190:193], v[226:229], v[32:35]
	v_mfma_f32_16x16x32_bf16 v[28:31], v[190:193], v[238:241], v[28:31]
	v_mfma_f32_16x16x32_bf16 v[24:27], v[198:201], v[226:229], v[24:27]
	v_mfma_f32_16x16x32_bf16 v[20:23], v[198:201], v[238:241], v[20:23]
	v_mfma_f32_16x16x32_bf16 v[16:19], v[206:209], v[226:229], v[16:19]
	v_mfma_f32_16x16x32_bf16 v[12:15], v[206:209], v[238:241], v[12:15]
	v_mfma_f32_16x16x32_bf16 v[8:11], v[214:217], v[226:229], v[8:11]
	v_mfma_f32_16x16x32_bf16 v[4:7], v[214:217], v[238:241], v[4:7]
	v_mfma_f32_16x16x32_bf16 v[32:35], v[194:197], v[230:233], v[32:35]
	v_mfma_f32_16x16x32_bf16 v[28:31], v[194:197], v[242:245], v[28:31]
	v_mfma_f32_16x16x32_bf16 v[24:27], v[202:205], v[230:233], v[24:27]
	v_mfma_f32_16x16x32_bf16 v[20:23], v[202:205], v[242:245], v[20:23]
	v_mfma_f32_16x16x32_bf16 v[16:19], v[210:213], v[230:233], v[16:19]
	v_mfma_f32_16x16x32_bf16 v[12:15], v[210:213], v[242:245], v[12:15]
	v_mfma_f32_16x16x32_bf16 v[8:11], v[218:221], v[230:233], v[8:11]
	v_mfma_f32_16x16x32_bf16 v[4:7], v[218:221], v[242:245], v[4:7]
	s_barrier
	ds_read_b128 v[174:177], v159
	ds_read_b128 v[178:181], v159 offset:1024
	ds_read_b128 v[182:185], v159 offset:2048
	ds_read_b128 v[186:189], v159 offset:3072
	v_lshl_add_u64 v[226:227], v[222:223], 0, s[44:45]
	s_or_b32 m0, s100, 0x4000
	ds_read_b128 v[190:193], v156 offset:32768
	ds_read_b128 v[194:197], v156 offset:33792
	ds_read_b128 v[198:201], v155 offset:32768
	ds_read_b128 v[202:205], v155 offset:33792
	ds_read_b128 v[206:209], v154 offset:32768
	ds_read_b128 v[210:213], v154 offset:33792
	ds_read_b128 v[214:217], v153 offset:32768
	ds_read_b128 v[218:221], v153 offset:33792
	global_load_lds_dwordx4 v[226:227], off
	v_lshl_add_u64 v[226:227], v[236:237], 0, s[44:45]
	s_or_b32 m0, s100, 0x6000
	s_nop 0
	global_load_lds_dwordx4 v[226:227], off
	s_waitcnt lgkmcnt(8)
	s_barrier
	s_waitcnt lgkmcnt(0)
	s_waitcnt lgkmcnt(0)
	v_mfma_f32_16x16x32_bf16 v[128:131], v[190:193], v[174:177], v[128:131]
	v_mfma_f32_16x16x32_bf16 v[124:127], v[190:193], v[182:185], v[124:127]
	v_mfma_f32_16x16x32_bf16 v[120:123], v[198:201], v[174:177], v[120:123]
	v_mfma_f32_16x16x32_bf16 v[116:119], v[198:201], v[182:185], v[116:119]
	v_mfma_f32_16x16x32_bf16 v[112:115], v[206:209], v[174:177], v[112:115]
	v_mfma_f32_16x16x32_bf16 v[108:111], v[206:209], v[182:185], v[108:111]
	v_mfma_f32_16x16x32_bf16 v[104:107], v[214:217], v[174:177], v[104:107]
	v_mfma_f32_16x16x32_bf16 v[100:103], v[214:217], v[182:185], v[100:103]
	v_mfma_f32_16x16x32_bf16 v[128:131], v[194:197], v[178:181], v[128:131]
	v_mfma_f32_16x16x32_bf16 v[124:127], v[194:197], v[186:189], v[124:127]
	v_mfma_f32_16x16x32_bf16 v[120:123], v[202:205], v[178:181], v[120:123]
	v_mfma_f32_16x16x32_bf16 v[116:119], v[202:205], v[186:189], v[116:119]
	v_mfma_f32_16x16x32_bf16 v[112:115], v[210:213], v[178:181], v[112:115]
	v_mfma_f32_16x16x32_bf16 v[108:111], v[210:213], v[186:189], v[108:111]
	v_mfma_f32_16x16x32_bf16 v[104:107], v[218:221], v[178:181], v[104:107]
	v_mfma_f32_16x16x32_bf16 v[100:103], v[218:221], v[186:189], v[100:103]
	s_barrier
	v_lshl_add_u64 v[250:251], v[246:247], 0, s[46:47]
	s_or_b32 m0, s100, 0x18000
	ds_read_b128 v[226:229], v158
	ds_read_b128 v[230:233], v158 offset:1024
	ds_read_b128 v[238:241], v158 offset:2048
	ds_read_b128 v[242:245], v158 offset:3072
	global_load_lds_dwordx4 v[250:251], off
	v_lshl_add_u64 v[250:251], v[248:249], 0, s[46:47]
	s_or_b32 m0, s100, 0x1a000
	s_nop 0
	global_load_lds_dwordx4 v[250:251], off
	s_barrier
	s_waitcnt lgkmcnt(0)
	s_waitcnt lgkmcnt(0)
	v_mfma_f32_16x16x32_bf16 v[96:99], v[190:193], v[226:229], v[96:99]
	v_mfma_f32_16x16x32_bf16 v[92:95], v[190:193], v[238:241], v[92:95]
	v_mfma_f32_16x16x32_bf16 v[88:91], v[198:201], v[226:229], v[88:91]
	v_mfma_f32_16x16x32_bf16 v[84:87], v[198:201], v[238:241], v[84:87]
	v_mfma_f32_16x16x32_bf16 v[80:83], v[206:209], v[226:229], v[80:83]
	v_mfma_f32_16x16x32_bf16 v[76:79], v[206:209], v[238:241], v[76:79]
	v_mfma_f32_16x16x32_bf16 v[72:75], v[214:217], v[226:229], v[72:75]
	v_mfma_f32_16x16x32_bf16 v[68:71], v[214:217], v[238:241], v[68:71]
	v_mfma_f32_16x16x32_bf16 v[96:99], v[194:197], v[230:233], v[96:99]
	v_mfma_f32_16x16x32_bf16 v[92:95], v[194:197], v[242:245], v[92:95]
	v_mfma_f32_16x16x32_bf16 v[88:91], v[202:205], v[230:233], v[88:91]
	v_mfma_f32_16x16x32_bf16 v[84:87], v[202:205], v[242:245], v[84:87]
	v_mfma_f32_16x16x32_bf16 v[80:83], v[210:213], v[230:233], v[80:83]
	v_mfma_f32_16x16x32_bf16 v[76:79], v[210:213], v[242:245], v[76:79]
	v_mfma_f32_16x16x32_bf16 v[72:75], v[218:221], v[230:233], v[72:75]
	v_mfma_f32_16x16x32_bf16 v[68:71], v[218:221], v[242:245], v[68:71]
	v_lshl_add_u64 v[222:223], v[222:223], 0, s[48:49]
	s_or_b32 m0, s100, 0x8000
	s_barrier
	ds_read_b128 v[190:193], v156 offset:49152
	ds_read_b128 v[194:197], v156 offset:50176
	ds_read_b128 v[198:201], v155 offset:49152
	ds_read_b128 v[202:205], v155 offset:50176
	ds_read_b128 v[206:209], v154 offset:49152
	ds_read_b128 v[210:213], v154 offset:50176
	ds_read_b128 v[214:217], v153 offset:49152
	ds_read_b128 v[218:221], v153 offset:50176
	global_load_lds_dwordx4 v[222:223], off
	v_lshl_add_u64 v[222:223], v[236:237], 0, s[48:49]
	s_or_b32 m0, s100, 0xa000
	s_nop 0
	global_load_lds_dwordx4 v[222:223], off
	s_barrier
; #define LDA8(dst, b, h) _Pragma("unroll") for (int m = 0; m < 4; ++m) _Pragma("unroll") for (int k = 0; k < 2; ++k) \
;     dst[m][k] = *(const bf16x8*)((const char*)SA8(b, h) + lds_byte8(wr * 64 + m * 16 + fr, k * 32 + fq * 8))
; #define LDB8(dst, b, h) _Pragma("unroll") for (int n = 0; n < 2; ++n) _Pragma("unroll") for (int k = 0; k < 2; ++k) \
;     dst[n][k] = *(const bf16x8*)((const char*)SB8(b, h) + lds_byte8(wc * 32 + n * 16 + fr, k * 32 + fq * 8))
; #define WAIT_V8(n) asm volatile("s_waitcnt vmcnt(" #n ")" ::: "memory")
; #define WAIT_L8(n) asm volatile("s_waitcnt lgkmcnt(" #n ")" ::: "memory")
; #define BAR8 __builtin_amdgcn_s_barrier()
; #define SCHED8 __builtin_amdgcn_sched_barrier(0)
;     ...
;     BAR8; WAIT_L8(0); MMA8(1, 0, At, B0); BAR8; SCHED8;
;     STAGE8(SB8(1, 1), Bt, K, bcol + 128, tt + 3);
;     WAIT_V8(6); BAR8; MMA8(1, 1, At, B1); BAR8;
;   }
;   { LDB8(B0, 0, 0); LDA8(At, 0, 0); STAGE8(SA8(1, 1), A, lda, brow + 128, nt - 1);
;     BAR8; WAIT_L8(0); MMA8(0, 0, At, B0); BAR8;
;     LDB8(B1, 0, 1); BAR8; WAIT_L8(0); MMA8(0, 1, At, B1); BAR8;
	s_waitcnt lgkmcnt(0)
	s_waitcnt lgkmcnt(0)
	v_mfma_f32_16x16x32_bf16 v[64:67], v[190:193], v[174:177], v[64:67]
	v_mfma_f32_16x16x32_bf16 v[60:63], v[190:193], v[182:185], v[60:63]
	v_mfma_f32_16x16x32_bf16 v[56:59], v[198:201], v[174:177], v[56:59]
	v_mfma_f32_16x16x32_bf16 v[52:55], v[198:201], v[182:185], v[52:55]
	v_mfma_f32_16x16x32_bf16 v[48:51], v[206:209], v[174:177], v[48:51]
	v_mfma_f32_16x16x32_bf16 v[44:47], v[206:209], v[182:185], v[44:47]
	v_mfma_f32_16x16x32_bf16 v[40:43], v[214:217], v[174:177], v[40:43]
	v_mfma_f32_16x16x32_bf16 v[36:39], v[214:217], v[182:185], v[36:39]
	v_mfma_f32_16x16x32_bf16 v[64:67], v[194:197], v[178:181], v[64:67]
	v_mfma_f32_16x16x32_bf16 v[60:63], v[194:197], v[186:189], v[60:63]
	v_mfma_f32_16x16x32_bf16 v[56:59], v[202:205], v[178:181], v[56:59]
	v_mfma_f32_16x16x32_bf16 v[52:55], v[202:205], v[186:189], v[52:55]
	v_mfma_f32_16x16x32_bf16 v[48:51], v[210:213], v[178:181], v[48:51]
	v_mfma_f32_16x16x32_bf16 v[44:47], v[210:213], v[186:189], v[44:47]
	v_mfma_f32_16x16x32_bf16 v[40:43], v[218:221], v[178:181], v[40:43]
	v_mfma_f32_16x16x32_bf16 v[36:39], v[218:221], v[186:189], v[36:39]
	s_barrier
	v_lshl_add_u64 v[174:175], v[246:247], 0, s[50:51]
	s_or_b32 m0, s100, 0x1c000
	s_nop 0
	global_load_lds_dwordx4 v[174:175], off
	v_lshl_add_u64 v[174:175], v[248:249], 0, s[50:51]
	s_or_b32 m0, s100, 0x1e000
	s_nop 0
	global_load_lds_dwordx4 v[174:175], off
	s_waitcnt vmcnt(6)
	s_barrier
	v_mfma_f32_16x16x32_bf16 v[32:35], v[190:193], v[226:229], v[32:35]
	v_mfma_f32_16x16x32_bf16 v[28:31], v[190:193], v[238:241], v[28:31]
	v_mfma_f32_16x16x32_bf16 v[24:27], v[198:201], v[226:229], v[24:27]
	v_mfma_f32_16x16x32_bf16 v[20:23], v[198:201], v[238:241], v[20:23]
	v_mfma_f32_16x16x32_bf16 v[16:19], v[206:209], v[226:229], v[16:19]
	v_mfma_f32_16x16x32_bf16 v[12:15], v[206:209], v[238:241], v[12:15]
	v_mfma_f32_16x16x32_bf16 v[8:11], v[214:217], v[226:229], v[8:11]
	v_mfma_f32_16x16x32_bf16 v[4:7], v[214:217], v[238:241], v[4:7]
	v_mfma_f32_16x16x32_bf16 v[32:35], v[194:197], v[230:233], v[32:35]
	v_mfma_f32_16x16x32_bf16 v[28:31], v[194:197], v[242:245], v[28:31]
	v_mfma_f32_16x16x32_bf16 v[24:27], v[202:205], v[230:233], v[24:27]
	v_mfma_f32_16x16x32_bf16 v[20:23], v[202:205], v[242:245], v[20:23]
	v_mfma_f32_16x16x32_bf16 v[16:19], v[210:213], v[230:233], v[16:19]
	v_mfma_f32_16x16x32_bf16 v[12:15], v[210:213], v[242:245], v[12:15]
	v_mfma_f32_16x16x32_bf16 v[8:11], v[218:221], v[230:233], v[8:11]
	v_mfma_f32_16x16x32_bf16 v[4:7], v[218:221], v[242:245], v[4:7]
	s_add_i32 s29, s29, 2
	s_add_u32 s12, s12, 0x100
	s_addc_u32 s13, s13, 0
	s_cmp_lt_u32 s29, 40
	s_barrier
	s_cbranch_scc1 .LBB0_1325
	s_add_i32 s27, s27, 0xb0000
	s_add_u32 s2, s2, s27
	s_addc_u32 s3, s3, 0
	s_add_u32 s2, s2, 0x2001580
	s_addc_u32 s3, s3, 0
	v_lshl_add_u64 v[132:133], v[132:133], 1, s[2:3]
	v_lshl_add_u64 v[0:1], v[0:1], 1, v[132:133]
	s_or_b32 m0, s100, 0xc000
	ds_read_b128 v[138:141], v171
	ds_read_b128 v[142:145], v171 offset:1024
	ds_read_b128 v[160:163], v171 offset:2048
	ds_read_b128 v[164:167], v171 offset:3072
	ds_read_b128 v[174:177], v156
	ds_read_b128 v[178:181], v156 offset:1024
	ds_read_b128 v[182:185], v155
	ds_read_b128 v[186:189], v155 offset:1024
	ds_read_b128 v[190:193], v154
	ds_read_b128 v[194:197], v154 offset:1024
	ds_read_b128 v[198:201], v153
	ds_read_b128 v[202:205], v153 offset:1024
	global_load_lds_dwordx4 v[0:1], off
	v_lshl_add_u64 v[0:1], v[136:137], 1, s[2:3]
	v_lshl_add_u64 v[0:1], v[134:135], 1, v[0:1]
	s_or_b32 m0, s100, 0xe000
	s_nop 0
	global_load_lds_dwordx4 v[0:1], off
	s_barrier
	s_waitcnt lgkmcnt(0)
	s_waitcnt lgkmcnt(0)
	v_mfma_f32_16x16x32_bf16 v[128:131], v[174:177], v[138:141], v[128:131]
	v_mfma_f32_16x16x32_bf16 v[124:127], v[174:177], v[160:163], v[124:127]
	v_mfma_f32_16x16x32_bf16 v[120:123], v[182:185], v[138:141], v[120:123]
	v_mfma_f32_16x16x32_bf16 v[112:115], v[190:193], v[138:141], v[112:115]
	v_mfma_f32_16x16x32_bf16 v[128:131], v[178:181], v[142:145], v[128:131]
	v_mfma_f32_16x16x32_bf16 v[124:127], v[178:181], v[164:167], v[124:127]
	v_mfma_f32_16x16x32_bf16 v[120:123], v[186:189], v[142:145], v[120:123]
	v_mfma_f32_16x16x32_bf16 v[116:119], v[182:185], v[160:163], v[116:119]
	v_mfma_f32_16x16x32_bf16 v[112:115], v[194:197], v[142:145], v[112:115]
	v_mfma_f32_16x16x32_bf16 v[108:111], v[190:193], v[160:163], v[108:111]
	v_mfma_f32_16x16x32_bf16 v[104:107], v[198:201], v[138:141], v[104:107]
	v_mfma_f32_16x16x32_bf16 v[100:103], v[198:201], v[160:163], v[100:103]
	v_mfma_f32_16x16x32_bf16 v[132:135], v[186:189], v[164:167], v[116:119]
	v_mfma_f32_16x16x32_bf16 v[170:173], v[194:197], v[164:167], v[108:111]
	v_mfma_f32_16x16x32_bf16 v[206:209], v[202:205], v[142:145], v[104:107]
	v_mfma_f32_16x16x32_bf16 v[210:213], v[202:205], v[164:167], v[100:103]
	s_barrier
	s_nop 1
	ds_read_b128 v[100:103], v169
	ds_read_b128 v[104:107], v169 offset:1024
	ds_read_b128 v[108:111], v169 offset:2048
	ds_read_b128 v[116:119], v169 offset:3072
	s_barrier
	s_waitcnt lgkmcnt(0)
	s_waitcnt lgkmcnt(0)
	v_mfma_f32_16x16x32_bf16 v[80:83], v[190:193], v[100:103], v[80:83]
	v_mfma_f32_16x16x32_bf16 v[76:79], v[190:193], v[108:111], v[76:79]
	v_mfma_f32_16x16x32_bf16 v[72:75], v[198:201], v[100:103], v[72:75]
	v_mfma_f32_16x16x32_bf16 v[68:71], v[198:201], v[108:111], v[68:71]
	v_mfma_f32_16x16x32_bf16 v[96:99], v[174:177], v[100:103], v[96:99]
	v_mfma_f32_16x16x32_bf16 v[92:95], v[174:177], v[108:111], v[92:95]
	v_mfma_f32_16x16x32_bf16 v[88:91], v[182:185], v[100:103], v[88:91]
	v_mfma_f32_16x16x32_bf16 v[84:87], v[182:185], v[108:111], v[84:87]
	v_mfma_f32_16x16x32_bf16 v[80:83], v[194:197], v[104:107], v[80:83]
	v_mfma_f32_16x16x32_bf16 v[76:79], v[194:197], v[116:119], v[76:79]
	v_mfma_f32_16x16x32_bf16 v[72:75], v[202:205], v[104:107], v[72:75]
	v_mfma_f32_16x16x32_bf16 v[68:71], v[202:205], v[116:119], v[68:71]
	v_mfma_f32_16x16x32_bf16 v[214:217], v[178:181], v[104:107], v[96:99]
	v_mfma_f32_16x16x32_bf16 v[174:177], v[178:181], v[116:119], v[92:95]
	v_mfma_f32_16x16x32_bf16 v[178:181], v[186:189], v[104:107], v[88:91]
	v_mfma_f32_16x16x32_bf16 v[182:185], v[186:189], v[116:119], v[84:87]
	s_barrier
; #define LDA8(dst, b, h) _Pragma("unroll") for (int m = 0; m < 4; ++m) _Pragma("unroll") for (int k = 0; k < 2; ++k) \
;     dst[m][k] = *(const bf16x8*)((const char*)SA8(b, h) + lds_byte8(wr * 64 + m * 16 + fr, k * 32 + fq * 8))
; #define LDB8(dst, b, h) _Pragma("unroll") for (int n = 0; n < 2; ++n) _Pragma("unroll") for (int k = 0; k < 2; ++k) \
;     dst[n][k] = *(const bf16x8*)((const char*)SB8(b, h) + lds_byte8(wc * 32 + n * 16 + fr, k * 32 + fq * 8))
; #define WAIT_V8(n) asm volatile("s_waitcnt vmcnt(" #n ")" ::: "memory")
; #define WAIT_L8(n) asm volatile("s_waitcnt lgkmcnt(" #n ")" ::: "memory")
; #define BAR8 __builtin_amdgcn_s_barrier()
;     ...
;     LDA8(At, 0, 1); WAIT_V8(4); BAR8; WAIT_L8(0); MMA8(1, 0, At, B0); MMA8(1, 1, At, B1); BAR8; }
;   { LDB8(B0, 1, 0); LDA8(At, 1, 0); WAIT_V8(2); BAR8; WAIT_L8(0); MMA8(0, 0, At, B0); BAR8;
	s_nop 0
	ds_read_b128 v[84:87], v156 offset:16384
	ds_read_b128 v[88:91], v156 offset:17408
	ds_read_b128 v[92:95], v155 offset:16384
	ds_read_b128 v[96:99], v155 offset:17408
	ds_read_b128 v[186:189], v154 offset:16384
	ds_read_b128 v[190:193], v154 offset:17408
	ds_read_b128 v[194:197], v153 offset:16384
	ds_read_b128 v[198:201], v153 offset:17408
	s_waitcnt vmcnt(4)
	s_barrier
	s_waitcnt lgkmcnt(0)
	s_waitcnt lgkmcnt(0)
	v_mfma_f32_16x16x32_bf16 v[64:67], v[84:87], v[138:141], v[64:67]
	v_mfma_f32_16x16x32_bf16 v[60:63], v[84:87], v[160:163], v[60:63]
	v_mfma_f32_16x16x32_bf16 v[56:59], v[92:95], v[138:141], v[56:59]
	v_mfma_f32_16x16x32_bf16 v[52:55], v[92:95], v[160:163], v[52:55]
	v_mfma_f32_16x16x32_bf16 v[48:51], v[186:189], v[138:141], v[48:51]
	v_mfma_f32_16x16x32_bf16 v[44:47], v[186:189], v[160:163], v[44:47]
	v_mfma_f32_16x16x32_bf16 v[40:43], v[194:197], v[138:141], v[40:43]
	v_mfma_f32_16x16x32_bf16 v[36:39], v[194:197], v[160:163], v[36:39]
	v_mfma_f32_16x16x32_bf16 v[64:67], v[88:91], v[142:145], v[64:67]
	v_mfma_f32_16x16x32_bf16 v[60:63], v[88:91], v[164:167], v[60:63]
	v_mfma_f32_16x16x32_bf16 v[56:59], v[96:99], v[142:145], v[56:59]
	v_mfma_f32_16x16x32_bf16 v[52:55], v[96:99], v[164:167], v[52:55]
	v_mfma_f32_16x16x32_bf16 v[48:51], v[190:193], v[142:145], v[48:51]
	v_mfma_f32_16x16x32_bf16 v[44:47], v[190:193], v[164:167], v[44:47]
	v_mfma_f32_16x16x32_bf16 v[40:43], v[198:201], v[142:145], v[40:43]
	v_mfma_f32_16x16x32_bf16 v[36:39], v[198:201], v[164:167], v[36:39]
	v_mfma_f32_16x16x32_bf16 v[32:35], v[84:87], v[100:103], v[32:35]
	v_mfma_f32_16x16x32_bf16 v[28:31], v[84:87], v[108:111], v[28:31]
	v_mfma_f32_16x16x32_bf16 v[24:27], v[92:95], v[100:103], v[24:27]
	v_mfma_f32_16x16x32_bf16 v[20:23], v[92:95], v[108:111], v[20:23]
	v_mfma_f32_16x16x32_bf16 v[16:19], v[186:189], v[100:103], v[16:19]
	v_mfma_f32_16x16x32_bf16 v[12:15], v[186:189], v[108:111], v[12:15]
	v_mfma_f32_16x16x32_bf16 v[8:11], v[194:197], v[100:103], v[8:11]
	v_mfma_f32_16x16x32_bf16 v[4:7], v[194:197], v[108:111], v[4:7]
	v_mfma_f32_16x16x32_bf16 v[136:139], v[88:91], v[104:107], v[32:35]
	v_mfma_f32_16x16x32_bf16 v[140:143], v[88:91], v[116:119], v[28:31]
	v_mfma_f32_16x16x32_bf16 v[160:163], v[96:99], v[104:107], v[24:27]
	v_mfma_f32_16x16x32_bf16 v[164:167], v[96:99], v[116:119], v[20:23]
	v_mfma_f32_16x16x32_bf16 v[202:205], v[190:193], v[104:107], v[16:19]
	v_mfma_f32_16x16x32_bf16 v[186:189], v[190:193], v[116:119], v[12:15]
	v_mfma_f32_16x16x32_bf16 v[190:193], v[198:201], v[104:107], v[8:11]
	v_mfma_f32_16x16x32_bf16 v[194:197], v[198:201], v[116:119], v[4:7]
	s_barrier
	ds_read_b128 v[198:201], v159
	ds_read_b128 v[218:221], v159 offset:1024
	ds_read_b128 v[226:229], v159 offset:2048
	ds_read_b128 v[230:233], v159 offset:3072
	ds_read_b128 v[8:11], v156 offset:32768
	ds_read_b128 v[12:15], v156 offset:33792
	ds_read_b128 v[16:19], v155 offset:32768
	ds_read_b128 v[24:27], v155 offset:33792
	ds_read_b128 v[28:31], v154 offset:32768
	ds_read_b128 v[32:35], v154 offset:33792
	ds_read_b128 v[238:241], v153 offset:32768
	ds_read_b128 v[242:245], v153 offset:33792
	s_waitcnt vmcnt(2)
	s_barrier
	s_waitcnt lgkmcnt(0)
	s_waitcnt lgkmcnt(0)
	v_mfma_f32_16x16x32_bf16 v[4:7], v[8:11], v[198:201], v[128:131]
	v_mfma_f32_16x16x32_bf16 v[104:107], v[12:15], v[218:221], v[4:7]
	v_mfma_f32_16x16x32_bf16 v[4:7], v[8:11], v[226:229], v[124:127]
	v_mfma_f32_16x16x32_bf16 v[116:119], v[12:15], v[230:233], v[4:7]
	v_mfma_f32_16x16x32_bf16 v[4:7], v[16:19], v[198:201], v[120:123]
	v_mfma_f32_16x16x32_bf16 v[100:103], v[24:27], v[218:221], v[4:7]
	v_mfma_f32_16x16x32_bf16 v[4:7], v[16:19], v[226:229], v[132:135]
	v_mfma_f32_16x16x32_bf16 v[108:111], v[24:27], v[230:233], v[4:7]
	v_mfma_f32_16x16x32_bf16 v[4:7], v[28:31], v[198:201], v[112:115]
	v_mfma_f32_16x16x32_bf16 v[92:95], v[32:35], v[218:221], v[4:7]
	v_mfma_f32_16x16x32_bf16 v[4:7], v[28:31], v[226:229], v[170:173]
	v_mfma_f32_16x16x32_bf16 v[96:99], v[32:35], v[230:233], v[4:7]
	v_mfma_f32_16x16x32_bf16 v[4:7], v[238:241], v[198:201], v[206:209]
	v_mfma_f32_16x16x32_bf16 v[84:87], v[242:245], v[218:221], v[4:7]
	v_mfma_f32_16x16x32_bf16 v[4:7], v[238:241], v[226:229], v[210:213]
	v_mfma_f32_16x16x32_bf16 v[88:91], v[242:245], v[230:233], v[4:7]
	s_barrier
; #define LDA8(dst, b, h) _Pragma("unroll") for (int m = 0; m < 4; ++m) _Pragma("unroll") for (int k = 0; k < 2; ++k) \
;     dst[m][k] = *(const bf16x8*)((const char*)SA8(b, h) + lds_byte8(wr * 64 + m * 16 + fr, k * 32 + fq * 8))
; #define LDB8(dst, b, h) _Pragma("unroll") for (int n = 0; n < 2; ++n) _Pragma("unroll") for (int k = 0; k < 2; ++k) \
;     dst[n][k] = *(const bf16x8*)((const char*)SB8(b, h) + lds_byte8(wc * 32 + n * 16 + fr, k * 32 + fq * 8))
; #define WAIT_V8(n) asm volatile("s_waitcnt vmcnt(" #n ")" ::: "memory")
; #define WAIT_L8(n) asm volatile("s_waitcnt lgkmcnt(" #n ")" ::: "memory")
; #define BAR8 __builtin_amdgcn_s_barrier()
;     ...
;     LDB8(B1, 1, 1); WAIT_V8(0); BAR8; WAIT_L8(0); MMA8(0, 1, At, B1); BAR8;
;     LDA8(At, 1, 1); BAR8; WAIT_L8(0); MMA8(1, 0, At, B0); MMA8(1, 1, At, B1); BAR8; }
;   if (wr == 0) BAR8;
;   __syncthreads();
	ds_read_b128 v[132:135], v158
	ds_read_b128 v[168:171], v158 offset:1024
	ds_read_b128 v[206:209], v158 offset:2048
	ds_read_b128 v[210:213], v158 offset:3072
	s_waitcnt vmcnt(0)
	s_barrier
	s_waitcnt lgkmcnt(0)
	s_waitcnt lgkmcnt(0)
	v_mfma_f32_16x16x32_bf16 v[4:7], v[8:11], v[132:135], v[214:217]
	v_mfma_f32_16x16x32_bf16 v[8:11], v[8:11], v[206:209], v[174:177]
	v_mfma_f32_16x16x32_bf16 v[4:7], v[12:15], v[168:171], v[4:7]
	v_mfma_f32_16x16x32_bf16 v[20:23], v[12:15], v[210:213], v[8:11]
	v_mfma_f32_16x16x32_bf16 v[8:11], v[16:19], v[132:135], v[178:181]
	v_mfma_f32_16x16x32_bf16 v[12:15], v[16:19], v[206:209], v[182:185]
	v_mfma_f32_16x16x32_bf16 v[8:11], v[24:27], v[168:171], v[8:11]
	v_mfma_f32_16x16x32_bf16 v[24:27], v[24:27], v[210:213], v[12:15]
	v_mfma_f32_16x16x32_bf16 v[12:15], v[28:31], v[132:135], v[80:83]
	v_mfma_f32_16x16x32_bf16 v[16:19], v[28:31], v[206:209], v[76:79]
	v_mfma_f32_16x16x32_bf16 v[12:15], v[32:35], v[168:171], v[12:15]
	v_mfma_f32_16x16x32_bf16 v[28:31], v[32:35], v[210:213], v[16:19]
	v_mfma_f32_16x16x32_bf16 v[16:19], v[238:241], v[132:135], v[72:75]
	v_mfma_f32_16x16x32_bf16 v[32:35], v[238:241], v[206:209], v[68:71]
	v_mfma_f32_16x16x32_bf16 v[16:19], v[242:245], v[168:171], v[16:19]
	v_mfma_f32_16x16x32_bf16 v[32:35], v[242:245], v[210:213], v[32:35]
	s_barrier
	ds_read_b128 v[172:175], v156 offset:49152
	ds_read_b128 v[156:159], v156 offset:50176
	ds_read_b128 v[176:179], v155 offset:49152
	ds_read_b128 v[180:183], v155 offset:50176
	ds_read_b128 v[214:217], v154 offset:49152
	ds_read_b128 v[238:241], v154 offset:50176
	ds_read_b128 v[242:245], v153 offset:49152
	ds_read_b128 v[150:153], v153 offset:50176
	s_barrier
	s_waitcnt lgkmcnt(0)
	s_waitcnt lgkmcnt(0)
	v_mfma_f32_16x16x32_bf16 v[64:67], v[172:175], v[198:201], v[64:67]
	v_mfma_f32_16x16x32_bf16 v[60:63], v[172:175], v[226:229], v[60:63]
	v_mfma_f32_16x16x32_bf16 v[56:59], v[176:179], v[198:201], v[56:59]
	v_mfma_f32_16x16x32_bf16 v[52:55], v[176:179], v[226:229], v[52:55]
	v_mfma_f32_16x16x32_bf16 v[48:51], v[214:217], v[198:201], v[48:51]
	v_mfma_f32_16x16x32_bf16 v[44:47], v[214:217], v[226:229], v[44:47]
	v_mfma_f32_16x16x32_bf16 v[40:43], v[242:245], v[198:201], v[40:43]
	v_mfma_f32_16x16x32_bf16 v[36:39], v[242:245], v[226:229], v[36:39]
	v_mfma_f32_16x16x32_bf16 v[128:131], v[156:159], v[218:221], v[64:67]
	v_mfma_f32_16x16x32_bf16 v[124:127], v[156:159], v[230:233], v[60:63]
	v_mfma_f32_16x16x32_bf16 v[120:123], v[180:183], v[218:221], v[56:59]
	v_mfma_f32_16x16x32_bf16 v[112:115], v[180:183], v[230:233], v[52:55]
	v_mfma_f32_16x16x32_bf16 v[80:83], v[238:241], v[218:221], v[48:51]
	v_mfma_f32_16x16x32_bf16 v[76:79], v[238:241], v[230:233], v[44:47]
	v_mfma_f32_16x16x32_bf16 v[72:75], v[150:153], v[218:221], v[40:43]
	v_mfma_f32_16x16x32_bf16 v[68:71], v[150:153], v[230:233], v[36:39]
	v_mfma_f32_16x16x32_bf16 v[40:43], v[172:175], v[206:209], v[140:143]
	v_mfma_f32_16x16x32_bf16 v[44:47], v[176:179], v[206:209], v[164:167]
	v_mfma_f32_16x16x32_bf16 v[48:51], v[214:217], v[206:209], v[186:189]
	v_mfma_f32_16x16x32_bf16 v[36:39], v[172:175], v[132:135], v[136:139]
	v_mfma_f32_16x16x32_bf16 v[52:55], v[156:159], v[210:213], v[40:43]
	v_mfma_f32_16x16x32_bf16 v[40:43], v[176:179], v[132:135], v[160:163]
	v_mfma_f32_16x16x32_bf16 v[56:59], v[180:183], v[210:213], v[44:47]
	v_mfma_f32_16x16x32_bf16 v[44:47], v[214:217], v[132:135], v[202:205]
	v_mfma_f32_16x16x32_bf16 v[60:63], v[238:241], v[210:213], v[48:51]
	v_mfma_f32_16x16x32_bf16 v[48:51], v[242:245], v[132:135], v[190:193]
	v_mfma_f32_16x16x32_bf16 v[64:67], v[242:245], v[206:209], v[194:197]
	v_mfma_f32_16x16x32_bf16 v[36:39], v[156:159], v[168:171], v[36:39]
	v_mfma_f32_16x16x32_bf16 v[40:43], v[180:183], v[168:171], v[40:43]
	v_mfma_f32_16x16x32_bf16 v[44:47], v[238:241], v[168:171], v[44:47]
	v_mfma_f32_16x16x32_bf16 v[48:51], v[150:153], v[168:171], v[48:51]
	v_mfma_f32_16x16x32_bf16 v[64:67], v[150:153], v[210:213], v[64:67]
	s_movk_i32 s2, 0x100
	v_cmp_gt_u32_e32 vcc, s2, v3
	s_barrier
	s_and_saveexec_b64 s[2:3], vcc
	s_cbranch_execz .LBB0_1328
	s_barrier
